# v60 + K-loop LOAD segment: ds_read_b128 issued first, vmcnt+lgkmcnt waits merged (no s_nop changes)
# baseline (speedup 1.0000x reference)
.LBB0_297:
	ds_read_b128 v[150:153], v146
	ds_read_b128 v[154:157], v146 offset:1024
	ds_read_b128 v[158:161], v146 offset:2048
	ds_read_b128 v[162:165], v146 offset:3072
	ds_read_b128 v[166:169], v147
	ds_read_b128 v[170:173], v147 offset:1024
	ds_read_b128 v[174:177], v147 offset:2048
	ds_read_b128 v[178:181], v147 offset:3072
	ds_read_b128 v[182:185], v148
	ds_read_b128 v[186:189], v148 offset:1024
	ds_read_b128 v[190:193], v148 offset:2048
	ds_read_b128 v[194:197], v148 offset:3072
	ds_read_b128 v[198:201], v148 offset:4096
	ds_read_b128 v[206:209], v148 offset:5120
	ds_read_b128 v[210:213], v148 offset:6144
	ds_read_b128 v[214:217], v148 offset:7168
	s_add_u32 s47, s38, s46
	s_addc_u32 s66, s39, 0
	s_add_u32 s64, s47, 0x100
	s_addc_u32 s65, s66, 0
	s_and_b64 s[48:49], s[44:45], exec
	s_cselect_b32 s49, s70, s65
	s_cselect_b32 s48, s71, s64
	s_add_u32 s46, s36, s46
	s_addc_u32 s64, s37, 0
	s_add_u32 s46, s46, 0x100
	s_addc_u32 s64, s64, 0
	s_and_b64 s[44:45], s[44:45], exec
	s_cselect_b32 s65, s72, s64
	s_cselect_b32 s64, s73, s46
	s_add_u32 s68, s47, 0x10080
	s_addc_u32 s69, s66, 0
	s_add_i32 s83, s30, s2
	s_add_i32 m0, s16, 0xc000
	s_add_i32 s84, s16, 0xe000
	s_add_i32 s80, s83, 0x2000
	s_add_u32 s66, s64, 0x40000
	s_addc_u32 s67, s65, 0
	s_add_i32 s82, s31, s2
	s_add_i32 s81, s82, 0x2000
	s_add_i32 s79, 0, 0x18000
	s_add_i32 s78, 0, 0x1c000
	s_add_u32 s46, s48, 0x10000
	s_addc_u32 s47, s49, 0
	s_add_i32 s77, s79, s2
	s_add_i32 s75, s77, 0x2000
	s_add_u32 s44, s64, 0x40080
	s_addc_u32 s45, s65, 0
	s_add_i32 s76, s78, s2
	s_add_i32 s74, s76, 0x2000
	v_lshl_add_u64 v[202:203], s[68:69], 0, v[130:131]
	global_load_lds_dwordx4 v[202:203], off
	v_lshl_add_u64 v[202:203], s[68:69], 0, v[132:133]
	s_mov_b32 m0, s84
	s_nop 0
	global_load_lds_dwordx4 v[202:203], off
	s_waitcnt vmcnt(8) lgkmcnt(0)
	s_setprio 1
	s_barrier
	v_mfma_f32_16x16x32_bf16 v[126:129], v[150:153], v[182:185], v[126:129]
	v_mfma_f32_16x16x32_bf16 v[122:125], v[158:161], v[182:185], v[122:125]
	v_mfma_f32_16x16x32_bf16 v[118:121], v[150:153], v[190:193], v[118:121]
	v_mfma_f32_16x16x32_bf16 v[114:117], v[158:161], v[190:193], v[114:117]
	v_mfma_f32_16x16x32_bf16 v[102:105], v[150:153], v[198:201], v[102:105]
	v_mfma_f32_16x16x32_bf16 v[98:101], v[158:161], v[198:201], v[98:101]
	v_mfma_f32_16x16x32_bf16 v[86:89], v[150:153], v[210:213], v[86:89]
	v_mfma_f32_16x16x32_bf16 v[82:85], v[158:161], v[210:213], v[82:85]
	v_mfma_f32_16x16x32_bf16 v[126:129], v[154:157], v[186:189], v[126:129]
	v_mfma_f32_16x16x32_bf16 v[122:125], v[162:165], v[186:189], v[122:125]
	v_mfma_f32_16x16x32_bf16 v[118:121], v[154:157], v[194:197], v[118:121]
	v_mfma_f32_16x16x32_bf16 v[114:117], v[162:165], v[194:197], v[114:117]
	v_mfma_f32_16x16x32_bf16 v[102:105], v[154:157], v[206:209], v[102:105]
	v_mfma_f32_16x16x32_bf16 v[98:101], v[162:165], v[206:209], v[98:101]
	v_mfma_f32_16x16x32_bf16 v[86:89], v[154:157], v[214:217], v[86:89]
	v_mfma_f32_16x16x32_bf16 v[82:85], v[162:165], v[214:217], v[82:85]
	v_mfma_f32_16x16x32_bf16 v[110:113], v[166:169], v[182:185], v[110:113]
	v_mfma_f32_16x16x32_bf16 v[106:109], v[174:177], v[182:185], v[106:109]
	v_mfma_f32_16x16x32_bf16 v[94:97], v[166:169], v[190:193], v[94:97]
	v_mfma_f32_16x16x32_bf16 v[90:93], v[174:177], v[190:193], v[90:93]
	v_mfma_f32_16x16x32_bf16 v[78:81], v[166:169], v[198:201], v[78:81]
	v_mfma_f32_16x16x32_bf16 v[74:77], v[174:177], v[198:201], v[74:77]
	v_mfma_f32_16x16x32_bf16 v[70:73], v[166:169], v[210:213], v[70:73]
	v_mfma_f32_16x16x32_bf16 v[66:69], v[174:177], v[210:213], v[66:69]
	v_mfma_f32_16x16x32_bf16 v[110:113], v[170:173], v[186:189], v[110:113]
	v_mfma_f32_16x16x32_bf16 v[106:109], v[178:181], v[186:189], v[106:109]
	v_mfma_f32_16x16x32_bf16 v[94:97], v[170:173], v[194:197], v[94:97]
	v_mfma_f32_16x16x32_bf16 v[90:93], v[178:181], v[194:197], v[90:93]
	v_mfma_f32_16x16x32_bf16 v[78:81], v[170:173], v[206:209], v[78:81]
	v_mfma_f32_16x16x32_bf16 v[74:77], v[178:181], v[206:209], v[74:77]
	v_mfma_f32_16x16x32_bf16 v[70:73], v[170:173], v[214:217], v[70:73]
	v_mfma_f32_16x16x32_bf16 v[66:69], v[178:181], v[214:217], v[66:69]
	s_setprio 0
	s_barrier
	ds_read_b128 v[182:185], v148 offset:16384
	ds_read_b128 v[186:189], v148 offset:17408
	ds_read_b128 v[190:193], v148 offset:18432
	ds_read_b128 v[194:197], v148 offset:19456
	ds_read_b128 v[198:201], v148 offset:20480
	ds_read_b128 v[206:209], v148 offset:21504
	ds_read_b128 v[210:213], v148 offset:22528
	ds_read_b128 v[214:217], v148 offset:23552
	s_mov_b32 m0, s83
	v_lshl_add_u64 v[202:203], s[64:65], 0, v[136:137]
	global_load_lds_dwordx4 v[202:203], off
	v_lshl_add_u64 v[218:219], s[64:65], 0, v[134:135]
	s_mov_b32 m0, s80
	v_lshl_add_u64 v[220:221], s[66:67], 0, v[136:137]
	global_load_lds_dwordx4 v[218:219], off
	s_mov_b32 m0, s82
	v_lshl_add_u64 v[222:223], s[48:49], 0, v[132:133]
	global_load_lds_dwordx4 v[220:221], off
	v_lshl_add_u64 v[220:221], s[66:67], 0, v[134:135]
	s_mov_b32 m0, s81
	s_nop 0
	global_load_lds_dwordx4 v[220:221], off
	v_lshl_add_u64 v[220:221], s[48:49], 0, v[130:131]
	s_mov_b32 m0, s16
	s_nop 0
	global_load_lds_dwordx4 v[220:221], off
	s_mov_b32 m0, s17
	s_nop 0
	global_load_lds_dwordx4 v[222:223], off
	s_waitcnt vmcnt(8) lgkmcnt(0)
	s_setprio 1
	s_barrier
	v_mfma_f32_16x16x32_bf16 v[62:65], v[150:153], v[182:185], v[62:65]
	v_mfma_f32_16x16x32_bf16 v[58:61], v[158:161], v[182:185], v[58:61]
	v_mfma_f32_16x16x32_bf16 v[54:57], v[150:153], v[190:193], v[54:57]
	v_mfma_f32_16x16x32_bf16 v[50:53], v[158:161], v[190:193], v[50:53]
	v_mfma_f32_16x16x32_bf16 v[38:41], v[150:153], v[198:201], v[38:41]
	v_mfma_f32_16x16x32_bf16 v[34:37], v[158:161], v[198:201], v[34:37]
	v_mfma_f32_16x16x32_bf16 v[22:25], v[150:153], v[210:213], v[22:25]
	v_mfma_f32_16x16x32_bf16 v[18:21], v[158:161], v[210:213], v[18:21]
	v_mfma_f32_16x16x32_bf16 v[62:65], v[154:157], v[186:189], v[62:65]
	v_mfma_f32_16x16x32_bf16 v[58:61], v[162:165], v[186:189], v[58:61]
	v_mfma_f32_16x16x32_bf16 v[54:57], v[154:157], v[194:197], v[54:57]
	v_mfma_f32_16x16x32_bf16 v[50:53], v[162:165], v[194:197], v[50:53]
	v_mfma_f32_16x16x32_bf16 v[38:41], v[154:157], v[206:209], v[38:41]
	v_mfma_f32_16x16x32_bf16 v[34:37], v[162:165], v[206:209], v[34:37]
	v_mfma_f32_16x16x32_bf16 v[22:25], v[154:157], v[214:217], v[22:25]
	v_mfma_f32_16x16x32_bf16 v[18:21], v[162:165], v[214:217], v[18:21]
	v_mfma_f32_16x16x32_bf16 v[46:49], v[166:169], v[182:185], v[46:49]
	v_mfma_f32_16x16x32_bf16 v[42:45], v[174:177], v[182:185], v[42:45]
	v_mfma_f32_16x16x32_bf16 v[30:33], v[166:169], v[190:193], v[30:33]
	v_mfma_f32_16x16x32_bf16 v[26:29], v[174:177], v[190:193], v[26:29]
	v_mfma_f32_16x16x32_bf16 v[14:17], v[166:169], v[198:201], v[14:17]
	v_mfma_f32_16x16x32_bf16 v[10:13], v[174:177], v[198:201], v[10:13]
	v_mfma_f32_16x16x32_bf16 v[6:9], v[166:169], v[210:213], v[6:9]
	v_mfma_f32_16x16x32_bf16 v[2:5], v[174:177], v[210:213], v[2:5]
	v_mfma_f32_16x16x32_bf16 v[46:49], v[170:173], v[186:189], v[46:49]
	v_mfma_f32_16x16x32_bf16 v[42:45], v[178:181], v[186:189], v[42:45]
	v_mfma_f32_16x16x32_bf16 v[30:33], v[170:173], v[194:197], v[30:33]
	v_mfma_f32_16x16x32_bf16 v[26:29], v[178:181], v[194:197], v[26:29]
	v_mfma_f32_16x16x32_bf16 v[14:17], v[170:173], v[206:209], v[14:17]
	v_mfma_f32_16x16x32_bf16 v[10:13], v[178:181], v[206:209], v[10:13]
	v_mfma_f32_16x16x32_bf16 v[6:9], v[170:173], v[214:217], v[6:9]
	v_mfma_f32_16x16x32_bf16 v[2:5], v[178:181], v[214:217], v[2:5]
	s_setprio 0
	s_barrier
	v_add_u32_e32 v149, s79, v145
	ds_read_b128 v[150:153], v149
	ds_read_b128 v[154:157], v149 offset:1024
	ds_read_b128 v[158:161], v149 offset:2048
	ds_read_b128 v[162:165], v149 offset:3072
	v_add_u32_e32 v149, s78, v145
	ds_read_b128 v[166:169], v149
	ds_read_b128 v[170:173], v149 offset:1024
	ds_read_b128 v[174:177], v149 offset:2048
	ds_read_b128 v[178:181], v149 offset:3072
	s_mov_b32 m0, s18
	v_lshl_add_u64 v[224:225], s[46:47], 0, v[130:131]
	ds_read_b128 v[182:185], v148 offset:32768
	ds_read_b128 v[186:189], v148 offset:33792
	ds_read_b128 v[190:193], v148 offset:34816
	ds_read_b128 v[194:197], v148 offset:35840
	ds_read_b128 v[198:201], v148 offset:36864
	ds_read_b128 v[206:209], v148 offset:37888
	ds_read_b128 v[210:213], v148 offset:38912
	ds_read_b128 v[214:217], v148 offset:39936
	global_load_lds_dwordx4 v[224:225], off
	v_lshl_add_u64 v[224:225], s[46:47], 0, v[132:133]
	s_mov_b32 m0, s19
	s_nop 0
	global_load_lds_dwordx4 v[224:225], off
	s_waitcnt vmcnt(8) lgkmcnt(0)
	s_setprio 1
	s_barrier
	v_mfma_f32_16x16x32_bf16 v[126:129], v[150:153], v[182:185], v[126:129]
	v_mfma_f32_16x16x32_bf16 v[122:125], v[158:161], v[182:185], v[122:125]
	v_mfma_f32_16x16x32_bf16 v[118:121], v[150:153], v[190:193], v[118:121]
	v_mfma_f32_16x16x32_bf16 v[114:117], v[158:161], v[190:193], v[114:117]
	v_mfma_f32_16x16x32_bf16 v[102:105], v[150:153], v[198:201], v[102:105]
	v_mfma_f32_16x16x32_bf16 v[98:101], v[158:161], v[198:201], v[98:101]
	v_mfma_f32_16x16x32_bf16 v[86:89], v[150:153], v[210:213], v[86:89]
	v_mfma_f32_16x16x32_bf16 v[82:85], v[158:161], v[210:213], v[82:85]
	v_mfma_f32_16x16x32_bf16 v[126:129], v[154:157], v[186:189], v[126:129]
	v_mfma_f32_16x16x32_bf16 v[122:125], v[162:165], v[186:189], v[122:125]
	v_mfma_f32_16x16x32_bf16 v[118:121], v[154:157], v[194:197], v[118:121]
	v_mfma_f32_16x16x32_bf16 v[114:117], v[162:165], v[194:197], v[114:117]
	v_mfma_f32_16x16x32_bf16 v[102:105], v[154:157], v[206:209], v[102:105]
	v_mfma_f32_16x16x32_bf16 v[98:101], v[162:165], v[206:209], v[98:101]
	v_mfma_f32_16x16x32_bf16 v[86:89], v[154:157], v[214:217], v[86:89]
	v_mfma_f32_16x16x32_bf16 v[82:85], v[162:165], v[214:217], v[82:85]
	v_mfma_f32_16x16x32_bf16 v[110:113], v[166:169], v[182:185], v[110:113]
	v_mfma_f32_16x16x32_bf16 v[106:109], v[174:177], v[182:185], v[106:109]
	v_mfma_f32_16x16x32_bf16 v[94:97], v[166:169], v[190:193], v[94:97]
	v_mfma_f32_16x16x32_bf16 v[90:93], v[174:177], v[190:193], v[90:93]
	v_mfma_f32_16x16x32_bf16 v[78:81], v[166:169], v[198:201], v[78:81]
	v_mfma_f32_16x16x32_bf16 v[74:77], v[174:177], v[198:201], v[74:77]
	v_mfma_f32_16x16x32_bf16 v[70:73], v[166:169], v[210:213], v[70:73]
	v_mfma_f32_16x16x32_bf16 v[66:69], v[174:177], v[210:213], v[66:69]
	v_mfma_f32_16x16x32_bf16 v[110:113], v[170:173], v[186:189], v[110:113]
	v_mfma_f32_16x16x32_bf16 v[106:109], v[178:181], v[186:189], v[106:109]
	v_mfma_f32_16x16x32_bf16 v[94:97], v[170:173], v[194:197], v[94:97]
	v_mfma_f32_16x16x32_bf16 v[90:93], v[178:181], v[194:197], v[90:93]
	v_mfma_f32_16x16x32_bf16 v[78:81], v[170:173], v[206:209], v[78:81]
	v_mfma_f32_16x16x32_bf16 v[74:77], v[178:181], v[206:209], v[74:77]
	v_mfma_f32_16x16x32_bf16 v[70:73], v[170:173], v[214:217], v[70:73]
	v_mfma_f32_16x16x32_bf16 v[66:69], v[178:181], v[214:217], v[66:69]
	s_setprio 0
	s_barrier
	ds_read_b128 v[182:185], v148 offset:49152
	ds_read_b128 v[186:189], v148 offset:50176
	ds_read_b128 v[190:193], v148 offset:51200
	ds_read_b128 v[194:197], v148 offset:52224
	ds_read_b128 v[198:201], v148 offset:53248
	ds_read_b128 v[206:209], v148 offset:54272
	ds_read_b128 v[210:213], v148 offset:55296
	ds_read_b128 v[214:217], v148 offset:56320
	s_mov_b32 m0, s77
	v_lshl_add_u64 v[202:203], v[202:203], 0, s[8:9]
	global_load_lds_dwordx4 v[202:203], off
	v_lshl_add_u64 v[202:203], v[218:219], 0, s[8:9]
	s_mov_b32 m0, s75
	s_nop 0
	global_load_lds_dwordx4 v[202:203], off
	v_lshl_add_u64 v[202:203], s[44:45], 0, v[136:137]
	s_mov_b32 m0, s76
	s_nop 0
	global_load_lds_dwordx4 v[202:203], off
	v_lshl_add_u64 v[202:203], s[44:45], 0, v[134:135]
	s_mov_b32 m0, s74
	s_nop 0
	global_load_lds_dwordx4 v[202:203], off
	v_lshl_add_u64 v[202:203], v[220:221], 0, s[8:9]
	s_mov_b32 m0, s28
	s_nop 0
	global_load_lds_dwordx4 v[202:203], off
	v_lshl_add_u64 v[202:203], v[222:223], 0, s[8:9]
	s_mov_b32 m0, s29
	s_nop 0
	global_load_lds_dwordx4 v[202:203], off
	s_waitcnt vmcnt(8) lgkmcnt(0)
	s_setprio 1
	s_barrier
	v_mfma_f32_16x16x32_bf16 v[62:65], v[150:153], v[182:185], v[62:65]
	v_mfma_f32_16x16x32_bf16 v[58:61], v[158:161], v[182:185], v[58:61]
	v_mfma_f32_16x16x32_bf16 v[54:57], v[150:153], v[190:193], v[54:57]
	v_mfma_f32_16x16x32_bf16 v[50:53], v[158:161], v[190:193], v[50:53]
	v_mfma_f32_16x16x32_bf16 v[38:41], v[150:153], v[198:201], v[38:41]
	v_mfma_f32_16x16x32_bf16 v[34:37], v[158:161], v[198:201], v[34:37]
	v_mfma_f32_16x16x32_bf16 v[22:25], v[150:153], v[210:213], v[22:25]
	v_mfma_f32_16x16x32_bf16 v[18:21], v[158:161], v[210:213], v[18:21]
	v_mfma_f32_16x16x32_bf16 v[62:65], v[154:157], v[186:189], v[62:65]
	v_mfma_f32_16x16x32_bf16 v[58:61], v[162:165], v[186:189], v[58:61]
	v_mfma_f32_16x16x32_bf16 v[54:57], v[154:157], v[194:197], v[54:57]
	v_mfma_f32_16x16x32_bf16 v[50:53], v[162:165], v[194:197], v[50:53]
	v_mfma_f32_16x16x32_bf16 v[38:41], v[154:157], v[206:209], v[38:41]
	v_mfma_f32_16x16x32_bf16 v[34:37], v[162:165], v[206:209], v[34:37]
	v_mfma_f32_16x16x32_bf16 v[22:25], v[154:157], v[214:217], v[22:25]
	v_mfma_f32_16x16x32_bf16 v[18:21], v[162:165], v[214:217], v[18:21]
	v_mfma_f32_16x16x32_bf16 v[46:49], v[166:169], v[182:185], v[46:49]
	v_mfma_f32_16x16x32_bf16 v[42:45], v[174:177], v[182:185], v[42:45]
	v_mfma_f32_16x16x32_bf16 v[30:33], v[166:169], v[190:193], v[30:33]
	v_mfma_f32_16x16x32_bf16 v[26:29], v[174:177], v[190:193], v[26:29]
	v_mfma_f32_16x16x32_bf16 v[14:17], v[166:169], v[198:201], v[14:17]
	v_mfma_f32_16x16x32_bf16 v[10:13], v[174:177], v[198:201], v[10:13]
	v_mfma_f32_16x16x32_bf16 v[6:9], v[166:169], v[210:213], v[6:9]
	v_mfma_f32_16x16x32_bf16 v[2:5], v[174:177], v[210:213], v[2:5]
	v_mfma_f32_16x16x32_bf16 v[46:49], v[170:173], v[186:189], v[46:49]
	v_mfma_f32_16x16x32_bf16 v[42:45], v[178:181], v[186:189], v[42:45]
	v_mfma_f32_16x16x32_bf16 v[30:33], v[170:173], v[194:197], v[30:33]
	v_mfma_f32_16x16x32_bf16 v[26:29], v[178:181], v[194:197], v[26:29]
	v_mfma_f32_16x16x32_bf16 v[14:17], v[170:173], v[206:209], v[14:17]
	v_mfma_f32_16x16x32_bf16 v[10:13], v[178:181], v[206:209], v[10:13]
	v_mfma_f32_16x16x32_bf16 v[6:9], v[170:173], v[214:217], v[6:9]
	v_mfma_f32_16x16x32_bf16 v[2:5], v[178:181], v[214:217], v[2:5]
	s_setprio 0
	s_barrier
	s_movk_i32 s46, 0x100
	s_andn2_b64 vcc, exec, s[42:43]
	s_mov_b64 s[44:45], -1
	s_mov_b64 s[42:43], 0
	s_cbranch_vccz .LBB0_297
	s_and_b64 vcc, exec, s[10:11]
	s_cbranch_vccz .LBB0_300
	s_barrier

.LBB0_313:
	ds_read_b128 v[144:147], v140
	ds_read_b128 v[148:151], v140 offset:1024
	ds_read_b128 v[152:155], v140 offset:2048
	ds_read_b128 v[156:159], v140 offset:3072
	ds_read_b128 v[160:163], v141
	ds_read_b128 v[164:167], v141 offset:1024
	ds_read_b128 v[168:171], v141 offset:2048
	ds_read_b128 v[172:175], v141 offset:3072
	ds_read_b128 v[176:179], v142
	ds_read_b128 v[180:183], v142 offset:1024
	ds_read_b128 v[184:187], v142 offset:2048
	ds_read_b128 v[188:191], v142 offset:3072
	ds_read_b128 v[192:195], v142 offset:4096
	ds_read_b128 v[196:199], v142 offset:5120
	ds_read_b128 v[200:203], v142 offset:6144
	ds_read_b128 v[206:209], v142 offset:7168
	s_add_u32 s49, s38, s48
	s_addc_u32 s68, s39, 0
	s_add_u32 s66, s49, 0x100
	s_addc_u32 s67, s68, 0
	s_and_b64 s[64:65], s[46:47], exec
	s_cselect_b32 s65, s43, s67
	s_cselect_b32 s64, s75, s66
	s_add_u32 s48, s36, s48
	s_addc_u32 s66, s37, 0
	s_add_u32 s48, s48, 0x100
	s_addc_u32 s66, s66, 0
	s_and_b64 s[46:47], s[46:47], exec
	s_cselect_b32 s67, s76, s66
	s_cselect_b32 s66, s77, s48
	s_add_u32 s70, s49, 0x10080
	s_addc_u32 s71, s68, 0
	s_add_i32 s87, s33, s2
	s_add_i32 m0, s16, 0xc000
	s_add_i32 s88, s16, 0xe000
	s_add_i32 s84, s87, 0x2000
	s_add_u32 s68, s66, 0x1000
	s_addc_u32 s69, s67, 0
	s_add_i32 s86, s34, s2
	s_add_i32 s85, s86, 0x2000
	s_add_i32 s83, 0, 0x18000
	s_add_i32 s82, 0, 0x1c000
	s_add_u32 s48, s64, 0x10000
	s_addc_u32 s49, s65, 0
	s_add_i32 s81, s83, s2
	s_add_i32 s79, s81, 0x2000
	s_add_u32 s46, s66, 0x1080
	s_addc_u32 s47, s67, 0
	s_add_i32 s80, s82, s2
	s_add_i32 s78, s80, 0x2000
	v_lshl_add_u64 v[210:211], s[70:71], 0, v[130:131]
	global_load_lds_dwordx4 v[210:211], off
	v_lshl_add_u64 v[210:211], s[70:71], 0, v[132:133]
	s_mov_b32 m0, s88
	s_nop 0
	global_load_lds_dwordx4 v[210:211], off
	s_waitcnt vmcnt(8) lgkmcnt(0)
	s_setprio 1
	s_barrier
	v_mfma_f32_16x16x32_bf16 v[126:129], v[144:147], v[176:179], v[126:129]
	v_mfma_f32_16x16x32_bf16 v[122:125], v[152:155], v[176:179], v[122:125]
	v_mfma_f32_16x16x32_bf16 v[118:121], v[144:147], v[184:187], v[118:121]
	v_mfma_f32_16x16x32_bf16 v[114:117], v[152:155], v[184:187], v[114:117]
	v_mfma_f32_16x16x32_bf16 v[102:105], v[144:147], v[192:195], v[102:105]
	v_mfma_f32_16x16x32_bf16 v[98:101], v[152:155], v[192:195], v[98:101]
	v_mfma_f32_16x16x32_bf16 v[86:89], v[144:147], v[200:203], v[86:89]
	v_mfma_f32_16x16x32_bf16 v[82:85], v[152:155], v[200:203], v[82:85]
	v_mfma_f32_16x16x32_bf16 v[126:129], v[148:151], v[180:183], v[126:129]
	v_mfma_f32_16x16x32_bf16 v[122:125], v[156:159], v[180:183], v[122:125]
	v_mfma_f32_16x16x32_bf16 v[118:121], v[148:151], v[188:191], v[118:121]
	v_mfma_f32_16x16x32_bf16 v[114:117], v[156:159], v[188:191], v[114:117]
	v_mfma_f32_16x16x32_bf16 v[102:105], v[148:151], v[196:199], v[102:105]
	v_mfma_f32_16x16x32_bf16 v[98:101], v[156:159], v[196:199], v[98:101]
	v_mfma_f32_16x16x32_bf16 v[86:89], v[148:151], v[206:209], v[86:89]
	v_mfma_f32_16x16x32_bf16 v[82:85], v[156:159], v[206:209], v[82:85]
	v_mfma_f32_16x16x32_bf16 v[110:113], v[160:163], v[176:179], v[110:113]
	v_mfma_f32_16x16x32_bf16 v[106:109], v[168:171], v[176:179], v[106:109]
	v_mfma_f32_16x16x32_bf16 v[94:97], v[160:163], v[184:187], v[94:97]
	v_mfma_f32_16x16x32_bf16 v[90:93], v[168:171], v[184:187], v[90:93]
	v_mfma_f32_16x16x32_bf16 v[78:81], v[160:163], v[192:195], v[78:81]
	v_mfma_f32_16x16x32_bf16 v[74:77], v[168:171], v[192:195], v[74:77]
	v_mfma_f32_16x16x32_bf16 v[70:73], v[160:163], v[200:203], v[70:73]
	v_mfma_f32_16x16x32_bf16 v[66:69], v[168:171], v[200:203], v[66:69]
	v_mfma_f32_16x16x32_bf16 v[110:113], v[164:167], v[180:183], v[110:113]
	v_mfma_f32_16x16x32_bf16 v[106:109], v[172:175], v[180:183], v[106:109]
	v_mfma_f32_16x16x32_bf16 v[94:97], v[164:167], v[188:191], v[94:97]
	v_mfma_f32_16x16x32_bf16 v[90:93], v[172:175], v[188:191], v[90:93]
	v_mfma_f32_16x16x32_bf16 v[78:81], v[164:167], v[196:199], v[78:81]
	v_mfma_f32_16x16x32_bf16 v[74:77], v[172:175], v[196:199], v[74:77]
	v_mfma_f32_16x16x32_bf16 v[70:73], v[164:167], v[206:209], v[70:73]
	v_mfma_f32_16x16x32_bf16 v[66:69], v[172:175], v[206:209], v[66:69]
	s_setprio 0
	s_barrier
	ds_read_b128 v[176:179], v142 offset:16384
	ds_read_b128 v[180:183], v142 offset:17408
	ds_read_b128 v[184:187], v142 offset:18432
	ds_read_b128 v[188:191], v142 offset:19456
	ds_read_b128 v[192:195], v142 offset:20480
	ds_read_b128 v[196:199], v142 offset:21504
	ds_read_b128 v[200:203], v142 offset:22528
	ds_read_b128 v[206:209], v142 offset:23552
	s_mov_b32 m0, s87
	v_lshl_add_u64 v[210:211], s[66:67], 0, v[136:137]
	global_load_lds_dwordx4 v[210:211], off
	v_lshl_add_u64 v[212:213], s[66:67], 0, v[134:135]
	s_mov_b32 m0, s84
	v_lshl_add_u64 v[214:215], s[68:69], 0, v[136:137]
	global_load_lds_dwordx4 v[212:213], off
	s_mov_b32 m0, s86
	v_lshl_add_u64 v[216:217], s[64:65], 0, v[132:133]
	global_load_lds_dwordx4 v[214:215], off
	v_lshl_add_u64 v[214:215], s[68:69], 0, v[134:135]
	s_mov_b32 m0, s85
	s_nop 0
	global_load_lds_dwordx4 v[214:215], off
	v_lshl_add_u64 v[214:215], s[64:65], 0, v[130:131]
	s_mov_b32 m0, s16
	s_nop 0
	global_load_lds_dwordx4 v[214:215], off
	s_mov_b32 m0, s17
	s_nop 0
	global_load_lds_dwordx4 v[216:217], off
	s_waitcnt vmcnt(8) lgkmcnt(0)
	s_setprio 1
	s_barrier
	v_mfma_f32_16x16x32_bf16 v[62:65], v[144:147], v[176:179], v[62:65]
	v_mfma_f32_16x16x32_bf16 v[58:61], v[152:155], v[176:179], v[58:61]
	v_mfma_f32_16x16x32_bf16 v[54:57], v[144:147], v[184:187], v[54:57]
	v_mfma_f32_16x16x32_bf16 v[50:53], v[152:155], v[184:187], v[50:53]
	v_mfma_f32_16x16x32_bf16 v[38:41], v[144:147], v[192:195], v[38:41]
	v_mfma_f32_16x16x32_bf16 v[34:37], v[152:155], v[192:195], v[34:37]
	v_mfma_f32_16x16x32_bf16 v[22:25], v[144:147], v[200:203], v[22:25]
	v_mfma_f32_16x16x32_bf16 v[18:21], v[152:155], v[200:203], v[18:21]
	v_mfma_f32_16x16x32_bf16 v[62:65], v[148:151], v[180:183], v[62:65]
	v_mfma_f32_16x16x32_bf16 v[58:61], v[156:159], v[180:183], v[58:61]
	v_mfma_f32_16x16x32_bf16 v[54:57], v[148:151], v[188:191], v[54:57]
	v_mfma_f32_16x16x32_bf16 v[50:53], v[156:159], v[188:191], v[50:53]
	v_mfma_f32_16x16x32_bf16 v[38:41], v[148:151], v[196:199], v[38:41]
	v_mfma_f32_16x16x32_bf16 v[34:37], v[156:159], v[196:199], v[34:37]
	v_mfma_f32_16x16x32_bf16 v[22:25], v[148:151], v[206:209], v[22:25]
	v_mfma_f32_16x16x32_bf16 v[18:21], v[156:159], v[206:209], v[18:21]
	v_mfma_f32_16x16x32_bf16 v[46:49], v[160:163], v[176:179], v[46:49]
	v_mfma_f32_16x16x32_bf16 v[42:45], v[168:171], v[176:179], v[42:45]
	v_mfma_f32_16x16x32_bf16 v[30:33], v[160:163], v[184:187], v[30:33]
	v_mfma_f32_16x16x32_bf16 v[26:29], v[168:171], v[184:187], v[26:29]
	v_mfma_f32_16x16x32_bf16 v[14:17], v[160:163], v[192:195], v[14:17]
	v_mfma_f32_16x16x32_bf16 v[10:13], v[168:171], v[192:195], v[10:13]
	v_mfma_f32_16x16x32_bf16 v[6:9], v[160:163], v[200:203], v[6:9]
	v_mfma_f32_16x16x32_bf16 v[2:5], v[168:171], v[200:203], v[2:5]
	v_mfma_f32_16x16x32_bf16 v[46:49], v[164:167], v[180:183], v[46:49]
	v_mfma_f32_16x16x32_bf16 v[42:45], v[172:175], v[180:183], v[42:45]
	v_mfma_f32_16x16x32_bf16 v[30:33], v[164:167], v[188:191], v[30:33]
	v_mfma_f32_16x16x32_bf16 v[26:29], v[172:175], v[188:191], v[26:29]
	v_mfma_f32_16x16x32_bf16 v[14:17], v[164:167], v[196:199], v[14:17]
	v_mfma_f32_16x16x32_bf16 v[10:13], v[172:175], v[196:199], v[10:13]
	v_mfma_f32_16x16x32_bf16 v[6:9], v[164:167], v[206:209], v[6:9]
	v_mfma_f32_16x16x32_bf16 v[2:5], v[172:175], v[206:209], v[2:5]
	s_setprio 0
	s_barrier
	v_add_u32_e32 v143, s83, v139
	ds_read_b128 v[144:147], v143
	ds_read_b128 v[148:151], v143 offset:1024
	ds_read_b128 v[152:155], v143 offset:2048
	ds_read_b128 v[156:159], v143 offset:3072
	v_add_u32_e32 v143, s82, v139
	ds_read_b128 v[160:163], v143
	ds_read_b128 v[164:167], v143 offset:1024
	ds_read_b128 v[168:171], v143 offset:2048
	ds_read_b128 v[172:175], v143 offset:3072
	s_mov_b32 m0, s18
	v_lshl_add_u64 v[218:219], s[48:49], 0, v[130:131]
	ds_read_b128 v[176:179], v142 offset:32768
	ds_read_b128 v[180:183], v142 offset:33792
	ds_read_b128 v[184:187], v142 offset:34816
	ds_read_b128 v[188:191], v142 offset:35840
	ds_read_b128 v[192:195], v142 offset:36864
	ds_read_b128 v[196:199], v142 offset:37888
	ds_read_b128 v[200:203], v142 offset:38912
	ds_read_b128 v[206:209], v142 offset:39936
	global_load_lds_dwordx4 v[218:219], off
	v_lshl_add_u64 v[218:219], s[48:49], 0, v[132:133]
	s_mov_b32 m0, s19
	s_nop 0
	global_load_lds_dwordx4 v[218:219], off
	s_waitcnt vmcnt(8) lgkmcnt(0)
	s_setprio 1
	s_barrier
	v_mfma_f32_16x16x32_bf16 v[126:129], v[144:147], v[176:179], v[126:129]
	v_mfma_f32_16x16x32_bf16 v[122:125], v[152:155], v[176:179], v[122:125]
	v_mfma_f32_16x16x32_bf16 v[118:121], v[144:147], v[184:187], v[118:121]
	v_mfma_f32_16x16x32_bf16 v[114:117], v[152:155], v[184:187], v[114:117]
	v_mfma_f32_16x16x32_bf16 v[102:105], v[144:147], v[192:195], v[102:105]
	v_mfma_f32_16x16x32_bf16 v[98:101], v[152:155], v[192:195], v[98:101]
	v_mfma_f32_16x16x32_bf16 v[86:89], v[144:147], v[200:203], v[86:89]
	v_mfma_f32_16x16x32_bf16 v[82:85], v[152:155], v[200:203], v[82:85]
	v_mfma_f32_16x16x32_bf16 v[126:129], v[148:151], v[180:183], v[126:129]
	v_mfma_f32_16x16x32_bf16 v[122:125], v[156:159], v[180:183], v[122:125]
	v_mfma_f32_16x16x32_bf16 v[118:121], v[148:151], v[188:191], v[118:121]
	v_mfma_f32_16x16x32_bf16 v[114:117], v[156:159], v[188:191], v[114:117]
	v_mfma_f32_16x16x32_bf16 v[102:105], v[148:151], v[196:199], v[102:105]
	v_mfma_f32_16x16x32_bf16 v[98:101], v[156:159], v[196:199], v[98:101]
	v_mfma_f32_16x16x32_bf16 v[86:89], v[148:151], v[206:209], v[86:89]
	v_mfma_f32_16x16x32_bf16 v[82:85], v[156:159], v[206:209], v[82:85]
	v_mfma_f32_16x16x32_bf16 v[110:113], v[160:163], v[176:179], v[110:113]
	v_mfma_f32_16x16x32_bf16 v[106:109], v[168:171], v[176:179], v[106:109]
	v_mfma_f32_16x16x32_bf16 v[94:97], v[160:163], v[184:187], v[94:97]
	v_mfma_f32_16x16x32_bf16 v[90:93], v[168:171], v[184:187], v[90:93]
	v_mfma_f32_16x16x32_bf16 v[78:81], v[160:163], v[192:195], v[78:81]
	v_mfma_f32_16x16x32_bf16 v[74:77], v[168:171], v[192:195], v[74:77]
	v_mfma_f32_16x16x32_bf16 v[70:73], v[160:163], v[200:203], v[70:73]
	v_mfma_f32_16x16x32_bf16 v[66:69], v[168:171], v[200:203], v[66:69]
	v_mfma_f32_16x16x32_bf16 v[110:113], v[164:167], v[180:183], v[110:113]
	v_mfma_f32_16x16x32_bf16 v[106:109], v[172:175], v[180:183], v[106:109]
	v_mfma_f32_16x16x32_bf16 v[94:97], v[164:167], v[188:191], v[94:97]
	v_mfma_f32_16x16x32_bf16 v[90:93], v[172:175], v[188:191], v[90:93]
	v_mfma_f32_16x16x32_bf16 v[78:81], v[164:167], v[196:199], v[78:81]
	v_mfma_f32_16x16x32_bf16 v[74:77], v[172:175], v[196:199], v[74:77]
	v_mfma_f32_16x16x32_bf16 v[70:73], v[164:167], v[206:209], v[70:73]
	v_mfma_f32_16x16x32_bf16 v[66:69], v[172:175], v[206:209], v[66:69]
	s_setprio 0
	s_barrier
	ds_read_b128 v[176:179], v142 offset:49152
	ds_read_b128 v[180:183], v142 offset:50176
	ds_read_b128 v[184:187], v142 offset:51200
	ds_read_b128 v[188:191], v142 offset:52224
	ds_read_b128 v[192:195], v142 offset:53248
	ds_read_b128 v[196:199], v142 offset:54272
	ds_read_b128 v[200:203], v142 offset:55296
	ds_read_b128 v[206:209], v142 offset:56320
	s_mov_b32 m0, s81
	v_lshl_add_u64 v[210:211], v[210:211], 0, s[8:9]
	global_load_lds_dwordx4 v[210:211], off
	v_lshl_add_u64 v[210:211], v[212:213], 0, s[8:9]
	s_mov_b32 m0, s79
	s_nop 0
	global_load_lds_dwordx4 v[210:211], off
	v_lshl_add_u64 v[210:211], s[46:47], 0, v[136:137]
	s_mov_b32 m0, s80
	s_nop 0
	global_load_lds_dwordx4 v[210:211], off
	v_lshl_add_u64 v[210:211], s[46:47], 0, v[134:135]
	s_mov_b32 m0, s78
	s_nop 0
	global_load_lds_dwordx4 v[210:211], off
	v_lshl_add_u64 v[210:211], v[214:215], 0, s[8:9]
	s_mov_b32 m0, s30
	s_nop 0
	global_load_lds_dwordx4 v[210:211], off
	v_lshl_add_u64 v[210:211], v[216:217], 0, s[8:9]
	s_mov_b32 m0, s31
	s_nop 0
	global_load_lds_dwordx4 v[210:211], off
	s_waitcnt vmcnt(8) lgkmcnt(0)
	s_setprio 1
	s_barrier
	v_mfma_f32_16x16x32_bf16 v[62:65], v[144:147], v[176:179], v[62:65]
	v_mfma_f32_16x16x32_bf16 v[58:61], v[152:155], v[176:179], v[58:61]
	v_mfma_f32_16x16x32_bf16 v[54:57], v[144:147], v[184:187], v[54:57]
	v_mfma_f32_16x16x32_bf16 v[50:53], v[152:155], v[184:187], v[50:53]
	v_mfma_f32_16x16x32_bf16 v[38:41], v[144:147], v[192:195], v[38:41]
	v_mfma_f32_16x16x32_bf16 v[34:37], v[152:155], v[192:195], v[34:37]
	v_mfma_f32_16x16x32_bf16 v[22:25], v[144:147], v[200:203], v[22:25]
	v_mfma_f32_16x16x32_bf16 v[18:21], v[152:155], v[200:203], v[18:21]
	v_mfma_f32_16x16x32_bf16 v[62:65], v[148:151], v[180:183], v[62:65]
	v_mfma_f32_16x16x32_bf16 v[58:61], v[156:159], v[180:183], v[58:61]
	v_mfma_f32_16x16x32_bf16 v[54:57], v[148:151], v[188:191], v[54:57]
	v_mfma_f32_16x16x32_bf16 v[50:53], v[156:159], v[188:191], v[50:53]
	v_mfma_f32_16x16x32_bf16 v[38:41], v[148:151], v[196:199], v[38:41]
	v_mfma_f32_16x16x32_bf16 v[34:37], v[156:159], v[196:199], v[34:37]
	v_mfma_f32_16x16x32_bf16 v[22:25], v[148:151], v[206:209], v[22:25]
	v_mfma_f32_16x16x32_bf16 v[18:21], v[156:159], v[206:209], v[18:21]
	v_mfma_f32_16x16x32_bf16 v[46:49], v[160:163], v[176:179], v[46:49]
	v_mfma_f32_16x16x32_bf16 v[42:45], v[168:171], v[176:179], v[42:45]
	v_mfma_f32_16x16x32_bf16 v[30:33], v[160:163], v[184:187], v[30:33]
	v_mfma_f32_16x16x32_bf16 v[26:29], v[168:171], v[184:187], v[26:29]
	v_mfma_f32_16x16x32_bf16 v[14:17], v[160:163], v[192:195], v[14:17]
	v_mfma_f32_16x16x32_bf16 v[10:13], v[168:171], v[192:195], v[10:13]
	v_mfma_f32_16x16x32_bf16 v[6:9], v[160:163], v[200:203], v[6:9]
	v_mfma_f32_16x16x32_bf16 v[2:5], v[168:171], v[200:203], v[2:5]
	v_mfma_f32_16x16x32_bf16 v[46:49], v[164:167], v[180:183], v[46:49]
	v_mfma_f32_16x16x32_bf16 v[42:45], v[172:175], v[180:183], v[42:45]
	v_mfma_f32_16x16x32_bf16 v[30:33], v[164:167], v[188:191], v[30:33]
	v_mfma_f32_16x16x32_bf16 v[26:29], v[172:175], v[188:191], v[26:29]
	v_mfma_f32_16x16x32_bf16 v[14:17], v[164:167], v[196:199], v[14:17]
	v_mfma_f32_16x16x32_bf16 v[10:13], v[172:175], v[196:199], v[10:13]
	v_mfma_f32_16x16x32_bf16 v[6:9], v[164:167], v[206:209], v[6:9]
	v_mfma_f32_16x16x32_bf16 v[2:5], v[172:175], v[206:209], v[2:5]
	s_setprio 0
	s_barrier
	s_movk_i32 s48, 0x100
	s_andn2_b64 vcc, exec, s[44:45]
	s_mov_b64 s[46:47], -1
	s_mov_b64 s[44:45], 0
	s_cbranch_vccz .LBB0_313
	s_and_b64 vcc, exec, s[10:11]
	s_cbranch_vccz .LBB0_316
	s_barrier

.LBB0_383:
	s_add_u32 s26, s0, s22
	s_addc_u32 s27, s1, s23
	s_and_b64 s[44:45], s[36:37], exec
	s_cselect_b32 s15, s27, s43
	s_cselect_b32 s39, s26, s42
	s_add_u32 s66, s42, 0x100
	s_addc_u32 s67, s43, 0
	s_mov_b32 s68, -2
	s_mov_b64 s[42:43], 0
	ds_read_b128 v[152:155], v146
	ds_read_b128 v[156:159], v146 offset:1024
	ds_read_b128 v[160:163], v146 offset:2048
	ds_read_b128 v[164:167], v146 offset:3072
	ds_read_b128 v[168:171], v147
	ds_read_b128 v[172:175], v147 offset:1024
	ds_read_b128 v[176:179], v147 offset:2048
	ds_read_b128 v[180:183], v147 offset:3072
	ds_read_b128 v[184:187], v148
	ds_read_b128 v[188:191], v148 offset:1024
	ds_read_b128 v[192:195], v148 offset:2048
	ds_read_b128 v[196:199], v148 offset:3072
	ds_read_b128 v[200:203], v148 offset:4096
	ds_read_b128 v[206:209], v148 offset:5120
	ds_read_b128 v[210:213], v148 offset:6144
	ds_read_b128 v[214:217], v148 offset:7168
	s_add_u32 s44, s42, 0x100
	s_addc_u32 s45, s43, 0
	s_add_u32 s46, s66, s42
	s_addc_u32 s47, s67, s43
	s_cmp_eq_u32 s68, 4
	s_cselect_b32 s48, 0, s44
	s_cselect_b32 s49, 0, s45
	s_cselect_b32 s46, s39, s46
	s_cselect_b32 s47, s15, s47
	s_add_u32 s48, s6, s48
	s_addc_u32 s49, s7, s49
	s_mov_b32 m0, s29
	v_lshl_add_u64 v[218:219], v[138:139], 0, s[42:43]
	global_load_lds_dwordx4 v[218:219], off
	v_lshl_add_u64 v[218:219], v[140:141], 0, s[42:43]
	s_mov_b32 m0, s30
	s_nop 0
	global_load_lds_dwordx4 v[218:219], off
	s_waitcnt vmcnt(8) lgkmcnt(0)
	s_setprio 1
	s_barrier
	v_mfma_f32_16x16x32_bf16 v[126:129], v[152:155], v[184:187], 0
	v_mfma_f32_16x16x32_bf16 v[122:125], v[160:163], v[184:187], 0
	v_mfma_f32_16x16x32_bf16 v[118:121], v[152:155], v[192:195], 0
	v_mfma_f32_16x16x32_bf16 v[114:117], v[160:163], v[192:195], 0
	v_mfma_f32_16x16x32_bf16 v[102:105], v[152:155], v[200:203], 0
	v_mfma_f32_16x16x32_bf16 v[98:101], v[160:163], v[200:203], 0
	v_mfma_f32_16x16x32_bf16 v[86:89], v[152:155], v[210:213], 0
	v_mfma_f32_16x16x32_bf16 v[82:85], v[160:163], v[210:213], 0
	v_mfma_f32_16x16x32_bf16 v[126:129], v[156:159], v[188:191], v[126:129]
	v_mfma_f32_16x16x32_bf16 v[122:125], v[164:167], v[188:191], v[122:125]
	v_mfma_f32_16x16x32_bf16 v[118:121], v[156:159], v[196:199], v[118:121]
	v_mfma_f32_16x16x32_bf16 v[114:117], v[164:167], v[196:199], v[114:117]
	v_mfma_f32_16x16x32_bf16 v[102:105], v[156:159], v[206:209], v[102:105]
	v_mfma_f32_16x16x32_bf16 v[98:101], v[164:167], v[206:209], v[98:101]
	v_mfma_f32_16x16x32_bf16 v[86:89], v[156:159], v[214:217], v[86:89]
	v_mfma_f32_16x16x32_bf16 v[82:85], v[164:167], v[214:217], v[82:85]
	v_mfma_f32_16x16x32_bf16 v[110:113], v[168:171], v[184:187], 0
	v_mfma_f32_16x16x32_bf16 v[106:109], v[176:179], v[184:187], 0
	v_mfma_f32_16x16x32_bf16 v[94:97], v[168:171], v[192:195], 0
	v_mfma_f32_16x16x32_bf16 v[90:93], v[176:179], v[192:195], 0
	v_mfma_f32_16x16x32_bf16 v[78:81], v[168:171], v[200:203], 0
	v_mfma_f32_16x16x32_bf16 v[74:77], v[176:179], v[200:203], 0
	v_mfma_f32_16x16x32_bf16 v[70:73], v[168:171], v[210:213], 0
	v_mfma_f32_16x16x32_bf16 v[66:69], v[176:179], v[210:213], 0
	v_mfma_f32_16x16x32_bf16 v[110:113], v[172:175], v[188:191], v[110:113]
	v_mfma_f32_16x16x32_bf16 v[106:109], v[180:183], v[188:191], v[106:109]
	v_mfma_f32_16x16x32_bf16 v[94:97], v[172:175], v[196:199], v[94:97]
	v_mfma_f32_16x16x32_bf16 v[90:93], v[180:183], v[196:199], v[90:93]
	v_mfma_f32_16x16x32_bf16 v[78:81], v[172:175], v[206:209], v[78:81]
	v_mfma_f32_16x16x32_bf16 v[74:77], v[180:183], v[206:209], v[74:77]
	v_mfma_f32_16x16x32_bf16 v[70:73], v[172:175], v[214:217], v[70:73]
	v_mfma_f32_16x16x32_bf16 v[66:69], v[180:183], v[214:217], v[66:69]
	s_setprio 0
	s_barrier
	ds_read_b128 v[184:187], v148 offset:16384
	ds_read_b128 v[188:191], v148 offset:17408
	ds_read_b128 v[192:195], v148 offset:18432
	ds_read_b128 v[196:199], v148 offset:19456
	ds_read_b128 v[200:203], v148 offset:20480
	ds_read_b128 v[206:209], v148 offset:21504
	ds_read_b128 v[210:213], v148 offset:22528
	ds_read_b128 v[214:217], v148 offset:23552
	s_mov_b32 m0, s31
	v_lshl_add_u64 v[218:219], s[46:47], 0, v[134:135]
	s_add_u32 s42, s46, 0x20000
	global_load_lds_dwordx4 v[218:219], off
	v_lshl_add_u64 v[220:221], s[46:47], 0, v[130:131]
	s_mov_b32 m0, s33
	s_addc_u32 s43, s47, 0
	global_load_lds_dwordx4 v[220:221], off
	v_lshl_add_u64 v[222:223], s[42:43], 0, v[134:135]
	s_mov_b32 m0, s34
	v_lshl_add_u64 v[224:225], s[48:49], 0, v[132:133]
	global_load_lds_dwordx4 v[222:223], off
	v_lshl_add_u64 v[222:223], s[42:43], 0, v[130:131]
	s_mov_b32 m0, s35
	s_nop 0
	global_load_lds_dwordx4 v[222:223], off
	v_lshl_add_u64 v[222:223], s[48:49], 0, v[136:137]
	s_mov_b32 m0, s2
	s_nop 0
	global_load_lds_dwordx4 v[222:223], off
	s_mov_b32 m0, s3
	s_nop 0
	global_load_lds_dwordx4 v[224:225], off
	s_waitcnt vmcnt(8) lgkmcnt(0)
	s_setprio 1
	s_barrier
	v_mfma_f32_16x16x32_bf16 v[62:65], v[152:155], v[184:187], 0
	v_mfma_f32_16x16x32_bf16 v[58:61], v[160:163], v[184:187], 0
	v_mfma_f32_16x16x32_bf16 v[54:57], v[152:155], v[192:195], 0
	v_mfma_f32_16x16x32_bf16 v[50:53], v[160:163], v[192:195], 0
	v_mfma_f32_16x16x32_bf16 v[38:41], v[152:155], v[200:203], 0
	v_mfma_f32_16x16x32_bf16 v[34:37], v[160:163], v[200:203], 0
	v_mfma_f32_16x16x32_bf16 v[22:25], v[152:155], v[210:213], 0
	v_mfma_f32_16x16x32_bf16 v[18:21], v[160:163], v[210:213], 0
	v_mfma_f32_16x16x32_bf16 v[62:65], v[156:159], v[188:191], v[62:65]
	v_mfma_f32_16x16x32_bf16 v[58:61], v[164:167], v[188:191], v[58:61]
	v_mfma_f32_16x16x32_bf16 v[54:57], v[156:159], v[196:199], v[54:57]
	v_mfma_f32_16x16x32_bf16 v[50:53], v[164:167], v[196:199], v[50:53]
	v_mfma_f32_16x16x32_bf16 v[38:41], v[156:159], v[206:209], v[38:41]
	v_mfma_f32_16x16x32_bf16 v[34:37], v[164:167], v[206:209], v[34:37]
	v_mfma_f32_16x16x32_bf16 v[22:25], v[156:159], v[214:217], v[22:25]
	v_mfma_f32_16x16x32_bf16 v[18:21], v[164:167], v[214:217], v[18:21]
	v_mfma_f32_16x16x32_bf16 v[46:49], v[168:171], v[184:187], 0
	v_mfma_f32_16x16x32_bf16 v[42:45], v[176:179], v[184:187], 0
	v_mfma_f32_16x16x32_bf16 v[30:33], v[168:171], v[192:195], 0
	v_mfma_f32_16x16x32_bf16 v[26:29], v[176:179], v[192:195], 0
	v_mfma_f32_16x16x32_bf16 v[14:17], v[168:171], v[200:203], 0
	v_mfma_f32_16x16x32_bf16 v[10:13], v[176:179], v[200:203], 0
	v_mfma_f32_16x16x32_bf16 v[6:9], v[168:171], v[210:213], 0
	v_mfma_f32_16x16x32_bf16 v[2:5], v[176:179], v[210:213], 0
	v_mfma_f32_16x16x32_bf16 v[46:49], v[172:175], v[188:191], v[46:49]
	v_mfma_f32_16x16x32_bf16 v[42:45], v[180:183], v[188:191], v[42:45]
	v_mfma_f32_16x16x32_bf16 v[30:33], v[172:175], v[196:199], v[30:33]
	v_mfma_f32_16x16x32_bf16 v[26:29], v[180:183], v[196:199], v[26:29]
	v_mfma_f32_16x16x32_bf16 v[14:17], v[172:175], v[206:209], v[14:17]
	v_mfma_f32_16x16x32_bf16 v[10:13], v[180:183], v[206:209], v[10:13]
	v_mfma_f32_16x16x32_bf16 v[6:9], v[172:175], v[214:217], v[6:9]
	v_mfma_f32_16x16x32_bf16 v[2:5], v[180:183], v[214:217], v[2:5]
	s_setprio 0
	s_barrier
	ds_read_b128 v[152:155], v149
	ds_read_b128 v[156:159], v149 offset:1024
	ds_read_b128 v[160:163], v149 offset:2048
	ds_read_b128 v[164:167], v149 offset:3072
	ds_read_b128 v[168:171], v150
	ds_read_b128 v[172:175], v150 offset:1024
	ds_read_b128 v[176:179], v150 offset:2048
	ds_read_b128 v[180:183], v150 offset:3072
	ds_read_b128 v[184:187], v148 offset:32768
	ds_read_b128 v[188:191], v148 offset:33792
	ds_read_b128 v[192:195], v148 offset:34816
	ds_read_b128 v[196:199], v148 offset:35840
	ds_read_b128 v[200:203], v148 offset:36864
	ds_read_b128 v[206:209], v148 offset:37888
	ds_read_b128 v[210:213], v148 offset:38912
	ds_read_b128 v[214:217], v148 offset:39936
	s_add_u32 s42, s48, 0x20000
	s_addc_u32 s43, s49, 0
	s_mov_b32 m0, s16
	v_lshl_add_u64 v[226:227], s[42:43], 0, v[136:137]
	global_load_lds_dwordx4 v[226:227], off
	v_lshl_add_u64 v[226:227], s[42:43], 0, v[132:133]
	s_mov_b32 m0, s17
	s_nop 0
	global_load_lds_dwordx4 v[226:227], off
	s_waitcnt vmcnt(8) lgkmcnt(0)
	s_setprio 1
	s_barrier
	v_mfma_f32_16x16x32_bf16 v[126:129], v[152:155], v[184:187], v[126:129]
	v_mfma_f32_16x16x32_bf16 v[122:125], v[160:163], v[184:187], v[122:125]
	v_mfma_f32_16x16x32_bf16 v[118:121], v[152:155], v[192:195], v[118:121]
	v_mfma_f32_16x16x32_bf16 v[114:117], v[160:163], v[192:195], v[114:117]
	v_mfma_f32_16x16x32_bf16 v[102:105], v[152:155], v[200:203], v[102:105]
	v_mfma_f32_16x16x32_bf16 v[98:101], v[160:163], v[200:203], v[98:101]
	v_mfma_f32_16x16x32_bf16 v[86:89], v[152:155], v[210:213], v[86:89]
	v_mfma_f32_16x16x32_bf16 v[82:85], v[160:163], v[210:213], v[82:85]
	v_mfma_f32_16x16x32_bf16 v[126:129], v[156:159], v[188:191], v[126:129]
	v_mfma_f32_16x16x32_bf16 v[122:125], v[164:167], v[188:191], v[122:125]
	v_mfma_f32_16x16x32_bf16 v[118:121], v[156:159], v[196:199], v[118:121]
	v_mfma_f32_16x16x32_bf16 v[114:117], v[164:167], v[196:199], v[114:117]
	v_mfma_f32_16x16x32_bf16 v[102:105], v[156:159], v[206:209], v[102:105]
	v_mfma_f32_16x16x32_bf16 v[98:101], v[164:167], v[206:209], v[98:101]
	v_mfma_f32_16x16x32_bf16 v[86:89], v[156:159], v[214:217], v[86:89]
	v_mfma_f32_16x16x32_bf16 v[82:85], v[164:167], v[214:217], v[82:85]
	v_mfma_f32_16x16x32_bf16 v[110:113], v[168:171], v[184:187], v[110:113]
	v_mfma_f32_16x16x32_bf16 v[106:109], v[176:179], v[184:187], v[106:109]
	v_mfma_f32_16x16x32_bf16 v[94:97], v[168:171], v[192:195], v[94:97]
	v_mfma_f32_16x16x32_bf16 v[90:93], v[176:179], v[192:195], v[90:93]
	v_mfma_f32_16x16x32_bf16 v[78:81], v[168:171], v[200:203], v[78:81]
	v_mfma_f32_16x16x32_bf16 v[74:77], v[176:179], v[200:203], v[74:77]
	v_mfma_f32_16x16x32_bf16 v[70:73], v[168:171], v[210:213], v[70:73]
	v_mfma_f32_16x16x32_bf16 v[66:69], v[176:179], v[210:213], v[66:69]
	v_mfma_f32_16x16x32_bf16 v[110:113], v[172:175], v[188:191], v[110:113]
	v_mfma_f32_16x16x32_bf16 v[106:109], v[180:183], v[188:191], v[106:109]
	v_mfma_f32_16x16x32_bf16 v[94:97], v[172:175], v[196:199], v[94:97]
	v_mfma_f32_16x16x32_bf16 v[90:93], v[180:183], v[196:199], v[90:93]
	v_mfma_f32_16x16x32_bf16 v[78:81], v[172:175], v[206:209], v[78:81]
	v_mfma_f32_16x16x32_bf16 v[74:77], v[180:183], v[206:209], v[74:77]
	v_mfma_f32_16x16x32_bf16 v[70:73], v[172:175], v[214:217], v[70:73]
	v_mfma_f32_16x16x32_bf16 v[66:69], v[180:183], v[214:217], v[66:69]
	s_setprio 0
	s_barrier
	ds_read_b128 v[184:187], v148 offset:49152
	ds_read_b128 v[188:191], v148 offset:50176
	ds_read_b128 v[192:195], v148 offset:51200
	ds_read_b128 v[196:199], v148 offset:52224
	ds_read_b128 v[200:203], v148 offset:53248
	ds_read_b128 v[206:209], v148 offset:54272
	ds_read_b128 v[210:213], v148 offset:55296
	ds_read_b128 v[214:217], v148 offset:56320
	s_mov_b32 m0, s62
	v_lshl_add_u64 v[218:219], v[218:219], 0, s[10:11]
	s_add_u32 s42, s46, 0x20080
	global_load_lds_dwordx4 v[218:219], off
	v_lshl_add_u64 v[218:219], v[220:221], 0, s[10:11]
	s_mov_b32 m0, s63
	s_addc_u32 s43, s47, 0
	global_load_lds_dwordx4 v[218:219], off
	v_lshl_add_u64 v[218:219], s[42:43], 0, v[134:135]
	s_mov_b32 m0, s64
	s_nop 0
	global_load_lds_dwordx4 v[218:219], off
	v_lshl_add_u64 v[218:219], s[42:43], 0, v[130:131]
	s_mov_b32 m0, s65
	s_nop 0
	global_load_lds_dwordx4 v[218:219], off
	v_lshl_add_u64 v[218:219], v[222:223], 0, s[10:11]
	s_mov_b32 m0, s25
	s_nop 0
	global_load_lds_dwordx4 v[218:219], off
	v_lshl_add_u64 v[218:219], v[224:225], 0, s[10:11]
	s_mov_b32 m0, s28
	s_nop 0
	global_load_lds_dwordx4 v[218:219], off
	s_waitcnt vmcnt(8) lgkmcnt(0)
	s_setprio 1
	s_barrier
	v_mfma_f32_16x16x32_bf16 v[62:65], v[152:155], v[184:187], v[62:65]
	v_mfma_f32_16x16x32_bf16 v[58:61], v[160:163], v[184:187], v[58:61]
	v_mfma_f32_16x16x32_bf16 v[54:57], v[152:155], v[192:195], v[54:57]
	v_mfma_f32_16x16x32_bf16 v[50:53], v[160:163], v[192:195], v[50:53]
	v_mfma_f32_16x16x32_bf16 v[38:41], v[152:155], v[200:203], v[38:41]
	v_mfma_f32_16x16x32_bf16 v[34:37], v[160:163], v[200:203], v[34:37]
	v_mfma_f32_16x16x32_bf16 v[22:25], v[152:155], v[210:213], v[22:25]
	v_mfma_f32_16x16x32_bf16 v[18:21], v[160:163], v[210:213], v[18:21]
	v_mfma_f32_16x16x32_bf16 v[62:65], v[156:159], v[188:191], v[62:65]
	v_mfma_f32_16x16x32_bf16 v[58:61], v[164:167], v[188:191], v[58:61]
	v_mfma_f32_16x16x32_bf16 v[54:57], v[156:159], v[196:199], v[54:57]
	v_mfma_f32_16x16x32_bf16 v[50:53], v[164:167], v[196:199], v[50:53]
	v_mfma_f32_16x16x32_bf16 v[38:41], v[156:159], v[206:209], v[38:41]
	v_mfma_f32_16x16x32_bf16 v[34:37], v[164:167], v[206:209], v[34:37]
	v_mfma_f32_16x16x32_bf16 v[22:25], v[156:159], v[214:217], v[22:25]
	v_mfma_f32_16x16x32_bf16 v[18:21], v[164:167], v[214:217], v[18:21]
	v_mfma_f32_16x16x32_bf16 v[46:49], v[168:171], v[184:187], v[46:49]
	v_mfma_f32_16x16x32_bf16 v[42:45], v[176:179], v[184:187], v[42:45]
	v_mfma_f32_16x16x32_bf16 v[30:33], v[168:171], v[192:195], v[30:33]
	v_mfma_f32_16x16x32_bf16 v[26:29], v[176:179], v[192:195], v[26:29]
	v_mfma_f32_16x16x32_bf16 v[14:17], v[168:171], v[200:203], v[14:17]
	v_mfma_f32_16x16x32_bf16 v[10:13], v[176:179], v[200:203], v[10:13]
	v_mfma_f32_16x16x32_bf16 v[6:9], v[168:171], v[210:213], v[6:9]
	v_mfma_f32_16x16x32_bf16 v[2:5], v[176:179], v[210:213], v[2:5]
	v_mfma_f32_16x16x32_bf16 v[46:49], v[172:175], v[188:191], v[46:49]
	v_mfma_f32_16x16x32_bf16 v[42:45], v[180:183], v[188:191], v[42:45]
	v_mfma_f32_16x16x32_bf16 v[30:33], v[172:175], v[196:199], v[30:33]
	v_mfma_f32_16x16x32_bf16 v[26:29], v[180:183], v[196:199], v[26:29]
	v_mfma_f32_16x16x32_bf16 v[14:17], v[172:175], v[206:209], v[14:17]
	v_mfma_f32_16x16x32_bf16 v[10:13], v[180:183], v[206:209], v[10:13]
	v_mfma_f32_16x16x32_bf16 v[6:9], v[172:175], v[214:217], v[6:9]
	v_mfma_f32_16x16x32_bf16 v[2:5], v[180:183], v[214:217], v[2:5]
	s_setprio 0
	s_barrier
	s_add_i32 s68, s68, 2
	s_cmp_gt_u32 s68, 5
	s_mov_b64 s[42:43], s[44:45]
.LBB0_384:
	ds_read_b128 v[152:155], v146
	ds_read_b128 v[156:159], v146 offset:1024
	ds_read_b128 v[160:163], v146 offset:2048
	ds_read_b128 v[164:167], v146 offset:3072
	ds_read_b128 v[168:171], v147
	ds_read_b128 v[172:175], v147 offset:1024
	ds_read_b128 v[176:179], v147 offset:2048
	ds_read_b128 v[180:183], v147 offset:3072
	ds_read_b128 v[184:187], v148
	ds_read_b128 v[188:191], v148 offset:1024
	ds_read_b128 v[192:195], v148 offset:2048
	ds_read_b128 v[196:199], v148 offset:3072
	ds_read_b128 v[200:203], v148 offset:4096
	ds_read_b128 v[206:209], v148 offset:5120
	ds_read_b128 v[210:213], v148 offset:6144
	ds_read_b128 v[214:217], v148 offset:7168
	s_add_u32 s44, s42, 0x100
	s_addc_u32 s45, s43, 0
	s_add_u32 s46, s66, s42
	s_addc_u32 s47, s67, s43
	s_cmp_eq_u32 s68, 4
	s_cselect_b32 s48, 0, s44
	s_cselect_b32 s49, 0, s45
	s_cselect_b32 s46, s39, s46
	s_cselect_b32 s47, s15, s47
	s_add_u32 s48, s6, s48
	s_addc_u32 s49, s7, s49
	s_mov_b32 m0, s29
	v_lshl_add_u64 v[218:219], v[138:139], 0, s[42:43]
	global_load_lds_dwordx4 v[218:219], off
	v_lshl_add_u64 v[218:219], v[140:141], 0, s[42:43]
	s_mov_b32 m0, s30
	s_nop 0
	global_load_lds_dwordx4 v[218:219], off
	s_waitcnt vmcnt(8) lgkmcnt(0)
	s_setprio 1
	s_barrier
	v_mfma_f32_16x16x32_bf16 v[126:129], v[152:155], v[184:187], v[126:129]
	v_mfma_f32_16x16x32_bf16 v[122:125], v[160:163], v[184:187], v[122:125]
	v_mfma_f32_16x16x32_bf16 v[118:121], v[152:155], v[192:195], v[118:121]
	v_mfma_f32_16x16x32_bf16 v[114:117], v[160:163], v[192:195], v[114:117]
	v_mfma_f32_16x16x32_bf16 v[102:105], v[152:155], v[200:203], v[102:105]
	v_mfma_f32_16x16x32_bf16 v[98:101], v[160:163], v[200:203], v[98:101]
	v_mfma_f32_16x16x32_bf16 v[86:89], v[152:155], v[210:213], v[86:89]
	v_mfma_f32_16x16x32_bf16 v[82:85], v[160:163], v[210:213], v[82:85]
	v_mfma_f32_16x16x32_bf16 v[126:129], v[156:159], v[188:191], v[126:129]
	v_mfma_f32_16x16x32_bf16 v[122:125], v[164:167], v[188:191], v[122:125]
	v_mfma_f32_16x16x32_bf16 v[118:121], v[156:159], v[196:199], v[118:121]
	v_mfma_f32_16x16x32_bf16 v[114:117], v[164:167], v[196:199], v[114:117]
	v_mfma_f32_16x16x32_bf16 v[102:105], v[156:159], v[206:209], v[102:105]
	v_mfma_f32_16x16x32_bf16 v[98:101], v[164:167], v[206:209], v[98:101]
	v_mfma_f32_16x16x32_bf16 v[86:89], v[156:159], v[214:217], v[86:89]
	v_mfma_f32_16x16x32_bf16 v[82:85], v[164:167], v[214:217], v[82:85]
	v_mfma_f32_16x16x32_bf16 v[110:113], v[168:171], v[184:187], v[110:113]
	v_mfma_f32_16x16x32_bf16 v[106:109], v[176:179], v[184:187], v[106:109]
	v_mfma_f32_16x16x32_bf16 v[94:97], v[168:171], v[192:195], v[94:97]
	v_mfma_f32_16x16x32_bf16 v[90:93], v[176:179], v[192:195], v[90:93]
	v_mfma_f32_16x16x32_bf16 v[78:81], v[168:171], v[200:203], v[78:81]
	v_mfma_f32_16x16x32_bf16 v[74:77], v[176:179], v[200:203], v[74:77]
	v_mfma_f32_16x16x32_bf16 v[70:73], v[168:171], v[210:213], v[70:73]
	v_mfma_f32_16x16x32_bf16 v[66:69], v[176:179], v[210:213], v[66:69]
	v_mfma_f32_16x16x32_bf16 v[110:113], v[172:175], v[188:191], v[110:113]
	v_mfma_f32_16x16x32_bf16 v[106:109], v[180:183], v[188:191], v[106:109]
	v_mfma_f32_16x16x32_bf16 v[94:97], v[172:175], v[196:199], v[94:97]
	v_mfma_f32_16x16x32_bf16 v[90:93], v[180:183], v[196:199], v[90:93]
	v_mfma_f32_16x16x32_bf16 v[78:81], v[172:175], v[206:209], v[78:81]
	v_mfma_f32_16x16x32_bf16 v[74:77], v[180:183], v[206:209], v[74:77]
	v_mfma_f32_16x16x32_bf16 v[70:73], v[172:175], v[214:217], v[70:73]
	v_mfma_f32_16x16x32_bf16 v[66:69], v[180:183], v[214:217], v[66:69]
	s_setprio 0
	s_barrier
	ds_read_b128 v[184:187], v148 offset:16384
	ds_read_b128 v[188:191], v148 offset:17408
	ds_read_b128 v[192:195], v148 offset:18432
	ds_read_b128 v[196:199], v148 offset:19456
	ds_read_b128 v[200:203], v148 offset:20480
	ds_read_b128 v[206:209], v148 offset:21504
	ds_read_b128 v[210:213], v148 offset:22528
	ds_read_b128 v[214:217], v148 offset:23552
	s_mov_b32 m0, s31
	v_lshl_add_u64 v[218:219], s[46:47], 0, v[134:135]
	s_add_u32 s42, s46, 0x20000
	global_load_lds_dwordx4 v[218:219], off
	v_lshl_add_u64 v[220:221], s[46:47], 0, v[130:131]
	s_mov_b32 m0, s33
	s_addc_u32 s43, s47, 0
	global_load_lds_dwordx4 v[220:221], off
	v_lshl_add_u64 v[222:223], s[42:43], 0, v[134:135]
	s_mov_b32 m0, s34
	v_lshl_add_u64 v[224:225], s[48:49], 0, v[132:133]
	global_load_lds_dwordx4 v[222:223], off
	v_lshl_add_u64 v[222:223], s[42:43], 0, v[130:131]
	s_mov_b32 m0, s35
	s_nop 0
	global_load_lds_dwordx4 v[222:223], off
	v_lshl_add_u64 v[222:223], s[48:49], 0, v[136:137]
	s_mov_b32 m0, s2
	s_nop 0
	global_load_lds_dwordx4 v[222:223], off
	s_mov_b32 m0, s3
	s_nop 0
	global_load_lds_dwordx4 v[224:225], off
	s_waitcnt vmcnt(8) lgkmcnt(0)
	s_setprio 1
	s_barrier
	v_mfma_f32_16x16x32_bf16 v[62:65], v[152:155], v[184:187], v[62:65]
	v_mfma_f32_16x16x32_bf16 v[58:61], v[160:163], v[184:187], v[58:61]
	v_mfma_f32_16x16x32_bf16 v[54:57], v[152:155], v[192:195], v[54:57]
	v_mfma_f32_16x16x32_bf16 v[50:53], v[160:163], v[192:195], v[50:53]
	v_mfma_f32_16x16x32_bf16 v[38:41], v[152:155], v[200:203], v[38:41]
	v_mfma_f32_16x16x32_bf16 v[34:37], v[160:163], v[200:203], v[34:37]
	v_mfma_f32_16x16x32_bf16 v[22:25], v[152:155], v[210:213], v[22:25]
	v_mfma_f32_16x16x32_bf16 v[18:21], v[160:163], v[210:213], v[18:21]
	v_mfma_f32_16x16x32_bf16 v[62:65], v[156:159], v[188:191], v[62:65]
	v_mfma_f32_16x16x32_bf16 v[58:61], v[164:167], v[188:191], v[58:61]
	v_mfma_f32_16x16x32_bf16 v[54:57], v[156:159], v[196:199], v[54:57]
	v_mfma_f32_16x16x32_bf16 v[50:53], v[164:167], v[196:199], v[50:53]
	v_mfma_f32_16x16x32_bf16 v[38:41], v[156:159], v[206:209], v[38:41]
	v_mfma_f32_16x16x32_bf16 v[34:37], v[164:167], v[206:209], v[34:37]
	v_mfma_f32_16x16x32_bf16 v[22:25], v[156:159], v[214:217], v[22:25]
	v_mfma_f32_16x16x32_bf16 v[18:21], v[164:167], v[214:217], v[18:21]
	v_mfma_f32_16x16x32_bf16 v[46:49], v[168:171], v[184:187], v[46:49]
	v_mfma_f32_16x16x32_bf16 v[42:45], v[176:179], v[184:187], v[42:45]
	v_mfma_f32_16x16x32_bf16 v[30:33], v[168:171], v[192:195], v[30:33]
	v_mfma_f32_16x16x32_bf16 v[26:29], v[176:179], v[192:195], v[26:29]
	v_mfma_f32_16x16x32_bf16 v[14:17], v[168:171], v[200:203], v[14:17]
	v_mfma_f32_16x16x32_bf16 v[10:13], v[176:179], v[200:203], v[10:13]
	v_mfma_f32_16x16x32_bf16 v[6:9], v[168:171], v[210:213], v[6:9]
	v_mfma_f32_16x16x32_bf16 v[2:5], v[176:179], v[210:213], v[2:5]
	v_mfma_f32_16x16x32_bf16 v[46:49], v[172:175], v[188:191], v[46:49]
	v_mfma_f32_16x16x32_bf16 v[42:45], v[180:183], v[188:191], v[42:45]
	v_mfma_f32_16x16x32_bf16 v[30:33], v[172:175], v[196:199], v[30:33]
	v_mfma_f32_16x16x32_bf16 v[26:29], v[180:183], v[196:199], v[26:29]
	v_mfma_f32_16x16x32_bf16 v[14:17], v[172:175], v[206:209], v[14:17]
	v_mfma_f32_16x16x32_bf16 v[10:13], v[180:183], v[206:209], v[10:13]
	v_mfma_f32_16x16x32_bf16 v[6:9], v[172:175], v[214:217], v[6:9]
	v_mfma_f32_16x16x32_bf16 v[2:5], v[180:183], v[214:217], v[2:5]
	s_setprio 0
	s_barrier
	ds_read_b128 v[152:155], v149
	ds_read_b128 v[156:159], v149 offset:1024
	ds_read_b128 v[160:163], v149 offset:2048
	ds_read_b128 v[164:167], v149 offset:3072
	ds_read_b128 v[168:171], v150
	ds_read_b128 v[172:175], v150 offset:1024
	ds_read_b128 v[176:179], v150 offset:2048
	ds_read_b128 v[180:183], v150 offset:3072
	ds_read_b128 v[184:187], v148 offset:32768
	ds_read_b128 v[188:191], v148 offset:33792
	ds_read_b128 v[192:195], v148 offset:34816
	ds_read_b128 v[196:199], v148 offset:35840
	ds_read_b128 v[200:203], v148 offset:36864
	ds_read_b128 v[206:209], v148 offset:37888
	ds_read_b128 v[210:213], v148 offset:38912
	ds_read_b128 v[214:217], v148 offset:39936
	s_add_u32 s42, s48, 0x20000
	s_addc_u32 s43, s49, 0
	s_mov_b32 m0, s16
	v_lshl_add_u64 v[226:227], s[42:43], 0, v[136:137]
	global_load_lds_dwordx4 v[226:227], off
	v_lshl_add_u64 v[226:227], s[42:43], 0, v[132:133]
	s_mov_b32 m0, s17
	s_nop 0
	global_load_lds_dwordx4 v[226:227], off
	s_waitcnt vmcnt(8) lgkmcnt(0)
	s_setprio 1
	s_barrier
	v_mfma_f32_16x16x32_bf16 v[126:129], v[152:155], v[184:187], v[126:129]
	v_mfma_f32_16x16x32_bf16 v[122:125], v[160:163], v[184:187], v[122:125]
	v_mfma_f32_16x16x32_bf16 v[118:121], v[152:155], v[192:195], v[118:121]
	v_mfma_f32_16x16x32_bf16 v[114:117], v[160:163], v[192:195], v[114:117]
	v_mfma_f32_16x16x32_bf16 v[102:105], v[152:155], v[200:203], v[102:105]
	v_mfma_f32_16x16x32_bf16 v[98:101], v[160:163], v[200:203], v[98:101]
	v_mfma_f32_16x16x32_bf16 v[86:89], v[152:155], v[210:213], v[86:89]
	v_mfma_f32_16x16x32_bf16 v[82:85], v[160:163], v[210:213], v[82:85]
	v_mfma_f32_16x16x32_bf16 v[126:129], v[156:159], v[188:191], v[126:129]
	v_mfma_f32_16x16x32_bf16 v[122:125], v[164:167], v[188:191], v[122:125]
	v_mfma_f32_16x16x32_bf16 v[118:121], v[156:159], v[196:199], v[118:121]
	v_mfma_f32_16x16x32_bf16 v[114:117], v[164:167], v[196:199], v[114:117]
	v_mfma_f32_16x16x32_bf16 v[102:105], v[156:159], v[206:209], v[102:105]
	v_mfma_f32_16x16x32_bf16 v[98:101], v[164:167], v[206:209], v[98:101]
	v_mfma_f32_16x16x32_bf16 v[86:89], v[156:159], v[214:217], v[86:89]
	v_mfma_f32_16x16x32_bf16 v[82:85], v[164:167], v[214:217], v[82:85]
	v_mfma_f32_16x16x32_bf16 v[110:113], v[168:171], v[184:187], v[110:113]
	v_mfma_f32_16x16x32_bf16 v[106:109], v[176:179], v[184:187], v[106:109]
	v_mfma_f32_16x16x32_bf16 v[94:97], v[168:171], v[192:195], v[94:97]
	v_mfma_f32_16x16x32_bf16 v[90:93], v[176:179], v[192:195], v[90:93]
	v_mfma_f32_16x16x32_bf16 v[78:81], v[168:171], v[200:203], v[78:81]
	v_mfma_f32_16x16x32_bf16 v[74:77], v[176:179], v[200:203], v[74:77]
	v_mfma_f32_16x16x32_bf16 v[70:73], v[168:171], v[210:213], v[70:73]
	v_mfma_f32_16x16x32_bf16 v[66:69], v[176:179], v[210:213], v[66:69]
	v_mfma_f32_16x16x32_bf16 v[110:113], v[172:175], v[188:191], v[110:113]
	v_mfma_f32_16x16x32_bf16 v[106:109], v[180:183], v[188:191], v[106:109]
	v_mfma_f32_16x16x32_bf16 v[94:97], v[172:175], v[196:199], v[94:97]
	v_mfma_f32_16x16x32_bf16 v[90:93], v[180:183], v[196:199], v[90:93]
	v_mfma_f32_16x16x32_bf16 v[78:81], v[172:175], v[206:209], v[78:81]
	v_mfma_f32_16x16x32_bf16 v[74:77], v[180:183], v[206:209], v[74:77]
	v_mfma_f32_16x16x32_bf16 v[70:73], v[172:175], v[214:217], v[70:73]
	v_mfma_f32_16x16x32_bf16 v[66:69], v[180:183], v[214:217], v[66:69]
	s_setprio 0
	s_barrier
	ds_read_b128 v[184:187], v148 offset:49152
	ds_read_b128 v[188:191], v148 offset:50176
	ds_read_b128 v[192:195], v148 offset:51200
	ds_read_b128 v[196:199], v148 offset:52224
	ds_read_b128 v[200:203], v148 offset:53248
	ds_read_b128 v[206:209], v148 offset:54272
	ds_read_b128 v[210:213], v148 offset:55296
	ds_read_b128 v[214:217], v148 offset:56320
	s_mov_b32 m0, s62
	v_lshl_add_u64 v[218:219], v[218:219], 0, s[10:11]
	s_add_u32 s42, s46, 0x20080
	global_load_lds_dwordx4 v[218:219], off
	v_lshl_add_u64 v[218:219], v[220:221], 0, s[10:11]
	s_mov_b32 m0, s63
	s_addc_u32 s43, s47, 0
	global_load_lds_dwordx4 v[218:219], off
	v_lshl_add_u64 v[218:219], s[42:43], 0, v[134:135]
	s_mov_b32 m0, s64
	s_nop 0
	global_load_lds_dwordx4 v[218:219], off
	v_lshl_add_u64 v[218:219], s[42:43], 0, v[130:131]
	s_mov_b32 m0, s65
	s_nop 0
	global_load_lds_dwordx4 v[218:219], off
	v_lshl_add_u64 v[218:219], v[222:223], 0, s[10:11]
	s_mov_b32 m0, s25
	s_nop 0
	global_load_lds_dwordx4 v[218:219], off
	v_lshl_add_u64 v[218:219], v[224:225], 0, s[10:11]
	s_mov_b32 m0, s28
	s_nop 0
	global_load_lds_dwordx4 v[218:219], off
	s_waitcnt vmcnt(8) lgkmcnt(0)
	s_setprio 1
	s_barrier
	v_mfma_f32_16x16x32_bf16 v[62:65], v[152:155], v[184:187], v[62:65]
	v_mfma_f32_16x16x32_bf16 v[58:61], v[160:163], v[184:187], v[58:61]
	v_mfma_f32_16x16x32_bf16 v[54:57], v[152:155], v[192:195], v[54:57]
	v_mfma_f32_16x16x32_bf16 v[50:53], v[160:163], v[192:195], v[50:53]
	v_mfma_f32_16x16x32_bf16 v[38:41], v[152:155], v[200:203], v[38:41]
	v_mfma_f32_16x16x32_bf16 v[34:37], v[160:163], v[200:203], v[34:37]
	v_mfma_f32_16x16x32_bf16 v[22:25], v[152:155], v[210:213], v[22:25]
	v_mfma_f32_16x16x32_bf16 v[18:21], v[160:163], v[210:213], v[18:21]
	v_mfma_f32_16x16x32_bf16 v[62:65], v[156:159], v[188:191], v[62:65]
	v_mfma_f32_16x16x32_bf16 v[58:61], v[164:167], v[188:191], v[58:61]
	v_mfma_f32_16x16x32_bf16 v[54:57], v[156:159], v[196:199], v[54:57]
	v_mfma_f32_16x16x32_bf16 v[50:53], v[164:167], v[196:199], v[50:53]
	v_mfma_f32_16x16x32_bf16 v[38:41], v[156:159], v[206:209], v[38:41]
	v_mfma_f32_16x16x32_bf16 v[34:37], v[164:167], v[206:209], v[34:37]
	v_mfma_f32_16x16x32_bf16 v[22:25], v[156:159], v[214:217], v[22:25]
	v_mfma_f32_16x16x32_bf16 v[18:21], v[164:167], v[214:217], v[18:21]
	v_mfma_f32_16x16x32_bf16 v[46:49], v[168:171], v[184:187], v[46:49]
	v_mfma_f32_16x16x32_bf16 v[42:45], v[176:179], v[184:187], v[42:45]
	v_mfma_f32_16x16x32_bf16 v[30:33], v[168:171], v[192:195], v[30:33]
	v_mfma_f32_16x16x32_bf16 v[26:29], v[176:179], v[192:195], v[26:29]
	v_mfma_f32_16x16x32_bf16 v[14:17], v[168:171], v[200:203], v[14:17]
	v_mfma_f32_16x16x32_bf16 v[10:13], v[176:179], v[200:203], v[10:13]
	v_mfma_f32_16x16x32_bf16 v[6:9], v[168:171], v[210:213], v[6:9]
	v_mfma_f32_16x16x32_bf16 v[2:5], v[176:179], v[210:213], v[2:5]
	v_mfma_f32_16x16x32_bf16 v[46:49], v[172:175], v[188:191], v[46:49]
	v_mfma_f32_16x16x32_bf16 v[42:45], v[180:183], v[188:191], v[42:45]
	v_mfma_f32_16x16x32_bf16 v[30:33], v[172:175], v[196:199], v[30:33]
	v_mfma_f32_16x16x32_bf16 v[26:29], v[180:183], v[196:199], v[26:29]
	v_mfma_f32_16x16x32_bf16 v[14:17], v[172:175], v[206:209], v[14:17]
	v_mfma_f32_16x16x32_bf16 v[10:13], v[180:183], v[206:209], v[10:13]
	v_mfma_f32_16x16x32_bf16 v[6:9], v[172:175], v[214:217], v[6:9]
	v_mfma_f32_16x16x32_bf16 v[2:5], v[180:183], v[214:217], v[2:5]
	s_setprio 0
	s_barrier
	s_add_i32 s68, s68, 2
	s_cmp_gt_u32 s68, 5
	s_mov_b64 s[42:43], s[44:45]
	s_cbranch_scc0 .LBB0_384
	s_and_b64 vcc, exec, s[12:13]
	s_cbranch_vccz .LBB0_387
	s_barrier

.LBB0_406:
	ds_read_b128 v[146:149], v141
	ds_read_b128 v[150:153], v141 offset:1024
	ds_read_b128 v[154:157], v141 offset:2048
	ds_read_b128 v[158:161], v141 offset:3072
	ds_read_b128 v[162:165], v143
	ds_read_b128 v[166:169], v143 offset:1024
	ds_read_b128 v[170:173], v143 offset:2048
	ds_read_b128 v[174:177], v143 offset:3072
	ds_read_b128 v[178:181], v144
	ds_read_b128 v[182:185], v144 offset:1024
	ds_read_b128 v[186:189], v144 offset:2048
	ds_read_b128 v[190:193], v144 offset:3072
	ds_read_b128 v[194:197], v144 offset:4096
	ds_read_b128 v[198:201], v144 offset:5120
	ds_read_b128 v[206:209], v144 offset:6144
	ds_read_b128 v[210:213], v144 offset:7168
	s_lshl_b32 s74, s12, 7
	s_add_i32 s12, s12, 2
	v_cndmask_b32_e64 v138, 0, 1, s[66:67]
	s_lshl_b64 s[66:67], s[12:13], 7
	s_and_b64 s[68:69], s[64:65], exec
	s_cselect_b32 s66, 0, s66
	s_cselect_b32 s67, 0, s67
	s_add_u32 s70, s8, s66
	s_addc_u32 s71, s9, s67
	s_lshl_b64 s[66:67], s[12:13], 12
	s_add_u32 s12, s48, s66
	s_addc_u32 s66, s49, s67
	s_and_b64 s[64:65], s[64:65], exec
	s_cselect_b32 s73, s14, s66
	s_cselect_b32 s72, s15, s12
	s_add_u32 s76, s10, s74
	s_addc_u32 s77, s11, 0
	s_add_i32 s91, s62, s16
	s_add_i32 m0, s17, 0xc000
	s_add_i32 s92, s17, 0xe000
	s_add_i32 s88, s91, 0x2000
	s_add_u32 s74, s72, 0x10000
	s_addc_u32 s75, s73, 0
	s_add_i32 s90, s63, s16
	s_add_i32 s89, s90, 0x2000
	s_add_i32 s87, 0, 0x18000
	s_add_i32 s86, 0, 0x1c000
	s_add_u32 s68, s70, 0x10000
	s_addc_u32 s69, s71, 0
	s_add_u32 s64, s72, 0x1000
	s_addc_u32 s65, s73, 0
	s_add_i32 s85, s87, s16
	s_add_i32 s83, s85, 0x2000
	s_add_u32 s66, s72, 0x11000
	s_addc_u32 s67, s73, 0
	s_add_i32 s84, s86, s16
	s_add_i32 s12, s84, 0x2000
	v_cmp_ne_u32_e32 vcc, 1, v138
	v_lshl_add_u64 v[202:203], s[76:77], 0, v[136:137]
	v_lshl_add_u64 v[202:203], v[202:203], 0, s[36:37]
	global_load_lds_dwordx4 v[202:203], off
	v_lshl_add_u64 v[202:203], s[76:77], 0, v[132:133]
	v_lshl_add_u64 v[202:203], v[202:203], 0, s[36:37]
	s_mov_b32 m0, s92
	s_nop 0
	global_load_lds_dwordx4 v[202:203], off
	s_waitcnt vmcnt(8) lgkmcnt(0)
	s_setprio 1
	s_barrier
	v_mfma_f32_16x16x32_bf16 v[126:129], v[146:149], v[178:181], v[126:129]
	v_mfma_f32_16x16x32_bf16 v[122:125], v[154:157], v[178:181], v[122:125]
	v_mfma_f32_16x16x32_bf16 v[118:121], v[146:149], v[186:189], v[118:121]
	v_mfma_f32_16x16x32_bf16 v[110:113], v[154:157], v[186:189], v[110:113]
	v_mfma_f32_16x16x32_bf16 v[102:105], v[146:149], v[194:197], v[102:105]
	v_mfma_f32_16x16x32_bf16 v[98:101], v[154:157], v[194:197], v[98:101]
	v_mfma_f32_16x16x32_bf16 v[86:89], v[146:149], v[206:209], v[86:89]
	v_mfma_f32_16x16x32_bf16 v[82:85], v[154:157], v[206:209], v[82:85]
	v_mfma_f32_16x16x32_bf16 v[126:129], v[150:153], v[182:185], v[126:129]
	v_mfma_f32_16x16x32_bf16 v[122:125], v[158:161], v[182:185], v[122:125]
	v_mfma_f32_16x16x32_bf16 v[118:121], v[150:153], v[190:193], v[118:121]
	v_mfma_f32_16x16x32_bf16 v[110:113], v[158:161], v[190:193], v[110:113]
	v_mfma_f32_16x16x32_bf16 v[102:105], v[150:153], v[198:201], v[102:105]
	v_mfma_f32_16x16x32_bf16 v[98:101], v[158:161], v[198:201], v[98:101]
	v_mfma_f32_16x16x32_bf16 v[86:89], v[150:153], v[210:213], v[86:89]
	v_mfma_f32_16x16x32_bf16 v[82:85], v[158:161], v[210:213], v[82:85]
	v_mfma_f32_16x16x32_bf16 v[114:117], v[162:165], v[178:181], v[114:117]
	v_mfma_f32_16x16x32_bf16 v[106:109], v[170:173], v[178:181], v[106:109]
	v_mfma_f32_16x16x32_bf16 v[94:97], v[162:165], v[186:189], v[94:97]
	v_mfma_f32_16x16x32_bf16 v[90:93], v[170:173], v[186:189], v[90:93]
	v_mfma_f32_16x16x32_bf16 v[78:81], v[162:165], v[194:197], v[78:81]
	v_mfma_f32_16x16x32_bf16 v[74:77], v[170:173], v[194:197], v[74:77]
	v_mfma_f32_16x16x32_bf16 v[70:73], v[162:165], v[206:209], v[70:73]
	v_mfma_f32_16x16x32_bf16 v[66:69], v[170:173], v[206:209], v[66:69]
	v_mfma_f32_16x16x32_bf16 v[114:117], v[166:169], v[182:185], v[114:117]
	v_mfma_f32_16x16x32_bf16 v[106:109], v[174:177], v[182:185], v[106:109]
	v_mfma_f32_16x16x32_bf16 v[94:97], v[166:169], v[190:193], v[94:97]
	v_mfma_f32_16x16x32_bf16 v[90:93], v[174:177], v[190:193], v[90:93]
	v_mfma_f32_16x16x32_bf16 v[78:81], v[166:169], v[198:201], v[78:81]
	v_mfma_f32_16x16x32_bf16 v[74:77], v[174:177], v[198:201], v[74:77]
	v_mfma_f32_16x16x32_bf16 v[70:73], v[166:169], v[210:213], v[70:73]
	v_mfma_f32_16x16x32_bf16 v[66:69], v[174:177], v[210:213], v[66:69]
	s_setprio 0
	s_barrier
	ds_read_b128 v[178:181], v144 offset:16384
	ds_read_b128 v[182:185], v144 offset:17408
	ds_read_b128 v[186:189], v144 offset:18432
	ds_read_b128 v[190:193], v144 offset:19456
	ds_read_b128 v[194:197], v144 offset:20480
	ds_read_b128 v[198:201], v144 offset:21504
	ds_read_b128 v[206:209], v144 offset:22528
	ds_read_b128 v[210:213], v144 offset:23552
	s_mov_b32 m0, s91
	v_lshl_add_u64 v[202:203], s[72:73], 0, v[134:135]
	global_load_lds_dwordx4 v[202:203], off
	v_lshl_add_u64 v[202:203], s[72:73], 0, v[130:131]
	s_mov_b32 m0, s88
	v_lshl_add_u64 v[214:215], s[70:71], 0, v[132:133]
	global_load_lds_dwordx4 v[202:203], off
	v_lshl_add_u64 v[202:203], s[74:75], 0, v[134:135]
	s_mov_b32 m0, s90
	s_nop 0
	global_load_lds_dwordx4 v[202:203], off
	v_lshl_add_u64 v[202:203], s[74:75], 0, v[130:131]
	s_mov_b32 m0, s89
	s_nop 0
	global_load_lds_dwordx4 v[202:203], off
	v_lshl_add_u64 v[202:203], s[70:71], 0, v[136:137]
	s_mov_b32 m0, s17
	s_nop 0
	global_load_lds_dwordx4 v[202:203], off
	s_mov_b32 m0, s18
	s_nop 0
	global_load_lds_dwordx4 v[214:215], off
	s_waitcnt vmcnt(8) lgkmcnt(0)
	s_setprio 1
	s_barrier
	v_mfma_f32_16x16x32_bf16 v[62:65], v[146:149], v[178:181], v[62:65]
	v_mfma_f32_16x16x32_bf16 v[58:61], v[154:157], v[178:181], v[58:61]
	v_mfma_f32_16x16x32_bf16 v[54:57], v[146:149], v[186:189], v[54:57]
	v_mfma_f32_16x16x32_bf16 v[50:53], v[154:157], v[186:189], v[50:53]
	v_mfma_f32_16x16x32_bf16 v[38:41], v[146:149], v[194:197], v[38:41]
	v_mfma_f32_16x16x32_bf16 v[34:37], v[154:157], v[194:197], v[34:37]
	v_mfma_f32_16x16x32_bf16 v[22:25], v[146:149], v[206:209], v[22:25]
	v_mfma_f32_16x16x32_bf16 v[18:21], v[154:157], v[206:209], v[18:21]
	v_mfma_f32_16x16x32_bf16 v[62:65], v[150:153], v[182:185], v[62:65]
	v_mfma_f32_16x16x32_bf16 v[58:61], v[158:161], v[182:185], v[58:61]
	v_mfma_f32_16x16x32_bf16 v[54:57], v[150:153], v[190:193], v[54:57]
	v_mfma_f32_16x16x32_bf16 v[50:53], v[158:161], v[190:193], v[50:53]
	v_mfma_f32_16x16x32_bf16 v[38:41], v[150:153], v[198:201], v[38:41]
	v_mfma_f32_16x16x32_bf16 v[34:37], v[158:161], v[198:201], v[34:37]
	v_mfma_f32_16x16x32_bf16 v[22:25], v[150:153], v[210:213], v[22:25]
	v_mfma_f32_16x16x32_bf16 v[18:21], v[158:161], v[210:213], v[18:21]
	v_mfma_f32_16x16x32_bf16 v[46:49], v[162:165], v[178:181], v[46:49]
	v_mfma_f32_16x16x32_bf16 v[42:45], v[170:173], v[178:181], v[42:45]
	v_mfma_f32_16x16x32_bf16 v[30:33], v[162:165], v[186:189], v[30:33]
	v_mfma_f32_16x16x32_bf16 v[26:29], v[170:173], v[186:189], v[26:29]
	v_mfma_f32_16x16x32_bf16 v[14:17], v[162:165], v[194:197], v[14:17]
	v_mfma_f32_16x16x32_bf16 v[10:13], v[170:173], v[194:197], v[10:13]
	v_mfma_f32_16x16x32_bf16 v[6:9], v[162:165], v[206:209], v[6:9]
	v_mfma_f32_16x16x32_bf16 v[2:5], v[170:173], v[206:209], v[2:5]
	v_mfma_f32_16x16x32_bf16 v[46:49], v[166:169], v[182:185], v[46:49]
	v_mfma_f32_16x16x32_bf16 v[42:45], v[174:177], v[182:185], v[42:45]
	v_mfma_f32_16x16x32_bf16 v[30:33], v[166:169], v[190:193], v[30:33]
	v_mfma_f32_16x16x32_bf16 v[26:29], v[174:177], v[190:193], v[26:29]
	v_mfma_f32_16x16x32_bf16 v[14:17], v[166:169], v[198:201], v[14:17]
	v_mfma_f32_16x16x32_bf16 v[10:13], v[174:177], v[198:201], v[10:13]
	v_mfma_f32_16x16x32_bf16 v[6:9], v[166:169], v[210:213], v[6:9]
	v_mfma_f32_16x16x32_bf16 v[2:5], v[174:177], v[210:213], v[2:5]
	s_setprio 0
	s_barrier
	v_add_u32_e32 v138, s87, v140
	ds_read_b128 v[146:149], v138
	ds_read_b128 v[150:153], v138 offset:1024
	ds_read_b128 v[154:157], v138 offset:2048
	ds_read_b128 v[158:161], v138 offset:3072
	v_add_u32_e32 v138, s86, v140
	ds_read_b128 v[162:165], v138
	ds_read_b128 v[166:169], v138 offset:1024
	ds_read_b128 v[170:173], v138 offset:2048
	ds_read_b128 v[174:177], v138 offset:3072
	s_mov_b32 m0, s19
	v_lshl_add_u64 v[216:217], s[68:69], 0, v[136:137]
	ds_read_b128 v[178:181], v144 offset:32768
	ds_read_b128 v[182:185], v144 offset:33792
	ds_read_b128 v[186:189], v144 offset:34816
	ds_read_b128 v[190:193], v144 offset:35840
	ds_read_b128 v[194:197], v144 offset:36864
	ds_read_b128 v[198:201], v144 offset:37888
	ds_read_b128 v[206:209], v144 offset:38912
	ds_read_b128 v[210:213], v144 offset:39936
	global_load_lds_dwordx4 v[216:217], off
	v_lshl_add_u64 v[216:217], s[68:69], 0, v[132:133]
	s_mov_b32 m0, s24
	s_nop 0
	global_load_lds_dwordx4 v[216:217], off
	s_waitcnt vmcnt(8) lgkmcnt(0)
	s_setprio 1
	s_barrier
	v_mfma_f32_16x16x32_bf16 v[126:129], v[146:149], v[178:181], v[126:129]
	v_mfma_f32_16x16x32_bf16 v[122:125], v[154:157], v[178:181], v[122:125]
	v_mfma_f32_16x16x32_bf16 v[118:121], v[146:149], v[186:189], v[118:121]
	v_mfma_f32_16x16x32_bf16 v[110:113], v[154:157], v[186:189], v[110:113]
	v_mfma_f32_16x16x32_bf16 v[102:105], v[146:149], v[194:197], v[102:105]
	v_mfma_f32_16x16x32_bf16 v[98:101], v[154:157], v[194:197], v[98:101]
	v_mfma_f32_16x16x32_bf16 v[86:89], v[146:149], v[206:209], v[86:89]
	v_mfma_f32_16x16x32_bf16 v[82:85], v[154:157], v[206:209], v[82:85]
	v_mfma_f32_16x16x32_bf16 v[126:129], v[150:153], v[182:185], v[126:129]
	v_mfma_f32_16x16x32_bf16 v[122:125], v[158:161], v[182:185], v[122:125]
	v_mfma_f32_16x16x32_bf16 v[118:121], v[150:153], v[190:193], v[118:121]
	v_mfma_f32_16x16x32_bf16 v[110:113], v[158:161], v[190:193], v[110:113]
	v_mfma_f32_16x16x32_bf16 v[102:105], v[150:153], v[198:201], v[102:105]
	v_mfma_f32_16x16x32_bf16 v[98:101], v[158:161], v[198:201], v[98:101]
	v_mfma_f32_16x16x32_bf16 v[86:89], v[150:153], v[210:213], v[86:89]
	v_mfma_f32_16x16x32_bf16 v[82:85], v[158:161], v[210:213], v[82:85]
	v_mfma_f32_16x16x32_bf16 v[114:117], v[162:165], v[178:181], v[114:117]
	v_mfma_f32_16x16x32_bf16 v[106:109], v[170:173], v[178:181], v[106:109]
	v_mfma_f32_16x16x32_bf16 v[94:97], v[162:165], v[186:189], v[94:97]
	v_mfma_f32_16x16x32_bf16 v[90:93], v[170:173], v[186:189], v[90:93]
	v_mfma_f32_16x16x32_bf16 v[78:81], v[162:165], v[194:197], v[78:81]
	v_mfma_f32_16x16x32_bf16 v[74:77], v[170:173], v[194:197], v[74:77]
	v_mfma_f32_16x16x32_bf16 v[70:73], v[162:165], v[206:209], v[70:73]
	v_mfma_f32_16x16x32_bf16 v[66:69], v[170:173], v[206:209], v[66:69]
	v_mfma_f32_16x16x32_bf16 v[114:117], v[166:169], v[182:185], v[114:117]
	v_mfma_f32_16x16x32_bf16 v[106:109], v[174:177], v[182:185], v[106:109]
	v_mfma_f32_16x16x32_bf16 v[94:97], v[166:169], v[190:193], v[94:97]
	v_mfma_f32_16x16x32_bf16 v[90:93], v[174:177], v[190:193], v[90:93]
	v_mfma_f32_16x16x32_bf16 v[78:81], v[166:169], v[198:201], v[78:81]
	v_mfma_f32_16x16x32_bf16 v[74:77], v[174:177], v[198:201], v[74:77]
	v_mfma_f32_16x16x32_bf16 v[70:73], v[166:169], v[210:213], v[70:73]
	v_mfma_f32_16x16x32_bf16 v[66:69], v[174:177], v[210:213], v[66:69]
	s_setprio 0
	s_barrier
	ds_read_b128 v[178:181], v144 offset:49152
	ds_read_b128 v[182:185], v144 offset:50176
	ds_read_b128 v[186:189], v144 offset:51200
	ds_read_b128 v[190:193], v144 offset:52224
	ds_read_b128 v[194:197], v144 offset:53248
	ds_read_b128 v[198:201], v144 offset:54272
	ds_read_b128 v[206:209], v144 offset:55296
	ds_read_b128 v[210:213], v144 offset:56320
	s_mov_b32 m0, s85
	v_lshl_add_u64 v[216:217], s[64:65], 0, v[134:135]
	global_load_lds_dwordx4 v[216:217], off
	v_lshl_add_u64 v[216:217], s[64:65], 0, v[130:131]
	s_mov_b32 m0, s83
	v_lshl_add_u64 v[202:203], v[202:203], 0, s[36:37]
	global_load_lds_dwordx4 v[216:217], off
	v_lshl_add_u64 v[216:217], s[66:67], 0, v[134:135]
	s_mov_b32 m0, s84
	s_nop 0
	global_load_lds_dwordx4 v[216:217], off
	v_lshl_add_u64 v[216:217], s[66:67], 0, v[130:131]
	s_mov_b32 m0, s12
	s_nop 0
	global_load_lds_dwordx4 v[216:217], off
	s_mov_b32 m0, s31
	s_nop 0
	global_load_lds_dwordx4 v[202:203], off
	v_lshl_add_u64 v[202:203], v[214:215], 0, s[36:37]
	s_mov_b32 m0, s33
	s_nop 0
	global_load_lds_dwordx4 v[202:203], off
	s_waitcnt vmcnt(8) lgkmcnt(0)
	s_setprio 1
	s_barrier
	v_mfma_f32_16x16x32_bf16 v[62:65], v[146:149], v[178:181], v[62:65]
	v_mfma_f32_16x16x32_bf16 v[58:61], v[154:157], v[178:181], v[58:61]
	v_mfma_f32_16x16x32_bf16 v[54:57], v[146:149], v[186:189], v[54:57]
	v_mfma_f32_16x16x32_bf16 v[50:53], v[154:157], v[186:189], v[50:53]
	v_mfma_f32_16x16x32_bf16 v[38:41], v[146:149], v[194:197], v[38:41]
	v_mfma_f32_16x16x32_bf16 v[34:37], v[154:157], v[194:197], v[34:37]
	v_mfma_f32_16x16x32_bf16 v[22:25], v[146:149], v[206:209], v[22:25]
	v_mfma_f32_16x16x32_bf16 v[18:21], v[154:157], v[206:209], v[18:21]
	v_mfma_f32_16x16x32_bf16 v[62:65], v[150:153], v[182:185], v[62:65]
	v_mfma_f32_16x16x32_bf16 v[58:61], v[158:161], v[182:185], v[58:61]
	v_mfma_f32_16x16x32_bf16 v[54:57], v[150:153], v[190:193], v[54:57]
	v_mfma_f32_16x16x32_bf16 v[50:53], v[158:161], v[190:193], v[50:53]
	v_mfma_f32_16x16x32_bf16 v[38:41], v[150:153], v[198:201], v[38:41]
	v_mfma_f32_16x16x32_bf16 v[34:37], v[158:161], v[198:201], v[34:37]
	v_mfma_f32_16x16x32_bf16 v[22:25], v[150:153], v[210:213], v[22:25]
	v_mfma_f32_16x16x32_bf16 v[18:21], v[158:161], v[210:213], v[18:21]
	v_mfma_f32_16x16x32_bf16 v[46:49], v[162:165], v[178:181], v[46:49]
	v_mfma_f32_16x16x32_bf16 v[42:45], v[170:173], v[178:181], v[42:45]
	v_mfma_f32_16x16x32_bf16 v[30:33], v[162:165], v[186:189], v[30:33]
	v_mfma_f32_16x16x32_bf16 v[26:29], v[170:173], v[186:189], v[26:29]
	v_mfma_f32_16x16x32_bf16 v[14:17], v[162:165], v[194:197], v[14:17]
	v_mfma_f32_16x16x32_bf16 v[10:13], v[170:173], v[194:197], v[10:13]
	v_mfma_f32_16x16x32_bf16 v[6:9], v[162:165], v[206:209], v[6:9]
	v_mfma_f32_16x16x32_bf16 v[2:5], v[170:173], v[206:209], v[2:5]
	v_mfma_f32_16x16x32_bf16 v[46:49], v[166:169], v[182:185], v[46:49]
	v_mfma_f32_16x16x32_bf16 v[42:45], v[174:177], v[182:185], v[42:45]
	v_mfma_f32_16x16x32_bf16 v[30:33], v[166:169], v[190:193], v[30:33]
	v_mfma_f32_16x16x32_bf16 v[26:29], v[174:177], v[190:193], v[26:29]
	v_mfma_f32_16x16x32_bf16 v[14:17], v[166:169], v[198:201], v[14:17]
	v_mfma_f32_16x16x32_bf16 v[10:13], v[174:177], v[198:201], v[10:13]
	v_mfma_f32_16x16x32_bf16 v[6:9], v[166:169], v[210:213], v[6:9]
	v_mfma_f32_16x16x32_bf16 v[2:5], v[174:177], v[210:213], v[2:5]
	s_setprio 0
	s_barrier
	s_mov_b64 s[66:67], 0
	s_mov_b64 s[64:65], -1
	s_mov_b32 s12, 2
	s_cbranch_vccz .LBB0_406
	s_and_b64 vcc, exec, s[22:23]
	s_cbranch_vccz .LBB0_409
	s_barrier

.LBB0_476:
	s_add_u32 s22, s2, s49
	s_addc_u32 s23, s3, s29
	s_and_b64 s[26:27], s[20:21], exec
	s_cselect_b32 s63, s23, s37
	s_cselect_b32 s64, s22, s36
	s_add_u32 s26, s16, s12
	s_addc_u32 s27, s17, s13
	s_and_b64 s[42:43], s[20:21], exec
	s_cselect_b32 s65, s27, s39
	s_cselect_b32 s66, s26, s38
	s_add_u32 s36, s36, 0x20080
	s_addc_u32 s37, s37, 0
	s_add_u32 s67, s38, 0x100
	s_addc_u32 s68, s39, 0
	s_mov_b32 s69, -2
	ds_read_b128 v[148:151], v144
	ds_read_b128 v[152:155], v144 offset:1024
	ds_read_b128 v[156:159], v144 offset:2048
	ds_read_b128 v[160:163], v144 offset:3072
	ds_read_b128 v[164:167], v145
	ds_read_b128 v[168:171], v145 offset:1024
	ds_read_b128 v[172:175], v145 offset:2048
	ds_read_b128 v[176:179], v145 offset:3072
	ds_read_b128 v[180:183], v146
	ds_read_b128 v[184:187], v146 offset:1024
	ds_read_b128 v[188:191], v146 offset:2048
	ds_read_b128 v[192:195], v146 offset:3072
	ds_read_b128 v[196:199], v146 offset:4096
	ds_read_b128 v[200:203], v146 offset:5120
	ds_read_b128 v[206:209], v146 offset:6144
	ds_read_b128 v[210:213], v146 offset:7168
	s_add_u32 s38, s36, 0xfffe0080
	s_addc_u32 s39, s37, -1
	s_cmp_eq_u32 s69, 4
	s_cselect_b32 s43, s63, s39
	s_cselect_b32 s42, s64, s38
	s_cselect_b32 s39, s65, s68
	s_cselect_b32 s38, s66, s67
	s_add_i32 m0, s19, 0xc000
	v_lshl_add_u64 v[214:215], s[36:37], 0, v[138:139]
	global_load_lds_dwordx4 v[214:215], off
	v_lshl_add_u64 v[214:215], s[36:37], 0, v[140:141]
	s_add_i32 m0, s19, 0xe000
	s_nop 0
	global_load_lds_dwordx4 v[214:215], off
	s_waitcnt vmcnt(8) lgkmcnt(0)
	s_setprio 1
	s_barrier
	v_mfma_f32_16x16x32_bf16 v[126:129], v[148:151], v[180:183], 0
	v_mfma_f32_16x16x32_bf16 v[122:125], v[156:159], v[180:183], 0
	v_mfma_f32_16x16x32_bf16 v[118:121], v[148:151], v[188:191], 0
	v_mfma_f32_16x16x32_bf16 v[114:117], v[156:159], v[188:191], 0
	v_mfma_f32_16x16x32_bf16 v[102:105], v[148:151], v[196:199], 0
	v_mfma_f32_16x16x32_bf16 v[98:101], v[156:159], v[196:199], 0
	v_mfma_f32_16x16x32_bf16 v[86:89], v[148:151], v[206:209], 0
	v_mfma_f32_16x16x32_bf16 v[82:85], v[156:159], v[206:209], 0
	v_mfma_f32_16x16x32_bf16 v[126:129], v[152:155], v[184:187], v[126:129]
	v_mfma_f32_16x16x32_bf16 v[122:125], v[160:163], v[184:187], v[122:125]
	v_mfma_f32_16x16x32_bf16 v[118:121], v[152:155], v[192:195], v[118:121]
	v_mfma_f32_16x16x32_bf16 v[114:117], v[160:163], v[192:195], v[114:117]
	v_mfma_f32_16x16x32_bf16 v[102:105], v[152:155], v[200:203], v[102:105]
	v_mfma_f32_16x16x32_bf16 v[98:101], v[160:163], v[200:203], v[98:101]
	v_mfma_f32_16x16x32_bf16 v[86:89], v[152:155], v[210:213], v[86:89]
	v_mfma_f32_16x16x32_bf16 v[82:85], v[160:163], v[210:213], v[82:85]
	v_mfma_f32_16x16x32_bf16 v[110:113], v[164:167], v[180:183], 0
	v_mfma_f32_16x16x32_bf16 v[106:109], v[172:175], v[180:183], 0
	v_mfma_f32_16x16x32_bf16 v[94:97], v[164:167], v[188:191], 0
	v_mfma_f32_16x16x32_bf16 v[90:93], v[172:175], v[188:191], 0
	v_mfma_f32_16x16x32_bf16 v[78:81], v[164:167], v[196:199], 0
	v_mfma_f32_16x16x32_bf16 v[74:77], v[172:175], v[196:199], 0
	v_mfma_f32_16x16x32_bf16 v[70:73], v[164:167], v[206:209], 0
	v_mfma_f32_16x16x32_bf16 v[66:69], v[172:175], v[206:209], 0
	v_mfma_f32_16x16x32_bf16 v[110:113], v[168:171], v[184:187], v[110:113]
	v_mfma_f32_16x16x32_bf16 v[106:109], v[176:179], v[184:187], v[106:109]
	v_mfma_f32_16x16x32_bf16 v[94:97], v[168:171], v[192:195], v[94:97]
	v_mfma_f32_16x16x32_bf16 v[90:93], v[176:179], v[192:195], v[90:93]
	v_mfma_f32_16x16x32_bf16 v[78:81], v[168:171], v[200:203], v[78:81]
	v_mfma_f32_16x16x32_bf16 v[74:77], v[176:179], v[200:203], v[74:77]
	v_mfma_f32_16x16x32_bf16 v[70:73], v[168:171], v[210:213], v[70:73]
	v_mfma_f32_16x16x32_bf16 v[66:69], v[176:179], v[210:213], v[66:69]
	s_setprio 0
	s_barrier
	ds_read_b128 v[180:183], v146 offset:16384
	ds_read_b128 v[184:187], v146 offset:17408
	ds_read_b128 v[188:191], v146 offset:18432
	ds_read_b128 v[192:195], v146 offset:19456
	ds_read_b128 v[196:199], v146 offset:20480
	ds_read_b128 v[200:203], v146 offset:21504
	ds_read_b128 v[206:209], v146 offset:22528
	ds_read_b128 v[210:213], v146 offset:23552
	s_add_i32 s70, s35, s18
	s_mov_b32 m0, s70
	v_lshl_add_u64 v[214:215], s[38:39], 0, v[134:135]
	global_load_lds_dwordx4 v[214:215], off
	s_add_i32 m0, s70, 0x2000
	s_add_u32 s70, s38, 0x200000
	v_lshl_add_u64 v[216:217], s[38:39], 0, v[130:131]
	s_addc_u32 s71, s39, 0
	s_add_i32 s72, s44, s18
	global_load_lds_dwordx4 v[216:217], off
	v_lshl_add_u64 v[218:219], s[70:71], 0, v[134:135]
	s_mov_b32 m0, s72
	v_lshl_add_u64 v[220:221], s[42:43], 0, v[132:133]
	global_load_lds_dwordx4 v[218:219], off
	v_lshl_add_u64 v[218:219], s[70:71], 0, v[130:131]
	s_add_i32 m0, s72, 0x2000
	s_nop 0
	global_load_lds_dwordx4 v[218:219], off
	v_lshl_add_u64 v[218:219], s[42:43], 0, v[136:137]
	s_mov_b32 m0, s19
	s_nop 0
	global_load_lds_dwordx4 v[218:219], off
	s_mov_b32 m0, s24
	s_nop 0
	global_load_lds_dwordx4 v[220:221], off
	s_waitcnt vmcnt(8) lgkmcnt(0)
	s_setprio 1
	s_barrier
	v_mfma_f32_16x16x32_bf16 v[62:65], v[148:151], v[180:183], 0
	v_mfma_f32_16x16x32_bf16 v[58:61], v[156:159], v[180:183], 0
	v_mfma_f32_16x16x32_bf16 v[54:57], v[148:151], v[188:191], 0
	v_mfma_f32_16x16x32_bf16 v[50:53], v[156:159], v[188:191], 0
	v_mfma_f32_16x16x32_bf16 v[38:41], v[148:151], v[196:199], 0
	v_mfma_f32_16x16x32_bf16 v[34:37], v[156:159], v[196:199], 0
	v_mfma_f32_16x16x32_bf16 v[22:25], v[148:151], v[206:209], 0
	v_mfma_f32_16x16x32_bf16 v[18:21], v[156:159], v[206:209], 0
	v_mfma_f32_16x16x32_bf16 v[62:65], v[152:155], v[184:187], v[62:65]
	v_mfma_f32_16x16x32_bf16 v[58:61], v[160:163], v[184:187], v[58:61]
	v_mfma_f32_16x16x32_bf16 v[54:57], v[152:155], v[192:195], v[54:57]
	v_mfma_f32_16x16x32_bf16 v[50:53], v[160:163], v[192:195], v[50:53]
	v_mfma_f32_16x16x32_bf16 v[38:41], v[152:155], v[200:203], v[38:41]
	v_mfma_f32_16x16x32_bf16 v[34:37], v[160:163], v[200:203], v[34:37]
	v_mfma_f32_16x16x32_bf16 v[22:25], v[152:155], v[210:213], v[22:25]
	v_mfma_f32_16x16x32_bf16 v[18:21], v[160:163], v[210:213], v[18:21]
	v_mfma_f32_16x16x32_bf16 v[46:49], v[164:167], v[180:183], 0
	v_mfma_f32_16x16x32_bf16 v[42:45], v[172:175], v[180:183], 0
	v_mfma_f32_16x16x32_bf16 v[30:33], v[164:167], v[188:191], 0
	v_mfma_f32_16x16x32_bf16 v[26:29], v[172:175], v[188:191], 0
	v_mfma_f32_16x16x32_bf16 v[14:17], v[164:167], v[196:199], 0
	v_mfma_f32_16x16x32_bf16 v[10:13], v[172:175], v[196:199], 0
	v_mfma_f32_16x16x32_bf16 v[6:9], v[164:167], v[206:209], 0
	v_mfma_f32_16x16x32_bf16 v[2:5], v[172:175], v[206:209], 0
	v_mfma_f32_16x16x32_bf16 v[46:49], v[168:171], v[184:187], v[46:49]
	v_mfma_f32_16x16x32_bf16 v[42:45], v[176:179], v[184:187], v[42:45]
	v_mfma_f32_16x16x32_bf16 v[30:33], v[168:171], v[192:195], v[30:33]
	v_mfma_f32_16x16x32_bf16 v[26:29], v[176:179], v[192:195], v[26:29]
	v_mfma_f32_16x16x32_bf16 v[14:17], v[168:171], v[200:203], v[14:17]
	v_mfma_f32_16x16x32_bf16 v[10:13], v[176:179], v[200:203], v[10:13]
	v_mfma_f32_16x16x32_bf16 v[6:9], v[168:171], v[210:213], v[6:9]
	v_mfma_f32_16x16x32_bf16 v[2:5], v[176:179], v[210:213], v[2:5]
	s_setprio 0
	s_barrier
	s_add_i32 s70, 0, 0x18000
	v_add_u32_e32 v147, s70, v143
	s_add_i32 s71, 0, 0x1c000
	ds_read_b128 v[148:151], v147
	ds_read_b128 v[152:155], v147 offset:1024
	ds_read_b128 v[156:159], v147 offset:2048
	ds_read_b128 v[160:163], v147 offset:3072
	v_add_u32_e32 v147, s71, v143
	ds_read_b128 v[164:167], v147
	ds_read_b128 v[168:171], v147 offset:1024
	ds_read_b128 v[172:175], v147 offset:2048
	ds_read_b128 v[176:179], v147 offset:3072
	s_add_u32 s42, s42, 0x20000
	s_addc_u32 s43, s43, 0
	s_mov_b32 m0, s25
	v_lshl_add_u64 v[222:223], s[42:43], 0, v[136:137]
	ds_read_b128 v[180:183], v146 offset:32768
	ds_read_b128 v[184:187], v146 offset:33792
	ds_read_b128 v[188:191], v146 offset:34816
	ds_read_b128 v[192:195], v146 offset:35840
	ds_read_b128 v[196:199], v146 offset:36864
	ds_read_b128 v[200:203], v146 offset:37888
	ds_read_b128 v[206:209], v146 offset:38912
	ds_read_b128 v[210:213], v146 offset:39936
	global_load_lds_dwordx4 v[222:223], off
	v_lshl_add_u64 v[222:223], s[42:43], 0, v[132:133]
	s_mov_b32 m0, s28
	s_nop 0
	global_load_lds_dwordx4 v[222:223], off
	s_waitcnt vmcnt(8) lgkmcnt(0)
	s_setprio 1
	s_barrier
	v_mfma_f32_16x16x32_bf16 v[126:129], v[148:151], v[180:183], v[126:129]
	v_mfma_f32_16x16x32_bf16 v[122:125], v[156:159], v[180:183], v[122:125]
	v_mfma_f32_16x16x32_bf16 v[118:121], v[148:151], v[188:191], v[118:121]
	v_mfma_f32_16x16x32_bf16 v[114:117], v[156:159], v[188:191], v[114:117]
	v_mfma_f32_16x16x32_bf16 v[102:105], v[148:151], v[196:199], v[102:105]
	v_mfma_f32_16x16x32_bf16 v[98:101], v[156:159], v[196:199], v[98:101]
	v_mfma_f32_16x16x32_bf16 v[86:89], v[148:151], v[206:209], v[86:89]
	v_mfma_f32_16x16x32_bf16 v[82:85], v[156:159], v[206:209], v[82:85]
	v_mfma_f32_16x16x32_bf16 v[126:129], v[152:155], v[184:187], v[126:129]
	v_mfma_f32_16x16x32_bf16 v[122:125], v[160:163], v[184:187], v[122:125]
	v_mfma_f32_16x16x32_bf16 v[118:121], v[152:155], v[192:195], v[118:121]
	v_mfma_f32_16x16x32_bf16 v[114:117], v[160:163], v[192:195], v[114:117]
	v_mfma_f32_16x16x32_bf16 v[102:105], v[152:155], v[200:203], v[102:105]
	v_mfma_f32_16x16x32_bf16 v[98:101], v[160:163], v[200:203], v[98:101]
	v_mfma_f32_16x16x32_bf16 v[86:89], v[152:155], v[210:213], v[86:89]
	v_mfma_f32_16x16x32_bf16 v[82:85], v[160:163], v[210:213], v[82:85]
	v_mfma_f32_16x16x32_bf16 v[110:113], v[164:167], v[180:183], v[110:113]
	v_mfma_f32_16x16x32_bf16 v[106:109], v[172:175], v[180:183], v[106:109]
	v_mfma_f32_16x16x32_bf16 v[94:97], v[164:167], v[188:191], v[94:97]
	v_mfma_f32_16x16x32_bf16 v[90:93], v[172:175], v[188:191], v[90:93]
	v_mfma_f32_16x16x32_bf16 v[78:81], v[164:167], v[196:199], v[78:81]
	v_mfma_f32_16x16x32_bf16 v[74:77], v[172:175], v[196:199], v[74:77]
	v_mfma_f32_16x16x32_bf16 v[70:73], v[164:167], v[206:209], v[70:73]
	v_mfma_f32_16x16x32_bf16 v[66:69], v[172:175], v[206:209], v[66:69]
	v_mfma_f32_16x16x32_bf16 v[110:113], v[168:171], v[184:187], v[110:113]
	v_mfma_f32_16x16x32_bf16 v[106:109], v[176:179], v[184:187], v[106:109]
	v_mfma_f32_16x16x32_bf16 v[94:97], v[168:171], v[192:195], v[94:97]
	v_mfma_f32_16x16x32_bf16 v[90:93], v[176:179], v[192:195], v[90:93]
	v_mfma_f32_16x16x32_bf16 v[78:81], v[168:171], v[200:203], v[78:81]
	v_mfma_f32_16x16x32_bf16 v[74:77], v[176:179], v[200:203], v[74:77]
	v_mfma_f32_16x16x32_bf16 v[70:73], v[168:171], v[210:213], v[70:73]
	v_mfma_f32_16x16x32_bf16 v[66:69], v[176:179], v[210:213], v[66:69]
	s_setprio 0
	s_barrier
	ds_read_b128 v[180:183], v146 offset:49152
	ds_read_b128 v[184:187], v146 offset:50176
	ds_read_b128 v[188:191], v146 offset:51200
	ds_read_b128 v[192:195], v146 offset:52224
	ds_read_b128 v[196:199], v146 offset:53248
	ds_read_b128 v[200:203], v146 offset:54272
	ds_read_b128 v[206:209], v146 offset:55296
	ds_read_b128 v[210:213], v146 offset:56320
	s_add_i32 s42, s70, s18
	s_mov_b32 m0, s42
	v_lshl_add_u64 v[214:215], v[214:215], 0, s[8:9]
	global_load_lds_dwordx4 v[214:215], off
	s_add_i32 m0, s42, 0x2000
	s_add_u32 s38, s38, 0x200080
	v_lshl_add_u64 v[214:215], v[216:217], 0, s[8:9]
	s_addc_u32 s39, s39, 0
	s_add_i32 s42, s71, s18
	global_load_lds_dwordx4 v[214:215], off
	v_lshl_add_u64 v[214:215], s[38:39], 0, v[134:135]
	s_mov_b32 m0, s42
	s_nop 0
	global_load_lds_dwordx4 v[214:215], off
	v_lshl_add_u64 v[214:215], s[38:39], 0, v[130:131]
	s_add_i32 m0, s42, 0x2000
	s_nop 0
	global_load_lds_dwordx4 v[214:215], off
	v_lshl_add_u64 v[214:215], v[218:219], 0, s[8:9]
	s_mov_b32 m0, s33
	s_nop 0
	global_load_lds_dwordx4 v[214:215], off
	v_lshl_add_u64 v[214:215], v[220:221], 0, s[8:9]
	s_mov_b32 m0, s34
	s_nop 0
	global_load_lds_dwordx4 v[214:215], off
	s_waitcnt vmcnt(8) lgkmcnt(0)
	s_setprio 1
	s_barrier
	v_mfma_f32_16x16x32_bf16 v[62:65], v[148:151], v[180:183], v[62:65]
	v_mfma_f32_16x16x32_bf16 v[58:61], v[156:159], v[180:183], v[58:61]
	v_mfma_f32_16x16x32_bf16 v[54:57], v[148:151], v[188:191], v[54:57]
	v_mfma_f32_16x16x32_bf16 v[50:53], v[156:159], v[188:191], v[50:53]
	v_mfma_f32_16x16x32_bf16 v[38:41], v[148:151], v[196:199], v[38:41]
	v_mfma_f32_16x16x32_bf16 v[34:37], v[156:159], v[196:199], v[34:37]
	v_mfma_f32_16x16x32_bf16 v[22:25], v[148:151], v[206:209], v[22:25]
	v_mfma_f32_16x16x32_bf16 v[18:21], v[156:159], v[206:209], v[18:21]
	v_mfma_f32_16x16x32_bf16 v[62:65], v[152:155], v[184:187], v[62:65]
	v_mfma_f32_16x16x32_bf16 v[58:61], v[160:163], v[184:187], v[58:61]
	v_mfma_f32_16x16x32_bf16 v[54:57], v[152:155], v[192:195], v[54:57]
	v_mfma_f32_16x16x32_bf16 v[50:53], v[160:163], v[192:195], v[50:53]
	v_mfma_f32_16x16x32_bf16 v[38:41], v[152:155], v[200:203], v[38:41]
	v_mfma_f32_16x16x32_bf16 v[34:37], v[160:163], v[200:203], v[34:37]
	v_mfma_f32_16x16x32_bf16 v[22:25], v[152:155], v[210:213], v[22:25]
	v_mfma_f32_16x16x32_bf16 v[18:21], v[160:163], v[210:213], v[18:21]
	v_mfma_f32_16x16x32_bf16 v[46:49], v[164:167], v[180:183], v[46:49]
	v_mfma_f32_16x16x32_bf16 v[42:45], v[172:175], v[180:183], v[42:45]
	v_mfma_f32_16x16x32_bf16 v[30:33], v[164:167], v[188:191], v[30:33]
	v_mfma_f32_16x16x32_bf16 v[26:29], v[172:175], v[188:191], v[26:29]
	v_mfma_f32_16x16x32_bf16 v[14:17], v[164:167], v[196:199], v[14:17]
	v_mfma_f32_16x16x32_bf16 v[10:13], v[172:175], v[196:199], v[10:13]
	v_mfma_f32_16x16x32_bf16 v[6:9], v[164:167], v[206:209], v[6:9]
	v_mfma_f32_16x16x32_bf16 v[2:5], v[172:175], v[206:209], v[2:5]
	v_mfma_f32_16x16x32_bf16 v[46:49], v[168:171], v[184:187], v[46:49]
	v_mfma_f32_16x16x32_bf16 v[42:45], v[176:179], v[184:187], v[42:45]
	v_mfma_f32_16x16x32_bf16 v[30:33], v[168:171], v[192:195], v[30:33]
	v_mfma_f32_16x16x32_bf16 v[26:29], v[176:179], v[192:195], v[26:29]
	v_mfma_f32_16x16x32_bf16 v[14:17], v[168:171], v[200:203], v[14:17]
	v_mfma_f32_16x16x32_bf16 v[10:13], v[176:179], v[200:203], v[10:13]
	v_mfma_f32_16x16x32_bf16 v[6:9], v[168:171], v[210:213], v[6:9]
	v_mfma_f32_16x16x32_bf16 v[2:5], v[176:179], v[210:213], v[2:5]
	s_setprio 0
	s_barrier
	s_add_i32 s69, s69, 2
	s_add_u32 s36, s36, 0x100
	s_addc_u32 s37, s37, 0
	s_add_u32 s67, s67, 0x100
	s_addc_u32 s68, s68, 0
	s_cmp_gt_u32 s69, 5
.LBB0_477:
	ds_read_b128 v[148:151], v144
	ds_read_b128 v[152:155], v144 offset:1024
	ds_read_b128 v[156:159], v144 offset:2048
	ds_read_b128 v[160:163], v144 offset:3072
	ds_read_b128 v[164:167], v145
	ds_read_b128 v[168:171], v145 offset:1024
	ds_read_b128 v[172:175], v145 offset:2048
	ds_read_b128 v[176:179], v145 offset:3072
	ds_read_b128 v[180:183], v146
	ds_read_b128 v[184:187], v146 offset:1024
	ds_read_b128 v[188:191], v146 offset:2048
	ds_read_b128 v[192:195], v146 offset:3072
	ds_read_b128 v[196:199], v146 offset:4096
	ds_read_b128 v[200:203], v146 offset:5120
	ds_read_b128 v[206:209], v146 offset:6144
	ds_read_b128 v[210:213], v146 offset:7168
	s_add_u32 s38, s36, 0xfffe0080
	s_addc_u32 s39, s37, -1
	s_cmp_eq_u32 s69, 4
	s_cselect_b32 s43, s63, s39
	s_cselect_b32 s42, s64, s38
	s_cselect_b32 s39, s65, s68
	s_cselect_b32 s38, s66, s67
	s_add_i32 m0, s19, 0xc000
	v_lshl_add_u64 v[214:215], s[36:37], 0, v[138:139]
	global_load_lds_dwordx4 v[214:215], off
	v_lshl_add_u64 v[214:215], s[36:37], 0, v[140:141]
	s_add_i32 m0, s19, 0xe000
	s_nop 0
	global_load_lds_dwordx4 v[214:215], off
	s_waitcnt vmcnt(8) lgkmcnt(0)
	s_setprio 1
	s_barrier
	v_mfma_f32_16x16x32_bf16 v[126:129], v[148:151], v[180:183], v[126:129]
	v_mfma_f32_16x16x32_bf16 v[122:125], v[156:159], v[180:183], v[122:125]
	v_mfma_f32_16x16x32_bf16 v[118:121], v[148:151], v[188:191], v[118:121]
	v_mfma_f32_16x16x32_bf16 v[114:117], v[156:159], v[188:191], v[114:117]
	v_mfma_f32_16x16x32_bf16 v[102:105], v[148:151], v[196:199], v[102:105]
	v_mfma_f32_16x16x32_bf16 v[98:101], v[156:159], v[196:199], v[98:101]
	v_mfma_f32_16x16x32_bf16 v[86:89], v[148:151], v[206:209], v[86:89]
	v_mfma_f32_16x16x32_bf16 v[82:85], v[156:159], v[206:209], v[82:85]
	v_mfma_f32_16x16x32_bf16 v[126:129], v[152:155], v[184:187], v[126:129]
	v_mfma_f32_16x16x32_bf16 v[122:125], v[160:163], v[184:187], v[122:125]
	v_mfma_f32_16x16x32_bf16 v[118:121], v[152:155], v[192:195], v[118:121]
	v_mfma_f32_16x16x32_bf16 v[114:117], v[160:163], v[192:195], v[114:117]
	v_mfma_f32_16x16x32_bf16 v[102:105], v[152:155], v[200:203], v[102:105]
	v_mfma_f32_16x16x32_bf16 v[98:101], v[160:163], v[200:203], v[98:101]
	v_mfma_f32_16x16x32_bf16 v[86:89], v[152:155], v[210:213], v[86:89]
	v_mfma_f32_16x16x32_bf16 v[82:85], v[160:163], v[210:213], v[82:85]
	v_mfma_f32_16x16x32_bf16 v[110:113], v[164:167], v[180:183], v[110:113]
	v_mfma_f32_16x16x32_bf16 v[106:109], v[172:175], v[180:183], v[106:109]
	v_mfma_f32_16x16x32_bf16 v[94:97], v[164:167], v[188:191], v[94:97]
	v_mfma_f32_16x16x32_bf16 v[90:93], v[172:175], v[188:191], v[90:93]
	v_mfma_f32_16x16x32_bf16 v[78:81], v[164:167], v[196:199], v[78:81]
	v_mfma_f32_16x16x32_bf16 v[74:77], v[172:175], v[196:199], v[74:77]
	v_mfma_f32_16x16x32_bf16 v[70:73], v[164:167], v[206:209], v[70:73]
	v_mfma_f32_16x16x32_bf16 v[66:69], v[172:175], v[206:209], v[66:69]
	v_mfma_f32_16x16x32_bf16 v[110:113], v[168:171], v[184:187], v[110:113]
	v_mfma_f32_16x16x32_bf16 v[106:109], v[176:179], v[184:187], v[106:109]
	v_mfma_f32_16x16x32_bf16 v[94:97], v[168:171], v[192:195], v[94:97]
	v_mfma_f32_16x16x32_bf16 v[90:93], v[176:179], v[192:195], v[90:93]
	v_mfma_f32_16x16x32_bf16 v[78:81], v[168:171], v[200:203], v[78:81]
	v_mfma_f32_16x16x32_bf16 v[74:77], v[176:179], v[200:203], v[74:77]
	v_mfma_f32_16x16x32_bf16 v[70:73], v[168:171], v[210:213], v[70:73]
	v_mfma_f32_16x16x32_bf16 v[66:69], v[176:179], v[210:213], v[66:69]
	s_setprio 0
	s_barrier
	ds_read_b128 v[180:183], v146 offset:16384
	ds_read_b128 v[184:187], v146 offset:17408
	ds_read_b128 v[188:191], v146 offset:18432
	ds_read_b128 v[192:195], v146 offset:19456
	ds_read_b128 v[196:199], v146 offset:20480
	ds_read_b128 v[200:203], v146 offset:21504
	ds_read_b128 v[206:209], v146 offset:22528
	ds_read_b128 v[210:213], v146 offset:23552
	s_add_i32 s70, s35, s18
	s_mov_b32 m0, s70
	v_lshl_add_u64 v[214:215], s[38:39], 0, v[134:135]
	global_load_lds_dwordx4 v[214:215], off
	s_add_i32 m0, s70, 0x2000
	s_add_u32 s70, s38, 0x200000
	v_lshl_add_u64 v[216:217], s[38:39], 0, v[130:131]
	s_addc_u32 s71, s39, 0
	s_add_i32 s72, s44, s18
	global_load_lds_dwordx4 v[216:217], off
	v_lshl_add_u64 v[218:219], s[70:71], 0, v[134:135]
	s_mov_b32 m0, s72
	v_lshl_add_u64 v[220:221], s[42:43], 0, v[132:133]
	global_load_lds_dwordx4 v[218:219], off
	v_lshl_add_u64 v[218:219], s[70:71], 0, v[130:131]
	s_add_i32 m0, s72, 0x2000
	s_nop 0
	global_load_lds_dwordx4 v[218:219], off
	v_lshl_add_u64 v[218:219], s[42:43], 0, v[136:137]
	s_mov_b32 m0, s19
	s_nop 0
	global_load_lds_dwordx4 v[218:219], off
	s_mov_b32 m0, s24
	s_nop 0
	global_load_lds_dwordx4 v[220:221], off
	s_waitcnt vmcnt(8) lgkmcnt(0)
	s_setprio 1
	s_barrier
	v_mfma_f32_16x16x32_bf16 v[62:65], v[148:151], v[180:183], v[62:65]
	v_mfma_f32_16x16x32_bf16 v[58:61], v[156:159], v[180:183], v[58:61]
	v_mfma_f32_16x16x32_bf16 v[54:57], v[148:151], v[188:191], v[54:57]
	v_mfma_f32_16x16x32_bf16 v[50:53], v[156:159], v[188:191], v[50:53]
	v_mfma_f32_16x16x32_bf16 v[38:41], v[148:151], v[196:199], v[38:41]
	v_mfma_f32_16x16x32_bf16 v[34:37], v[156:159], v[196:199], v[34:37]
	v_mfma_f32_16x16x32_bf16 v[22:25], v[148:151], v[206:209], v[22:25]
	v_mfma_f32_16x16x32_bf16 v[18:21], v[156:159], v[206:209], v[18:21]
	v_mfma_f32_16x16x32_bf16 v[62:65], v[152:155], v[184:187], v[62:65]
	v_mfma_f32_16x16x32_bf16 v[58:61], v[160:163], v[184:187], v[58:61]
	v_mfma_f32_16x16x32_bf16 v[54:57], v[152:155], v[192:195], v[54:57]
	v_mfma_f32_16x16x32_bf16 v[50:53], v[160:163], v[192:195], v[50:53]
	v_mfma_f32_16x16x32_bf16 v[38:41], v[152:155], v[200:203], v[38:41]
	v_mfma_f32_16x16x32_bf16 v[34:37], v[160:163], v[200:203], v[34:37]
	v_mfma_f32_16x16x32_bf16 v[22:25], v[152:155], v[210:213], v[22:25]
	v_mfma_f32_16x16x32_bf16 v[18:21], v[160:163], v[210:213], v[18:21]
	v_mfma_f32_16x16x32_bf16 v[46:49], v[164:167], v[180:183], v[46:49]
	v_mfma_f32_16x16x32_bf16 v[42:45], v[172:175], v[180:183], v[42:45]
	v_mfma_f32_16x16x32_bf16 v[30:33], v[164:167], v[188:191], v[30:33]
	v_mfma_f32_16x16x32_bf16 v[26:29], v[172:175], v[188:191], v[26:29]
	v_mfma_f32_16x16x32_bf16 v[14:17], v[164:167], v[196:199], v[14:17]
	v_mfma_f32_16x16x32_bf16 v[10:13], v[172:175], v[196:199], v[10:13]
	v_mfma_f32_16x16x32_bf16 v[6:9], v[164:167], v[206:209], v[6:9]
	v_mfma_f32_16x16x32_bf16 v[2:5], v[172:175], v[206:209], v[2:5]
	v_mfma_f32_16x16x32_bf16 v[46:49], v[168:171], v[184:187], v[46:49]
	v_mfma_f32_16x16x32_bf16 v[42:45], v[176:179], v[184:187], v[42:45]
	v_mfma_f32_16x16x32_bf16 v[30:33], v[168:171], v[192:195], v[30:33]
	v_mfma_f32_16x16x32_bf16 v[26:29], v[176:179], v[192:195], v[26:29]
	v_mfma_f32_16x16x32_bf16 v[14:17], v[168:171], v[200:203], v[14:17]
	v_mfma_f32_16x16x32_bf16 v[10:13], v[176:179], v[200:203], v[10:13]
	v_mfma_f32_16x16x32_bf16 v[6:9], v[168:171], v[210:213], v[6:9]
	v_mfma_f32_16x16x32_bf16 v[2:5], v[176:179], v[210:213], v[2:5]
	s_setprio 0
	s_barrier
	s_add_i32 s70, 0, 0x18000
	v_add_u32_e32 v147, s70, v143
	s_add_i32 s71, 0, 0x1c000
	ds_read_b128 v[148:151], v147
	ds_read_b128 v[152:155], v147 offset:1024
	ds_read_b128 v[156:159], v147 offset:2048
	ds_read_b128 v[160:163], v147 offset:3072
	v_add_u32_e32 v147, s71, v143
	ds_read_b128 v[164:167], v147
	ds_read_b128 v[168:171], v147 offset:1024
	ds_read_b128 v[172:175], v147 offset:2048
	ds_read_b128 v[176:179], v147 offset:3072
	s_add_u32 s42, s42, 0x20000
	s_addc_u32 s43, s43, 0
	s_mov_b32 m0, s25
	v_lshl_add_u64 v[222:223], s[42:43], 0, v[136:137]
	ds_read_b128 v[180:183], v146 offset:32768
	ds_read_b128 v[184:187], v146 offset:33792
	ds_read_b128 v[188:191], v146 offset:34816
	ds_read_b128 v[192:195], v146 offset:35840
	ds_read_b128 v[196:199], v146 offset:36864
	ds_read_b128 v[200:203], v146 offset:37888
	ds_read_b128 v[206:209], v146 offset:38912
	ds_read_b128 v[210:213], v146 offset:39936
	global_load_lds_dwordx4 v[222:223], off
	v_lshl_add_u64 v[222:223], s[42:43], 0, v[132:133]
	s_mov_b32 m0, s28
	s_nop 0
	global_load_lds_dwordx4 v[222:223], off
	s_waitcnt vmcnt(8) lgkmcnt(0)
	s_setprio 1
	s_barrier
	v_mfma_f32_16x16x32_bf16 v[126:129], v[148:151], v[180:183], v[126:129]
	v_mfma_f32_16x16x32_bf16 v[122:125], v[156:159], v[180:183], v[122:125]
	v_mfma_f32_16x16x32_bf16 v[118:121], v[148:151], v[188:191], v[118:121]
	v_mfma_f32_16x16x32_bf16 v[114:117], v[156:159], v[188:191], v[114:117]
	v_mfma_f32_16x16x32_bf16 v[102:105], v[148:151], v[196:199], v[102:105]
	v_mfma_f32_16x16x32_bf16 v[98:101], v[156:159], v[196:199], v[98:101]
	v_mfma_f32_16x16x32_bf16 v[86:89], v[148:151], v[206:209], v[86:89]
	v_mfma_f32_16x16x32_bf16 v[82:85], v[156:159], v[206:209], v[82:85]
	v_mfma_f32_16x16x32_bf16 v[126:129], v[152:155], v[184:187], v[126:129]
	v_mfma_f32_16x16x32_bf16 v[122:125], v[160:163], v[184:187], v[122:125]
	v_mfma_f32_16x16x32_bf16 v[118:121], v[152:155], v[192:195], v[118:121]
	v_mfma_f32_16x16x32_bf16 v[114:117], v[160:163], v[192:195], v[114:117]
	v_mfma_f32_16x16x32_bf16 v[102:105], v[152:155], v[200:203], v[102:105]
	v_mfma_f32_16x16x32_bf16 v[98:101], v[160:163], v[200:203], v[98:101]
	v_mfma_f32_16x16x32_bf16 v[86:89], v[152:155], v[210:213], v[86:89]
	v_mfma_f32_16x16x32_bf16 v[82:85], v[160:163], v[210:213], v[82:85]
	v_mfma_f32_16x16x32_bf16 v[110:113], v[164:167], v[180:183], v[110:113]
	v_mfma_f32_16x16x32_bf16 v[106:109], v[172:175], v[180:183], v[106:109]
	v_mfma_f32_16x16x32_bf16 v[94:97], v[164:167], v[188:191], v[94:97]
	v_mfma_f32_16x16x32_bf16 v[90:93], v[172:175], v[188:191], v[90:93]
	v_mfma_f32_16x16x32_bf16 v[78:81], v[164:167], v[196:199], v[78:81]
	v_mfma_f32_16x16x32_bf16 v[74:77], v[172:175], v[196:199], v[74:77]
	v_mfma_f32_16x16x32_bf16 v[70:73], v[164:167], v[206:209], v[70:73]
	v_mfma_f32_16x16x32_bf16 v[66:69], v[172:175], v[206:209], v[66:69]
	v_mfma_f32_16x16x32_bf16 v[110:113], v[168:171], v[184:187], v[110:113]
	v_mfma_f32_16x16x32_bf16 v[106:109], v[176:179], v[184:187], v[106:109]
	v_mfma_f32_16x16x32_bf16 v[94:97], v[168:171], v[192:195], v[94:97]
	v_mfma_f32_16x16x32_bf16 v[90:93], v[176:179], v[192:195], v[90:93]
	v_mfma_f32_16x16x32_bf16 v[78:81], v[168:171], v[200:203], v[78:81]
	v_mfma_f32_16x16x32_bf16 v[74:77], v[176:179], v[200:203], v[74:77]
	v_mfma_f32_16x16x32_bf16 v[70:73], v[168:171], v[210:213], v[70:73]
	v_mfma_f32_16x16x32_bf16 v[66:69], v[176:179], v[210:213], v[66:69]
	s_setprio 0
	s_barrier
	ds_read_b128 v[180:183], v146 offset:49152
	ds_read_b128 v[184:187], v146 offset:50176
	ds_read_b128 v[188:191], v146 offset:51200
	ds_read_b128 v[192:195], v146 offset:52224
	ds_read_b128 v[196:199], v146 offset:53248
	ds_read_b128 v[200:203], v146 offset:54272
	ds_read_b128 v[206:209], v146 offset:55296
	ds_read_b128 v[210:213], v146 offset:56320
	s_add_i32 s42, s70, s18
	s_mov_b32 m0, s42
	v_lshl_add_u64 v[214:215], v[214:215], 0, s[8:9]
	global_load_lds_dwordx4 v[214:215], off
	s_add_i32 m0, s42, 0x2000
	s_add_u32 s38, s38, 0x200080
	v_lshl_add_u64 v[214:215], v[216:217], 0, s[8:9]
	s_addc_u32 s39, s39, 0
	s_add_i32 s42, s71, s18
	global_load_lds_dwordx4 v[214:215], off
	v_lshl_add_u64 v[214:215], s[38:39], 0, v[134:135]
	s_mov_b32 m0, s42
	s_nop 0
	global_load_lds_dwordx4 v[214:215], off
	v_lshl_add_u64 v[214:215], s[38:39], 0, v[130:131]
	s_add_i32 m0, s42, 0x2000
	s_nop 0
	global_load_lds_dwordx4 v[214:215], off
	v_lshl_add_u64 v[214:215], v[218:219], 0, s[8:9]
	s_mov_b32 m0, s33
	s_nop 0
	global_load_lds_dwordx4 v[214:215], off
	v_lshl_add_u64 v[214:215], v[220:221], 0, s[8:9]
	s_mov_b32 m0, s34
	s_nop 0
	global_load_lds_dwordx4 v[214:215], off
	s_waitcnt vmcnt(8) lgkmcnt(0)
	s_setprio 1
	s_barrier
	v_mfma_f32_16x16x32_bf16 v[62:65], v[148:151], v[180:183], v[62:65]
	v_mfma_f32_16x16x32_bf16 v[58:61], v[156:159], v[180:183], v[58:61]
	v_mfma_f32_16x16x32_bf16 v[54:57], v[148:151], v[188:191], v[54:57]
	v_mfma_f32_16x16x32_bf16 v[50:53], v[156:159], v[188:191], v[50:53]
	v_mfma_f32_16x16x32_bf16 v[38:41], v[148:151], v[196:199], v[38:41]
	v_mfma_f32_16x16x32_bf16 v[34:37], v[156:159], v[196:199], v[34:37]
	v_mfma_f32_16x16x32_bf16 v[22:25], v[148:151], v[206:209], v[22:25]
	v_mfma_f32_16x16x32_bf16 v[18:21], v[156:159], v[206:209], v[18:21]
	v_mfma_f32_16x16x32_bf16 v[62:65], v[152:155], v[184:187], v[62:65]
	v_mfma_f32_16x16x32_bf16 v[58:61], v[160:163], v[184:187], v[58:61]
	v_mfma_f32_16x16x32_bf16 v[54:57], v[152:155], v[192:195], v[54:57]
	v_mfma_f32_16x16x32_bf16 v[50:53], v[160:163], v[192:195], v[50:53]
	v_mfma_f32_16x16x32_bf16 v[38:41], v[152:155], v[200:203], v[38:41]
	v_mfma_f32_16x16x32_bf16 v[34:37], v[160:163], v[200:203], v[34:37]
	v_mfma_f32_16x16x32_bf16 v[22:25], v[152:155], v[210:213], v[22:25]
	v_mfma_f32_16x16x32_bf16 v[18:21], v[160:163], v[210:213], v[18:21]
	v_mfma_f32_16x16x32_bf16 v[46:49], v[164:167], v[180:183], v[46:49]
	v_mfma_f32_16x16x32_bf16 v[42:45], v[172:175], v[180:183], v[42:45]
	v_mfma_f32_16x16x32_bf16 v[30:33], v[164:167], v[188:191], v[30:33]
	v_mfma_f32_16x16x32_bf16 v[26:29], v[172:175], v[188:191], v[26:29]
	v_mfma_f32_16x16x32_bf16 v[14:17], v[164:167], v[196:199], v[14:17]
	v_mfma_f32_16x16x32_bf16 v[10:13], v[172:175], v[196:199], v[10:13]
	v_mfma_f32_16x16x32_bf16 v[6:9], v[164:167], v[206:209], v[6:9]
	v_mfma_f32_16x16x32_bf16 v[2:5], v[172:175], v[206:209], v[2:5]
	v_mfma_f32_16x16x32_bf16 v[46:49], v[168:171], v[184:187], v[46:49]
	v_mfma_f32_16x16x32_bf16 v[42:45], v[176:179], v[184:187], v[42:45]
	v_mfma_f32_16x16x32_bf16 v[30:33], v[168:171], v[192:195], v[30:33]
	v_mfma_f32_16x16x32_bf16 v[26:29], v[176:179], v[192:195], v[26:29]
	v_mfma_f32_16x16x32_bf16 v[14:17], v[168:171], v[200:203], v[14:17]
	v_mfma_f32_16x16x32_bf16 v[10:13], v[176:179], v[200:203], v[10:13]
	v_mfma_f32_16x16x32_bf16 v[6:9], v[168:171], v[210:213], v[6:9]
	v_mfma_f32_16x16x32_bf16 v[2:5], v[176:179], v[210:213], v[2:5]
	s_setprio 0
	s_barrier
	s_add_i32 s69, s69, 2
	s_add_u32 s36, s36, 0x100
	s_addc_u32 s37, s37, 0
	s_add_u32 s67, s67, 0x100
	s_addc_u32 s68, s68, 0
	s_cmp_gt_u32 s69, 5
	s_cbranch_scc0 .LBB0_477
	s_and_b64 vcc, exec, s[10:11]
	s_cbranch_vccz .LBB0_480
	s_barrier

.LBB0_565:
	v_readlane_b32 s62, v249, 27
	v_readlane_b32 s63, v249, 28
	s_add_u32 s72, s62, s68
	s_addc_u32 s73, s63, s69
	s_and_b64 s[62:63], s[70:71], exec
	s_cselect_b32 s31, s73, s77
	s_cselect_b32 s33, s72, s76
	s_add_u32 s74, s35, s66
	s_addc_u32 s75, s85, s67
	s_and_b64 s[62:63], s[70:71], exec
	s_cselect_b32 s34, s75, s79
	s_cselect_b32 s39, s74, s78
	s_add_i32 s45, s7, -2
	s_add_u32 s76, s76, 0x40080
	s_addc_u32 s77, s77, 0
	s_add_u32 s47, s78, 0x100
	s_addc_u32 s62, s79, 0
	s_mov_b32 s63, 0
	ds_read_b128 v[114:117], v190
	ds_read_b128 v[118:121], v190 offset:1024
	ds_read_b128 v[122:125], v190 offset:2048
	ds_read_b128 v[126:129], v190 offset:3072
	ds_read_b128 v[146:149], v191
	ds_read_b128 v[150:153], v191 offset:1024
	ds_read_b128 v[154:157], v191 offset:2048
	ds_read_b128 v[158:161], v191 offset:3072
	ds_read_b128 v[162:165], v192
	ds_read_b128 v[166:169], v192 offset:1024
	ds_read_b128 v[194:197], v192 offset:2048
	ds_read_b128 v[198:201], v192 offset:3072
	ds_read_b128 v[206:209], v192 offset:4096
	ds_read_b128 v[210:213], v192 offset:5120
	ds_read_b128 v[214:217], v192 offset:6144
	ds_read_b128 v[218:221], v192 offset:7168
	s_waitcnt vmcnt(0)
	s_add_i32 s82, s63, 2
	s_add_u32 s78, s76, 0xfffc0080
	s_addc_u32 s79, s77, -1
	s_cmp_eq_u32 s45, s63
	s_cselect_b32 s81, s31, s79
	s_cselect_b32 s80, s33, s78
	s_cselect_b32 s79, s34, s62
	s_cselect_b32 s78, s39, s47
	s_add_i32 m0, s87, 0xc000
	v_lshl_add_u64 v[186:187], s[76:77], 0, v[180:181]
	global_load_lds_dwordx4 v[186:187], off
	v_lshl_add_u64 v[186:187], s[76:77], 0, v[182:183]
	s_add_i32 m0, s87, 0xe000
	s_nop 0
	global_load_lds_dwordx4 v[186:187], off
	s_waitcnt vmcnt(8)
	s_waitcnt lgkmcnt(0)
	s_setprio 1
	s_barrier
	v_mfma_f32_16x16x32_bf16 v[142:145], v[114:117], v[162:165], 0
	v_mfma_f32_16x16x32_bf16 v[138:141], v[122:125], v[162:165], 0
	v_mfma_f32_16x16x32_bf16 v[110:113], v[114:117], v[194:197], 0
	v_mfma_f32_16x16x32_bf16 v[106:109], v[122:125], v[194:197], 0
	v_mfma_f32_16x16x32_bf16 v[98:101], v[114:117], v[206:209], 0
	v_mfma_f32_16x16x32_bf16 v[90:93], v[122:125], v[206:209], 0
	v_mfma_f32_16x16x32_bf16 v[82:85], v[114:117], v[214:217], 0
	v_mfma_f32_16x16x32_bf16 v[74:77], v[122:125], v[214:217], 0
	v_mfma_f32_16x16x32_bf16 v[142:145], v[118:121], v[166:169], v[142:145]
	v_mfma_f32_16x16x32_bf16 v[138:141], v[126:129], v[166:169], v[138:141]
	v_mfma_f32_16x16x32_bf16 v[110:113], v[118:121], v[198:201], v[110:113]
	v_mfma_f32_16x16x32_bf16 v[106:109], v[126:129], v[198:201], v[106:109]
	v_mfma_f32_16x16x32_bf16 v[98:101], v[118:121], v[210:213], v[98:101]
	v_mfma_f32_16x16x32_bf16 v[90:93], v[126:129], v[210:213], v[90:93]
	v_mfma_f32_16x16x32_bf16 v[82:85], v[118:121], v[218:221], v[82:85]
	v_mfma_f32_16x16x32_bf16 v[74:77], v[126:129], v[218:221], v[74:77]
	v_mfma_f32_16x16x32_bf16 v[134:137], v[146:149], v[162:165], 0
	v_mfma_f32_16x16x32_bf16 v[130:133], v[154:157], v[162:165], 0
	v_mfma_f32_16x16x32_bf16 v[102:105], v[146:149], v[194:197], 0
	v_mfma_f32_16x16x32_bf16 v[94:97], v[154:157], v[194:197], 0
	v_mfma_f32_16x16x32_bf16 v[86:89], v[146:149], v[206:209], 0
	v_mfma_f32_16x16x32_bf16 v[78:81], v[154:157], v[206:209], 0
	v_mfma_f32_16x16x32_bf16 v[70:73], v[146:149], v[214:217], 0
	v_mfma_f32_16x16x32_bf16 v[66:69], v[154:157], v[214:217], 0
	v_mfma_f32_16x16x32_bf16 v[134:137], v[150:153], v[166:169], v[134:137]
	v_mfma_f32_16x16x32_bf16 v[130:133], v[158:161], v[166:169], v[130:133]
	v_mfma_f32_16x16x32_bf16 v[102:105], v[150:153], v[198:201], v[102:105]
	v_mfma_f32_16x16x32_bf16 v[94:97], v[158:161], v[198:201], v[94:97]
	v_mfma_f32_16x16x32_bf16 v[86:89], v[150:153], v[210:213], v[86:89]
	v_mfma_f32_16x16x32_bf16 v[78:81], v[158:161], v[210:213], v[78:81]
	v_mfma_f32_16x16x32_bf16 v[70:73], v[150:153], v[218:221], v[70:73]
	v_mfma_f32_16x16x32_bf16 v[66:69], v[158:161], v[218:221], v[66:69]
	s_setprio 0
	s_barrier
	ds_read_b128 v[162:165], v192 offset:16384
	ds_read_b128 v[166:169], v192 offset:17408
	ds_read_b128 v[194:197], v192 offset:18432
	ds_read_b128 v[198:201], v192 offset:19456
	ds_read_b128 v[206:209], v192 offset:20480
	ds_read_b128 v[210:213], v192 offset:21504
	ds_read_b128 v[214:217], v192 offset:22528
	ds_read_b128 v[218:221], v192 offset:23552
	s_add_i32 s63, s24, s86
	s_mov_b32 m0, s63
	v_lshl_add_u64 v[186:187], s[78:79], 0, v[172:173]
	global_load_lds_dwordx4 v[186:187], off
	s_add_i32 m0, s63, 0x2000
	s_add_u32 vcc_lo, s78, 0x40000
	v_lshl_add_u64 v[202:203], s[78:79], 0, v[176:177]
	s_addc_u32 vcc_hi, s79, 0
	s_add_i32 s63, s25, s86
	global_load_lds_dwordx4 v[202:203], off
	v_lshl_add_u64 v[222:223], vcc, 0, v[172:173]
	s_mov_b32 m0, s63
	v_lshl_add_u64 v[224:225], s[80:81], 0, v[174:175]
	global_load_lds_dwordx4 v[222:223], off
	v_lshl_add_u64 v[222:223], vcc, 0, v[176:177]
	s_add_i32 m0, s63, 0x2000
	s_nop 0
	global_load_lds_dwordx4 v[222:223], off
	v_lshl_add_u64 v[222:223], s[80:81], 0, v[170:171]
	s_mov_b32 m0, s87
	s_nop 0
	global_load_lds_dwordx4 v[222:223], off
	s_mov_b32 m0, s88
	s_nop 0
	global_load_lds_dwordx4 v[224:225], off
	s_waitcnt vmcnt(8) lgkmcnt(0)
	s_setprio 1
	s_barrier
	v_mfma_f32_16x16x32_bf16 v[62:65], v[114:117], v[162:165], 0
	v_mfma_f32_16x16x32_bf16 v[58:61], v[122:125], v[162:165], 0
	v_mfma_f32_16x16x32_bf16 v[50:53], v[114:117], v[194:197], 0
	v_mfma_f32_16x16x32_bf16 v[42:45], v[122:125], v[194:197], 0
	v_mfma_f32_16x16x32_bf16 v[34:37], v[114:117], v[206:209], 0
	v_mfma_f32_16x16x32_bf16 v[26:29], v[122:125], v[206:209], 0
	v_mfma_f32_16x16x32_bf16 v[18:21], v[114:117], v[214:217], 0
	v_mfma_f32_16x16x32_bf16 v[10:13], v[122:125], v[214:217], 0
	v_mfma_f32_16x16x32_bf16 v[62:65], v[118:121], v[166:169], v[62:65]
	v_mfma_f32_16x16x32_bf16 v[58:61], v[126:129], v[166:169], v[58:61]
	v_mfma_f32_16x16x32_bf16 v[50:53], v[118:121], v[198:201], v[50:53]
	v_mfma_f32_16x16x32_bf16 v[42:45], v[126:129], v[198:201], v[42:45]
	v_mfma_f32_16x16x32_bf16 v[34:37], v[118:121], v[210:213], v[34:37]
	v_mfma_f32_16x16x32_bf16 v[26:29], v[126:129], v[210:213], v[26:29]
	v_mfma_f32_16x16x32_bf16 v[18:21], v[118:121], v[218:221], v[18:21]
	v_mfma_f32_16x16x32_bf16 v[10:13], v[126:129], v[218:221], v[10:13]
	v_mfma_f32_16x16x32_bf16 v[54:57], v[146:149], v[162:165], 0
	v_mfma_f32_16x16x32_bf16 v[46:49], v[154:157], v[162:165], 0
	v_mfma_f32_16x16x32_bf16 v[38:41], v[146:149], v[194:197], 0
	v_mfma_f32_16x16x32_bf16 v[30:33], v[154:157], v[194:197], 0
	v_mfma_f32_16x16x32_bf16 v[22:25], v[146:149], v[206:209], 0
	v_mfma_f32_16x16x32_bf16 v[14:17], v[154:157], v[206:209], 0
	v_mfma_f32_16x16x32_bf16 v[6:9], v[146:149], v[214:217], 0
	v_mfma_f32_16x16x32_bf16 v[2:5], v[154:157], v[214:217], 0
	v_mfma_f32_16x16x32_bf16 v[54:57], v[150:153], v[166:169], v[54:57]
	v_mfma_f32_16x16x32_bf16 v[46:49], v[158:161], v[166:169], v[46:49]
	v_mfma_f32_16x16x32_bf16 v[38:41], v[150:153], v[198:201], v[38:41]
	v_mfma_f32_16x16x32_bf16 v[30:33], v[158:161], v[198:201], v[30:33]
	v_mfma_f32_16x16x32_bf16 v[22:25], v[150:153], v[210:213], v[22:25]
	v_mfma_f32_16x16x32_bf16 v[14:17], v[158:161], v[210:213], v[14:17]
	v_mfma_f32_16x16x32_bf16 v[6:9], v[150:153], v[218:221], v[6:9]
	v_mfma_f32_16x16x32_bf16 v[2:5], v[158:161], v[218:221], v[2:5]
	s_setprio 0
	s_barrier
	s_add_i32 s63, 0, 0x18000
	s_add_i32 s83, 0, 0x1c000
	v_add_u32_e32 v126, s63, v189
	v_add_u32_e32 v158, s83, v189
	ds_read_b128 v[114:117], v126
	ds_read_b128 v[118:121], v126 offset:1024
	ds_read_b128 v[122:125], v126 offset:2048
	ds_read_b128 v[126:129], v126 offset:3072
	ds_read_b128 v[146:149], v158
	ds_read_b128 v[150:153], v158 offset:1024
	ds_read_b128 v[154:157], v158 offset:2048
	ds_read_b128 v[158:161], v158 offset:3072
	s_add_u32 s80, s80, 0x40000
	s_addc_u32 s81, s81, 0
	s_mov_b32 m0, s89
	v_lshl_add_u64 v[226:227], s[80:81], 0, v[170:171]
	ds_read_b128 v[162:165], v192 offset:32768
	ds_read_b128 v[166:169], v192 offset:33792
	ds_read_b128 v[194:197], v192 offset:34816
	ds_read_b128 v[198:201], v192 offset:35840
	ds_read_b128 v[206:209], v192 offset:36864
	ds_read_b128 v[210:213], v192 offset:37888
	ds_read_b128 v[214:217], v192 offset:38912
	ds_read_b128 v[218:221], v192 offset:39936
	global_load_lds_dwordx4 v[226:227], off
	v_lshl_add_u64 v[226:227], s[80:81], 0, v[174:175]
	s_mov_b32 m0, s90
	s_nop 0
	global_load_lds_dwordx4 v[226:227], off
	s_waitcnt vmcnt(8) lgkmcnt(0)
	s_setprio 1
	s_barrier
	v_mfma_f32_16x16x32_bf16 v[142:145], v[114:117], v[162:165], v[142:145]
	v_mfma_f32_16x16x32_bf16 v[138:141], v[122:125], v[162:165], v[138:141]
	v_mfma_f32_16x16x32_bf16 v[110:113], v[114:117], v[194:197], v[110:113]
	v_mfma_f32_16x16x32_bf16 v[106:109], v[122:125], v[194:197], v[106:109]
	v_mfma_f32_16x16x32_bf16 v[98:101], v[114:117], v[206:209], v[98:101]
	v_mfma_f32_16x16x32_bf16 v[90:93], v[122:125], v[206:209], v[90:93]
	v_mfma_f32_16x16x32_bf16 v[82:85], v[114:117], v[214:217], v[82:85]
	v_mfma_f32_16x16x32_bf16 v[74:77], v[122:125], v[214:217], v[74:77]
	v_mfma_f32_16x16x32_bf16 v[142:145], v[118:121], v[166:169], v[142:145]
	v_mfma_f32_16x16x32_bf16 v[138:141], v[126:129], v[166:169], v[138:141]
	v_mfma_f32_16x16x32_bf16 v[110:113], v[118:121], v[198:201], v[110:113]
	v_mfma_f32_16x16x32_bf16 v[106:109], v[126:129], v[198:201], v[106:109]
	v_mfma_f32_16x16x32_bf16 v[98:101], v[118:121], v[210:213], v[98:101]
	v_mfma_f32_16x16x32_bf16 v[90:93], v[126:129], v[210:213], v[90:93]
	v_mfma_f32_16x16x32_bf16 v[82:85], v[118:121], v[218:221], v[82:85]
	v_mfma_f32_16x16x32_bf16 v[74:77], v[126:129], v[218:221], v[74:77]
	v_mfma_f32_16x16x32_bf16 v[134:137], v[146:149], v[162:165], v[134:137]
	v_mfma_f32_16x16x32_bf16 v[130:133], v[154:157], v[162:165], v[130:133]
	v_mfma_f32_16x16x32_bf16 v[102:105], v[146:149], v[194:197], v[102:105]
	v_mfma_f32_16x16x32_bf16 v[94:97], v[154:157], v[194:197], v[94:97]
	v_mfma_f32_16x16x32_bf16 v[86:89], v[146:149], v[206:209], v[86:89]
	v_mfma_f32_16x16x32_bf16 v[78:81], v[154:157], v[206:209], v[78:81]
	v_mfma_f32_16x16x32_bf16 v[70:73], v[146:149], v[214:217], v[70:73]
	v_mfma_f32_16x16x32_bf16 v[66:69], v[154:157], v[214:217], v[66:69]
	v_mfma_f32_16x16x32_bf16 v[134:137], v[150:153], v[166:169], v[134:137]
	v_mfma_f32_16x16x32_bf16 v[130:133], v[158:161], v[166:169], v[130:133]
	v_mfma_f32_16x16x32_bf16 v[102:105], v[150:153], v[198:201], v[102:105]
	v_mfma_f32_16x16x32_bf16 v[94:97], v[158:161], v[198:201], v[94:97]
	v_mfma_f32_16x16x32_bf16 v[86:89], v[150:153], v[210:213], v[86:89]
	v_mfma_f32_16x16x32_bf16 v[78:81], v[158:161], v[210:213], v[78:81]
	v_mfma_f32_16x16x32_bf16 v[70:73], v[150:153], v[218:221], v[70:73]
	v_mfma_f32_16x16x32_bf16 v[66:69], v[158:161], v[218:221], v[66:69]
	s_setprio 0
	s_barrier
	ds_read_b128 v[162:165], v192 offset:49152
	ds_read_b128 v[166:169], v192 offset:50176
	ds_read_b128 v[194:197], v192 offset:51200
	ds_read_b128 v[198:201], v192 offset:52224
	ds_read_b128 v[206:209], v192 offset:53248
	ds_read_b128 v[210:213], v192 offset:54272
	ds_read_b128 v[214:217], v192 offset:55296
	ds_read_b128 v[218:221], v192 offset:56320
	s_add_i32 s63, s63, s86
	s_mov_b32 m0, s63
	v_lshl_add_u64 v[186:187], v[186:187], 0, s[22:23]
	global_load_lds_dwordx4 v[186:187], off
	s_add_i32 m0, s63, 0x2000
	s_add_u32 s78, s78, 0x40080
	v_lshl_add_u64 v[186:187], v[202:203], 0, s[22:23]
	s_addc_u32 s79, s79, 0
	s_add_i32 s63, s83, s86
	global_load_lds_dwordx4 v[186:187], off
	v_lshl_add_u64 v[186:187], s[78:79], 0, v[172:173]
	s_mov_b32 m0, s63
	s_nop 0
	global_load_lds_dwordx4 v[186:187], off
	v_lshl_add_u64 v[186:187], s[78:79], 0, v[176:177]
	s_add_i32 m0, s63, 0x2000
	s_nop 0
	global_load_lds_dwordx4 v[186:187], off
	v_lshl_add_u64 v[186:187], v[222:223], 0, s[22:23]
	s_mov_b32 m0, s95
	s_nop 0
	global_load_lds_dwordx4 v[186:187], off
	v_lshl_add_u64 v[186:187], v[224:225], 0, s[22:23]
	s_mov_b32 m0, s96
	s_nop 0
	global_load_lds_dwordx4 v[186:187], off
	s_waitcnt vmcnt(8) lgkmcnt(0)
	s_setprio 1
	s_barrier
	v_mfma_f32_16x16x32_bf16 v[62:65], v[114:117], v[162:165], v[62:65]
	v_mfma_f32_16x16x32_bf16 v[58:61], v[122:125], v[162:165], v[58:61]
	v_mfma_f32_16x16x32_bf16 v[50:53], v[114:117], v[194:197], v[50:53]
	v_mfma_f32_16x16x32_bf16 v[42:45], v[122:125], v[194:197], v[42:45]
	v_mfma_f32_16x16x32_bf16 v[34:37], v[114:117], v[206:209], v[34:37]
	v_mfma_f32_16x16x32_bf16 v[26:29], v[122:125], v[206:209], v[26:29]
	v_mfma_f32_16x16x32_bf16 v[18:21], v[114:117], v[214:217], v[18:21]
	v_mfma_f32_16x16x32_bf16 v[10:13], v[122:125], v[214:217], v[10:13]
	v_mfma_f32_16x16x32_bf16 v[62:65], v[118:121], v[166:169], v[62:65]
	v_mfma_f32_16x16x32_bf16 v[58:61], v[126:129], v[166:169], v[58:61]
	v_mfma_f32_16x16x32_bf16 v[50:53], v[118:121], v[198:201], v[50:53]
	v_mfma_f32_16x16x32_bf16 v[42:45], v[126:129], v[198:201], v[42:45]
	v_mfma_f32_16x16x32_bf16 v[34:37], v[118:121], v[210:213], v[34:37]
	v_mfma_f32_16x16x32_bf16 v[26:29], v[126:129], v[210:213], v[26:29]
	v_mfma_f32_16x16x32_bf16 v[18:21], v[118:121], v[218:221], v[18:21]
	v_mfma_f32_16x16x32_bf16 v[10:13], v[126:129], v[218:221], v[10:13]
	v_mfma_f32_16x16x32_bf16 v[54:57], v[146:149], v[162:165], v[54:57]
	v_mfma_f32_16x16x32_bf16 v[46:49], v[154:157], v[162:165], v[46:49]
	v_mfma_f32_16x16x32_bf16 v[38:41], v[146:149], v[194:197], v[38:41]
	v_mfma_f32_16x16x32_bf16 v[30:33], v[154:157], v[194:197], v[30:33]
	v_mfma_f32_16x16x32_bf16 v[22:25], v[146:149], v[206:209], v[22:25]
	v_mfma_f32_16x16x32_bf16 v[14:17], v[154:157], v[206:209], v[14:17]
	v_mfma_f32_16x16x32_bf16 v[6:9], v[146:149], v[214:217], v[6:9]
	v_mfma_f32_16x16x32_bf16 v[2:5], v[154:157], v[214:217], v[2:5]
	v_mfma_f32_16x16x32_bf16 v[54:57], v[150:153], v[166:169], v[54:57]
	v_mfma_f32_16x16x32_bf16 v[46:49], v[158:161], v[166:169], v[46:49]
	v_mfma_f32_16x16x32_bf16 v[38:41], v[150:153], v[198:201], v[38:41]
	v_mfma_f32_16x16x32_bf16 v[30:33], v[158:161], v[198:201], v[30:33]
	v_mfma_f32_16x16x32_bf16 v[22:25], v[150:153], v[210:213], v[22:25]
	v_mfma_f32_16x16x32_bf16 v[14:17], v[158:161], v[210:213], v[14:17]
	v_mfma_f32_16x16x32_bf16 v[6:9], v[150:153], v[218:221], v[6:9]
	v_mfma_f32_16x16x32_bf16 v[2:5], v[158:161], v[218:221], v[2:5]
	s_setprio 0
	s_barrier
	s_add_u32 s76, s76, 0x100
	s_addc_u32 s77, s77, 0
	s_add_u32 s47, s47, 0x100
	s_addc_u32 s62, s62, 0
	s_cmp_ge_i32 s82, s7
	s_mov_b32 s63, s82
.LBB0_566:
	ds_read_b128 v[114:117], v190
	ds_read_b128 v[118:121], v190 offset:1024
	ds_read_b128 v[122:125], v190 offset:2048
	ds_read_b128 v[126:129], v190 offset:3072
	ds_read_b128 v[146:149], v191
	ds_read_b128 v[150:153], v191 offset:1024
	ds_read_b128 v[154:157], v191 offset:2048
	ds_read_b128 v[158:161], v191 offset:3072
	ds_read_b128 v[162:165], v192
	ds_read_b128 v[166:169], v192 offset:1024
	ds_read_b128 v[194:197], v192 offset:2048
	ds_read_b128 v[198:201], v192 offset:3072
	ds_read_b128 v[206:209], v192 offset:4096
	ds_read_b128 v[210:213], v192 offset:5120
	ds_read_b128 v[214:217], v192 offset:6144
	ds_read_b128 v[218:221], v192 offset:7168
	s_waitcnt vmcnt(0)
	s_add_i32 s82, s63, 2
	s_add_u32 s78, s76, 0xfffc0080
	s_addc_u32 s79, s77, -1
	s_cmp_eq_u32 s45, s63
	s_cselect_b32 s81, s31, s79
	s_cselect_b32 s80, s33, s78
	s_cselect_b32 s79, s34, s62
	s_cselect_b32 s78, s39, s47
	s_add_i32 m0, s87, 0xc000
	v_lshl_add_u64 v[186:187], s[76:77], 0, v[180:181]
	global_load_lds_dwordx4 v[186:187], off
	v_lshl_add_u64 v[186:187], s[76:77], 0, v[182:183]
	s_add_i32 m0, s87, 0xe000
	s_nop 0
	global_load_lds_dwordx4 v[186:187], off
	s_waitcnt vmcnt(8)
	s_waitcnt lgkmcnt(0)
	s_setprio 1
	s_barrier
	v_mfma_f32_16x16x32_bf16 v[142:145], v[114:117], v[162:165], v[142:145]
	v_mfma_f32_16x16x32_bf16 v[138:141], v[122:125], v[162:165], v[138:141]
	v_mfma_f32_16x16x32_bf16 v[110:113], v[114:117], v[194:197], v[110:113]
	v_mfma_f32_16x16x32_bf16 v[106:109], v[122:125], v[194:197], v[106:109]
	v_mfma_f32_16x16x32_bf16 v[98:101], v[114:117], v[206:209], v[98:101]
	v_mfma_f32_16x16x32_bf16 v[90:93], v[122:125], v[206:209], v[90:93]
	v_mfma_f32_16x16x32_bf16 v[82:85], v[114:117], v[214:217], v[82:85]
	v_mfma_f32_16x16x32_bf16 v[74:77], v[122:125], v[214:217], v[74:77]
	v_mfma_f32_16x16x32_bf16 v[142:145], v[118:121], v[166:169], v[142:145]
	v_mfma_f32_16x16x32_bf16 v[138:141], v[126:129], v[166:169], v[138:141]
	v_mfma_f32_16x16x32_bf16 v[110:113], v[118:121], v[198:201], v[110:113]
	v_mfma_f32_16x16x32_bf16 v[106:109], v[126:129], v[198:201], v[106:109]
	v_mfma_f32_16x16x32_bf16 v[98:101], v[118:121], v[210:213], v[98:101]
	v_mfma_f32_16x16x32_bf16 v[90:93], v[126:129], v[210:213], v[90:93]
	v_mfma_f32_16x16x32_bf16 v[82:85], v[118:121], v[218:221], v[82:85]
	v_mfma_f32_16x16x32_bf16 v[74:77], v[126:129], v[218:221], v[74:77]
	v_mfma_f32_16x16x32_bf16 v[134:137], v[146:149], v[162:165], v[134:137]
	v_mfma_f32_16x16x32_bf16 v[130:133], v[154:157], v[162:165], v[130:133]
	v_mfma_f32_16x16x32_bf16 v[102:105], v[146:149], v[194:197], v[102:105]
	v_mfma_f32_16x16x32_bf16 v[94:97], v[154:157], v[194:197], v[94:97]
	v_mfma_f32_16x16x32_bf16 v[86:89], v[146:149], v[206:209], v[86:89]
	v_mfma_f32_16x16x32_bf16 v[78:81], v[154:157], v[206:209], v[78:81]
	v_mfma_f32_16x16x32_bf16 v[70:73], v[146:149], v[214:217], v[70:73]
	v_mfma_f32_16x16x32_bf16 v[66:69], v[154:157], v[214:217], v[66:69]
	v_mfma_f32_16x16x32_bf16 v[134:137], v[150:153], v[166:169], v[134:137]
	v_mfma_f32_16x16x32_bf16 v[130:133], v[158:161], v[166:169], v[130:133]
	v_mfma_f32_16x16x32_bf16 v[102:105], v[150:153], v[198:201], v[102:105]
	v_mfma_f32_16x16x32_bf16 v[94:97], v[158:161], v[198:201], v[94:97]
	v_mfma_f32_16x16x32_bf16 v[86:89], v[150:153], v[210:213], v[86:89]
	v_mfma_f32_16x16x32_bf16 v[78:81], v[158:161], v[210:213], v[78:81]
	v_mfma_f32_16x16x32_bf16 v[70:73], v[150:153], v[218:221], v[70:73]
	v_mfma_f32_16x16x32_bf16 v[66:69], v[158:161], v[218:221], v[66:69]
	s_setprio 0
	s_barrier
	ds_read_b128 v[162:165], v192 offset:16384
	ds_read_b128 v[166:169], v192 offset:17408
	ds_read_b128 v[194:197], v192 offset:18432
	ds_read_b128 v[198:201], v192 offset:19456
	ds_read_b128 v[206:209], v192 offset:20480
	ds_read_b128 v[210:213], v192 offset:21504
	ds_read_b128 v[214:217], v192 offset:22528
	ds_read_b128 v[218:221], v192 offset:23552
	s_add_i32 s63, s24, s86
	s_mov_b32 m0, s63
	v_lshl_add_u64 v[186:187], s[78:79], 0, v[172:173]
	global_load_lds_dwordx4 v[186:187], off
	s_add_i32 m0, s63, 0x2000
	s_add_u32 vcc_lo, s78, 0x40000
	v_lshl_add_u64 v[202:203], s[78:79], 0, v[176:177]
	s_addc_u32 vcc_hi, s79, 0
	s_add_i32 s63, s25, s86
	global_load_lds_dwordx4 v[202:203], off
	v_lshl_add_u64 v[222:223], vcc, 0, v[172:173]
	s_mov_b32 m0, s63
	v_lshl_add_u64 v[224:225], s[80:81], 0, v[174:175]
	global_load_lds_dwordx4 v[222:223], off
	v_lshl_add_u64 v[222:223], vcc, 0, v[176:177]
	s_add_i32 m0, s63, 0x2000
	s_nop 0
	global_load_lds_dwordx4 v[222:223], off
	v_lshl_add_u64 v[222:223], s[80:81], 0, v[170:171]
	s_mov_b32 m0, s87
	s_nop 0
	global_load_lds_dwordx4 v[222:223], off
	s_mov_b32 m0, s88
	s_nop 0
	global_load_lds_dwordx4 v[224:225], off
	s_waitcnt vmcnt(8) lgkmcnt(0)
	s_setprio 1
	s_barrier
	v_mfma_f32_16x16x32_bf16 v[62:65], v[114:117], v[162:165], v[62:65]
	v_mfma_f32_16x16x32_bf16 v[58:61], v[122:125], v[162:165], v[58:61]
	v_mfma_f32_16x16x32_bf16 v[50:53], v[114:117], v[194:197], v[50:53]
	v_mfma_f32_16x16x32_bf16 v[42:45], v[122:125], v[194:197], v[42:45]
	v_mfma_f32_16x16x32_bf16 v[34:37], v[114:117], v[206:209], v[34:37]
	v_mfma_f32_16x16x32_bf16 v[26:29], v[122:125], v[206:209], v[26:29]
	v_mfma_f32_16x16x32_bf16 v[18:21], v[114:117], v[214:217], v[18:21]
	v_mfma_f32_16x16x32_bf16 v[10:13], v[122:125], v[214:217], v[10:13]
	v_mfma_f32_16x16x32_bf16 v[62:65], v[118:121], v[166:169], v[62:65]
	v_mfma_f32_16x16x32_bf16 v[58:61], v[126:129], v[166:169], v[58:61]
	v_mfma_f32_16x16x32_bf16 v[50:53], v[118:121], v[198:201], v[50:53]
	v_mfma_f32_16x16x32_bf16 v[42:45], v[126:129], v[198:201], v[42:45]
	v_mfma_f32_16x16x32_bf16 v[34:37], v[118:121], v[210:213], v[34:37]
	v_mfma_f32_16x16x32_bf16 v[26:29], v[126:129], v[210:213], v[26:29]
	v_mfma_f32_16x16x32_bf16 v[18:21], v[118:121], v[218:221], v[18:21]
	v_mfma_f32_16x16x32_bf16 v[10:13], v[126:129], v[218:221], v[10:13]
	v_mfma_f32_16x16x32_bf16 v[54:57], v[146:149], v[162:165], v[54:57]
	v_mfma_f32_16x16x32_bf16 v[46:49], v[154:157], v[162:165], v[46:49]
	v_mfma_f32_16x16x32_bf16 v[38:41], v[146:149], v[194:197], v[38:41]
	v_mfma_f32_16x16x32_bf16 v[30:33], v[154:157], v[194:197], v[30:33]
	v_mfma_f32_16x16x32_bf16 v[22:25], v[146:149], v[206:209], v[22:25]
	v_mfma_f32_16x16x32_bf16 v[14:17], v[154:157], v[206:209], v[14:17]
	v_mfma_f32_16x16x32_bf16 v[6:9], v[146:149], v[214:217], v[6:9]
	v_mfma_f32_16x16x32_bf16 v[2:5], v[154:157], v[214:217], v[2:5]
	v_mfma_f32_16x16x32_bf16 v[54:57], v[150:153], v[166:169], v[54:57]
	v_mfma_f32_16x16x32_bf16 v[46:49], v[158:161], v[166:169], v[46:49]
	v_mfma_f32_16x16x32_bf16 v[38:41], v[150:153], v[198:201], v[38:41]
	v_mfma_f32_16x16x32_bf16 v[30:33], v[158:161], v[198:201], v[30:33]
	v_mfma_f32_16x16x32_bf16 v[22:25], v[150:153], v[210:213], v[22:25]
	v_mfma_f32_16x16x32_bf16 v[14:17], v[158:161], v[210:213], v[14:17]
	v_mfma_f32_16x16x32_bf16 v[6:9], v[150:153], v[218:221], v[6:9]
	v_mfma_f32_16x16x32_bf16 v[2:5], v[158:161], v[218:221], v[2:5]
	s_setprio 0
	s_barrier
	s_add_i32 s63, 0, 0x18000
	s_add_i32 s83, 0, 0x1c000
	v_add_u32_e32 v126, s63, v189
	v_add_u32_e32 v158, s83, v189
	ds_read_b128 v[114:117], v126
	ds_read_b128 v[118:121], v126 offset:1024
	ds_read_b128 v[122:125], v126 offset:2048
	ds_read_b128 v[126:129], v126 offset:3072
	ds_read_b128 v[146:149], v158
	ds_read_b128 v[150:153], v158 offset:1024
	ds_read_b128 v[154:157], v158 offset:2048
	ds_read_b128 v[158:161], v158 offset:3072
	s_add_u32 s80, s80, 0x40000
	s_addc_u32 s81, s81, 0
	s_mov_b32 m0, s89
	v_lshl_add_u64 v[226:227], s[80:81], 0, v[170:171]
	ds_read_b128 v[162:165], v192 offset:32768
	ds_read_b128 v[166:169], v192 offset:33792
	ds_read_b128 v[194:197], v192 offset:34816
	ds_read_b128 v[198:201], v192 offset:35840
	ds_read_b128 v[206:209], v192 offset:36864
	ds_read_b128 v[210:213], v192 offset:37888
	ds_read_b128 v[214:217], v192 offset:38912
	ds_read_b128 v[218:221], v192 offset:39936
	global_load_lds_dwordx4 v[226:227], off
	v_lshl_add_u64 v[226:227], s[80:81], 0, v[174:175]
	s_mov_b32 m0, s90
	s_nop 0
	global_load_lds_dwordx4 v[226:227], off
	s_waitcnt vmcnt(8) lgkmcnt(0)
	s_setprio 1
	s_barrier
	v_mfma_f32_16x16x32_bf16 v[142:145], v[114:117], v[162:165], v[142:145]
	v_mfma_f32_16x16x32_bf16 v[138:141], v[122:125], v[162:165], v[138:141]
	v_mfma_f32_16x16x32_bf16 v[110:113], v[114:117], v[194:197], v[110:113]
	v_mfma_f32_16x16x32_bf16 v[106:109], v[122:125], v[194:197], v[106:109]
	v_mfma_f32_16x16x32_bf16 v[98:101], v[114:117], v[206:209], v[98:101]
	v_mfma_f32_16x16x32_bf16 v[90:93], v[122:125], v[206:209], v[90:93]
	v_mfma_f32_16x16x32_bf16 v[82:85], v[114:117], v[214:217], v[82:85]
	v_mfma_f32_16x16x32_bf16 v[74:77], v[122:125], v[214:217], v[74:77]
	v_mfma_f32_16x16x32_bf16 v[142:145], v[118:121], v[166:169], v[142:145]
	v_mfma_f32_16x16x32_bf16 v[138:141], v[126:129], v[166:169], v[138:141]
	v_mfma_f32_16x16x32_bf16 v[110:113], v[118:121], v[198:201], v[110:113]
	v_mfma_f32_16x16x32_bf16 v[106:109], v[126:129], v[198:201], v[106:109]
	v_mfma_f32_16x16x32_bf16 v[98:101], v[118:121], v[210:213], v[98:101]
	v_mfma_f32_16x16x32_bf16 v[90:93], v[126:129], v[210:213], v[90:93]
	v_mfma_f32_16x16x32_bf16 v[82:85], v[118:121], v[218:221], v[82:85]
	v_mfma_f32_16x16x32_bf16 v[74:77], v[126:129], v[218:221], v[74:77]
	v_mfma_f32_16x16x32_bf16 v[134:137], v[146:149], v[162:165], v[134:137]
	v_mfma_f32_16x16x32_bf16 v[130:133], v[154:157], v[162:165], v[130:133]
	v_mfma_f32_16x16x32_bf16 v[102:105], v[146:149], v[194:197], v[102:105]
	v_mfma_f32_16x16x32_bf16 v[94:97], v[154:157], v[194:197], v[94:97]
	v_mfma_f32_16x16x32_bf16 v[86:89], v[146:149], v[206:209], v[86:89]
	v_mfma_f32_16x16x32_bf16 v[78:81], v[154:157], v[206:209], v[78:81]
	v_mfma_f32_16x16x32_bf16 v[70:73], v[146:149], v[214:217], v[70:73]
	v_mfma_f32_16x16x32_bf16 v[66:69], v[154:157], v[214:217], v[66:69]
	v_mfma_f32_16x16x32_bf16 v[134:137], v[150:153], v[166:169], v[134:137]
	v_mfma_f32_16x16x32_bf16 v[130:133], v[158:161], v[166:169], v[130:133]
	v_mfma_f32_16x16x32_bf16 v[102:105], v[150:153], v[198:201], v[102:105]
	v_mfma_f32_16x16x32_bf16 v[94:97], v[158:161], v[198:201], v[94:97]
	v_mfma_f32_16x16x32_bf16 v[86:89], v[150:153], v[210:213], v[86:89]
	v_mfma_f32_16x16x32_bf16 v[78:81], v[158:161], v[210:213], v[78:81]
	v_mfma_f32_16x16x32_bf16 v[70:73], v[150:153], v[218:221], v[70:73]
	v_mfma_f32_16x16x32_bf16 v[66:69], v[158:161], v[218:221], v[66:69]
	s_setprio 0
	s_barrier
	ds_read_b128 v[162:165], v192 offset:49152
	ds_read_b128 v[166:169], v192 offset:50176
	ds_read_b128 v[194:197], v192 offset:51200
	ds_read_b128 v[198:201], v192 offset:52224
	ds_read_b128 v[206:209], v192 offset:53248
	ds_read_b128 v[210:213], v192 offset:54272
	ds_read_b128 v[214:217], v192 offset:55296
	ds_read_b128 v[218:221], v192 offset:56320
	s_add_i32 s63, s63, s86
	s_mov_b32 m0, s63
	v_lshl_add_u64 v[186:187], v[186:187], 0, s[22:23]
	global_load_lds_dwordx4 v[186:187], off
	s_add_i32 m0, s63, 0x2000
	s_add_u32 s78, s78, 0x40080
	v_lshl_add_u64 v[186:187], v[202:203], 0, s[22:23]
	s_addc_u32 s79, s79, 0
	s_add_i32 s63, s83, s86
	global_load_lds_dwordx4 v[186:187], off
	v_lshl_add_u64 v[186:187], s[78:79], 0, v[172:173]
	s_mov_b32 m0, s63
	s_nop 0
	global_load_lds_dwordx4 v[186:187], off
	v_lshl_add_u64 v[186:187], s[78:79], 0, v[176:177]
	s_add_i32 m0, s63, 0x2000
	s_nop 0
	global_load_lds_dwordx4 v[186:187], off
	v_lshl_add_u64 v[186:187], v[222:223], 0, s[22:23]
	s_mov_b32 m0, s95
	s_nop 0
	global_load_lds_dwordx4 v[186:187], off
	v_lshl_add_u64 v[186:187], v[224:225], 0, s[22:23]
	s_mov_b32 m0, s96
	s_nop 0
	global_load_lds_dwordx4 v[186:187], off
	s_waitcnt vmcnt(8) lgkmcnt(0)
	s_setprio 1
	s_barrier
	v_mfma_f32_16x16x32_bf16 v[62:65], v[114:117], v[162:165], v[62:65]
	v_mfma_f32_16x16x32_bf16 v[58:61], v[122:125], v[162:165], v[58:61]
	v_mfma_f32_16x16x32_bf16 v[50:53], v[114:117], v[194:197], v[50:53]
	v_mfma_f32_16x16x32_bf16 v[42:45], v[122:125], v[194:197], v[42:45]
	v_mfma_f32_16x16x32_bf16 v[34:37], v[114:117], v[206:209], v[34:37]
	v_mfma_f32_16x16x32_bf16 v[26:29], v[122:125], v[206:209], v[26:29]
	v_mfma_f32_16x16x32_bf16 v[18:21], v[114:117], v[214:217], v[18:21]
	v_mfma_f32_16x16x32_bf16 v[10:13], v[122:125], v[214:217], v[10:13]
	v_mfma_f32_16x16x32_bf16 v[62:65], v[118:121], v[166:169], v[62:65]
	v_mfma_f32_16x16x32_bf16 v[58:61], v[126:129], v[166:169], v[58:61]
	v_mfma_f32_16x16x32_bf16 v[50:53], v[118:121], v[198:201], v[50:53]
	v_mfma_f32_16x16x32_bf16 v[42:45], v[126:129], v[198:201], v[42:45]
	v_mfma_f32_16x16x32_bf16 v[34:37], v[118:121], v[210:213], v[34:37]
	v_mfma_f32_16x16x32_bf16 v[26:29], v[126:129], v[210:213], v[26:29]
	v_mfma_f32_16x16x32_bf16 v[18:21], v[118:121], v[218:221], v[18:21]
	v_mfma_f32_16x16x32_bf16 v[10:13], v[126:129], v[218:221], v[10:13]
	v_mfma_f32_16x16x32_bf16 v[54:57], v[146:149], v[162:165], v[54:57]
	v_mfma_f32_16x16x32_bf16 v[46:49], v[154:157], v[162:165], v[46:49]
	v_mfma_f32_16x16x32_bf16 v[38:41], v[146:149], v[194:197], v[38:41]
	v_mfma_f32_16x16x32_bf16 v[30:33], v[154:157], v[194:197], v[30:33]
	v_mfma_f32_16x16x32_bf16 v[22:25], v[146:149], v[206:209], v[22:25]
	v_mfma_f32_16x16x32_bf16 v[14:17], v[154:157], v[206:209], v[14:17]
	v_mfma_f32_16x16x32_bf16 v[6:9], v[146:149], v[214:217], v[6:9]
	v_mfma_f32_16x16x32_bf16 v[2:5], v[154:157], v[214:217], v[2:5]
	v_mfma_f32_16x16x32_bf16 v[54:57], v[150:153], v[166:169], v[54:57]
	v_mfma_f32_16x16x32_bf16 v[46:49], v[158:161], v[166:169], v[46:49]
	v_mfma_f32_16x16x32_bf16 v[38:41], v[150:153], v[198:201], v[38:41]
	v_mfma_f32_16x16x32_bf16 v[30:33], v[158:161], v[198:201], v[30:33]
	v_mfma_f32_16x16x32_bf16 v[22:25], v[150:153], v[210:213], v[22:25]
	v_mfma_f32_16x16x32_bf16 v[14:17], v[158:161], v[210:213], v[14:17]
	v_mfma_f32_16x16x32_bf16 v[6:9], v[150:153], v[218:221], v[6:9]
	v_mfma_f32_16x16x32_bf16 v[2:5], v[158:161], v[218:221], v[2:5]
	s_setprio 0
	s_barrier
	s_add_u32 s76, s76, 0x100
	s_addc_u32 s77, s77, 0
	s_add_u32 s47, s47, 0x100
	s_addc_u32 s62, s62, 0
	s_cmp_ge_i32 s82, s7
	s_mov_b32 s63, s82
	s_cbranch_scc0 .LBB0_566
	s_and_b64 vcc, exec, s[26:27]
	s_cbranch_vccz .LBB0_569
	s_barrier

.LBB0_744:
	s_add_u32 s36, s96, s22
	s_addc_u32 s37, s97, s23
	s_and_b64 s[14:15], s[4:5], exec
	s_cselect_b32 s14, s37, s43
	s_cselect_b32 s15, s36, s42
	s_add_u32 s38, s2, s26
	s_addc_u32 s39, s3, s27
	s_and_b64 s[46:47], s[4:5], exec
	s_cselect_b32 s21, s39, s45
	s_cselect_b32 s65, s38, s44
	s_add_u32 s42, s42, 0x40080
	s_addc_u32 s43, s43, 0
	s_add_u32 s66, s44, 0x100
	s_addc_u32 s67, s45, 0
	s_mov_b32 s68, -2
	ds_read_b128 v[154:157], v150
	ds_read_b128 v[158:161], v150 offset:1024
	ds_read_b128 v[162:165], v150 offset:2048
	ds_read_b128 v[166:169], v150 offset:3072
	ds_read_b128 v[170:173], v151
	ds_read_b128 v[174:177], v151 offset:1024
	ds_read_b128 v[178:181], v151 offset:2048
	ds_read_b128 v[182:185], v151 offset:3072
	ds_read_b128 v[186:189], v152
	ds_read_b128 v[190:193], v152 offset:1024
	ds_read_b128 v[194:197], v152 offset:2048
	ds_read_b128 v[198:201], v152 offset:3072
	ds_read_b128 v[206:209], v152 offset:4096
	ds_read_b128 v[210:213], v152 offset:5120
	ds_read_b128 v[214:217], v152 offset:6144
	ds_read_b128 v[218:221], v152 offset:7168
	s_add_u32 s44, s42, 0xfffc0080
	s_addc_u32 s45, s43, -1
	s_cmp_eq_u32 s68, 12
	s_cselect_b32 s47, s14, s45
	s_cselect_b32 s46, s15, s44
	s_cselect_b32 s45, s21, s67
	s_cselect_b32 s44, s65, s66
	s_add_i32 m0, s19, 0xc000
	v_lshl_add_u64 v[146:147], s[42:43], 0, v[138:139]
	global_load_lds_dwordx4 v[146:147], off
	v_lshl_add_u64 v[146:147], s[42:43], 0, v[140:141]
	s_add_i32 m0, s19, 0xe000
	s_nop 0
	global_load_lds_dwordx4 v[146:147], off
	s_waitcnt vmcnt(8) lgkmcnt(0)
	s_setprio 1
	s_barrier
	v_mfma_f32_16x16x32_bf16 v[126:129], v[154:157], v[186:189], 0
	v_mfma_f32_16x16x32_bf16 v[122:125], v[162:165], v[186:189], 0
	v_mfma_f32_16x16x32_bf16 v[110:113], v[154:157], v[194:197], 0
	v_mfma_f32_16x16x32_bf16 v[106:109], v[162:165], v[194:197], 0
	v_mfma_f32_16x16x32_bf16 v[94:97], v[154:157], v[206:209], 0
	v_mfma_f32_16x16x32_bf16 v[90:93], v[162:165], v[206:209], 0
	v_mfma_f32_16x16x32_bf16 v[78:81], v[154:157], v[214:217], 0
	v_mfma_f32_16x16x32_bf16 v[74:77], v[162:165], v[214:217], 0
	v_mfma_f32_16x16x32_bf16 v[126:129], v[158:161], v[190:193], v[126:129]
	v_mfma_f32_16x16x32_bf16 v[122:125], v[166:169], v[190:193], v[122:125]
	v_mfma_f32_16x16x32_bf16 v[110:113], v[158:161], v[198:201], v[110:113]
	v_mfma_f32_16x16x32_bf16 v[106:109], v[166:169], v[198:201], v[106:109]
	v_mfma_f32_16x16x32_bf16 v[94:97], v[158:161], v[210:213], v[94:97]
	v_mfma_f32_16x16x32_bf16 v[90:93], v[166:169], v[210:213], v[90:93]
	v_mfma_f32_16x16x32_bf16 v[78:81], v[158:161], v[218:221], v[78:81]
	v_mfma_f32_16x16x32_bf16 v[74:77], v[166:169], v[218:221], v[74:77]
	v_mfma_f32_16x16x32_bf16 v[118:121], v[170:173], v[186:189], 0
	v_mfma_f32_16x16x32_bf16 v[114:117], v[178:181], v[186:189], 0
	v_mfma_f32_16x16x32_bf16 v[102:105], v[170:173], v[194:197], 0
	v_mfma_f32_16x16x32_bf16 v[98:101], v[178:181], v[194:197], 0
	v_mfma_f32_16x16x32_bf16 v[86:89], v[170:173], v[206:209], 0
	v_mfma_f32_16x16x32_bf16 v[82:85], v[178:181], v[206:209], 0
	v_mfma_f32_16x16x32_bf16 v[70:73], v[170:173], v[214:217], 0
	v_mfma_f32_16x16x32_bf16 v[66:69], v[178:181], v[214:217], 0
	v_mfma_f32_16x16x32_bf16 v[118:121], v[174:177], v[190:193], v[118:121]
	v_mfma_f32_16x16x32_bf16 v[114:117], v[182:185], v[190:193], v[114:117]
	v_mfma_f32_16x16x32_bf16 v[102:105], v[174:177], v[198:201], v[102:105]
	v_mfma_f32_16x16x32_bf16 v[98:101], v[182:185], v[198:201], v[98:101]
	v_mfma_f32_16x16x32_bf16 v[86:89], v[174:177], v[210:213], v[86:89]
	v_mfma_f32_16x16x32_bf16 v[82:85], v[182:185], v[210:213], v[82:85]
	v_mfma_f32_16x16x32_bf16 v[70:73], v[174:177], v[218:221], v[70:73]
	v_mfma_f32_16x16x32_bf16 v[66:69], v[182:185], v[218:221], v[66:69]
	s_setprio 0
	s_barrier
	ds_read_b128 v[186:189], v152 offset:16384
	ds_read_b128 v[190:193], v152 offset:17408
	ds_read_b128 v[194:197], v152 offset:18432
	ds_read_b128 v[198:201], v152 offset:19456
	ds_read_b128 v[206:209], v152 offset:20480
	ds_read_b128 v[210:213], v152 offset:21504
	ds_read_b128 v[214:217], v152 offset:22528
	ds_read_b128 v[218:221], v152 offset:23552
	s_add_i32 s69, s49, s16
	s_mov_b32 m0, s69
	v_lshl_add_u64 v[146:147], s[44:45], 0, v[134:135]
	global_load_lds_dwordx4 v[146:147], off
	s_add_i32 m0, s69, 0x2000
	s_add_u32 s70, s44, 0x40000
	v_lshl_add_u64 v[202:203], s[44:45], 0, v[130:131]
	s_addc_u32 s71, s45, 0
	s_add_i32 s69, s62, s16
	global_load_lds_dwordx4 v[202:203], off
	v_lshl_add_u64 v[222:223], s[70:71], 0, v[134:135]
	s_mov_b32 m0, s69
	v_lshl_add_u64 v[224:225], s[46:47], 0, v[132:133]
	global_load_lds_dwordx4 v[222:223], off
	v_lshl_add_u64 v[222:223], s[70:71], 0, v[130:131]
	s_add_i32 m0, s69, 0x2000
	s_nop 0
	global_load_lds_dwordx4 v[222:223], off
	v_lshl_add_u64 v[222:223], s[46:47], 0, v[136:137]
	s_mov_b32 m0, s19
	s_nop 0
	global_load_lds_dwordx4 v[222:223], off
	s_mov_b32 m0, s24
	s_nop 0
	global_load_lds_dwordx4 v[224:225], off
	s_waitcnt vmcnt(8) lgkmcnt(0)
	s_setprio 1
	s_barrier
	v_mfma_f32_16x16x32_bf16 v[62:65], v[154:157], v[186:189], 0
	v_mfma_f32_16x16x32_bf16 v[58:61], v[162:165], v[186:189], 0
	v_mfma_f32_16x16x32_bf16 v[46:49], v[154:157], v[194:197], 0
	v_mfma_f32_16x16x32_bf16 v[42:45], v[162:165], v[194:197], 0
	v_mfma_f32_16x16x32_bf16 v[30:33], v[154:157], v[206:209], 0
	v_mfma_f32_16x16x32_bf16 v[26:29], v[162:165], v[206:209], 0
	v_mfma_f32_16x16x32_bf16 v[14:17], v[154:157], v[214:217], 0
	v_mfma_f32_16x16x32_bf16 v[10:13], v[162:165], v[214:217], 0
	v_mfma_f32_16x16x32_bf16 v[62:65], v[158:161], v[190:193], v[62:65]
	v_mfma_f32_16x16x32_bf16 v[58:61], v[166:169], v[190:193], v[58:61]
	v_mfma_f32_16x16x32_bf16 v[46:49], v[158:161], v[198:201], v[46:49]
	v_mfma_f32_16x16x32_bf16 v[42:45], v[166:169], v[198:201], v[42:45]
	v_mfma_f32_16x16x32_bf16 v[30:33], v[158:161], v[210:213], v[30:33]
	v_mfma_f32_16x16x32_bf16 v[26:29], v[166:169], v[210:213], v[26:29]
	v_mfma_f32_16x16x32_bf16 v[14:17], v[158:161], v[218:221], v[14:17]
	v_mfma_f32_16x16x32_bf16 v[10:13], v[166:169], v[218:221], v[10:13]
	v_mfma_f32_16x16x32_bf16 v[54:57], v[170:173], v[186:189], 0
	v_mfma_f32_16x16x32_bf16 v[50:53], v[178:181], v[186:189], 0
	v_mfma_f32_16x16x32_bf16 v[38:41], v[170:173], v[194:197], 0
	v_mfma_f32_16x16x32_bf16 v[34:37], v[178:181], v[194:197], 0
	v_mfma_f32_16x16x32_bf16 v[22:25], v[170:173], v[206:209], 0
	v_mfma_f32_16x16x32_bf16 v[18:21], v[178:181], v[206:209], 0
	v_mfma_f32_16x16x32_bf16 v[6:9], v[170:173], v[214:217], 0
	v_mfma_f32_16x16x32_bf16 v[2:5], v[178:181], v[214:217], 0
	v_mfma_f32_16x16x32_bf16 v[54:57], v[174:177], v[190:193], v[54:57]
	v_mfma_f32_16x16x32_bf16 v[50:53], v[182:185], v[190:193], v[50:53]
	v_mfma_f32_16x16x32_bf16 v[38:41], v[174:177], v[198:201], v[38:41]
	v_mfma_f32_16x16x32_bf16 v[34:37], v[182:185], v[198:201], v[34:37]
	v_mfma_f32_16x16x32_bf16 v[22:25], v[174:177], v[210:213], v[22:25]
	v_mfma_f32_16x16x32_bf16 v[18:21], v[182:185], v[210:213], v[18:21]
	v_mfma_f32_16x16x32_bf16 v[6:9], v[174:177], v[218:221], v[6:9]
	v_mfma_f32_16x16x32_bf16 v[2:5], v[182:185], v[218:221], v[2:5]
	s_setprio 0
	s_barrier
	s_add_i32 s69, 0, 0x18000
	v_add_u32_e32 v153, s69, v149
	s_add_i32 s70, 0, 0x1c000
	ds_read_b128 v[154:157], v153
	ds_read_b128 v[158:161], v153 offset:1024
	ds_read_b128 v[162:165], v153 offset:2048
	ds_read_b128 v[166:169], v153 offset:3072
	v_add_u32_e32 v153, s70, v149
	ds_read_b128 v[170:173], v153
	ds_read_b128 v[174:177], v153 offset:1024
	ds_read_b128 v[178:181], v153 offset:2048
	ds_read_b128 v[182:185], v153 offset:3072
	s_add_u32 s46, s46, 0x40000
	s_addc_u32 s47, s47, 0
	s_mov_b32 m0, s25
	v_lshl_add_u64 v[226:227], s[46:47], 0, v[136:137]
	ds_read_b128 v[186:189], v152 offset:32768
	ds_read_b128 v[190:193], v152 offset:33792
	ds_read_b128 v[194:197], v152 offset:34816
	ds_read_b128 v[198:201], v152 offset:35840
	ds_read_b128 v[206:209], v152 offset:36864
	ds_read_b128 v[210:213], v152 offset:37888
	ds_read_b128 v[214:217], v152 offset:38912
	ds_read_b128 v[218:221], v152 offset:39936
	global_load_lds_dwordx4 v[226:227], off
	v_lshl_add_u64 v[226:227], s[46:47], 0, v[132:133]
	s_mov_b32 m0, s28
	s_nop 0
	global_load_lds_dwordx4 v[226:227], off
	s_waitcnt vmcnt(8) lgkmcnt(0)
	s_setprio 1
	s_barrier
	v_mfma_f32_16x16x32_bf16 v[126:129], v[154:157], v[186:189], v[126:129]
	v_mfma_f32_16x16x32_bf16 v[122:125], v[162:165], v[186:189], v[122:125]
	v_mfma_f32_16x16x32_bf16 v[110:113], v[154:157], v[194:197], v[110:113]
	v_mfma_f32_16x16x32_bf16 v[106:109], v[162:165], v[194:197], v[106:109]
	v_mfma_f32_16x16x32_bf16 v[94:97], v[154:157], v[206:209], v[94:97]
	v_mfma_f32_16x16x32_bf16 v[90:93], v[162:165], v[206:209], v[90:93]
	v_mfma_f32_16x16x32_bf16 v[78:81], v[154:157], v[214:217], v[78:81]
	v_mfma_f32_16x16x32_bf16 v[74:77], v[162:165], v[214:217], v[74:77]
	v_mfma_f32_16x16x32_bf16 v[126:129], v[158:161], v[190:193], v[126:129]
	v_mfma_f32_16x16x32_bf16 v[122:125], v[166:169], v[190:193], v[122:125]
	v_mfma_f32_16x16x32_bf16 v[110:113], v[158:161], v[198:201], v[110:113]
	v_mfma_f32_16x16x32_bf16 v[106:109], v[166:169], v[198:201], v[106:109]
	v_mfma_f32_16x16x32_bf16 v[94:97], v[158:161], v[210:213], v[94:97]
	v_mfma_f32_16x16x32_bf16 v[90:93], v[166:169], v[210:213], v[90:93]
	v_mfma_f32_16x16x32_bf16 v[78:81], v[158:161], v[218:221], v[78:81]
	v_mfma_f32_16x16x32_bf16 v[74:77], v[166:169], v[218:221], v[74:77]
	v_mfma_f32_16x16x32_bf16 v[118:121], v[170:173], v[186:189], v[118:121]
	v_mfma_f32_16x16x32_bf16 v[114:117], v[178:181], v[186:189], v[114:117]
	v_mfma_f32_16x16x32_bf16 v[102:105], v[170:173], v[194:197], v[102:105]
	v_mfma_f32_16x16x32_bf16 v[98:101], v[178:181], v[194:197], v[98:101]
	v_mfma_f32_16x16x32_bf16 v[86:89], v[170:173], v[206:209], v[86:89]
	v_mfma_f32_16x16x32_bf16 v[82:85], v[178:181], v[206:209], v[82:85]
	v_mfma_f32_16x16x32_bf16 v[70:73], v[170:173], v[214:217], v[70:73]
	v_mfma_f32_16x16x32_bf16 v[66:69], v[178:181], v[214:217], v[66:69]
	v_mfma_f32_16x16x32_bf16 v[118:121], v[174:177], v[190:193], v[118:121]
	v_mfma_f32_16x16x32_bf16 v[114:117], v[182:185], v[190:193], v[114:117]
	v_mfma_f32_16x16x32_bf16 v[102:105], v[174:177], v[198:201], v[102:105]
	v_mfma_f32_16x16x32_bf16 v[98:101], v[182:185], v[198:201], v[98:101]
	v_mfma_f32_16x16x32_bf16 v[86:89], v[174:177], v[210:213], v[86:89]
	v_mfma_f32_16x16x32_bf16 v[82:85], v[182:185], v[210:213], v[82:85]
	v_mfma_f32_16x16x32_bf16 v[70:73], v[174:177], v[218:221], v[70:73]
	v_mfma_f32_16x16x32_bf16 v[66:69], v[182:185], v[218:221], v[66:69]
	s_setprio 0
	s_barrier
	ds_read_b128 v[186:189], v152 offset:49152
	ds_read_b128 v[190:193], v152 offset:50176
	ds_read_b128 v[194:197], v152 offset:51200
	ds_read_b128 v[198:201], v152 offset:52224
	ds_read_b128 v[206:209], v152 offset:53248
	ds_read_b128 v[210:213], v152 offset:54272
	ds_read_b128 v[214:217], v152 offset:55296
	ds_read_b128 v[218:221], v152 offset:56320
	s_add_i32 s46, s69, s16
	s_mov_b32 m0, s46
	v_lshl_add_u64 v[146:147], v[146:147], 0, s[10:11]
	global_load_lds_dwordx4 v[146:147], off
	s_add_i32 m0, s46, 0x2000
	s_add_u32 s44, s44, 0x40080
	v_lshl_add_u64 v[146:147], v[202:203], 0, s[10:11]
	s_addc_u32 s45, s45, 0
	s_add_i32 s46, s70, s16
	global_load_lds_dwordx4 v[146:147], off
	v_lshl_add_u64 v[146:147], s[44:45], 0, v[134:135]
	s_mov_b32 m0, s46
	s_nop 0
	global_load_lds_dwordx4 v[146:147], off
	v_lshl_add_u64 v[146:147], s[44:45], 0, v[130:131]
	s_add_i32 m0, s46, 0x2000
	s_nop 0
	global_load_lds_dwordx4 v[146:147], off
	v_lshl_add_u64 v[146:147], v[222:223], 0, s[10:11]
	s_mov_b32 m0, s33
	s_nop 0
	global_load_lds_dwordx4 v[146:147], off
	v_lshl_add_u64 v[146:147], v[224:225], 0, s[10:11]
	s_mov_b32 m0, s35
	s_nop 0
	global_load_lds_dwordx4 v[146:147], off
	s_waitcnt vmcnt(8) lgkmcnt(0)
	s_setprio 1
	s_barrier
	v_mfma_f32_16x16x32_bf16 v[62:65], v[154:157], v[186:189], v[62:65]
	v_mfma_f32_16x16x32_bf16 v[58:61], v[162:165], v[186:189], v[58:61]
	v_mfma_f32_16x16x32_bf16 v[46:49], v[154:157], v[194:197], v[46:49]
	v_mfma_f32_16x16x32_bf16 v[42:45], v[162:165], v[194:197], v[42:45]
	v_mfma_f32_16x16x32_bf16 v[30:33], v[154:157], v[206:209], v[30:33]
	v_mfma_f32_16x16x32_bf16 v[26:29], v[162:165], v[206:209], v[26:29]
	v_mfma_f32_16x16x32_bf16 v[14:17], v[154:157], v[214:217], v[14:17]
	v_mfma_f32_16x16x32_bf16 v[10:13], v[162:165], v[214:217], v[10:13]
	v_mfma_f32_16x16x32_bf16 v[62:65], v[158:161], v[190:193], v[62:65]
	v_mfma_f32_16x16x32_bf16 v[58:61], v[166:169], v[190:193], v[58:61]
	v_mfma_f32_16x16x32_bf16 v[46:49], v[158:161], v[198:201], v[46:49]
	v_mfma_f32_16x16x32_bf16 v[42:45], v[166:169], v[198:201], v[42:45]
	v_mfma_f32_16x16x32_bf16 v[30:33], v[158:161], v[210:213], v[30:33]
	v_mfma_f32_16x16x32_bf16 v[26:29], v[166:169], v[210:213], v[26:29]
	v_mfma_f32_16x16x32_bf16 v[14:17], v[158:161], v[218:221], v[14:17]
	v_mfma_f32_16x16x32_bf16 v[10:13], v[166:169], v[218:221], v[10:13]
	v_mfma_f32_16x16x32_bf16 v[54:57], v[170:173], v[186:189], v[54:57]
	v_mfma_f32_16x16x32_bf16 v[50:53], v[178:181], v[186:189], v[50:53]
	v_mfma_f32_16x16x32_bf16 v[38:41], v[170:173], v[194:197], v[38:41]
	v_mfma_f32_16x16x32_bf16 v[34:37], v[178:181], v[194:197], v[34:37]
	v_mfma_f32_16x16x32_bf16 v[22:25], v[170:173], v[206:209], v[22:25]
	v_mfma_f32_16x16x32_bf16 v[18:21], v[178:181], v[206:209], v[18:21]
	v_mfma_f32_16x16x32_bf16 v[6:9], v[170:173], v[214:217], v[6:9]
	v_mfma_f32_16x16x32_bf16 v[2:5], v[178:181], v[214:217], v[2:5]
	v_mfma_f32_16x16x32_bf16 v[54:57], v[174:177], v[190:193], v[54:57]
	v_mfma_f32_16x16x32_bf16 v[50:53], v[182:185], v[190:193], v[50:53]
	v_mfma_f32_16x16x32_bf16 v[38:41], v[174:177], v[198:201], v[38:41]
	v_mfma_f32_16x16x32_bf16 v[34:37], v[182:185], v[198:201], v[34:37]
	v_mfma_f32_16x16x32_bf16 v[22:25], v[174:177], v[210:213], v[22:25]
	v_mfma_f32_16x16x32_bf16 v[18:21], v[182:185], v[210:213], v[18:21]
	v_mfma_f32_16x16x32_bf16 v[6:9], v[174:177], v[218:221], v[6:9]
	v_mfma_f32_16x16x32_bf16 v[2:5], v[182:185], v[218:221], v[2:5]
	s_setprio 0
	s_barrier
	s_add_i32 s68, s68, 2
	s_add_u32 s42, s42, 0x100
	s_addc_u32 s43, s43, 0
	s_add_u32 s66, s66, 0x100
	s_addc_u32 s67, s67, 0
	s_cmp_gt_u32 s68, 13
.LBB0_745:
	ds_read_b128 v[154:157], v150
	ds_read_b128 v[158:161], v150 offset:1024
	ds_read_b128 v[162:165], v150 offset:2048
	ds_read_b128 v[166:169], v150 offset:3072
	ds_read_b128 v[170:173], v151
	ds_read_b128 v[174:177], v151 offset:1024
	ds_read_b128 v[178:181], v151 offset:2048
	ds_read_b128 v[182:185], v151 offset:3072
	ds_read_b128 v[186:189], v152
	ds_read_b128 v[190:193], v152 offset:1024
	ds_read_b128 v[194:197], v152 offset:2048
	ds_read_b128 v[198:201], v152 offset:3072
	ds_read_b128 v[206:209], v152 offset:4096
	ds_read_b128 v[210:213], v152 offset:5120
	ds_read_b128 v[214:217], v152 offset:6144
	ds_read_b128 v[218:221], v152 offset:7168
	s_add_u32 s44, s42, 0xfffc0080
	s_addc_u32 s45, s43, -1
	s_cmp_eq_u32 s68, 12
	s_cselect_b32 s47, s14, s45
	s_cselect_b32 s46, s15, s44
	s_cselect_b32 s45, s21, s67
	s_cselect_b32 s44, s65, s66
	s_add_i32 m0, s19, 0xc000
	v_lshl_add_u64 v[146:147], s[42:43], 0, v[138:139]
	global_load_lds_dwordx4 v[146:147], off
	v_lshl_add_u64 v[146:147], s[42:43], 0, v[140:141]
	s_add_i32 m0, s19, 0xe000
	s_nop 0
	global_load_lds_dwordx4 v[146:147], off
	s_waitcnt vmcnt(8) lgkmcnt(0)
	s_setprio 1
	s_barrier
	v_mfma_f32_16x16x32_bf16 v[126:129], v[154:157], v[186:189], v[126:129]
	v_mfma_f32_16x16x32_bf16 v[122:125], v[162:165], v[186:189], v[122:125]
	v_mfma_f32_16x16x32_bf16 v[110:113], v[154:157], v[194:197], v[110:113]
	v_mfma_f32_16x16x32_bf16 v[106:109], v[162:165], v[194:197], v[106:109]
	v_mfma_f32_16x16x32_bf16 v[94:97], v[154:157], v[206:209], v[94:97]
	v_mfma_f32_16x16x32_bf16 v[90:93], v[162:165], v[206:209], v[90:93]
	v_mfma_f32_16x16x32_bf16 v[78:81], v[154:157], v[214:217], v[78:81]
	v_mfma_f32_16x16x32_bf16 v[74:77], v[162:165], v[214:217], v[74:77]
	v_mfma_f32_16x16x32_bf16 v[126:129], v[158:161], v[190:193], v[126:129]
	v_mfma_f32_16x16x32_bf16 v[122:125], v[166:169], v[190:193], v[122:125]
	v_mfma_f32_16x16x32_bf16 v[110:113], v[158:161], v[198:201], v[110:113]
	v_mfma_f32_16x16x32_bf16 v[106:109], v[166:169], v[198:201], v[106:109]
	v_mfma_f32_16x16x32_bf16 v[94:97], v[158:161], v[210:213], v[94:97]
	v_mfma_f32_16x16x32_bf16 v[90:93], v[166:169], v[210:213], v[90:93]
	v_mfma_f32_16x16x32_bf16 v[78:81], v[158:161], v[218:221], v[78:81]
	v_mfma_f32_16x16x32_bf16 v[74:77], v[166:169], v[218:221], v[74:77]
	v_mfma_f32_16x16x32_bf16 v[118:121], v[170:173], v[186:189], v[118:121]
	v_mfma_f32_16x16x32_bf16 v[114:117], v[178:181], v[186:189], v[114:117]
	v_mfma_f32_16x16x32_bf16 v[102:105], v[170:173], v[194:197], v[102:105]
	v_mfma_f32_16x16x32_bf16 v[98:101], v[178:181], v[194:197], v[98:101]
	v_mfma_f32_16x16x32_bf16 v[86:89], v[170:173], v[206:209], v[86:89]
	v_mfma_f32_16x16x32_bf16 v[82:85], v[178:181], v[206:209], v[82:85]
	v_mfma_f32_16x16x32_bf16 v[70:73], v[170:173], v[214:217], v[70:73]
	v_mfma_f32_16x16x32_bf16 v[66:69], v[178:181], v[214:217], v[66:69]
	v_mfma_f32_16x16x32_bf16 v[118:121], v[174:177], v[190:193], v[118:121]
	v_mfma_f32_16x16x32_bf16 v[114:117], v[182:185], v[190:193], v[114:117]
	v_mfma_f32_16x16x32_bf16 v[102:105], v[174:177], v[198:201], v[102:105]
	v_mfma_f32_16x16x32_bf16 v[98:101], v[182:185], v[198:201], v[98:101]
	v_mfma_f32_16x16x32_bf16 v[86:89], v[174:177], v[210:213], v[86:89]
	v_mfma_f32_16x16x32_bf16 v[82:85], v[182:185], v[210:213], v[82:85]
	v_mfma_f32_16x16x32_bf16 v[70:73], v[174:177], v[218:221], v[70:73]
	v_mfma_f32_16x16x32_bf16 v[66:69], v[182:185], v[218:221], v[66:69]
	s_setprio 0
	s_barrier
	ds_read_b128 v[186:189], v152 offset:16384
	ds_read_b128 v[190:193], v152 offset:17408
	ds_read_b128 v[194:197], v152 offset:18432
	ds_read_b128 v[198:201], v152 offset:19456
	ds_read_b128 v[206:209], v152 offset:20480
	ds_read_b128 v[210:213], v152 offset:21504
	ds_read_b128 v[214:217], v152 offset:22528
	ds_read_b128 v[218:221], v152 offset:23552
	s_add_i32 s69, s49, s16
	s_mov_b32 m0, s69
	v_lshl_add_u64 v[146:147], s[44:45], 0, v[134:135]
	global_load_lds_dwordx4 v[146:147], off
	s_add_i32 m0, s69, 0x2000
	s_add_u32 s70, s44, 0x40000
	v_lshl_add_u64 v[202:203], s[44:45], 0, v[130:131]
	s_addc_u32 s71, s45, 0
	s_add_i32 s69, s62, s16
	global_load_lds_dwordx4 v[202:203], off
	v_lshl_add_u64 v[222:223], s[70:71], 0, v[134:135]
	s_mov_b32 m0, s69
	v_lshl_add_u64 v[224:225], s[46:47], 0, v[132:133]
	global_load_lds_dwordx4 v[222:223], off
	v_lshl_add_u64 v[222:223], s[70:71], 0, v[130:131]
	s_add_i32 m0, s69, 0x2000
	s_nop 0
	global_load_lds_dwordx4 v[222:223], off
	v_lshl_add_u64 v[222:223], s[46:47], 0, v[136:137]
	s_mov_b32 m0, s19
	s_nop 0
	global_load_lds_dwordx4 v[222:223], off
	s_mov_b32 m0, s24
	s_nop 0
	global_load_lds_dwordx4 v[224:225], off
	s_waitcnt vmcnt(8) lgkmcnt(0)
	s_setprio 1
	s_barrier
	v_mfma_f32_16x16x32_bf16 v[62:65], v[154:157], v[186:189], v[62:65]
	v_mfma_f32_16x16x32_bf16 v[58:61], v[162:165], v[186:189], v[58:61]
	v_mfma_f32_16x16x32_bf16 v[46:49], v[154:157], v[194:197], v[46:49]
	v_mfma_f32_16x16x32_bf16 v[42:45], v[162:165], v[194:197], v[42:45]
	v_mfma_f32_16x16x32_bf16 v[30:33], v[154:157], v[206:209], v[30:33]
	v_mfma_f32_16x16x32_bf16 v[26:29], v[162:165], v[206:209], v[26:29]
	v_mfma_f32_16x16x32_bf16 v[14:17], v[154:157], v[214:217], v[14:17]
	v_mfma_f32_16x16x32_bf16 v[10:13], v[162:165], v[214:217], v[10:13]
	v_mfma_f32_16x16x32_bf16 v[62:65], v[158:161], v[190:193], v[62:65]
	v_mfma_f32_16x16x32_bf16 v[58:61], v[166:169], v[190:193], v[58:61]
	v_mfma_f32_16x16x32_bf16 v[46:49], v[158:161], v[198:201], v[46:49]
	v_mfma_f32_16x16x32_bf16 v[42:45], v[166:169], v[198:201], v[42:45]
	v_mfma_f32_16x16x32_bf16 v[30:33], v[158:161], v[210:213], v[30:33]
	v_mfma_f32_16x16x32_bf16 v[26:29], v[166:169], v[210:213], v[26:29]
	v_mfma_f32_16x16x32_bf16 v[14:17], v[158:161], v[218:221], v[14:17]
	v_mfma_f32_16x16x32_bf16 v[10:13], v[166:169], v[218:221], v[10:13]
	v_mfma_f32_16x16x32_bf16 v[54:57], v[170:173], v[186:189], v[54:57]
	v_mfma_f32_16x16x32_bf16 v[50:53], v[178:181], v[186:189], v[50:53]
	v_mfma_f32_16x16x32_bf16 v[38:41], v[170:173], v[194:197], v[38:41]
	v_mfma_f32_16x16x32_bf16 v[34:37], v[178:181], v[194:197], v[34:37]
	v_mfma_f32_16x16x32_bf16 v[22:25], v[170:173], v[206:209], v[22:25]
	v_mfma_f32_16x16x32_bf16 v[18:21], v[178:181], v[206:209], v[18:21]
	v_mfma_f32_16x16x32_bf16 v[6:9], v[170:173], v[214:217], v[6:9]
	v_mfma_f32_16x16x32_bf16 v[2:5], v[178:181], v[214:217], v[2:5]
	v_mfma_f32_16x16x32_bf16 v[54:57], v[174:177], v[190:193], v[54:57]
	v_mfma_f32_16x16x32_bf16 v[50:53], v[182:185], v[190:193], v[50:53]
	v_mfma_f32_16x16x32_bf16 v[38:41], v[174:177], v[198:201], v[38:41]
	v_mfma_f32_16x16x32_bf16 v[34:37], v[182:185], v[198:201], v[34:37]
	v_mfma_f32_16x16x32_bf16 v[22:25], v[174:177], v[210:213], v[22:25]
	v_mfma_f32_16x16x32_bf16 v[18:21], v[182:185], v[210:213], v[18:21]
	v_mfma_f32_16x16x32_bf16 v[6:9], v[174:177], v[218:221], v[6:9]
	v_mfma_f32_16x16x32_bf16 v[2:5], v[182:185], v[218:221], v[2:5]
	s_setprio 0
	s_barrier
	s_add_i32 s69, 0, 0x18000
	v_add_u32_e32 v153, s69, v149
	s_add_i32 s70, 0, 0x1c000
	ds_read_b128 v[154:157], v153
	ds_read_b128 v[158:161], v153 offset:1024
	ds_read_b128 v[162:165], v153 offset:2048
	ds_read_b128 v[166:169], v153 offset:3072
	v_add_u32_e32 v153, s70, v149
	ds_read_b128 v[170:173], v153
	ds_read_b128 v[174:177], v153 offset:1024
	ds_read_b128 v[178:181], v153 offset:2048
	ds_read_b128 v[182:185], v153 offset:3072
	s_add_u32 s46, s46, 0x40000
	s_addc_u32 s47, s47, 0
	s_mov_b32 m0, s25
	v_lshl_add_u64 v[226:227], s[46:47], 0, v[136:137]
	ds_read_b128 v[186:189], v152 offset:32768
	ds_read_b128 v[190:193], v152 offset:33792
	ds_read_b128 v[194:197], v152 offset:34816
	ds_read_b128 v[198:201], v152 offset:35840
	ds_read_b128 v[206:209], v152 offset:36864
	ds_read_b128 v[210:213], v152 offset:37888
	ds_read_b128 v[214:217], v152 offset:38912
	ds_read_b128 v[218:221], v152 offset:39936
	global_load_lds_dwordx4 v[226:227], off
	v_lshl_add_u64 v[226:227], s[46:47], 0, v[132:133]
	s_mov_b32 m0, s28
	s_nop 0
	global_load_lds_dwordx4 v[226:227], off
	s_waitcnt vmcnt(8) lgkmcnt(0)
	s_setprio 1
	s_barrier
	v_mfma_f32_16x16x32_bf16 v[126:129], v[154:157], v[186:189], v[126:129]
	v_mfma_f32_16x16x32_bf16 v[122:125], v[162:165], v[186:189], v[122:125]
	v_mfma_f32_16x16x32_bf16 v[110:113], v[154:157], v[194:197], v[110:113]
	v_mfma_f32_16x16x32_bf16 v[106:109], v[162:165], v[194:197], v[106:109]
	v_mfma_f32_16x16x32_bf16 v[94:97], v[154:157], v[206:209], v[94:97]
	v_mfma_f32_16x16x32_bf16 v[90:93], v[162:165], v[206:209], v[90:93]
	v_mfma_f32_16x16x32_bf16 v[78:81], v[154:157], v[214:217], v[78:81]
	v_mfma_f32_16x16x32_bf16 v[74:77], v[162:165], v[214:217], v[74:77]
	v_mfma_f32_16x16x32_bf16 v[126:129], v[158:161], v[190:193], v[126:129]
	v_mfma_f32_16x16x32_bf16 v[122:125], v[166:169], v[190:193], v[122:125]
	v_mfma_f32_16x16x32_bf16 v[110:113], v[158:161], v[198:201], v[110:113]
	v_mfma_f32_16x16x32_bf16 v[106:109], v[166:169], v[198:201], v[106:109]
	v_mfma_f32_16x16x32_bf16 v[94:97], v[158:161], v[210:213], v[94:97]
	v_mfma_f32_16x16x32_bf16 v[90:93], v[166:169], v[210:213], v[90:93]
	v_mfma_f32_16x16x32_bf16 v[78:81], v[158:161], v[218:221], v[78:81]
	v_mfma_f32_16x16x32_bf16 v[74:77], v[166:169], v[218:221], v[74:77]
	v_mfma_f32_16x16x32_bf16 v[118:121], v[170:173], v[186:189], v[118:121]
	v_mfma_f32_16x16x32_bf16 v[114:117], v[178:181], v[186:189], v[114:117]
	v_mfma_f32_16x16x32_bf16 v[102:105], v[170:173], v[194:197], v[102:105]
	v_mfma_f32_16x16x32_bf16 v[98:101], v[178:181], v[194:197], v[98:101]
	v_mfma_f32_16x16x32_bf16 v[86:89], v[170:173], v[206:209], v[86:89]
	v_mfma_f32_16x16x32_bf16 v[82:85], v[178:181], v[206:209], v[82:85]
	v_mfma_f32_16x16x32_bf16 v[70:73], v[170:173], v[214:217], v[70:73]
	v_mfma_f32_16x16x32_bf16 v[66:69], v[178:181], v[214:217], v[66:69]
	v_mfma_f32_16x16x32_bf16 v[118:121], v[174:177], v[190:193], v[118:121]
	v_mfma_f32_16x16x32_bf16 v[114:117], v[182:185], v[190:193], v[114:117]
	v_mfma_f32_16x16x32_bf16 v[102:105], v[174:177], v[198:201], v[102:105]
	v_mfma_f32_16x16x32_bf16 v[98:101], v[182:185], v[198:201], v[98:101]
	v_mfma_f32_16x16x32_bf16 v[86:89], v[174:177], v[210:213], v[86:89]
	v_mfma_f32_16x16x32_bf16 v[82:85], v[182:185], v[210:213], v[82:85]
	v_mfma_f32_16x16x32_bf16 v[70:73], v[174:177], v[218:221], v[70:73]
	v_mfma_f32_16x16x32_bf16 v[66:69], v[182:185], v[218:221], v[66:69]
	s_setprio 0
	s_barrier
	ds_read_b128 v[186:189], v152 offset:49152
	ds_read_b128 v[190:193], v152 offset:50176
	ds_read_b128 v[194:197], v152 offset:51200
	ds_read_b128 v[198:201], v152 offset:52224
	ds_read_b128 v[206:209], v152 offset:53248
	ds_read_b128 v[210:213], v152 offset:54272
	ds_read_b128 v[214:217], v152 offset:55296
	ds_read_b128 v[218:221], v152 offset:56320
	s_add_i32 s46, s69, s16
	s_mov_b32 m0, s46
	v_lshl_add_u64 v[146:147], v[146:147], 0, s[10:11]
	global_load_lds_dwordx4 v[146:147], off
	s_add_i32 m0, s46, 0x2000
	s_add_u32 s44, s44, 0x40080
	v_lshl_add_u64 v[146:147], v[202:203], 0, s[10:11]
	s_addc_u32 s45, s45, 0
	s_add_i32 s46, s70, s16
	global_load_lds_dwordx4 v[146:147], off
	v_lshl_add_u64 v[146:147], s[44:45], 0, v[134:135]
	s_mov_b32 m0, s46
	s_nop 0
	global_load_lds_dwordx4 v[146:147], off
	v_lshl_add_u64 v[146:147], s[44:45], 0, v[130:131]
	s_add_i32 m0, s46, 0x2000
	s_nop 0
	global_load_lds_dwordx4 v[146:147], off
	v_lshl_add_u64 v[146:147], v[222:223], 0, s[10:11]
	s_mov_b32 m0, s33
	s_nop 0
	global_load_lds_dwordx4 v[146:147], off
	v_lshl_add_u64 v[146:147], v[224:225], 0, s[10:11]
	s_mov_b32 m0, s35
	s_nop 0
	global_load_lds_dwordx4 v[146:147], off
	s_waitcnt vmcnt(8) lgkmcnt(0)
	s_setprio 1
	s_barrier
	v_mfma_f32_16x16x32_bf16 v[62:65], v[154:157], v[186:189], v[62:65]
	v_mfma_f32_16x16x32_bf16 v[58:61], v[162:165], v[186:189], v[58:61]
	v_mfma_f32_16x16x32_bf16 v[46:49], v[154:157], v[194:197], v[46:49]
	v_mfma_f32_16x16x32_bf16 v[42:45], v[162:165], v[194:197], v[42:45]
	v_mfma_f32_16x16x32_bf16 v[30:33], v[154:157], v[206:209], v[30:33]
	v_mfma_f32_16x16x32_bf16 v[26:29], v[162:165], v[206:209], v[26:29]
	v_mfma_f32_16x16x32_bf16 v[14:17], v[154:157], v[214:217], v[14:17]
	v_mfma_f32_16x16x32_bf16 v[10:13], v[162:165], v[214:217], v[10:13]
	v_mfma_f32_16x16x32_bf16 v[62:65], v[158:161], v[190:193], v[62:65]
	v_mfma_f32_16x16x32_bf16 v[58:61], v[166:169], v[190:193], v[58:61]
	v_mfma_f32_16x16x32_bf16 v[46:49], v[158:161], v[198:201], v[46:49]
	v_mfma_f32_16x16x32_bf16 v[42:45], v[166:169], v[198:201], v[42:45]
	v_mfma_f32_16x16x32_bf16 v[30:33], v[158:161], v[210:213], v[30:33]
	v_mfma_f32_16x16x32_bf16 v[26:29], v[166:169], v[210:213], v[26:29]
	v_mfma_f32_16x16x32_bf16 v[14:17], v[158:161], v[218:221], v[14:17]
	v_mfma_f32_16x16x32_bf16 v[10:13], v[166:169], v[218:221], v[10:13]
	v_mfma_f32_16x16x32_bf16 v[54:57], v[170:173], v[186:189], v[54:57]
	v_mfma_f32_16x16x32_bf16 v[50:53], v[178:181], v[186:189], v[50:53]
	v_mfma_f32_16x16x32_bf16 v[38:41], v[170:173], v[194:197], v[38:41]
	v_mfma_f32_16x16x32_bf16 v[34:37], v[178:181], v[194:197], v[34:37]
	v_mfma_f32_16x16x32_bf16 v[22:25], v[170:173], v[206:209], v[22:25]
	v_mfma_f32_16x16x32_bf16 v[18:21], v[178:181], v[206:209], v[18:21]
	v_mfma_f32_16x16x32_bf16 v[6:9], v[170:173], v[214:217], v[6:9]
	v_mfma_f32_16x16x32_bf16 v[2:5], v[178:181], v[214:217], v[2:5]
	v_mfma_f32_16x16x32_bf16 v[54:57], v[174:177], v[190:193], v[54:57]
	v_mfma_f32_16x16x32_bf16 v[50:53], v[182:185], v[190:193], v[50:53]
	v_mfma_f32_16x16x32_bf16 v[38:41], v[174:177], v[198:201], v[38:41]
	v_mfma_f32_16x16x32_bf16 v[34:37], v[182:185], v[198:201], v[34:37]
	v_mfma_f32_16x16x32_bf16 v[22:25], v[174:177], v[210:213], v[22:25]
	v_mfma_f32_16x16x32_bf16 v[18:21], v[182:185], v[210:213], v[18:21]
	v_mfma_f32_16x16x32_bf16 v[6:9], v[174:177], v[218:221], v[6:9]
	v_mfma_f32_16x16x32_bf16 v[2:5], v[182:185], v[218:221], v[2:5]
	s_setprio 0
	s_barrier
	s_add_i32 s68, s68, 2
	s_add_u32 s42, s42, 0x100
	s_addc_u32 s43, s43, 0
	s_add_u32 s66, s66, 0x100
	s_addc_u32 s67, s67, 0
	s_cmp_gt_u32 s68, 13
	s_cbranch_scc0 .LBB0_745
	s_and_b64 vcc, exec, s[12:13]
	s_cbranch_vccz .LBB0_748
	s_barrier

.LBB0_833:
	s_add_u32 s72, s0, s68
	s_addc_u32 s73, s1, s69
	s_and_b64 s[62:63], s[70:71], exec
	s_cselect_b32 s15, s73, s77
	s_cselect_b32 s33, s72, s76
	s_add_u32 s74, s35, s66
	s_addc_u32 s75, s85, s67
	s_and_b64 s[62:63], s[70:71], exec
	s_cselect_b32 s34, s75, s79
	s_cselect_b32 s39, s74, s78
	s_add_i32 s45, s7, -2
	s_add_u32 s76, s76, 0x100080
	s_addc_u32 s77, s77, 0
	s_add_u32 s47, s78, 0x100
	s_addc_u32 s62, s79, 0
	s_mov_b32 s63, 0
	s_waitcnt vmcnt(0)
	ds_read_b128 v[114:117], v190
	ds_read_b128 v[118:121], v190 offset:1024
	ds_read_b128 v[122:125], v190 offset:2048
	ds_read_b128 v[126:129], v190 offset:3072
	ds_read_b128 v[146:149], v191
	ds_read_b128 v[150:153], v191 offset:1024
	ds_read_b128 v[154:157], v191 offset:2048
	ds_read_b128 v[158:161], v191 offset:3072
	ds_read_b128 v[162:165], v192
	ds_read_b128 v[166:169], v192 offset:1024
	ds_read_b128 v[194:197], v192 offset:2048
	ds_read_b128 v[198:201], v192 offset:3072
	ds_read_b128 v[206:209], v192 offset:4096
	ds_read_b128 v[210:213], v192 offset:5120
	ds_read_b128 v[214:217], v192 offset:6144
	ds_read_b128 v[218:221], v192 offset:7168
	s_add_i32 s82, s63, 2
	s_add_u32 s78, s76, 0xfff00080
	s_addc_u32 s79, s77, -1
	s_cmp_eq_u32 s45, s63
	s_cselect_b32 s81, s15, s79
	s_cselect_b32 s80, s33, s78
	s_cselect_b32 s79, s34, s62
	s_cselect_b32 s78, s39, s47
	s_add_i32 m0, s87, 0xc000
	v_lshl_add_u64 v[186:187], s[76:77], 0, v[180:181]
	global_load_lds_dwordx4 v[186:187], off
	v_lshl_add_u64 v[186:187], s[76:77], 0, v[182:183]
	s_add_i32 m0, s87, 0xe000
	s_nop 0
	global_load_lds_dwordx4 v[186:187], off
	s_waitcnt vmcnt(8) lgkmcnt(0)
	s_setprio 1
	s_barrier
	v_mfma_f32_16x16x32_bf16 v[142:145], v[114:117], v[162:165], 0
	v_mfma_f32_16x16x32_bf16 v[138:141], v[122:125], v[162:165], 0
	v_mfma_f32_16x16x32_bf16 v[110:113], v[114:117], v[194:197], 0
	v_mfma_f32_16x16x32_bf16 v[106:109], v[122:125], v[194:197], 0
	v_mfma_f32_16x16x32_bf16 v[98:101], v[114:117], v[206:209], 0
	v_mfma_f32_16x16x32_bf16 v[90:93], v[122:125], v[206:209], 0
	v_mfma_f32_16x16x32_bf16 v[82:85], v[114:117], v[214:217], 0
	v_mfma_f32_16x16x32_bf16 v[74:77], v[122:125], v[214:217], 0
	v_mfma_f32_16x16x32_bf16 v[142:145], v[118:121], v[166:169], v[142:145]
	v_mfma_f32_16x16x32_bf16 v[138:141], v[126:129], v[166:169], v[138:141]
	v_mfma_f32_16x16x32_bf16 v[110:113], v[118:121], v[198:201], v[110:113]
	v_mfma_f32_16x16x32_bf16 v[106:109], v[126:129], v[198:201], v[106:109]
	v_mfma_f32_16x16x32_bf16 v[98:101], v[118:121], v[210:213], v[98:101]
	v_mfma_f32_16x16x32_bf16 v[90:93], v[126:129], v[210:213], v[90:93]
	v_mfma_f32_16x16x32_bf16 v[82:85], v[118:121], v[218:221], v[82:85]
	v_mfma_f32_16x16x32_bf16 v[74:77], v[126:129], v[218:221], v[74:77]
	v_mfma_f32_16x16x32_bf16 v[134:137], v[146:149], v[162:165], 0
	v_mfma_f32_16x16x32_bf16 v[130:133], v[154:157], v[162:165], 0
	v_mfma_f32_16x16x32_bf16 v[102:105], v[146:149], v[194:197], 0
	v_mfma_f32_16x16x32_bf16 v[94:97], v[154:157], v[194:197], 0
	v_mfma_f32_16x16x32_bf16 v[86:89], v[146:149], v[206:209], 0
	v_mfma_f32_16x16x32_bf16 v[78:81], v[154:157], v[206:209], 0
	v_mfma_f32_16x16x32_bf16 v[70:73], v[146:149], v[214:217], 0
	v_mfma_f32_16x16x32_bf16 v[66:69], v[154:157], v[214:217], 0
	v_mfma_f32_16x16x32_bf16 v[134:137], v[150:153], v[166:169], v[134:137]
	v_mfma_f32_16x16x32_bf16 v[130:133], v[158:161], v[166:169], v[130:133]
	v_mfma_f32_16x16x32_bf16 v[102:105], v[150:153], v[198:201], v[102:105]
	v_mfma_f32_16x16x32_bf16 v[94:97], v[158:161], v[198:201], v[94:97]
	v_mfma_f32_16x16x32_bf16 v[86:89], v[150:153], v[210:213], v[86:89]
	v_mfma_f32_16x16x32_bf16 v[78:81], v[158:161], v[210:213], v[78:81]
	v_mfma_f32_16x16x32_bf16 v[70:73], v[150:153], v[218:221], v[70:73]
	v_mfma_f32_16x16x32_bf16 v[66:69], v[158:161], v[218:221], v[66:69]
	s_setprio 0
	s_barrier
	ds_read_b128 v[162:165], v192 offset:16384
	ds_read_b128 v[166:169], v192 offset:17408
	ds_read_b128 v[194:197], v192 offset:18432
	ds_read_b128 v[198:201], v192 offset:19456
	ds_read_b128 v[206:209], v192 offset:20480
	ds_read_b128 v[210:213], v192 offset:21504
	ds_read_b128 v[214:217], v192 offset:22528
	ds_read_b128 v[218:221], v192 offset:23552
	s_add_i32 s63, s24, s86
	s_mov_b32 m0, s63
	v_lshl_add_u64 v[186:187], s[78:79], 0, v[172:173]
	global_load_lds_dwordx4 v[186:187], off
	s_add_i32 m0, s63, 0x2000
	s_add_u32 vcc_lo, s78, 0x100000
	v_lshl_add_u64 v[202:203], s[78:79], 0, v[176:177]
	s_addc_u32 vcc_hi, s79, 0
	s_add_i32 s63, s25, s86
	global_load_lds_dwordx4 v[202:203], off
	v_lshl_add_u64 v[222:223], vcc, 0, v[172:173]
	s_mov_b32 m0, s63
	v_lshl_add_u64 v[224:225], s[80:81], 0, v[174:175]
	global_load_lds_dwordx4 v[222:223], off
	v_lshl_add_u64 v[222:223], vcc, 0, v[176:177]
	s_add_i32 m0, s63, 0x2000
	s_nop 0
	global_load_lds_dwordx4 v[222:223], off
	v_lshl_add_u64 v[222:223], s[80:81], 0, v[170:171]
	s_mov_b32 m0, s87
	s_nop 0
	global_load_lds_dwordx4 v[222:223], off
	s_mov_b32 m0, s88
	s_nop 0
	global_load_lds_dwordx4 v[224:225], off
	s_waitcnt vmcnt(8) lgkmcnt(0)
	s_setprio 1
	s_barrier
	v_mfma_f32_16x16x32_bf16 v[62:65], v[114:117], v[162:165], 0
	v_mfma_f32_16x16x32_bf16 v[58:61], v[122:125], v[162:165], 0
	v_mfma_f32_16x16x32_bf16 v[50:53], v[114:117], v[194:197], 0
	v_mfma_f32_16x16x32_bf16 v[42:45], v[122:125], v[194:197], 0
	v_mfma_f32_16x16x32_bf16 v[34:37], v[114:117], v[206:209], 0
	v_mfma_f32_16x16x32_bf16 v[26:29], v[122:125], v[206:209], 0
	v_mfma_f32_16x16x32_bf16 v[18:21], v[114:117], v[214:217], 0
	v_mfma_f32_16x16x32_bf16 v[10:13], v[122:125], v[214:217], 0
	v_mfma_f32_16x16x32_bf16 v[62:65], v[118:121], v[166:169], v[62:65]
	v_mfma_f32_16x16x32_bf16 v[58:61], v[126:129], v[166:169], v[58:61]
	v_mfma_f32_16x16x32_bf16 v[50:53], v[118:121], v[198:201], v[50:53]
	v_mfma_f32_16x16x32_bf16 v[42:45], v[126:129], v[198:201], v[42:45]
	v_mfma_f32_16x16x32_bf16 v[34:37], v[118:121], v[210:213], v[34:37]
	v_mfma_f32_16x16x32_bf16 v[26:29], v[126:129], v[210:213], v[26:29]
	v_mfma_f32_16x16x32_bf16 v[18:21], v[118:121], v[218:221], v[18:21]
	v_mfma_f32_16x16x32_bf16 v[10:13], v[126:129], v[218:221], v[10:13]
	v_mfma_f32_16x16x32_bf16 v[54:57], v[146:149], v[162:165], 0
	v_mfma_f32_16x16x32_bf16 v[46:49], v[154:157], v[162:165], 0
	v_mfma_f32_16x16x32_bf16 v[38:41], v[146:149], v[194:197], 0
	v_mfma_f32_16x16x32_bf16 v[30:33], v[154:157], v[194:197], 0
	v_mfma_f32_16x16x32_bf16 v[22:25], v[146:149], v[206:209], 0
	v_mfma_f32_16x16x32_bf16 v[14:17], v[154:157], v[206:209], 0
	v_mfma_f32_16x16x32_bf16 v[6:9], v[146:149], v[214:217], 0
	v_mfma_f32_16x16x32_bf16 v[2:5], v[154:157], v[214:217], 0
	v_mfma_f32_16x16x32_bf16 v[54:57], v[150:153], v[166:169], v[54:57]
	v_mfma_f32_16x16x32_bf16 v[46:49], v[158:161], v[166:169], v[46:49]
	v_mfma_f32_16x16x32_bf16 v[38:41], v[150:153], v[198:201], v[38:41]
	v_mfma_f32_16x16x32_bf16 v[30:33], v[158:161], v[198:201], v[30:33]
	v_mfma_f32_16x16x32_bf16 v[22:25], v[150:153], v[210:213], v[22:25]
	v_mfma_f32_16x16x32_bf16 v[14:17], v[158:161], v[210:213], v[14:17]
	v_mfma_f32_16x16x32_bf16 v[6:9], v[150:153], v[218:221], v[6:9]
	v_mfma_f32_16x16x32_bf16 v[2:5], v[158:161], v[218:221], v[2:5]
	s_setprio 0
	s_barrier
	s_add_i32 s63, 0, 0x18000
	s_add_i32 s83, 0, 0x1c000
	v_add_u32_e32 v126, s63, v189
	v_add_u32_e32 v158, s83, v189
	ds_read_b128 v[114:117], v126
	ds_read_b128 v[118:121], v126 offset:1024
	ds_read_b128 v[122:125], v126 offset:2048
	ds_read_b128 v[126:129], v126 offset:3072
	ds_read_b128 v[146:149], v158
	ds_read_b128 v[150:153], v158 offset:1024
	ds_read_b128 v[154:157], v158 offset:2048
	ds_read_b128 v[158:161], v158 offset:3072
	s_add_u32 s80, s80, 0x100000
	s_addc_u32 s81, s81, 0
	s_mov_b32 m0, s89
	v_lshl_add_u64 v[226:227], s[80:81], 0, v[170:171]
	ds_read_b128 v[162:165], v192 offset:32768
	ds_read_b128 v[166:169], v192 offset:33792
	ds_read_b128 v[194:197], v192 offset:34816
	ds_read_b128 v[198:201], v192 offset:35840
	ds_read_b128 v[206:209], v192 offset:36864
	ds_read_b128 v[210:213], v192 offset:37888
	ds_read_b128 v[214:217], v192 offset:38912
	ds_read_b128 v[218:221], v192 offset:39936
	global_load_lds_dwordx4 v[226:227], off
	v_lshl_add_u64 v[226:227], s[80:81], 0, v[174:175]
	s_mov_b32 m0, s90
	s_nop 0
	global_load_lds_dwordx4 v[226:227], off
	s_waitcnt vmcnt(8) lgkmcnt(0)
	s_setprio 1
	s_barrier
	v_mfma_f32_16x16x32_bf16 v[142:145], v[114:117], v[162:165], v[142:145]
	v_mfma_f32_16x16x32_bf16 v[138:141], v[122:125], v[162:165], v[138:141]
	v_mfma_f32_16x16x32_bf16 v[110:113], v[114:117], v[194:197], v[110:113]
	v_mfma_f32_16x16x32_bf16 v[106:109], v[122:125], v[194:197], v[106:109]
	v_mfma_f32_16x16x32_bf16 v[98:101], v[114:117], v[206:209], v[98:101]
	v_mfma_f32_16x16x32_bf16 v[90:93], v[122:125], v[206:209], v[90:93]
	v_mfma_f32_16x16x32_bf16 v[82:85], v[114:117], v[214:217], v[82:85]
	v_mfma_f32_16x16x32_bf16 v[74:77], v[122:125], v[214:217], v[74:77]
	v_mfma_f32_16x16x32_bf16 v[142:145], v[118:121], v[166:169], v[142:145]
	v_mfma_f32_16x16x32_bf16 v[138:141], v[126:129], v[166:169], v[138:141]
	v_mfma_f32_16x16x32_bf16 v[110:113], v[118:121], v[198:201], v[110:113]
	v_mfma_f32_16x16x32_bf16 v[106:109], v[126:129], v[198:201], v[106:109]
	v_mfma_f32_16x16x32_bf16 v[98:101], v[118:121], v[210:213], v[98:101]
	v_mfma_f32_16x16x32_bf16 v[90:93], v[126:129], v[210:213], v[90:93]
	v_mfma_f32_16x16x32_bf16 v[82:85], v[118:121], v[218:221], v[82:85]
	v_mfma_f32_16x16x32_bf16 v[74:77], v[126:129], v[218:221], v[74:77]
	v_mfma_f32_16x16x32_bf16 v[134:137], v[146:149], v[162:165], v[134:137]
	v_mfma_f32_16x16x32_bf16 v[130:133], v[154:157], v[162:165], v[130:133]
	v_mfma_f32_16x16x32_bf16 v[102:105], v[146:149], v[194:197], v[102:105]
	v_mfma_f32_16x16x32_bf16 v[94:97], v[154:157], v[194:197], v[94:97]
	v_mfma_f32_16x16x32_bf16 v[86:89], v[146:149], v[206:209], v[86:89]
	v_mfma_f32_16x16x32_bf16 v[78:81], v[154:157], v[206:209], v[78:81]
	v_mfma_f32_16x16x32_bf16 v[70:73], v[146:149], v[214:217], v[70:73]
	v_mfma_f32_16x16x32_bf16 v[66:69], v[154:157], v[214:217], v[66:69]
	v_mfma_f32_16x16x32_bf16 v[134:137], v[150:153], v[166:169], v[134:137]
	v_mfma_f32_16x16x32_bf16 v[130:133], v[158:161], v[166:169], v[130:133]
	v_mfma_f32_16x16x32_bf16 v[102:105], v[150:153], v[198:201], v[102:105]
	v_mfma_f32_16x16x32_bf16 v[94:97], v[158:161], v[198:201], v[94:97]
	v_mfma_f32_16x16x32_bf16 v[86:89], v[150:153], v[210:213], v[86:89]
	v_mfma_f32_16x16x32_bf16 v[78:81], v[158:161], v[210:213], v[78:81]
	v_mfma_f32_16x16x32_bf16 v[70:73], v[150:153], v[218:221], v[70:73]
	v_mfma_f32_16x16x32_bf16 v[66:69], v[158:161], v[218:221], v[66:69]
	s_setprio 0
	s_barrier
	ds_read_b128 v[162:165], v192 offset:49152
	ds_read_b128 v[166:169], v192 offset:50176
	ds_read_b128 v[194:197], v192 offset:51200
	ds_read_b128 v[198:201], v192 offset:52224
	ds_read_b128 v[206:209], v192 offset:53248
	ds_read_b128 v[210:213], v192 offset:54272
	ds_read_b128 v[214:217], v192 offset:55296
	ds_read_b128 v[218:221], v192 offset:56320
	s_add_i32 s63, s63, s86
	s_mov_b32 m0, s63
	v_lshl_add_u64 v[186:187], v[186:187], 0, s[22:23]
	global_load_lds_dwordx4 v[186:187], off
	s_add_i32 m0, s63, 0x2000
	s_add_u32 s78, s78, 0x100080
	v_lshl_add_u64 v[186:187], v[202:203], 0, s[22:23]
	s_addc_u32 s79, s79, 0
	s_add_i32 s63, s83, s86
	global_load_lds_dwordx4 v[186:187], off
	v_lshl_add_u64 v[186:187], s[78:79], 0, v[172:173]
	s_mov_b32 m0, s63
	s_nop 0
	global_load_lds_dwordx4 v[186:187], off
	v_lshl_add_u64 v[186:187], s[78:79], 0, v[176:177]
	s_add_i32 m0, s63, 0x2000
	s_nop 0
	global_load_lds_dwordx4 v[186:187], off
	v_lshl_add_u64 v[186:187], v[222:223], 0, s[22:23]
	s_mov_b32 m0, s95
	s_nop 0
	global_load_lds_dwordx4 v[186:187], off
	v_lshl_add_u64 v[186:187], v[224:225], 0, s[22:23]
	s_mov_b32 m0, s96
	s_nop 0
	global_load_lds_dwordx4 v[186:187], off
	s_waitcnt vmcnt(8) lgkmcnt(0)
	s_setprio 1
	s_barrier
	v_mfma_f32_16x16x32_bf16 v[62:65], v[114:117], v[162:165], v[62:65]
	v_mfma_f32_16x16x32_bf16 v[58:61], v[122:125], v[162:165], v[58:61]
	v_mfma_f32_16x16x32_bf16 v[50:53], v[114:117], v[194:197], v[50:53]
	v_mfma_f32_16x16x32_bf16 v[42:45], v[122:125], v[194:197], v[42:45]
	v_mfma_f32_16x16x32_bf16 v[34:37], v[114:117], v[206:209], v[34:37]
	v_mfma_f32_16x16x32_bf16 v[26:29], v[122:125], v[206:209], v[26:29]
	v_mfma_f32_16x16x32_bf16 v[18:21], v[114:117], v[214:217], v[18:21]
	v_mfma_f32_16x16x32_bf16 v[10:13], v[122:125], v[214:217], v[10:13]
	v_mfma_f32_16x16x32_bf16 v[62:65], v[118:121], v[166:169], v[62:65]
	v_mfma_f32_16x16x32_bf16 v[58:61], v[126:129], v[166:169], v[58:61]
	v_mfma_f32_16x16x32_bf16 v[50:53], v[118:121], v[198:201], v[50:53]
	v_mfma_f32_16x16x32_bf16 v[42:45], v[126:129], v[198:201], v[42:45]
	v_mfma_f32_16x16x32_bf16 v[34:37], v[118:121], v[210:213], v[34:37]
	v_mfma_f32_16x16x32_bf16 v[26:29], v[126:129], v[210:213], v[26:29]
	v_mfma_f32_16x16x32_bf16 v[18:21], v[118:121], v[218:221], v[18:21]
	v_mfma_f32_16x16x32_bf16 v[10:13], v[126:129], v[218:221], v[10:13]
	v_mfma_f32_16x16x32_bf16 v[54:57], v[146:149], v[162:165], v[54:57]
	v_mfma_f32_16x16x32_bf16 v[46:49], v[154:157], v[162:165], v[46:49]
	v_mfma_f32_16x16x32_bf16 v[38:41], v[146:149], v[194:197], v[38:41]
	v_mfma_f32_16x16x32_bf16 v[30:33], v[154:157], v[194:197], v[30:33]
	v_mfma_f32_16x16x32_bf16 v[22:25], v[146:149], v[206:209], v[22:25]
	v_mfma_f32_16x16x32_bf16 v[14:17], v[154:157], v[206:209], v[14:17]
	v_mfma_f32_16x16x32_bf16 v[6:9], v[146:149], v[214:217], v[6:9]
	v_mfma_f32_16x16x32_bf16 v[2:5], v[154:157], v[214:217], v[2:5]
	v_mfma_f32_16x16x32_bf16 v[54:57], v[150:153], v[166:169], v[54:57]
	v_mfma_f32_16x16x32_bf16 v[46:49], v[158:161], v[166:169], v[46:49]
	v_mfma_f32_16x16x32_bf16 v[38:41], v[150:153], v[198:201], v[38:41]
	v_mfma_f32_16x16x32_bf16 v[30:33], v[158:161], v[198:201], v[30:33]
	v_mfma_f32_16x16x32_bf16 v[22:25], v[150:153], v[210:213], v[22:25]
	v_mfma_f32_16x16x32_bf16 v[14:17], v[158:161], v[210:213], v[14:17]
	v_mfma_f32_16x16x32_bf16 v[6:9], v[150:153], v[218:221], v[6:9]
	v_mfma_f32_16x16x32_bf16 v[2:5], v[158:161], v[218:221], v[2:5]
	s_setprio 0
	s_barrier
	s_add_u32 s76, s76, 0x100
	s_addc_u32 s77, s77, 0
	s_add_u32 s47, s47, 0x100
	s_addc_u32 s62, s62, 0
	s_cmp_ge_i32 s82, s7
	s_mov_b32 s63, s82
.LBB0_834:
	ds_read_b128 v[114:117], v190
	ds_read_b128 v[118:121], v190 offset:1024
	ds_read_b128 v[122:125], v190 offset:2048
	ds_read_b128 v[126:129], v190 offset:3072
	ds_read_b128 v[146:149], v191
	ds_read_b128 v[150:153], v191 offset:1024
	ds_read_b128 v[154:157], v191 offset:2048
	ds_read_b128 v[158:161], v191 offset:3072
	ds_read_b128 v[162:165], v192
	ds_read_b128 v[166:169], v192 offset:1024
	ds_read_b128 v[194:197], v192 offset:2048
	ds_read_b128 v[198:201], v192 offset:3072
	ds_read_b128 v[206:209], v192 offset:4096
	ds_read_b128 v[210:213], v192 offset:5120
	ds_read_b128 v[214:217], v192 offset:6144
	ds_read_b128 v[218:221], v192 offset:7168
	s_add_i32 s82, s63, 2
	s_add_u32 s78, s76, 0xfff00080
	s_addc_u32 s79, s77, -1
	s_cmp_eq_u32 s45, s63
	s_cselect_b32 s81, s15, s79
	s_cselect_b32 s80, s33, s78
	s_cselect_b32 s79, s34, s62
	s_cselect_b32 s78, s39, s47
	s_add_i32 m0, s87, 0xc000
	v_lshl_add_u64 v[186:187], s[76:77], 0, v[180:181]
	global_load_lds_dwordx4 v[186:187], off
	v_lshl_add_u64 v[186:187], s[76:77], 0, v[182:183]
	s_add_i32 m0, s87, 0xe000
	s_nop 0
	global_load_lds_dwordx4 v[186:187], off
	s_waitcnt vmcnt(8) lgkmcnt(0)
	s_setprio 1
	s_barrier
	v_mfma_f32_16x16x32_bf16 v[142:145], v[114:117], v[162:165], v[142:145]
	v_mfma_f32_16x16x32_bf16 v[138:141], v[122:125], v[162:165], v[138:141]
	v_mfma_f32_16x16x32_bf16 v[110:113], v[114:117], v[194:197], v[110:113]
	v_mfma_f32_16x16x32_bf16 v[106:109], v[122:125], v[194:197], v[106:109]
	v_mfma_f32_16x16x32_bf16 v[98:101], v[114:117], v[206:209], v[98:101]
	v_mfma_f32_16x16x32_bf16 v[90:93], v[122:125], v[206:209], v[90:93]
	v_mfma_f32_16x16x32_bf16 v[82:85], v[114:117], v[214:217], v[82:85]
	v_mfma_f32_16x16x32_bf16 v[74:77], v[122:125], v[214:217], v[74:77]
	v_mfma_f32_16x16x32_bf16 v[142:145], v[118:121], v[166:169], v[142:145]
	v_mfma_f32_16x16x32_bf16 v[138:141], v[126:129], v[166:169], v[138:141]
	v_mfma_f32_16x16x32_bf16 v[110:113], v[118:121], v[198:201], v[110:113]
	v_mfma_f32_16x16x32_bf16 v[106:109], v[126:129], v[198:201], v[106:109]
	v_mfma_f32_16x16x32_bf16 v[98:101], v[118:121], v[210:213], v[98:101]
	v_mfma_f32_16x16x32_bf16 v[90:93], v[126:129], v[210:213], v[90:93]
	v_mfma_f32_16x16x32_bf16 v[82:85], v[118:121], v[218:221], v[82:85]
	v_mfma_f32_16x16x32_bf16 v[74:77], v[126:129], v[218:221], v[74:77]
	v_mfma_f32_16x16x32_bf16 v[134:137], v[146:149], v[162:165], v[134:137]
	v_mfma_f32_16x16x32_bf16 v[130:133], v[154:157], v[162:165], v[130:133]
	v_mfma_f32_16x16x32_bf16 v[102:105], v[146:149], v[194:197], v[102:105]
	v_mfma_f32_16x16x32_bf16 v[94:97], v[154:157], v[194:197], v[94:97]
	v_mfma_f32_16x16x32_bf16 v[86:89], v[146:149], v[206:209], v[86:89]
	v_mfma_f32_16x16x32_bf16 v[78:81], v[154:157], v[206:209], v[78:81]
	v_mfma_f32_16x16x32_bf16 v[70:73], v[146:149], v[214:217], v[70:73]
	v_mfma_f32_16x16x32_bf16 v[66:69], v[154:157], v[214:217], v[66:69]
	v_mfma_f32_16x16x32_bf16 v[134:137], v[150:153], v[166:169], v[134:137]
	v_mfma_f32_16x16x32_bf16 v[130:133], v[158:161], v[166:169], v[130:133]
	v_mfma_f32_16x16x32_bf16 v[102:105], v[150:153], v[198:201], v[102:105]
	v_mfma_f32_16x16x32_bf16 v[94:97], v[158:161], v[198:201], v[94:97]
	v_mfma_f32_16x16x32_bf16 v[86:89], v[150:153], v[210:213], v[86:89]
	v_mfma_f32_16x16x32_bf16 v[78:81], v[158:161], v[210:213], v[78:81]
	v_mfma_f32_16x16x32_bf16 v[70:73], v[150:153], v[218:221], v[70:73]
	v_mfma_f32_16x16x32_bf16 v[66:69], v[158:161], v[218:221], v[66:69]
	s_setprio 0
	s_barrier
	ds_read_b128 v[162:165], v192 offset:16384
	ds_read_b128 v[166:169], v192 offset:17408
	ds_read_b128 v[194:197], v192 offset:18432
	ds_read_b128 v[198:201], v192 offset:19456
	ds_read_b128 v[206:209], v192 offset:20480
	ds_read_b128 v[210:213], v192 offset:21504
	ds_read_b128 v[214:217], v192 offset:22528
	ds_read_b128 v[218:221], v192 offset:23552
	s_add_i32 s63, s24, s86
	s_mov_b32 m0, s63
	v_lshl_add_u64 v[186:187], s[78:79], 0, v[172:173]
	global_load_lds_dwordx4 v[186:187], off
	s_add_i32 m0, s63, 0x2000
	s_add_u32 vcc_lo, s78, 0x100000
	v_lshl_add_u64 v[202:203], s[78:79], 0, v[176:177]
	s_addc_u32 vcc_hi, s79, 0
	s_add_i32 s63, s25, s86
	global_load_lds_dwordx4 v[202:203], off
	v_lshl_add_u64 v[222:223], vcc, 0, v[172:173]
	s_mov_b32 m0, s63
	v_lshl_add_u64 v[224:225], s[80:81], 0, v[174:175]
	global_load_lds_dwordx4 v[222:223], off
	v_lshl_add_u64 v[222:223], vcc, 0, v[176:177]
	s_add_i32 m0, s63, 0x2000
	s_nop 0
	global_load_lds_dwordx4 v[222:223], off
	v_lshl_add_u64 v[222:223], s[80:81], 0, v[170:171]
	s_mov_b32 m0, s87
	s_nop 0
	global_load_lds_dwordx4 v[222:223], off
	s_mov_b32 m0, s88
	s_nop 0
	global_load_lds_dwordx4 v[224:225], off
	s_waitcnt vmcnt(8) lgkmcnt(0)
	s_setprio 1
	s_barrier
	v_mfma_f32_16x16x32_bf16 v[62:65], v[114:117], v[162:165], v[62:65]
	v_mfma_f32_16x16x32_bf16 v[58:61], v[122:125], v[162:165], v[58:61]
	v_mfma_f32_16x16x32_bf16 v[50:53], v[114:117], v[194:197], v[50:53]
	v_mfma_f32_16x16x32_bf16 v[42:45], v[122:125], v[194:197], v[42:45]
	v_mfma_f32_16x16x32_bf16 v[34:37], v[114:117], v[206:209], v[34:37]
	v_mfma_f32_16x16x32_bf16 v[26:29], v[122:125], v[206:209], v[26:29]
	v_mfma_f32_16x16x32_bf16 v[18:21], v[114:117], v[214:217], v[18:21]
	v_mfma_f32_16x16x32_bf16 v[10:13], v[122:125], v[214:217], v[10:13]
	v_mfma_f32_16x16x32_bf16 v[62:65], v[118:121], v[166:169], v[62:65]
	v_mfma_f32_16x16x32_bf16 v[58:61], v[126:129], v[166:169], v[58:61]
	v_mfma_f32_16x16x32_bf16 v[50:53], v[118:121], v[198:201], v[50:53]
	v_mfma_f32_16x16x32_bf16 v[42:45], v[126:129], v[198:201], v[42:45]
	v_mfma_f32_16x16x32_bf16 v[34:37], v[118:121], v[210:213], v[34:37]
	v_mfma_f32_16x16x32_bf16 v[26:29], v[126:129], v[210:213], v[26:29]
	v_mfma_f32_16x16x32_bf16 v[18:21], v[118:121], v[218:221], v[18:21]
	v_mfma_f32_16x16x32_bf16 v[10:13], v[126:129], v[218:221], v[10:13]
	v_mfma_f32_16x16x32_bf16 v[54:57], v[146:149], v[162:165], v[54:57]
	v_mfma_f32_16x16x32_bf16 v[46:49], v[154:157], v[162:165], v[46:49]
	v_mfma_f32_16x16x32_bf16 v[38:41], v[146:149], v[194:197], v[38:41]
	v_mfma_f32_16x16x32_bf16 v[30:33], v[154:157], v[194:197], v[30:33]
	v_mfma_f32_16x16x32_bf16 v[22:25], v[146:149], v[206:209], v[22:25]
	v_mfma_f32_16x16x32_bf16 v[14:17], v[154:157], v[206:209], v[14:17]
	v_mfma_f32_16x16x32_bf16 v[6:9], v[146:149], v[214:217], v[6:9]
	v_mfma_f32_16x16x32_bf16 v[2:5], v[154:157], v[214:217], v[2:5]
	v_mfma_f32_16x16x32_bf16 v[54:57], v[150:153], v[166:169], v[54:57]
	v_mfma_f32_16x16x32_bf16 v[46:49], v[158:161], v[166:169], v[46:49]
	v_mfma_f32_16x16x32_bf16 v[38:41], v[150:153], v[198:201], v[38:41]
	v_mfma_f32_16x16x32_bf16 v[30:33], v[158:161], v[198:201], v[30:33]
	v_mfma_f32_16x16x32_bf16 v[22:25], v[150:153], v[210:213], v[22:25]
	v_mfma_f32_16x16x32_bf16 v[14:17], v[158:161], v[210:213], v[14:17]
	v_mfma_f32_16x16x32_bf16 v[6:9], v[150:153], v[218:221], v[6:9]
	v_mfma_f32_16x16x32_bf16 v[2:5], v[158:161], v[218:221], v[2:5]
	s_setprio 0
	s_barrier
	s_add_i32 s63, 0, 0x18000
	s_add_i32 s83, 0, 0x1c000
	v_add_u32_e32 v126, s63, v189
	v_add_u32_e32 v158, s83, v189
	ds_read_b128 v[114:117], v126
	ds_read_b128 v[118:121], v126 offset:1024
	ds_read_b128 v[122:125], v126 offset:2048
	ds_read_b128 v[126:129], v126 offset:3072
	ds_read_b128 v[146:149], v158
	ds_read_b128 v[150:153], v158 offset:1024
	ds_read_b128 v[154:157], v158 offset:2048
	ds_read_b128 v[158:161], v158 offset:3072
	s_add_u32 s80, s80, 0x100000
	s_addc_u32 s81, s81, 0
	s_mov_b32 m0, s89
	v_lshl_add_u64 v[226:227], s[80:81], 0, v[170:171]
	ds_read_b128 v[162:165], v192 offset:32768
	ds_read_b128 v[166:169], v192 offset:33792
	ds_read_b128 v[194:197], v192 offset:34816
	ds_read_b128 v[198:201], v192 offset:35840
	ds_read_b128 v[206:209], v192 offset:36864
	ds_read_b128 v[210:213], v192 offset:37888
	ds_read_b128 v[214:217], v192 offset:38912
	ds_read_b128 v[218:221], v192 offset:39936
	global_load_lds_dwordx4 v[226:227], off
	v_lshl_add_u64 v[226:227], s[80:81], 0, v[174:175]
	s_mov_b32 m0, s90
	s_nop 0
	global_load_lds_dwordx4 v[226:227], off
	s_waitcnt vmcnt(8) lgkmcnt(0)
	s_setprio 1
	s_barrier
	v_mfma_f32_16x16x32_bf16 v[142:145], v[114:117], v[162:165], v[142:145]
	v_mfma_f32_16x16x32_bf16 v[138:141], v[122:125], v[162:165], v[138:141]
	v_mfma_f32_16x16x32_bf16 v[110:113], v[114:117], v[194:197], v[110:113]
	v_mfma_f32_16x16x32_bf16 v[106:109], v[122:125], v[194:197], v[106:109]
	v_mfma_f32_16x16x32_bf16 v[98:101], v[114:117], v[206:209], v[98:101]
	v_mfma_f32_16x16x32_bf16 v[90:93], v[122:125], v[206:209], v[90:93]
	v_mfma_f32_16x16x32_bf16 v[82:85], v[114:117], v[214:217], v[82:85]
	v_mfma_f32_16x16x32_bf16 v[74:77], v[122:125], v[214:217], v[74:77]
	v_mfma_f32_16x16x32_bf16 v[142:145], v[118:121], v[166:169], v[142:145]
	v_mfma_f32_16x16x32_bf16 v[138:141], v[126:129], v[166:169], v[138:141]
	v_mfma_f32_16x16x32_bf16 v[110:113], v[118:121], v[198:201], v[110:113]
	v_mfma_f32_16x16x32_bf16 v[106:109], v[126:129], v[198:201], v[106:109]
	v_mfma_f32_16x16x32_bf16 v[98:101], v[118:121], v[210:213], v[98:101]
	v_mfma_f32_16x16x32_bf16 v[90:93], v[126:129], v[210:213], v[90:93]
	v_mfma_f32_16x16x32_bf16 v[82:85], v[118:121], v[218:221], v[82:85]
	v_mfma_f32_16x16x32_bf16 v[74:77], v[126:129], v[218:221], v[74:77]
	v_mfma_f32_16x16x32_bf16 v[134:137], v[146:149], v[162:165], v[134:137]
	v_mfma_f32_16x16x32_bf16 v[130:133], v[154:157], v[162:165], v[130:133]
	v_mfma_f32_16x16x32_bf16 v[102:105], v[146:149], v[194:197], v[102:105]
	v_mfma_f32_16x16x32_bf16 v[94:97], v[154:157], v[194:197], v[94:97]
	v_mfma_f32_16x16x32_bf16 v[86:89], v[146:149], v[206:209], v[86:89]
	v_mfma_f32_16x16x32_bf16 v[78:81], v[154:157], v[206:209], v[78:81]
	v_mfma_f32_16x16x32_bf16 v[70:73], v[146:149], v[214:217], v[70:73]
	v_mfma_f32_16x16x32_bf16 v[66:69], v[154:157], v[214:217], v[66:69]
	v_mfma_f32_16x16x32_bf16 v[134:137], v[150:153], v[166:169], v[134:137]
	v_mfma_f32_16x16x32_bf16 v[130:133], v[158:161], v[166:169], v[130:133]
	v_mfma_f32_16x16x32_bf16 v[102:105], v[150:153], v[198:201], v[102:105]
	v_mfma_f32_16x16x32_bf16 v[94:97], v[158:161], v[198:201], v[94:97]
	v_mfma_f32_16x16x32_bf16 v[86:89], v[150:153], v[210:213], v[86:89]
	v_mfma_f32_16x16x32_bf16 v[78:81], v[158:161], v[210:213], v[78:81]
	v_mfma_f32_16x16x32_bf16 v[70:73], v[150:153], v[218:221], v[70:73]
	v_mfma_f32_16x16x32_bf16 v[66:69], v[158:161], v[218:221], v[66:69]
	s_setprio 0
	s_barrier
	ds_read_b128 v[162:165], v192 offset:49152
	ds_read_b128 v[166:169], v192 offset:50176
	ds_read_b128 v[194:197], v192 offset:51200
	ds_read_b128 v[198:201], v192 offset:52224
	ds_read_b128 v[206:209], v192 offset:53248
	ds_read_b128 v[210:213], v192 offset:54272
	ds_read_b128 v[214:217], v192 offset:55296
	ds_read_b128 v[218:221], v192 offset:56320
	s_add_i32 s63, s63, s86
	s_mov_b32 m0, s63
	v_lshl_add_u64 v[186:187], v[186:187], 0, s[22:23]
	global_load_lds_dwordx4 v[186:187], off
	s_add_i32 m0, s63, 0x2000
	s_add_u32 s78, s78, 0x100080
	v_lshl_add_u64 v[186:187], v[202:203], 0, s[22:23]
	s_addc_u32 s79, s79, 0
	s_add_i32 s63, s83, s86
	global_load_lds_dwordx4 v[186:187], off
	v_lshl_add_u64 v[186:187], s[78:79], 0, v[172:173]
	s_mov_b32 m0, s63
	s_nop 0
	global_load_lds_dwordx4 v[186:187], off
	v_lshl_add_u64 v[186:187], s[78:79], 0, v[176:177]
	s_add_i32 m0, s63, 0x2000
	s_nop 0
	global_load_lds_dwordx4 v[186:187], off
	v_lshl_add_u64 v[186:187], v[222:223], 0, s[22:23]
	s_mov_b32 m0, s95
	s_nop 0
	global_load_lds_dwordx4 v[186:187], off
	v_lshl_add_u64 v[186:187], v[224:225], 0, s[22:23]
	s_mov_b32 m0, s96
	s_nop 0
	global_load_lds_dwordx4 v[186:187], off
	s_waitcnt vmcnt(8) lgkmcnt(0)
	s_setprio 1
	s_barrier
	v_mfma_f32_16x16x32_bf16 v[62:65], v[114:117], v[162:165], v[62:65]
	v_mfma_f32_16x16x32_bf16 v[58:61], v[122:125], v[162:165], v[58:61]
	v_mfma_f32_16x16x32_bf16 v[50:53], v[114:117], v[194:197], v[50:53]
	v_mfma_f32_16x16x32_bf16 v[42:45], v[122:125], v[194:197], v[42:45]
	v_mfma_f32_16x16x32_bf16 v[34:37], v[114:117], v[206:209], v[34:37]
	v_mfma_f32_16x16x32_bf16 v[26:29], v[122:125], v[206:209], v[26:29]
	v_mfma_f32_16x16x32_bf16 v[18:21], v[114:117], v[214:217], v[18:21]
	v_mfma_f32_16x16x32_bf16 v[10:13], v[122:125], v[214:217], v[10:13]
	v_mfma_f32_16x16x32_bf16 v[62:65], v[118:121], v[166:169], v[62:65]
	v_mfma_f32_16x16x32_bf16 v[58:61], v[126:129], v[166:169], v[58:61]
	v_mfma_f32_16x16x32_bf16 v[50:53], v[118:121], v[198:201], v[50:53]
	v_mfma_f32_16x16x32_bf16 v[42:45], v[126:129], v[198:201], v[42:45]
	v_mfma_f32_16x16x32_bf16 v[34:37], v[118:121], v[210:213], v[34:37]
	v_mfma_f32_16x16x32_bf16 v[26:29], v[126:129], v[210:213], v[26:29]
	v_mfma_f32_16x16x32_bf16 v[18:21], v[118:121], v[218:221], v[18:21]
	v_mfma_f32_16x16x32_bf16 v[10:13], v[126:129], v[218:221], v[10:13]
	v_mfma_f32_16x16x32_bf16 v[54:57], v[146:149], v[162:165], v[54:57]
	v_mfma_f32_16x16x32_bf16 v[46:49], v[154:157], v[162:165], v[46:49]
	v_mfma_f32_16x16x32_bf16 v[38:41], v[146:149], v[194:197], v[38:41]
	v_mfma_f32_16x16x32_bf16 v[30:33], v[154:157], v[194:197], v[30:33]
	v_mfma_f32_16x16x32_bf16 v[22:25], v[146:149], v[206:209], v[22:25]
	v_mfma_f32_16x16x32_bf16 v[14:17], v[154:157], v[206:209], v[14:17]
	v_mfma_f32_16x16x32_bf16 v[6:9], v[146:149], v[214:217], v[6:9]
	v_mfma_f32_16x16x32_bf16 v[2:5], v[154:157], v[214:217], v[2:5]
	v_mfma_f32_16x16x32_bf16 v[54:57], v[150:153], v[166:169], v[54:57]
	v_mfma_f32_16x16x32_bf16 v[46:49], v[158:161], v[166:169], v[46:49]
	v_mfma_f32_16x16x32_bf16 v[38:41], v[150:153], v[198:201], v[38:41]
	v_mfma_f32_16x16x32_bf16 v[30:33], v[158:161], v[198:201], v[30:33]
	v_mfma_f32_16x16x32_bf16 v[22:25], v[150:153], v[210:213], v[22:25]
	v_mfma_f32_16x16x32_bf16 v[14:17], v[158:161], v[210:213], v[14:17]
	v_mfma_f32_16x16x32_bf16 v[6:9], v[150:153], v[218:221], v[6:9]
	v_mfma_f32_16x16x32_bf16 v[2:5], v[158:161], v[218:221], v[2:5]
	s_setprio 0
	s_barrier
	s_add_u32 s76, s76, 0x100
	s_addc_u32 s77, s77, 0
	s_add_u32 s47, s47, 0x100
	s_addc_u32 s62, s62, 0
	s_cmp_ge_i32 s82, s7
	s_mov_b32 s63, s82
	s_cbranch_scc0 .LBB0_834
	s_and_b64 vcc, exec, s[26:27]
	s_cbranch_vccz .LBB0_837
	s_barrier

.LBB0_1012:
	s_add_u32 s48, s96, s44
	s_addc_u32 s49, s97, s45
	s_and_b64 s[14:15], s[4:5], exec
	s_cselect_b32 s6, s49, s65
	s_cselect_b32 s14, s48, s64
	s_add_u32 s50, s3, s46
	s_addc_u32 s51, s35, s47
	s_and_b64 s[18:19], s[4:5], exec
	s_cselect_b32 s15, s51, s67
	s_cselect_b32 s17, s50, s66
	s_add_u32 s64, s64, 0x40080
	s_addc_u32 s65, s65, 0
	s_add_u32 s18, s66, 0x100
	s_addc_u32 s19, s67, 0
	s_mov_b32 s24, -2
	s_waitcnt vmcnt(0)
	ds_read_b128 v[130:133], v172
	ds_read_b128 v[134:137], v172 offset:1024
	ds_read_b128 v[138:141], v172 offset:2048
	ds_read_b128 v[142:145], v172 offset:3072
	ds_read_b128 v[164:167], v173
	ds_read_b128 v[176:179], v173 offset:1024
	ds_read_b128 v[180:183], v173 offset:2048
	ds_read_b128 v[184:187], v173 offset:3072
	ds_read_b128 v[188:191], v174
	ds_read_b128 v[192:195], v174 offset:1024
	ds_read_b128 v[196:199], v174 offset:2048
	ds_read_b128 v[200:203], v174 offset:3072
	ds_read_b128 v[206:209], v174 offset:4096
	ds_read_b128 v[210:213], v174 offset:5120
	ds_read_b128 v[214:217], v174 offset:6144
	ds_read_b128 v[218:221], v174 offset:7168
	s_add_u32 s25, s64, 0xfffc0080
	s_addc_u32 s28, s65, -1
	s_cmp_eq_u32 s24, 12
	s_cselect_b32 s69, s6, s28
	s_cselect_b32 s68, s14, s25
	s_cselect_b32 s67, s15, s19
	s_cselect_b32 s66, s17, s18
	s_add_i32 m0, s73, 0xc000
	v_lshl_add_u64 v[168:169], s[64:65], 0, v[156:157]
	global_load_lds_dwordx4 v[168:169], off
	v_lshl_add_u64 v[168:169], s[64:65], 0, v[158:159]
	s_add_i32 m0, s73, 0xe000
	s_nop 0
	global_load_lds_dwordx4 v[168:169], off
	s_waitcnt vmcnt(8) lgkmcnt(0)
	s_setprio 1
	s_barrier
	v_mfma_f32_16x16x32_bf16 v[126:129], v[130:133], v[188:191], 0
	v_mfma_f32_16x16x32_bf16 v[122:125], v[138:141], v[188:191], 0
	v_mfma_f32_16x16x32_bf16 v[110:113], v[130:133], v[196:199], 0
	v_mfma_f32_16x16x32_bf16 v[106:109], v[138:141], v[196:199], 0
	v_mfma_f32_16x16x32_bf16 v[94:97], v[130:133], v[206:209], 0
	v_mfma_f32_16x16x32_bf16 v[90:93], v[138:141], v[206:209], 0
	v_mfma_f32_16x16x32_bf16 v[78:81], v[130:133], v[214:217], 0
	v_mfma_f32_16x16x32_bf16 v[74:77], v[138:141], v[214:217], 0
	v_mfma_f32_16x16x32_bf16 v[126:129], v[134:137], v[192:195], v[126:129]
	v_mfma_f32_16x16x32_bf16 v[122:125], v[142:145], v[192:195], v[122:125]
	v_mfma_f32_16x16x32_bf16 v[110:113], v[134:137], v[200:203], v[110:113]
	v_mfma_f32_16x16x32_bf16 v[106:109], v[142:145], v[200:203], v[106:109]
	v_mfma_f32_16x16x32_bf16 v[94:97], v[134:137], v[210:213], v[94:97]
	v_mfma_f32_16x16x32_bf16 v[90:93], v[142:145], v[210:213], v[90:93]
	v_mfma_f32_16x16x32_bf16 v[78:81], v[134:137], v[218:221], v[78:81]
	v_mfma_f32_16x16x32_bf16 v[74:77], v[142:145], v[218:221], v[74:77]
	v_mfma_f32_16x16x32_bf16 v[118:121], v[164:167], v[188:191], 0
	v_mfma_f32_16x16x32_bf16 v[114:117], v[180:183], v[188:191], 0
	v_mfma_f32_16x16x32_bf16 v[102:105], v[164:167], v[196:199], 0
	v_mfma_f32_16x16x32_bf16 v[98:101], v[180:183], v[196:199], 0
	v_mfma_f32_16x16x32_bf16 v[86:89], v[164:167], v[206:209], 0
	v_mfma_f32_16x16x32_bf16 v[82:85], v[180:183], v[206:209], 0
	v_mfma_f32_16x16x32_bf16 v[70:73], v[164:167], v[214:217], 0
	v_mfma_f32_16x16x32_bf16 v[66:69], v[180:183], v[214:217], 0
	v_mfma_f32_16x16x32_bf16 v[118:121], v[176:179], v[192:195], v[118:121]
	v_mfma_f32_16x16x32_bf16 v[114:117], v[184:187], v[192:195], v[114:117]
	v_mfma_f32_16x16x32_bf16 v[102:105], v[176:179], v[200:203], v[102:105]
	v_mfma_f32_16x16x32_bf16 v[98:101], v[184:187], v[200:203], v[98:101]
	v_mfma_f32_16x16x32_bf16 v[86:89], v[176:179], v[210:213], v[86:89]
	v_mfma_f32_16x16x32_bf16 v[82:85], v[184:187], v[210:213], v[82:85]
	v_mfma_f32_16x16x32_bf16 v[70:73], v[176:179], v[218:221], v[70:73]
	v_mfma_f32_16x16x32_bf16 v[66:69], v[184:187], v[218:221], v[66:69]
	s_setprio 0
	s_barrier
	ds_read_b128 v[188:191], v174 offset:16384
	ds_read_b128 v[192:195], v174 offset:17408
	ds_read_b128 v[196:199], v174 offset:18432
	ds_read_b128 v[200:203], v174 offset:19456
	ds_read_b128 v[206:209], v174 offset:20480
	ds_read_b128 v[210:213], v174 offset:21504
	ds_read_b128 v[214:217], v174 offset:22528
	ds_read_b128 v[218:221], v174 offset:23552
	s_add_i32 s25, s82, s70
	s_mov_b32 m0, s25
	v_lshl_add_u64 v[168:169], s[66:67], 0, v[150:151]
	global_load_lds_dwordx4 v[168:169], off
	s_add_i32 m0, s25, 0x2000
	s_add_u32 s28, s66, 0x40000
	v_lshl_add_u64 v[222:223], s[66:67], 0, v[146:147]
	s_addc_u32 s29, s67, 0
	s_add_i32 s25, s83, s70
	global_load_lds_dwordx4 v[222:223], off
	v_lshl_add_u64 v[224:225], s[28:29], 0, v[150:151]
	s_mov_b32 m0, s25
	v_lshl_add_u64 v[226:227], s[68:69], 0, v[148:149]
	global_load_lds_dwordx4 v[224:225], off
	v_lshl_add_u64 v[224:225], s[28:29], 0, v[146:147]
	s_add_i32 m0, s25, 0x2000
	s_nop 0
	global_load_lds_dwordx4 v[224:225], off
	v_lshl_add_u64 v[224:225], s[68:69], 0, v[152:153]
	s_mov_b32 m0, s73
	s_nop 0
	global_load_lds_dwordx4 v[224:225], off
	s_mov_b32 m0, s74
	s_nop 0
	global_load_lds_dwordx4 v[226:227], off
	s_waitcnt vmcnt(8) lgkmcnt(0)
	s_setprio 1
	s_barrier
	v_mfma_f32_16x16x32_bf16 v[62:65], v[130:133], v[188:191], 0
	v_mfma_f32_16x16x32_bf16 v[58:61], v[138:141], v[188:191], 0
	v_mfma_f32_16x16x32_bf16 v[46:49], v[130:133], v[196:199], 0
	v_mfma_f32_16x16x32_bf16 v[42:45], v[138:141], v[196:199], 0
	v_mfma_f32_16x16x32_bf16 v[30:33], v[130:133], v[206:209], 0
	v_mfma_f32_16x16x32_bf16 v[26:29], v[138:141], v[206:209], 0
	v_mfma_f32_16x16x32_bf16 v[14:17], v[130:133], v[214:217], 0
	v_mfma_f32_16x16x32_bf16 v[10:13], v[138:141], v[214:217], 0
	v_mfma_f32_16x16x32_bf16 v[62:65], v[134:137], v[192:195], v[62:65]
	v_mfma_f32_16x16x32_bf16 v[58:61], v[142:145], v[192:195], v[58:61]
	v_mfma_f32_16x16x32_bf16 v[46:49], v[134:137], v[200:203], v[46:49]
	v_mfma_f32_16x16x32_bf16 v[42:45], v[142:145], v[200:203], v[42:45]
	v_mfma_f32_16x16x32_bf16 v[30:33], v[134:137], v[210:213], v[30:33]
	v_mfma_f32_16x16x32_bf16 v[26:29], v[142:145], v[210:213], v[26:29]
	v_mfma_f32_16x16x32_bf16 v[14:17], v[134:137], v[218:221], v[14:17]
	v_mfma_f32_16x16x32_bf16 v[10:13], v[142:145], v[218:221], v[10:13]
	v_mfma_f32_16x16x32_bf16 v[54:57], v[164:167], v[188:191], 0
	v_mfma_f32_16x16x32_bf16 v[50:53], v[180:183], v[188:191], 0
	v_mfma_f32_16x16x32_bf16 v[38:41], v[164:167], v[196:199], 0
	v_mfma_f32_16x16x32_bf16 v[34:37], v[180:183], v[196:199], 0
	v_mfma_f32_16x16x32_bf16 v[22:25], v[164:167], v[206:209], 0
	v_mfma_f32_16x16x32_bf16 v[18:21], v[180:183], v[206:209], 0
	v_mfma_f32_16x16x32_bf16 v[6:9], v[164:167], v[214:217], 0
	v_mfma_f32_16x16x32_bf16 v[2:5], v[180:183], v[214:217], 0
	v_mfma_f32_16x16x32_bf16 v[54:57], v[176:179], v[192:195], v[54:57]
	v_mfma_f32_16x16x32_bf16 v[50:53], v[184:187], v[192:195], v[50:53]
	v_mfma_f32_16x16x32_bf16 v[38:41], v[176:179], v[200:203], v[38:41]
	v_mfma_f32_16x16x32_bf16 v[34:37], v[184:187], v[200:203], v[34:37]
	v_mfma_f32_16x16x32_bf16 v[22:25], v[176:179], v[210:213], v[22:25]
	v_mfma_f32_16x16x32_bf16 v[18:21], v[184:187], v[210:213], v[18:21]
	v_mfma_f32_16x16x32_bf16 v[6:9], v[176:179], v[218:221], v[6:9]
	v_mfma_f32_16x16x32_bf16 v[2:5], v[184:187], v[218:221], v[2:5]
	s_setprio 0
	s_barrier
	s_add_i32 s25, 0, 0x18000
	s_add_i32 s30, 0, 0x1c000
	v_add_u32_e32 v142, s25, v171
	v_add_u32_e32 v175, s30, v171
	ds_read_b128 v[130:133], v142
	ds_read_b128 v[134:137], v142 offset:1024
	ds_read_b128 v[138:141], v142 offset:2048
	ds_read_b128 v[142:145], v142 offset:3072
	ds_read_b128 v[164:167], v175
	ds_read_b128 v[176:179], v175 offset:1024
	ds_read_b128 v[180:183], v175 offset:2048
	ds_read_b128 v[184:187], v175 offset:3072
	s_add_u32 s28, s68, 0x40000
	s_addc_u32 s29, s69, 0
	s_mov_b32 m0, s75
	v_lshl_add_u64 v[228:229], s[28:29], 0, v[152:153]
	ds_read_b128 v[188:191], v174 offset:32768
	ds_read_b128 v[192:195], v174 offset:33792
	ds_read_b128 v[196:199], v174 offset:34816
	ds_read_b128 v[200:203], v174 offset:35840
	ds_read_b128 v[206:209], v174 offset:36864
	ds_read_b128 v[210:213], v174 offset:37888
	ds_read_b128 v[214:217], v174 offset:38912
	ds_read_b128 v[218:221], v174 offset:39936
	global_load_lds_dwordx4 v[228:229], off
	v_lshl_add_u64 v[228:229], s[28:29], 0, v[148:149]
	s_mov_b32 m0, s76
	s_nop 0
	global_load_lds_dwordx4 v[228:229], off
	s_waitcnt vmcnt(8) lgkmcnt(0)
	s_setprio 1
	s_barrier
	v_mfma_f32_16x16x32_bf16 v[126:129], v[130:133], v[188:191], v[126:129]
	v_mfma_f32_16x16x32_bf16 v[122:125], v[138:141], v[188:191], v[122:125]
	v_mfma_f32_16x16x32_bf16 v[110:113], v[130:133], v[196:199], v[110:113]
	v_mfma_f32_16x16x32_bf16 v[106:109], v[138:141], v[196:199], v[106:109]
	v_mfma_f32_16x16x32_bf16 v[94:97], v[130:133], v[206:209], v[94:97]
	v_mfma_f32_16x16x32_bf16 v[90:93], v[138:141], v[206:209], v[90:93]
	v_mfma_f32_16x16x32_bf16 v[78:81], v[130:133], v[214:217], v[78:81]
	v_mfma_f32_16x16x32_bf16 v[74:77], v[138:141], v[214:217], v[74:77]
	v_mfma_f32_16x16x32_bf16 v[126:129], v[134:137], v[192:195], v[126:129]
	v_mfma_f32_16x16x32_bf16 v[122:125], v[142:145], v[192:195], v[122:125]
	v_mfma_f32_16x16x32_bf16 v[110:113], v[134:137], v[200:203], v[110:113]
	v_mfma_f32_16x16x32_bf16 v[106:109], v[142:145], v[200:203], v[106:109]
	v_mfma_f32_16x16x32_bf16 v[94:97], v[134:137], v[210:213], v[94:97]
	v_mfma_f32_16x16x32_bf16 v[90:93], v[142:145], v[210:213], v[90:93]
	v_mfma_f32_16x16x32_bf16 v[78:81], v[134:137], v[218:221], v[78:81]
	v_mfma_f32_16x16x32_bf16 v[74:77], v[142:145], v[218:221], v[74:77]
	v_mfma_f32_16x16x32_bf16 v[118:121], v[164:167], v[188:191], v[118:121]
	v_mfma_f32_16x16x32_bf16 v[114:117], v[180:183], v[188:191], v[114:117]
	v_mfma_f32_16x16x32_bf16 v[102:105], v[164:167], v[196:199], v[102:105]
	v_mfma_f32_16x16x32_bf16 v[98:101], v[180:183], v[196:199], v[98:101]
	v_mfma_f32_16x16x32_bf16 v[86:89], v[164:167], v[206:209], v[86:89]
	v_mfma_f32_16x16x32_bf16 v[82:85], v[180:183], v[206:209], v[82:85]
	v_mfma_f32_16x16x32_bf16 v[70:73], v[164:167], v[214:217], v[70:73]
	v_mfma_f32_16x16x32_bf16 v[66:69], v[180:183], v[214:217], v[66:69]
	v_mfma_f32_16x16x32_bf16 v[118:121], v[176:179], v[192:195], v[118:121]
	v_mfma_f32_16x16x32_bf16 v[114:117], v[184:187], v[192:195], v[114:117]
	v_mfma_f32_16x16x32_bf16 v[102:105], v[176:179], v[200:203], v[102:105]
	v_mfma_f32_16x16x32_bf16 v[98:101], v[184:187], v[200:203], v[98:101]
	v_mfma_f32_16x16x32_bf16 v[86:89], v[176:179], v[210:213], v[86:89]
	v_mfma_f32_16x16x32_bf16 v[82:85], v[184:187], v[210:213], v[82:85]
	v_mfma_f32_16x16x32_bf16 v[70:73], v[176:179], v[218:221], v[70:73]
	v_mfma_f32_16x16x32_bf16 v[66:69], v[184:187], v[218:221], v[66:69]
	s_setprio 0
	s_barrier
	ds_read_b128 v[188:191], v174 offset:49152
	ds_read_b128 v[192:195], v174 offset:50176
	ds_read_b128 v[196:199], v174 offset:51200
	ds_read_b128 v[200:203], v174 offset:52224
	ds_read_b128 v[206:209], v174 offset:53248
	ds_read_b128 v[210:213], v174 offset:54272
	ds_read_b128 v[214:217], v174 offset:55296
	ds_read_b128 v[218:221], v174 offset:56320
	s_add_i32 s25, s25, s70
	s_mov_b32 m0, s25
	v_lshl_add_u64 v[168:169], v[168:169], 0, s[36:37]
	global_load_lds_dwordx4 v[168:169], off
	s_add_i32 m0, s25, 0x2000
	s_add_u32 s28, s66, 0x40080
	v_lshl_add_u64 v[168:169], v[222:223], 0, s[36:37]
	s_addc_u32 s29, s67, 0
	s_add_i32 s25, s30, s70
	global_load_lds_dwordx4 v[168:169], off
	v_lshl_add_u64 v[168:169], s[28:29], 0, v[150:151]
	s_mov_b32 m0, s25
	s_nop 0
	global_load_lds_dwordx4 v[168:169], off
	v_lshl_add_u64 v[168:169], s[28:29], 0, v[146:147]
	s_add_i32 m0, s25, 0x2000
	s_nop 0
	global_load_lds_dwordx4 v[168:169], off
	v_lshl_add_u64 v[168:169], v[224:225], 0, s[36:37]
	s_mov_b32 m0, s79
	s_nop 0
	global_load_lds_dwordx4 v[168:169], off
	v_lshl_add_u64 v[168:169], v[226:227], 0, s[36:37]
	s_mov_b32 m0, s80
	s_nop 0
	global_load_lds_dwordx4 v[168:169], off
	s_waitcnt vmcnt(8) lgkmcnt(0)
	s_setprio 1
	s_barrier
	v_mfma_f32_16x16x32_bf16 v[62:65], v[130:133], v[188:191], v[62:65]
	v_mfma_f32_16x16x32_bf16 v[58:61], v[138:141], v[188:191], v[58:61]
	v_mfma_f32_16x16x32_bf16 v[46:49], v[130:133], v[196:199], v[46:49]
	v_mfma_f32_16x16x32_bf16 v[42:45], v[138:141], v[196:199], v[42:45]
	v_mfma_f32_16x16x32_bf16 v[30:33], v[130:133], v[206:209], v[30:33]
	v_mfma_f32_16x16x32_bf16 v[26:29], v[138:141], v[206:209], v[26:29]
	v_mfma_f32_16x16x32_bf16 v[14:17], v[130:133], v[214:217], v[14:17]
	v_mfma_f32_16x16x32_bf16 v[10:13], v[138:141], v[214:217], v[10:13]
	v_mfma_f32_16x16x32_bf16 v[62:65], v[134:137], v[192:195], v[62:65]
	v_mfma_f32_16x16x32_bf16 v[58:61], v[142:145], v[192:195], v[58:61]
	v_mfma_f32_16x16x32_bf16 v[46:49], v[134:137], v[200:203], v[46:49]
	v_mfma_f32_16x16x32_bf16 v[42:45], v[142:145], v[200:203], v[42:45]
	v_mfma_f32_16x16x32_bf16 v[30:33], v[134:137], v[210:213], v[30:33]
	v_mfma_f32_16x16x32_bf16 v[26:29], v[142:145], v[210:213], v[26:29]
	v_mfma_f32_16x16x32_bf16 v[14:17], v[134:137], v[218:221], v[14:17]
	v_mfma_f32_16x16x32_bf16 v[10:13], v[142:145], v[218:221], v[10:13]
	v_mfma_f32_16x16x32_bf16 v[54:57], v[164:167], v[188:191], v[54:57]
	v_mfma_f32_16x16x32_bf16 v[50:53], v[180:183], v[188:191], v[50:53]
	v_mfma_f32_16x16x32_bf16 v[38:41], v[164:167], v[196:199], v[38:41]
	v_mfma_f32_16x16x32_bf16 v[34:37], v[180:183], v[196:199], v[34:37]
	v_mfma_f32_16x16x32_bf16 v[22:25], v[164:167], v[206:209], v[22:25]
	v_mfma_f32_16x16x32_bf16 v[18:21], v[180:183], v[206:209], v[18:21]
	v_mfma_f32_16x16x32_bf16 v[6:9], v[164:167], v[214:217], v[6:9]
	v_mfma_f32_16x16x32_bf16 v[2:5], v[180:183], v[214:217], v[2:5]
	v_mfma_f32_16x16x32_bf16 v[54:57], v[176:179], v[192:195], v[54:57]
	v_mfma_f32_16x16x32_bf16 v[50:53], v[184:187], v[192:195], v[50:53]
	v_mfma_f32_16x16x32_bf16 v[38:41], v[176:179], v[200:203], v[38:41]
	v_mfma_f32_16x16x32_bf16 v[34:37], v[184:187], v[200:203], v[34:37]
	v_mfma_f32_16x16x32_bf16 v[22:25], v[176:179], v[210:213], v[22:25]
	v_mfma_f32_16x16x32_bf16 v[18:21], v[184:187], v[210:213], v[18:21]
	v_mfma_f32_16x16x32_bf16 v[6:9], v[176:179], v[218:221], v[6:9]
	v_mfma_f32_16x16x32_bf16 v[2:5], v[184:187], v[218:221], v[2:5]
	s_setprio 0
	s_barrier
	s_add_i32 s24, s24, 2
	s_add_u32 s64, s64, 0x100
	s_addc_u32 s65, s65, 0
	s_add_u32 s18, s18, 0x100
	s_addc_u32 s19, s19, 0
	s_cmp_gt_u32 s24, 13
.LBB0_1013:
	ds_read_b128 v[130:133], v172
	ds_read_b128 v[134:137], v172 offset:1024
	ds_read_b128 v[138:141], v172 offset:2048
	ds_read_b128 v[142:145], v172 offset:3072
	ds_read_b128 v[164:167], v173
	ds_read_b128 v[176:179], v173 offset:1024
	ds_read_b128 v[180:183], v173 offset:2048
	ds_read_b128 v[184:187], v173 offset:3072
	ds_read_b128 v[188:191], v174
	ds_read_b128 v[192:195], v174 offset:1024
	ds_read_b128 v[196:199], v174 offset:2048
	ds_read_b128 v[200:203], v174 offset:3072
	ds_read_b128 v[206:209], v174 offset:4096
	ds_read_b128 v[210:213], v174 offset:5120
	ds_read_b128 v[214:217], v174 offset:6144
	ds_read_b128 v[218:221], v174 offset:7168
	s_add_u32 s25, s64, 0xfffc0080
	s_addc_u32 s28, s65, -1
	s_cmp_eq_u32 s24, 12
	s_cselect_b32 s69, s6, s28
	s_cselect_b32 s68, s14, s25
	s_cselect_b32 s67, s15, s19
	s_cselect_b32 s66, s17, s18
	s_add_i32 m0, s73, 0xc000
	v_lshl_add_u64 v[168:169], s[64:65], 0, v[156:157]
	global_load_lds_dwordx4 v[168:169], off
	v_lshl_add_u64 v[168:169], s[64:65], 0, v[158:159]
	s_add_i32 m0, s73, 0xe000
	s_nop 0
	global_load_lds_dwordx4 v[168:169], off
	s_waitcnt vmcnt(8) lgkmcnt(0)
	s_setprio 1
	s_barrier
	v_mfma_f32_16x16x32_bf16 v[126:129], v[130:133], v[188:191], v[126:129]
	v_mfma_f32_16x16x32_bf16 v[122:125], v[138:141], v[188:191], v[122:125]
	v_mfma_f32_16x16x32_bf16 v[110:113], v[130:133], v[196:199], v[110:113]
	v_mfma_f32_16x16x32_bf16 v[106:109], v[138:141], v[196:199], v[106:109]
	v_mfma_f32_16x16x32_bf16 v[94:97], v[130:133], v[206:209], v[94:97]
	v_mfma_f32_16x16x32_bf16 v[90:93], v[138:141], v[206:209], v[90:93]
	v_mfma_f32_16x16x32_bf16 v[78:81], v[130:133], v[214:217], v[78:81]
	v_mfma_f32_16x16x32_bf16 v[74:77], v[138:141], v[214:217], v[74:77]
	v_mfma_f32_16x16x32_bf16 v[126:129], v[134:137], v[192:195], v[126:129]
	v_mfma_f32_16x16x32_bf16 v[122:125], v[142:145], v[192:195], v[122:125]
	v_mfma_f32_16x16x32_bf16 v[110:113], v[134:137], v[200:203], v[110:113]
	v_mfma_f32_16x16x32_bf16 v[106:109], v[142:145], v[200:203], v[106:109]
	v_mfma_f32_16x16x32_bf16 v[94:97], v[134:137], v[210:213], v[94:97]
	v_mfma_f32_16x16x32_bf16 v[90:93], v[142:145], v[210:213], v[90:93]
	v_mfma_f32_16x16x32_bf16 v[78:81], v[134:137], v[218:221], v[78:81]
	v_mfma_f32_16x16x32_bf16 v[74:77], v[142:145], v[218:221], v[74:77]
	v_mfma_f32_16x16x32_bf16 v[118:121], v[164:167], v[188:191], v[118:121]
	v_mfma_f32_16x16x32_bf16 v[114:117], v[180:183], v[188:191], v[114:117]
	v_mfma_f32_16x16x32_bf16 v[102:105], v[164:167], v[196:199], v[102:105]
	v_mfma_f32_16x16x32_bf16 v[98:101], v[180:183], v[196:199], v[98:101]
	v_mfma_f32_16x16x32_bf16 v[86:89], v[164:167], v[206:209], v[86:89]
	v_mfma_f32_16x16x32_bf16 v[82:85], v[180:183], v[206:209], v[82:85]
	v_mfma_f32_16x16x32_bf16 v[70:73], v[164:167], v[214:217], v[70:73]
	v_mfma_f32_16x16x32_bf16 v[66:69], v[180:183], v[214:217], v[66:69]
	v_mfma_f32_16x16x32_bf16 v[118:121], v[176:179], v[192:195], v[118:121]
	v_mfma_f32_16x16x32_bf16 v[114:117], v[184:187], v[192:195], v[114:117]
	v_mfma_f32_16x16x32_bf16 v[102:105], v[176:179], v[200:203], v[102:105]
	v_mfma_f32_16x16x32_bf16 v[98:101], v[184:187], v[200:203], v[98:101]
	v_mfma_f32_16x16x32_bf16 v[86:89], v[176:179], v[210:213], v[86:89]
	v_mfma_f32_16x16x32_bf16 v[82:85], v[184:187], v[210:213], v[82:85]
	v_mfma_f32_16x16x32_bf16 v[70:73], v[176:179], v[218:221], v[70:73]
	v_mfma_f32_16x16x32_bf16 v[66:69], v[184:187], v[218:221], v[66:69]
	s_setprio 0
	s_barrier
	ds_read_b128 v[188:191], v174 offset:16384
	ds_read_b128 v[192:195], v174 offset:17408
	ds_read_b128 v[196:199], v174 offset:18432
	ds_read_b128 v[200:203], v174 offset:19456
	ds_read_b128 v[206:209], v174 offset:20480
	ds_read_b128 v[210:213], v174 offset:21504
	ds_read_b128 v[214:217], v174 offset:22528
	ds_read_b128 v[218:221], v174 offset:23552
	s_add_i32 s25, s82, s70
	s_mov_b32 m0, s25
	v_lshl_add_u64 v[168:169], s[66:67], 0, v[150:151]
	global_load_lds_dwordx4 v[168:169], off
	s_add_i32 m0, s25, 0x2000
	s_add_u32 s28, s66, 0x40000
	v_lshl_add_u64 v[222:223], s[66:67], 0, v[146:147]
	s_addc_u32 s29, s67, 0
	s_add_i32 s25, s83, s70
	global_load_lds_dwordx4 v[222:223], off
	v_lshl_add_u64 v[224:225], s[28:29], 0, v[150:151]
	s_mov_b32 m0, s25
	v_lshl_add_u64 v[226:227], s[68:69], 0, v[148:149]
	global_load_lds_dwordx4 v[224:225], off
	v_lshl_add_u64 v[224:225], s[28:29], 0, v[146:147]
	s_add_i32 m0, s25, 0x2000
	s_nop 0
	global_load_lds_dwordx4 v[224:225], off
	v_lshl_add_u64 v[224:225], s[68:69], 0, v[152:153]
	s_mov_b32 m0, s73
	s_nop 0
	global_load_lds_dwordx4 v[224:225], off
	s_mov_b32 m0, s74
	s_nop 0
	global_load_lds_dwordx4 v[226:227], off
	s_waitcnt vmcnt(8) lgkmcnt(0)
	s_setprio 1
	s_barrier
	v_mfma_f32_16x16x32_bf16 v[62:65], v[130:133], v[188:191], v[62:65]
	v_mfma_f32_16x16x32_bf16 v[58:61], v[138:141], v[188:191], v[58:61]
	v_mfma_f32_16x16x32_bf16 v[46:49], v[130:133], v[196:199], v[46:49]
	v_mfma_f32_16x16x32_bf16 v[42:45], v[138:141], v[196:199], v[42:45]
	v_mfma_f32_16x16x32_bf16 v[30:33], v[130:133], v[206:209], v[30:33]
	v_mfma_f32_16x16x32_bf16 v[26:29], v[138:141], v[206:209], v[26:29]
	v_mfma_f32_16x16x32_bf16 v[14:17], v[130:133], v[214:217], v[14:17]
	v_mfma_f32_16x16x32_bf16 v[10:13], v[138:141], v[214:217], v[10:13]
	v_mfma_f32_16x16x32_bf16 v[62:65], v[134:137], v[192:195], v[62:65]
	v_mfma_f32_16x16x32_bf16 v[58:61], v[142:145], v[192:195], v[58:61]
	v_mfma_f32_16x16x32_bf16 v[46:49], v[134:137], v[200:203], v[46:49]
	v_mfma_f32_16x16x32_bf16 v[42:45], v[142:145], v[200:203], v[42:45]
	v_mfma_f32_16x16x32_bf16 v[30:33], v[134:137], v[210:213], v[30:33]
	v_mfma_f32_16x16x32_bf16 v[26:29], v[142:145], v[210:213], v[26:29]
	v_mfma_f32_16x16x32_bf16 v[14:17], v[134:137], v[218:221], v[14:17]
	v_mfma_f32_16x16x32_bf16 v[10:13], v[142:145], v[218:221], v[10:13]
	v_mfma_f32_16x16x32_bf16 v[54:57], v[164:167], v[188:191], v[54:57]
	v_mfma_f32_16x16x32_bf16 v[50:53], v[180:183], v[188:191], v[50:53]
	v_mfma_f32_16x16x32_bf16 v[38:41], v[164:167], v[196:199], v[38:41]
	v_mfma_f32_16x16x32_bf16 v[34:37], v[180:183], v[196:199], v[34:37]
	v_mfma_f32_16x16x32_bf16 v[22:25], v[164:167], v[206:209], v[22:25]
	v_mfma_f32_16x16x32_bf16 v[18:21], v[180:183], v[206:209], v[18:21]
	v_mfma_f32_16x16x32_bf16 v[6:9], v[164:167], v[214:217], v[6:9]
	v_mfma_f32_16x16x32_bf16 v[2:5], v[180:183], v[214:217], v[2:5]
	v_mfma_f32_16x16x32_bf16 v[54:57], v[176:179], v[192:195], v[54:57]
	v_mfma_f32_16x16x32_bf16 v[50:53], v[184:187], v[192:195], v[50:53]
	v_mfma_f32_16x16x32_bf16 v[38:41], v[176:179], v[200:203], v[38:41]
	v_mfma_f32_16x16x32_bf16 v[34:37], v[184:187], v[200:203], v[34:37]
	v_mfma_f32_16x16x32_bf16 v[22:25], v[176:179], v[210:213], v[22:25]
	v_mfma_f32_16x16x32_bf16 v[18:21], v[184:187], v[210:213], v[18:21]
	v_mfma_f32_16x16x32_bf16 v[6:9], v[176:179], v[218:221], v[6:9]
	v_mfma_f32_16x16x32_bf16 v[2:5], v[184:187], v[218:221], v[2:5]
	s_setprio 0
	s_barrier
	s_add_i32 s25, 0, 0x18000
	s_add_i32 s30, 0, 0x1c000
	v_add_u32_e32 v142, s25, v171
	v_add_u32_e32 v175, s30, v171
	ds_read_b128 v[130:133], v142
	ds_read_b128 v[134:137], v142 offset:1024
	ds_read_b128 v[138:141], v142 offset:2048
	ds_read_b128 v[142:145], v142 offset:3072
	ds_read_b128 v[164:167], v175
	ds_read_b128 v[176:179], v175 offset:1024
	ds_read_b128 v[180:183], v175 offset:2048
	ds_read_b128 v[184:187], v175 offset:3072
	s_add_u32 s28, s68, 0x40000
	s_addc_u32 s29, s69, 0
	s_mov_b32 m0, s75
	v_lshl_add_u64 v[228:229], s[28:29], 0, v[152:153]
	ds_read_b128 v[188:191], v174 offset:32768
	ds_read_b128 v[192:195], v174 offset:33792
	ds_read_b128 v[196:199], v174 offset:34816
	ds_read_b128 v[200:203], v174 offset:35840
	ds_read_b128 v[206:209], v174 offset:36864
	ds_read_b128 v[210:213], v174 offset:37888
	ds_read_b128 v[214:217], v174 offset:38912
	ds_read_b128 v[218:221], v174 offset:39936
	global_load_lds_dwordx4 v[228:229], off
	v_lshl_add_u64 v[228:229], s[28:29], 0, v[148:149]
	s_mov_b32 m0, s76
	s_nop 0
	global_load_lds_dwordx4 v[228:229], off
	s_waitcnt vmcnt(8) lgkmcnt(0)
	s_setprio 1
	s_barrier
	v_mfma_f32_16x16x32_bf16 v[126:129], v[130:133], v[188:191], v[126:129]
	v_mfma_f32_16x16x32_bf16 v[122:125], v[138:141], v[188:191], v[122:125]
	v_mfma_f32_16x16x32_bf16 v[110:113], v[130:133], v[196:199], v[110:113]
	v_mfma_f32_16x16x32_bf16 v[106:109], v[138:141], v[196:199], v[106:109]
	v_mfma_f32_16x16x32_bf16 v[94:97], v[130:133], v[206:209], v[94:97]
	v_mfma_f32_16x16x32_bf16 v[90:93], v[138:141], v[206:209], v[90:93]
	v_mfma_f32_16x16x32_bf16 v[78:81], v[130:133], v[214:217], v[78:81]
	v_mfma_f32_16x16x32_bf16 v[74:77], v[138:141], v[214:217], v[74:77]
	v_mfma_f32_16x16x32_bf16 v[126:129], v[134:137], v[192:195], v[126:129]
	v_mfma_f32_16x16x32_bf16 v[122:125], v[142:145], v[192:195], v[122:125]
	v_mfma_f32_16x16x32_bf16 v[110:113], v[134:137], v[200:203], v[110:113]
	v_mfma_f32_16x16x32_bf16 v[106:109], v[142:145], v[200:203], v[106:109]
	v_mfma_f32_16x16x32_bf16 v[94:97], v[134:137], v[210:213], v[94:97]
	v_mfma_f32_16x16x32_bf16 v[90:93], v[142:145], v[210:213], v[90:93]
	v_mfma_f32_16x16x32_bf16 v[78:81], v[134:137], v[218:221], v[78:81]
	v_mfma_f32_16x16x32_bf16 v[74:77], v[142:145], v[218:221], v[74:77]
	v_mfma_f32_16x16x32_bf16 v[118:121], v[164:167], v[188:191], v[118:121]
	v_mfma_f32_16x16x32_bf16 v[114:117], v[180:183], v[188:191], v[114:117]
	v_mfma_f32_16x16x32_bf16 v[102:105], v[164:167], v[196:199], v[102:105]
	v_mfma_f32_16x16x32_bf16 v[98:101], v[180:183], v[196:199], v[98:101]
	v_mfma_f32_16x16x32_bf16 v[86:89], v[164:167], v[206:209], v[86:89]
	v_mfma_f32_16x16x32_bf16 v[82:85], v[180:183], v[206:209], v[82:85]
	v_mfma_f32_16x16x32_bf16 v[70:73], v[164:167], v[214:217], v[70:73]
	v_mfma_f32_16x16x32_bf16 v[66:69], v[180:183], v[214:217], v[66:69]
	v_mfma_f32_16x16x32_bf16 v[118:121], v[176:179], v[192:195], v[118:121]
	v_mfma_f32_16x16x32_bf16 v[114:117], v[184:187], v[192:195], v[114:117]
	v_mfma_f32_16x16x32_bf16 v[102:105], v[176:179], v[200:203], v[102:105]
	v_mfma_f32_16x16x32_bf16 v[98:101], v[184:187], v[200:203], v[98:101]
	v_mfma_f32_16x16x32_bf16 v[86:89], v[176:179], v[210:213], v[86:89]
	v_mfma_f32_16x16x32_bf16 v[82:85], v[184:187], v[210:213], v[82:85]
	v_mfma_f32_16x16x32_bf16 v[70:73], v[176:179], v[218:221], v[70:73]
	v_mfma_f32_16x16x32_bf16 v[66:69], v[184:187], v[218:221], v[66:69]
	s_setprio 0
	s_barrier
	ds_read_b128 v[188:191], v174 offset:49152
	ds_read_b128 v[192:195], v174 offset:50176
	ds_read_b128 v[196:199], v174 offset:51200
	ds_read_b128 v[200:203], v174 offset:52224
	ds_read_b128 v[206:209], v174 offset:53248
	ds_read_b128 v[210:213], v174 offset:54272
	ds_read_b128 v[214:217], v174 offset:55296
	ds_read_b128 v[218:221], v174 offset:56320
	s_add_i32 s25, s25, s70
	s_mov_b32 m0, s25
	v_lshl_add_u64 v[168:169], v[168:169], 0, s[36:37]
	global_load_lds_dwordx4 v[168:169], off
	s_add_i32 m0, s25, 0x2000
	s_add_u32 s28, s66, 0x40080
	v_lshl_add_u64 v[168:169], v[222:223], 0, s[36:37]
	s_addc_u32 s29, s67, 0
	s_add_i32 s25, s30, s70
	global_load_lds_dwordx4 v[168:169], off
	v_lshl_add_u64 v[168:169], s[28:29], 0, v[150:151]
	s_mov_b32 m0, s25
	s_nop 0
	global_load_lds_dwordx4 v[168:169], off
	v_lshl_add_u64 v[168:169], s[28:29], 0, v[146:147]
	s_add_i32 m0, s25, 0x2000
	s_nop 0
	global_load_lds_dwordx4 v[168:169], off
	v_lshl_add_u64 v[168:169], v[224:225], 0, s[36:37]
	s_mov_b32 m0, s79
	s_nop 0
	global_load_lds_dwordx4 v[168:169], off
	v_lshl_add_u64 v[168:169], v[226:227], 0, s[36:37]
	s_mov_b32 m0, s80
	s_nop 0
	global_load_lds_dwordx4 v[168:169], off
	s_waitcnt vmcnt(8) lgkmcnt(0)
	s_setprio 1
	s_barrier
	v_mfma_f32_16x16x32_bf16 v[62:65], v[130:133], v[188:191], v[62:65]
	v_mfma_f32_16x16x32_bf16 v[58:61], v[138:141], v[188:191], v[58:61]
	v_mfma_f32_16x16x32_bf16 v[46:49], v[130:133], v[196:199], v[46:49]
	v_mfma_f32_16x16x32_bf16 v[42:45], v[138:141], v[196:199], v[42:45]
	v_mfma_f32_16x16x32_bf16 v[30:33], v[130:133], v[206:209], v[30:33]
	v_mfma_f32_16x16x32_bf16 v[26:29], v[138:141], v[206:209], v[26:29]
	v_mfma_f32_16x16x32_bf16 v[14:17], v[130:133], v[214:217], v[14:17]
	v_mfma_f32_16x16x32_bf16 v[10:13], v[138:141], v[214:217], v[10:13]
	v_mfma_f32_16x16x32_bf16 v[62:65], v[134:137], v[192:195], v[62:65]
	v_mfma_f32_16x16x32_bf16 v[58:61], v[142:145], v[192:195], v[58:61]
	v_mfma_f32_16x16x32_bf16 v[46:49], v[134:137], v[200:203], v[46:49]
	v_mfma_f32_16x16x32_bf16 v[42:45], v[142:145], v[200:203], v[42:45]
	v_mfma_f32_16x16x32_bf16 v[30:33], v[134:137], v[210:213], v[30:33]
	v_mfma_f32_16x16x32_bf16 v[26:29], v[142:145], v[210:213], v[26:29]
	v_mfma_f32_16x16x32_bf16 v[14:17], v[134:137], v[218:221], v[14:17]
	v_mfma_f32_16x16x32_bf16 v[10:13], v[142:145], v[218:221], v[10:13]
	v_mfma_f32_16x16x32_bf16 v[54:57], v[164:167], v[188:191], v[54:57]
	v_mfma_f32_16x16x32_bf16 v[50:53], v[180:183], v[188:191], v[50:53]
	v_mfma_f32_16x16x32_bf16 v[38:41], v[164:167], v[196:199], v[38:41]
	v_mfma_f32_16x16x32_bf16 v[34:37], v[180:183], v[196:199], v[34:37]
	v_mfma_f32_16x16x32_bf16 v[22:25], v[164:167], v[206:209], v[22:25]
	v_mfma_f32_16x16x32_bf16 v[18:21], v[180:183], v[206:209], v[18:21]
	v_mfma_f32_16x16x32_bf16 v[6:9], v[164:167], v[214:217], v[6:9]
	v_mfma_f32_16x16x32_bf16 v[2:5], v[180:183], v[214:217], v[2:5]
	v_mfma_f32_16x16x32_bf16 v[54:57], v[176:179], v[192:195], v[54:57]
	v_mfma_f32_16x16x32_bf16 v[50:53], v[184:187], v[192:195], v[50:53]
	v_mfma_f32_16x16x32_bf16 v[38:41], v[176:179], v[200:203], v[38:41]
	v_mfma_f32_16x16x32_bf16 v[34:37], v[184:187], v[200:203], v[34:37]
	v_mfma_f32_16x16x32_bf16 v[22:25], v[176:179], v[210:213], v[22:25]
	v_mfma_f32_16x16x32_bf16 v[18:21], v[184:187], v[210:213], v[18:21]
	v_mfma_f32_16x16x32_bf16 v[6:9], v[176:179], v[218:221], v[6:9]
	v_mfma_f32_16x16x32_bf16 v[2:5], v[184:187], v[218:221], v[2:5]
	s_setprio 0
	s_barrier
	s_add_i32 s24, s24, 2
	s_add_u32 s64, s64, 0x100
	s_addc_u32 s65, s65, 0
	s_add_u32 s18, s18, 0x100
	s_addc_u32 s19, s19, 0
	s_cmp_gt_u32 s24, 13
	s_cbranch_scc0 .LBB0_1013
	s_and_b64 vcc, exec, s[38:39]
	s_cbranch_vccz .LBB0_1016
	s_barrier

.LBB0_1427:
	s_add_u32 s90, s35, s86
	s_addc_u32 s91, s64, s87
	s_and_b64 s[14:15], s[88:89], exec
	s_cselect_b32 s14, s91, s11
	s_cselect_b32 s15, s90, s10
	s_add_u32 s92, s65, s74
	s_addc_u32 s93, s68, s75
	s_and_b64 s[66:67], s[88:89], exec
	s_cselect_b32 s51, s93, s95
	s_cselect_b32 s84, s92, s94
	s_add_i32 s85, s18, -2
	s_add_u32 s10, s10, 0x40080
	s_addc_u32 s11, s11, 0
	s_add_u32 vcc_lo, s94, 0x100
	s_addc_u32 vcc_hi, s95, 0
	s_mov_b32 s94, 0
	s_waitcnt vmcnt(0)
	s_add_i32 s66, s94, 2
	s_add_u32 s67, s10, 0xfffc0080
	s_addc_u32 s72, s11, -1
	s_cmp_eq_u32 s85, s94
	s_cselect_b32 s97, s14, s72
	s_cselect_b32 s96, s15, s67
	s_cselect_b32 s95, s51, vcc_hi
	s_cselect_b32 s94, s84, vcc_lo
	s_add_i32 s67, 0, 0x10000
	s_add_i32 s62, 0, 0x14000
	v_add_u32_e32 v126, s67, v199
	v_add_u32_e32 v158, s62, v199
	ds_read_b128 v[114:117], v126
	ds_read_b128 v[118:121], v126 offset:1024
	ds_read_b128 v[122:125], v126 offset:2048
	ds_read_b128 v[126:129], v126 offset:3072
	ds_read_b128 v[146:149], v158
	ds_read_b128 v[150:153], v158 offset:1024
	ds_read_b128 v[154:157], v158 offset:2048
	ds_read_b128 v[158:161], v158 offset:3072
	v_lshl_add_u64 v[202:203], s[10:11], 0, v[196:197]
	s_add_i32 m0, s28, 0xc000
	ds_read_b128 v[162:165], v214
	ds_read_b128 v[166:169], v214 offset:1024
	ds_read_b128 v[216:219], v214 offset:2048
	ds_read_b128 v[220:223], v214 offset:3072
	ds_read_b128 v[224:227], v214 offset:4096
	ds_read_b128 v[228:231], v214 offset:5120
	ds_read_b128 v[232:235], v214 offset:6144
	ds_read_b128 v[236:239], v214 offset:7168
	global_load_lds_dwordx4 v[202:203], off
	v_lshl_add_u64 v[202:203], s[10:11], 0, v[176:177]
	s_add_i32 m0, s28, 0xe000
	s_nop 0
	global_load_lds_dwordx4 v[202:203], off
	s_waitcnt vmcnt(8) lgkmcnt(0)
	s_setprio 1
	s_barrier
	v_mfma_f32_16x16x32_bf16 v[142:145], v[114:117], v[162:165], 0
	v_mfma_f32_16x16x32_bf16 v[138:141], v[122:125], v[162:165], 0
	v_mfma_f32_16x16x32_bf16 v[110:113], v[114:117], v[216:219], 0
	v_mfma_f32_16x16x32_bf16 v[106:109], v[122:125], v[216:219], 0
	v_mfma_f32_16x16x32_bf16 v[98:101], v[114:117], v[224:227], 0
	v_mfma_f32_16x16x32_bf16 v[90:93], v[122:125], v[224:227], 0
	v_mfma_f32_16x16x32_bf16 v[82:85], v[114:117], v[232:235], 0
	v_mfma_f32_16x16x32_bf16 v[74:77], v[122:125], v[232:235], 0
	v_mfma_f32_16x16x32_bf16 v[142:145], v[118:121], v[166:169], v[142:145]
	v_mfma_f32_16x16x32_bf16 v[138:141], v[126:129], v[166:169], v[138:141]
	v_mfma_f32_16x16x32_bf16 v[110:113], v[118:121], v[220:223], v[110:113]
	v_mfma_f32_16x16x32_bf16 v[106:109], v[126:129], v[220:223], v[106:109]
	v_mfma_f32_16x16x32_bf16 v[98:101], v[118:121], v[228:231], v[98:101]
	v_mfma_f32_16x16x32_bf16 v[90:93], v[126:129], v[228:231], v[90:93]
	v_mfma_f32_16x16x32_bf16 v[82:85], v[118:121], v[236:239], v[82:85]
	v_mfma_f32_16x16x32_bf16 v[74:77], v[126:129], v[236:239], v[74:77]
	v_mfma_f32_16x16x32_bf16 v[134:137], v[146:149], v[162:165], 0
	v_mfma_f32_16x16x32_bf16 v[130:133], v[154:157], v[162:165], 0
	v_mfma_f32_16x16x32_bf16 v[102:105], v[146:149], v[216:219], 0
	v_mfma_f32_16x16x32_bf16 v[94:97], v[154:157], v[216:219], 0
	v_mfma_f32_16x16x32_bf16 v[86:89], v[146:149], v[224:227], 0
	v_mfma_f32_16x16x32_bf16 v[78:81], v[154:157], v[224:227], 0
	v_mfma_f32_16x16x32_bf16 v[70:73], v[146:149], v[232:235], 0
	v_mfma_f32_16x16x32_bf16 v[66:69], v[154:157], v[232:235], 0
	v_mfma_f32_16x16x32_bf16 v[134:137], v[150:153], v[166:169], v[134:137]
	v_mfma_f32_16x16x32_bf16 v[130:133], v[158:161], v[166:169], v[130:133]
	v_mfma_f32_16x16x32_bf16 v[102:105], v[150:153], v[220:223], v[102:105]
	v_mfma_f32_16x16x32_bf16 v[94:97], v[158:161], v[220:223], v[94:97]
	v_mfma_f32_16x16x32_bf16 v[86:89], v[150:153], v[228:231], v[86:89]
	v_mfma_f32_16x16x32_bf16 v[78:81], v[158:161], v[228:231], v[78:81]
	v_mfma_f32_16x16x32_bf16 v[70:73], v[150:153], v[236:239], v[70:73]
	v_mfma_f32_16x16x32_bf16 v[66:69], v[158:161], v[236:239], v[66:69]
	s_setprio 0
	s_barrier
	ds_read_b128 v[162:165], v214 offset:16384
	ds_read_b128 v[166:169], v214 offset:17408
	ds_read_b128 v[216:219], v214 offset:18432
	ds_read_b128 v[220:223], v214 offset:19456
	ds_read_b128 v[224:227], v214 offset:20480
	ds_read_b128 v[228:231], v214 offset:21504
	ds_read_b128 v[232:235], v214 offset:22528
	ds_read_b128 v[236:239], v214 offset:23552
	s_add_i32 s63, s67, s17
	s_mov_b32 m0, s63
	v_lshl_add_u64 v[202:203], s[94:95], 0, v[174:175]
	global_load_lds_dwordx4 v[202:203], off
	s_add_i32 m0, s63, 0x2000
	s_add_u32 s72, s94, 0x40000
	v_lshl_add_u64 v[240:241], s[94:95], 0, v[178:179]
	s_addc_u32 s73, s95, 0
	s_add_i32 s62, s62, s17
	global_load_lds_dwordx4 v[240:241], off
	v_lshl_add_u64 v[242:243], s[72:73], 0, v[174:175]
	s_mov_b32 m0, s62
	v_lshl_add_u64 v[244:245], s[96:97], 0, v[176:177]
	global_load_lds_dwordx4 v[242:243], off
	v_lshl_add_u64 v[242:243], s[72:73], 0, v[178:179]
	s_add_i32 m0, s62, 0x2000
	s_nop 0
	global_load_lds_dwordx4 v[242:243], off
	v_lshl_add_u64 v[242:243], s[96:97], 0, v[172:173]
	s_mov_b32 m0, s28
	s_nop 0
	global_load_lds_dwordx4 v[242:243], off
	s_mov_b32 m0, s29
	s_nop 0
	global_load_lds_dwordx4 v[244:245], off
	s_waitcnt vmcnt(8) lgkmcnt(0)
	s_setprio 1
	s_barrier
	v_mfma_f32_16x16x32_bf16 v[62:65], v[114:117], v[162:165], 0
	v_mfma_f32_16x16x32_bf16 v[58:61], v[122:125], v[162:165], 0
	v_mfma_f32_16x16x32_bf16 v[50:53], v[114:117], v[216:219], 0
	v_mfma_f32_16x16x32_bf16 v[42:45], v[122:125], v[216:219], 0
	v_mfma_f32_16x16x32_bf16 v[34:37], v[114:117], v[224:227], 0
	v_mfma_f32_16x16x32_bf16 v[26:29], v[122:125], v[224:227], 0
	v_mfma_f32_16x16x32_bf16 v[18:21], v[114:117], v[232:235], 0
	v_mfma_f32_16x16x32_bf16 v[10:13], v[122:125], v[232:235], 0
	v_mfma_f32_16x16x32_bf16 v[62:65], v[118:121], v[166:169], v[62:65]
	v_mfma_f32_16x16x32_bf16 v[58:61], v[126:129], v[166:169], v[58:61]
	v_mfma_f32_16x16x32_bf16 v[50:53], v[118:121], v[220:223], v[50:53]
	v_mfma_f32_16x16x32_bf16 v[42:45], v[126:129], v[220:223], v[42:45]
	v_mfma_f32_16x16x32_bf16 v[34:37], v[118:121], v[228:231], v[34:37]
	v_mfma_f32_16x16x32_bf16 v[26:29], v[126:129], v[228:231], v[26:29]
	v_mfma_f32_16x16x32_bf16 v[18:21], v[118:121], v[236:239], v[18:21]
	v_mfma_f32_16x16x32_bf16 v[10:13], v[126:129], v[236:239], v[10:13]
	v_mfma_f32_16x16x32_bf16 v[54:57], v[146:149], v[162:165], 0
	v_mfma_f32_16x16x32_bf16 v[46:49], v[154:157], v[162:165], 0
	v_mfma_f32_16x16x32_bf16 v[38:41], v[146:149], v[216:219], 0
	v_mfma_f32_16x16x32_bf16 v[30:33], v[154:157], v[216:219], 0
	v_mfma_f32_16x16x32_bf16 v[22:25], v[146:149], v[224:227], 0
	v_mfma_f32_16x16x32_bf16 v[14:17], v[154:157], v[224:227], 0
	v_mfma_f32_16x16x32_bf16 v[6:9], v[146:149], v[232:235], 0
	v_mfma_f32_16x16x32_bf16 v[2:5], v[154:157], v[232:235], 0
	v_mfma_f32_16x16x32_bf16 v[54:57], v[150:153], v[166:169], v[54:57]
	v_mfma_f32_16x16x32_bf16 v[46:49], v[158:161], v[166:169], v[46:49]
	v_mfma_f32_16x16x32_bf16 v[38:41], v[150:153], v[220:223], v[38:41]
	v_mfma_f32_16x16x32_bf16 v[30:33], v[158:161], v[220:223], v[30:33]
	v_mfma_f32_16x16x32_bf16 v[22:25], v[150:153], v[228:231], v[22:25]
	v_mfma_f32_16x16x32_bf16 v[14:17], v[158:161], v[228:231], v[14:17]
	v_mfma_f32_16x16x32_bf16 v[6:9], v[150:153], v[236:239], v[6:9]
	v_mfma_f32_16x16x32_bf16 v[2:5], v[158:161], v[236:239], v[2:5]
	s_setprio 0
	s_barrier
	s_add_i32 s62, 0, 0x18000
	s_add_i32 s63, 0, 0x1c000
	v_add_u32_e32 v126, s62, v199
	v_add_u32_e32 v158, s63, v199
	ds_read_b128 v[114:117], v126
	ds_read_b128 v[118:121], v126 offset:1024
	ds_read_b128 v[122:125], v126 offset:2048
	ds_read_b128 v[126:129], v126 offset:3072
	ds_read_b128 v[146:149], v158
	ds_read_b128 v[150:153], v158 offset:1024
	ds_read_b128 v[154:157], v158 offset:2048
	ds_read_b128 v[158:161], v158 offset:3072
	s_add_u32 s72, s96, 0x40000
	s_addc_u32 s73, s97, 0
	s_mov_b32 m0, s30
	v_lshl_add_u64 v[246:247], s[72:73], 0, v[172:173]
	ds_read_b128 v[162:165], v214 offset:32768
	ds_read_b128 v[166:169], v214 offset:33792
	ds_read_b128 v[216:219], v214 offset:34816
	ds_read_b128 v[220:223], v214 offset:35840
	ds_read_b128 v[224:227], v214 offset:36864
	ds_read_b128 v[228:231], v214 offset:37888
	ds_read_b128 v[232:235], v214 offset:38912
	ds_read_b128 v[236:239], v214 offset:39936
	global_load_lds_dwordx4 v[246:247], off
	v_lshl_add_u64 v[246:247], s[72:73], 0, v[176:177]
	s_mov_b32 m0, s31
	s_nop 0
	global_load_lds_dwordx4 v[246:247], off
	s_waitcnt vmcnt(8) lgkmcnt(0)
	s_setprio 1
	s_barrier
	v_mfma_f32_16x16x32_bf16 v[142:145], v[114:117], v[162:165], v[142:145]
	v_mfma_f32_16x16x32_bf16 v[138:141], v[122:125], v[162:165], v[138:141]
	v_mfma_f32_16x16x32_bf16 v[110:113], v[114:117], v[216:219], v[110:113]
	v_mfma_f32_16x16x32_bf16 v[106:109], v[122:125], v[216:219], v[106:109]
	v_mfma_f32_16x16x32_bf16 v[98:101], v[114:117], v[224:227], v[98:101]
	v_mfma_f32_16x16x32_bf16 v[90:93], v[122:125], v[224:227], v[90:93]
	v_mfma_f32_16x16x32_bf16 v[82:85], v[114:117], v[232:235], v[82:85]
	v_mfma_f32_16x16x32_bf16 v[74:77], v[122:125], v[232:235], v[74:77]
	v_mfma_f32_16x16x32_bf16 v[142:145], v[118:121], v[166:169], v[142:145]
	v_mfma_f32_16x16x32_bf16 v[138:141], v[126:129], v[166:169], v[138:141]
	v_mfma_f32_16x16x32_bf16 v[110:113], v[118:121], v[220:223], v[110:113]
	v_mfma_f32_16x16x32_bf16 v[106:109], v[126:129], v[220:223], v[106:109]
	v_mfma_f32_16x16x32_bf16 v[98:101], v[118:121], v[228:231], v[98:101]
	v_mfma_f32_16x16x32_bf16 v[90:93], v[126:129], v[228:231], v[90:93]
	v_mfma_f32_16x16x32_bf16 v[82:85], v[118:121], v[236:239], v[82:85]
	v_mfma_f32_16x16x32_bf16 v[74:77], v[126:129], v[236:239], v[74:77]
	v_mfma_f32_16x16x32_bf16 v[134:137], v[146:149], v[162:165], v[134:137]
	v_mfma_f32_16x16x32_bf16 v[130:133], v[154:157], v[162:165], v[130:133]
	v_mfma_f32_16x16x32_bf16 v[102:105], v[146:149], v[216:219], v[102:105]
	v_mfma_f32_16x16x32_bf16 v[94:97], v[154:157], v[216:219], v[94:97]
	v_mfma_f32_16x16x32_bf16 v[86:89], v[146:149], v[224:227], v[86:89]
	v_mfma_f32_16x16x32_bf16 v[78:81], v[154:157], v[224:227], v[78:81]
	v_mfma_f32_16x16x32_bf16 v[70:73], v[146:149], v[232:235], v[70:73]
	v_mfma_f32_16x16x32_bf16 v[66:69], v[154:157], v[232:235], v[66:69]
	v_mfma_f32_16x16x32_bf16 v[134:137], v[150:153], v[166:169], v[134:137]
	v_mfma_f32_16x16x32_bf16 v[130:133], v[158:161], v[166:169], v[130:133]
	v_mfma_f32_16x16x32_bf16 v[102:105], v[150:153], v[220:223], v[102:105]
	v_mfma_f32_16x16x32_bf16 v[94:97], v[158:161], v[220:223], v[94:97]
	v_mfma_f32_16x16x32_bf16 v[86:89], v[150:153], v[228:231], v[86:89]
	v_mfma_f32_16x16x32_bf16 v[78:81], v[158:161], v[228:231], v[78:81]
	v_mfma_f32_16x16x32_bf16 v[70:73], v[150:153], v[236:239], v[70:73]
	v_mfma_f32_16x16x32_bf16 v[66:69], v[158:161], v[236:239], v[66:69]
	s_setprio 0
	s_barrier
	ds_read_b128 v[162:165], v214 offset:49152
	ds_read_b128 v[166:169], v214 offset:50176
	ds_read_b128 v[216:219], v214 offset:51200
	ds_read_b128 v[220:223], v214 offset:52224
	ds_read_b128 v[224:227], v214 offset:53248
	ds_read_b128 v[228:231], v214 offset:54272
	ds_read_b128 v[232:235], v214 offset:55296
	ds_read_b128 v[236:239], v214 offset:56320
	s_add_i32 s62, s62, s17
	s_mov_b32 m0, s62
	v_lshl_add_u64 v[202:203], v[202:203], 0, s[76:77]
	global_load_lds_dwordx4 v[202:203], off
	s_add_i32 m0, s62, 0x2000
	s_add_u32 s72, s94, 0x40080
	v_lshl_add_u64 v[202:203], v[240:241], 0, s[76:77]
	s_addc_u32 s73, s95, 0
	s_add_i32 s62, s63, s17
	global_load_lds_dwordx4 v[202:203], off
	v_lshl_add_u64 v[202:203], s[72:73], 0, v[174:175]
	s_mov_b32 m0, s62
	s_nop 0
	global_load_lds_dwordx4 v[202:203], off
	v_lshl_add_u64 v[202:203], s[72:73], 0, v[178:179]
	s_add_i32 m0, s62, 0x2000
	s_nop 0
	global_load_lds_dwordx4 v[202:203], off
	v_lshl_add_u64 v[202:203], v[242:243], 0, s[76:77]
	s_mov_b32 m0, s44
	s_nop 0
	global_load_lds_dwordx4 v[202:203], off
	v_lshl_add_u64 v[202:203], v[244:245], 0, s[76:77]
	s_mov_b32 m0, s36
	s_nop 0
	global_load_lds_dwordx4 v[202:203], off
	s_waitcnt vmcnt(8) lgkmcnt(0)
	s_setprio 1
	s_barrier
	v_mfma_f32_16x16x32_bf16 v[62:65], v[114:117], v[162:165], v[62:65]
	v_mfma_f32_16x16x32_bf16 v[58:61], v[122:125], v[162:165], v[58:61]
	v_mfma_f32_16x16x32_bf16 v[50:53], v[114:117], v[216:219], v[50:53]
	v_mfma_f32_16x16x32_bf16 v[42:45], v[122:125], v[216:219], v[42:45]
	v_mfma_f32_16x16x32_bf16 v[34:37], v[114:117], v[224:227], v[34:37]
	v_mfma_f32_16x16x32_bf16 v[26:29], v[122:125], v[224:227], v[26:29]
	v_mfma_f32_16x16x32_bf16 v[18:21], v[114:117], v[232:235], v[18:21]
	v_mfma_f32_16x16x32_bf16 v[10:13], v[122:125], v[232:235], v[10:13]
	v_mfma_f32_16x16x32_bf16 v[62:65], v[118:121], v[166:169], v[62:65]
	v_mfma_f32_16x16x32_bf16 v[58:61], v[126:129], v[166:169], v[58:61]
	v_mfma_f32_16x16x32_bf16 v[50:53], v[118:121], v[220:223], v[50:53]
	v_mfma_f32_16x16x32_bf16 v[42:45], v[126:129], v[220:223], v[42:45]
	v_mfma_f32_16x16x32_bf16 v[34:37], v[118:121], v[228:231], v[34:37]
	v_mfma_f32_16x16x32_bf16 v[26:29], v[126:129], v[228:231], v[26:29]
	v_mfma_f32_16x16x32_bf16 v[18:21], v[118:121], v[236:239], v[18:21]
	v_mfma_f32_16x16x32_bf16 v[10:13], v[126:129], v[236:239], v[10:13]
	v_mfma_f32_16x16x32_bf16 v[54:57], v[146:149], v[162:165], v[54:57]
	v_mfma_f32_16x16x32_bf16 v[46:49], v[154:157], v[162:165], v[46:49]
	v_mfma_f32_16x16x32_bf16 v[38:41], v[146:149], v[216:219], v[38:41]
	v_mfma_f32_16x16x32_bf16 v[30:33], v[154:157], v[216:219], v[30:33]
	v_mfma_f32_16x16x32_bf16 v[22:25], v[146:149], v[224:227], v[22:25]
	v_mfma_f32_16x16x32_bf16 v[14:17], v[154:157], v[224:227], v[14:17]
	v_mfma_f32_16x16x32_bf16 v[6:9], v[146:149], v[232:235], v[6:9]
	v_mfma_f32_16x16x32_bf16 v[2:5], v[154:157], v[232:235], v[2:5]
	v_mfma_f32_16x16x32_bf16 v[54:57], v[150:153], v[166:169], v[54:57]
	v_mfma_f32_16x16x32_bf16 v[46:49], v[158:161], v[166:169], v[46:49]
	v_mfma_f32_16x16x32_bf16 v[38:41], v[150:153], v[220:223], v[38:41]
	v_mfma_f32_16x16x32_bf16 v[30:33], v[158:161], v[220:223], v[30:33]
	v_mfma_f32_16x16x32_bf16 v[22:25], v[150:153], v[228:231], v[22:25]
	v_mfma_f32_16x16x32_bf16 v[14:17], v[158:161], v[228:231], v[14:17]
	v_mfma_f32_16x16x32_bf16 v[6:9], v[150:153], v[236:239], v[6:9]
	v_mfma_f32_16x16x32_bf16 v[2:5], v[158:161], v[236:239], v[2:5]
	s_setprio 0
	s_barrier
	s_add_u32 s10, s10, 0x100
	s_addc_u32 s11, s11, 0
	s_add_u32 vcc_lo, vcc_lo, 0x100
	s_addc_u32 vcc_hi, vcc_hi, 0
	s_cmp_ge_i32 s66, s18
	s_mov_b32 s94, s66
.LBB0_1428:
	s_add_i32 s66, s94, 2
	s_add_u32 s67, s10, 0xfffc0080
	s_addc_u32 s72, s11, -1
	s_cmp_eq_u32 s85, s94
	s_cselect_b32 s97, s14, s72
	s_cselect_b32 s96, s15, s67
	s_cselect_b32 s95, s51, vcc_hi
	s_cselect_b32 s94, s84, vcc_lo
	s_add_i32 s67, 0, 0x10000
	s_add_i32 s62, 0, 0x14000
	v_add_u32_e32 v126, s67, v199
	v_add_u32_e32 v158, s62, v199
	ds_read_b128 v[114:117], v126
	ds_read_b128 v[118:121], v126 offset:1024
	ds_read_b128 v[122:125], v126 offset:2048
	ds_read_b128 v[126:129], v126 offset:3072
	ds_read_b128 v[146:149], v158
	ds_read_b128 v[150:153], v158 offset:1024
	ds_read_b128 v[154:157], v158 offset:2048
	ds_read_b128 v[158:161], v158 offset:3072
	v_lshl_add_u64 v[202:203], s[10:11], 0, v[196:197]
	s_add_i32 m0, s28, 0xc000
	ds_read_b128 v[162:165], v214
	ds_read_b128 v[166:169], v214 offset:1024
	ds_read_b128 v[216:219], v214 offset:2048
	ds_read_b128 v[220:223], v214 offset:3072
	ds_read_b128 v[224:227], v214 offset:4096
	ds_read_b128 v[228:231], v214 offset:5120
	ds_read_b128 v[232:235], v214 offset:6144
	ds_read_b128 v[236:239], v214 offset:7168
	global_load_lds_dwordx4 v[202:203], off
	v_lshl_add_u64 v[202:203], s[10:11], 0, v[176:177]
	s_add_i32 m0, s28, 0xe000
	s_nop 0
	global_load_lds_dwordx4 v[202:203], off
	s_waitcnt vmcnt(8) lgkmcnt(0)
	s_setprio 1
	s_barrier
	v_mfma_f32_16x16x32_bf16 v[142:145], v[114:117], v[162:165], v[142:145]
	v_mfma_f32_16x16x32_bf16 v[138:141], v[122:125], v[162:165], v[138:141]
	v_mfma_f32_16x16x32_bf16 v[110:113], v[114:117], v[216:219], v[110:113]
	v_mfma_f32_16x16x32_bf16 v[106:109], v[122:125], v[216:219], v[106:109]
	v_mfma_f32_16x16x32_bf16 v[98:101], v[114:117], v[224:227], v[98:101]
	v_mfma_f32_16x16x32_bf16 v[90:93], v[122:125], v[224:227], v[90:93]
	v_mfma_f32_16x16x32_bf16 v[82:85], v[114:117], v[232:235], v[82:85]
	v_mfma_f32_16x16x32_bf16 v[74:77], v[122:125], v[232:235], v[74:77]
	v_mfma_f32_16x16x32_bf16 v[142:145], v[118:121], v[166:169], v[142:145]
	v_mfma_f32_16x16x32_bf16 v[138:141], v[126:129], v[166:169], v[138:141]
	v_mfma_f32_16x16x32_bf16 v[110:113], v[118:121], v[220:223], v[110:113]
	v_mfma_f32_16x16x32_bf16 v[106:109], v[126:129], v[220:223], v[106:109]
	v_mfma_f32_16x16x32_bf16 v[98:101], v[118:121], v[228:231], v[98:101]
	v_mfma_f32_16x16x32_bf16 v[90:93], v[126:129], v[228:231], v[90:93]
	v_mfma_f32_16x16x32_bf16 v[82:85], v[118:121], v[236:239], v[82:85]
	v_mfma_f32_16x16x32_bf16 v[74:77], v[126:129], v[236:239], v[74:77]
	v_mfma_f32_16x16x32_bf16 v[134:137], v[146:149], v[162:165], v[134:137]
	v_mfma_f32_16x16x32_bf16 v[130:133], v[154:157], v[162:165], v[130:133]
	v_mfma_f32_16x16x32_bf16 v[102:105], v[146:149], v[216:219], v[102:105]
	v_mfma_f32_16x16x32_bf16 v[94:97], v[154:157], v[216:219], v[94:97]
	v_mfma_f32_16x16x32_bf16 v[86:89], v[146:149], v[224:227], v[86:89]
	v_mfma_f32_16x16x32_bf16 v[78:81], v[154:157], v[224:227], v[78:81]
	v_mfma_f32_16x16x32_bf16 v[70:73], v[146:149], v[232:235], v[70:73]
	v_mfma_f32_16x16x32_bf16 v[66:69], v[154:157], v[232:235], v[66:69]
	v_mfma_f32_16x16x32_bf16 v[134:137], v[150:153], v[166:169], v[134:137]
	v_mfma_f32_16x16x32_bf16 v[130:133], v[158:161], v[166:169], v[130:133]
	v_mfma_f32_16x16x32_bf16 v[102:105], v[150:153], v[220:223], v[102:105]
	v_mfma_f32_16x16x32_bf16 v[94:97], v[158:161], v[220:223], v[94:97]
	v_mfma_f32_16x16x32_bf16 v[86:89], v[150:153], v[228:231], v[86:89]
	v_mfma_f32_16x16x32_bf16 v[78:81], v[158:161], v[228:231], v[78:81]
	v_mfma_f32_16x16x32_bf16 v[70:73], v[150:153], v[236:239], v[70:73]
	v_mfma_f32_16x16x32_bf16 v[66:69], v[158:161], v[236:239], v[66:69]
	s_setprio 0
	s_barrier
	ds_read_b128 v[162:165], v214 offset:16384
	ds_read_b128 v[166:169], v214 offset:17408
	ds_read_b128 v[216:219], v214 offset:18432
	ds_read_b128 v[220:223], v214 offset:19456
	ds_read_b128 v[224:227], v214 offset:20480
	ds_read_b128 v[228:231], v214 offset:21504
	ds_read_b128 v[232:235], v214 offset:22528
	ds_read_b128 v[236:239], v214 offset:23552
	s_add_i32 s63, s67, s17
	s_mov_b32 m0, s63
	v_lshl_add_u64 v[202:203], s[94:95], 0, v[174:175]
	global_load_lds_dwordx4 v[202:203], off
	s_add_i32 m0, s63, 0x2000
	s_add_u32 s72, s94, 0x40000
	v_lshl_add_u64 v[240:241], s[94:95], 0, v[178:179]
	s_addc_u32 s73, s95, 0
	s_add_i32 s62, s62, s17
	global_load_lds_dwordx4 v[240:241], off
	v_lshl_add_u64 v[242:243], s[72:73], 0, v[174:175]
	s_mov_b32 m0, s62
	v_lshl_add_u64 v[244:245], s[96:97], 0, v[176:177]
	global_load_lds_dwordx4 v[242:243], off
	v_lshl_add_u64 v[242:243], s[72:73], 0, v[178:179]
	s_add_i32 m0, s62, 0x2000
	s_nop 0
	global_load_lds_dwordx4 v[242:243], off
	v_lshl_add_u64 v[242:243], s[96:97], 0, v[172:173]
	s_mov_b32 m0, s28
	s_nop 0
	global_load_lds_dwordx4 v[242:243], off
	s_mov_b32 m0, s29
	s_nop 0
	global_load_lds_dwordx4 v[244:245], off
	s_waitcnt vmcnt(8) lgkmcnt(0)
	s_setprio 1
	s_barrier
	v_mfma_f32_16x16x32_bf16 v[62:65], v[114:117], v[162:165], v[62:65]
	v_mfma_f32_16x16x32_bf16 v[58:61], v[122:125], v[162:165], v[58:61]
	v_mfma_f32_16x16x32_bf16 v[50:53], v[114:117], v[216:219], v[50:53]
	v_mfma_f32_16x16x32_bf16 v[42:45], v[122:125], v[216:219], v[42:45]
	v_mfma_f32_16x16x32_bf16 v[34:37], v[114:117], v[224:227], v[34:37]
	v_mfma_f32_16x16x32_bf16 v[26:29], v[122:125], v[224:227], v[26:29]
	v_mfma_f32_16x16x32_bf16 v[18:21], v[114:117], v[232:235], v[18:21]
	v_mfma_f32_16x16x32_bf16 v[10:13], v[122:125], v[232:235], v[10:13]
	v_mfma_f32_16x16x32_bf16 v[62:65], v[118:121], v[166:169], v[62:65]
	v_mfma_f32_16x16x32_bf16 v[58:61], v[126:129], v[166:169], v[58:61]
	v_mfma_f32_16x16x32_bf16 v[50:53], v[118:121], v[220:223], v[50:53]
	v_mfma_f32_16x16x32_bf16 v[42:45], v[126:129], v[220:223], v[42:45]
	v_mfma_f32_16x16x32_bf16 v[34:37], v[118:121], v[228:231], v[34:37]
	v_mfma_f32_16x16x32_bf16 v[26:29], v[126:129], v[228:231], v[26:29]
	v_mfma_f32_16x16x32_bf16 v[18:21], v[118:121], v[236:239], v[18:21]
	v_mfma_f32_16x16x32_bf16 v[10:13], v[126:129], v[236:239], v[10:13]
	v_mfma_f32_16x16x32_bf16 v[54:57], v[146:149], v[162:165], v[54:57]
	v_mfma_f32_16x16x32_bf16 v[46:49], v[154:157], v[162:165], v[46:49]
	v_mfma_f32_16x16x32_bf16 v[38:41], v[146:149], v[216:219], v[38:41]
	v_mfma_f32_16x16x32_bf16 v[30:33], v[154:157], v[216:219], v[30:33]
	v_mfma_f32_16x16x32_bf16 v[22:25], v[146:149], v[224:227], v[22:25]
	v_mfma_f32_16x16x32_bf16 v[14:17], v[154:157], v[224:227], v[14:17]
	v_mfma_f32_16x16x32_bf16 v[6:9], v[146:149], v[232:235], v[6:9]
	v_mfma_f32_16x16x32_bf16 v[2:5], v[154:157], v[232:235], v[2:5]
	v_mfma_f32_16x16x32_bf16 v[54:57], v[150:153], v[166:169], v[54:57]
	v_mfma_f32_16x16x32_bf16 v[46:49], v[158:161], v[166:169], v[46:49]
	v_mfma_f32_16x16x32_bf16 v[38:41], v[150:153], v[220:223], v[38:41]
	v_mfma_f32_16x16x32_bf16 v[30:33], v[158:161], v[220:223], v[30:33]
	v_mfma_f32_16x16x32_bf16 v[22:25], v[150:153], v[228:231], v[22:25]
	v_mfma_f32_16x16x32_bf16 v[14:17], v[158:161], v[228:231], v[14:17]
	v_mfma_f32_16x16x32_bf16 v[6:9], v[150:153], v[236:239], v[6:9]
	v_mfma_f32_16x16x32_bf16 v[2:5], v[158:161], v[236:239], v[2:5]
	s_setprio 0
	s_barrier
	s_add_i32 s62, 0, 0x18000
	s_add_i32 s63, 0, 0x1c000
	v_add_u32_e32 v126, s62, v199
	v_add_u32_e32 v158, s63, v199
	ds_read_b128 v[114:117], v126
	ds_read_b128 v[118:121], v126 offset:1024
	ds_read_b128 v[122:125], v126 offset:2048
	ds_read_b128 v[126:129], v126 offset:3072
	ds_read_b128 v[146:149], v158
	ds_read_b128 v[150:153], v158 offset:1024
	ds_read_b128 v[154:157], v158 offset:2048
	ds_read_b128 v[158:161], v158 offset:3072
	s_add_u32 s72, s96, 0x40000
	s_addc_u32 s73, s97, 0
	s_mov_b32 m0, s30
	v_lshl_add_u64 v[246:247], s[72:73], 0, v[172:173]
	ds_read_b128 v[162:165], v214 offset:32768
	ds_read_b128 v[166:169], v214 offset:33792
	ds_read_b128 v[216:219], v214 offset:34816
	ds_read_b128 v[220:223], v214 offset:35840
	ds_read_b128 v[224:227], v214 offset:36864
	ds_read_b128 v[228:231], v214 offset:37888
	ds_read_b128 v[232:235], v214 offset:38912
	ds_read_b128 v[236:239], v214 offset:39936
	global_load_lds_dwordx4 v[246:247], off
	v_lshl_add_u64 v[246:247], s[72:73], 0, v[176:177]
	s_mov_b32 m0, s31
	s_nop 0
	global_load_lds_dwordx4 v[246:247], off
	s_waitcnt vmcnt(8) lgkmcnt(0)
	s_setprio 1
	s_barrier
	v_mfma_f32_16x16x32_bf16 v[142:145], v[114:117], v[162:165], v[142:145]
	v_mfma_f32_16x16x32_bf16 v[138:141], v[122:125], v[162:165], v[138:141]
	v_mfma_f32_16x16x32_bf16 v[110:113], v[114:117], v[216:219], v[110:113]
	v_mfma_f32_16x16x32_bf16 v[106:109], v[122:125], v[216:219], v[106:109]
	v_mfma_f32_16x16x32_bf16 v[98:101], v[114:117], v[224:227], v[98:101]
	v_mfma_f32_16x16x32_bf16 v[90:93], v[122:125], v[224:227], v[90:93]
	v_mfma_f32_16x16x32_bf16 v[82:85], v[114:117], v[232:235], v[82:85]
	v_mfma_f32_16x16x32_bf16 v[74:77], v[122:125], v[232:235], v[74:77]
	v_mfma_f32_16x16x32_bf16 v[142:145], v[118:121], v[166:169], v[142:145]
	v_mfma_f32_16x16x32_bf16 v[138:141], v[126:129], v[166:169], v[138:141]
	v_mfma_f32_16x16x32_bf16 v[110:113], v[118:121], v[220:223], v[110:113]
	v_mfma_f32_16x16x32_bf16 v[106:109], v[126:129], v[220:223], v[106:109]
	v_mfma_f32_16x16x32_bf16 v[98:101], v[118:121], v[228:231], v[98:101]
	v_mfma_f32_16x16x32_bf16 v[90:93], v[126:129], v[228:231], v[90:93]
	v_mfma_f32_16x16x32_bf16 v[82:85], v[118:121], v[236:239], v[82:85]
	v_mfma_f32_16x16x32_bf16 v[74:77], v[126:129], v[236:239], v[74:77]
	v_mfma_f32_16x16x32_bf16 v[134:137], v[146:149], v[162:165], v[134:137]
	v_mfma_f32_16x16x32_bf16 v[130:133], v[154:157], v[162:165], v[130:133]
	v_mfma_f32_16x16x32_bf16 v[102:105], v[146:149], v[216:219], v[102:105]
	v_mfma_f32_16x16x32_bf16 v[94:97], v[154:157], v[216:219], v[94:97]
	v_mfma_f32_16x16x32_bf16 v[86:89], v[146:149], v[224:227], v[86:89]
	v_mfma_f32_16x16x32_bf16 v[78:81], v[154:157], v[224:227], v[78:81]
	v_mfma_f32_16x16x32_bf16 v[70:73], v[146:149], v[232:235], v[70:73]
	v_mfma_f32_16x16x32_bf16 v[66:69], v[154:157], v[232:235], v[66:69]
	v_mfma_f32_16x16x32_bf16 v[134:137], v[150:153], v[166:169], v[134:137]
	v_mfma_f32_16x16x32_bf16 v[130:133], v[158:161], v[166:169], v[130:133]
	v_mfma_f32_16x16x32_bf16 v[102:105], v[150:153], v[220:223], v[102:105]
	v_mfma_f32_16x16x32_bf16 v[94:97], v[158:161], v[220:223], v[94:97]
	v_mfma_f32_16x16x32_bf16 v[86:89], v[150:153], v[228:231], v[86:89]
	v_mfma_f32_16x16x32_bf16 v[78:81], v[158:161], v[228:231], v[78:81]
	v_mfma_f32_16x16x32_bf16 v[70:73], v[150:153], v[236:239], v[70:73]
	v_mfma_f32_16x16x32_bf16 v[66:69], v[158:161], v[236:239], v[66:69]
	s_setprio 0
	s_barrier
	ds_read_b128 v[162:165], v214 offset:49152
	ds_read_b128 v[166:169], v214 offset:50176
	ds_read_b128 v[216:219], v214 offset:51200
	ds_read_b128 v[220:223], v214 offset:52224
	ds_read_b128 v[224:227], v214 offset:53248
	ds_read_b128 v[228:231], v214 offset:54272
	ds_read_b128 v[232:235], v214 offset:55296
	ds_read_b128 v[236:239], v214 offset:56320
	s_add_i32 s62, s62, s17
	s_mov_b32 m0, s62
	v_lshl_add_u64 v[202:203], v[202:203], 0, s[76:77]
	global_load_lds_dwordx4 v[202:203], off
	s_add_i32 m0, s62, 0x2000
	s_add_u32 s72, s94, 0x40080
	v_lshl_add_u64 v[202:203], v[240:241], 0, s[76:77]
	s_addc_u32 s73, s95, 0
	s_add_i32 s62, s63, s17
	global_load_lds_dwordx4 v[202:203], off
	v_lshl_add_u64 v[202:203], s[72:73], 0, v[174:175]
	s_mov_b32 m0, s62
	s_nop 0
	global_load_lds_dwordx4 v[202:203], off
	v_lshl_add_u64 v[202:203], s[72:73], 0, v[178:179]
	s_add_i32 m0, s62, 0x2000
	s_nop 0
	global_load_lds_dwordx4 v[202:203], off
	v_lshl_add_u64 v[202:203], v[242:243], 0, s[76:77]
	s_mov_b32 m0, s44
	s_nop 0
	global_load_lds_dwordx4 v[202:203], off
	v_lshl_add_u64 v[202:203], v[244:245], 0, s[76:77]
	s_mov_b32 m0, s36
	s_nop 0
	global_load_lds_dwordx4 v[202:203], off
	s_waitcnt vmcnt(8) lgkmcnt(0)
	s_setprio 1
	s_barrier
	v_mfma_f32_16x16x32_bf16 v[62:65], v[114:117], v[162:165], v[62:65]
	v_mfma_f32_16x16x32_bf16 v[58:61], v[122:125], v[162:165], v[58:61]
	v_mfma_f32_16x16x32_bf16 v[50:53], v[114:117], v[216:219], v[50:53]
	v_mfma_f32_16x16x32_bf16 v[42:45], v[122:125], v[216:219], v[42:45]
	v_mfma_f32_16x16x32_bf16 v[34:37], v[114:117], v[224:227], v[34:37]
	v_mfma_f32_16x16x32_bf16 v[26:29], v[122:125], v[224:227], v[26:29]
	v_mfma_f32_16x16x32_bf16 v[18:21], v[114:117], v[232:235], v[18:21]
	v_mfma_f32_16x16x32_bf16 v[10:13], v[122:125], v[232:235], v[10:13]
	v_mfma_f32_16x16x32_bf16 v[62:65], v[118:121], v[166:169], v[62:65]
	v_mfma_f32_16x16x32_bf16 v[58:61], v[126:129], v[166:169], v[58:61]
	v_mfma_f32_16x16x32_bf16 v[50:53], v[118:121], v[220:223], v[50:53]
	v_mfma_f32_16x16x32_bf16 v[42:45], v[126:129], v[220:223], v[42:45]
	v_mfma_f32_16x16x32_bf16 v[34:37], v[118:121], v[228:231], v[34:37]
	v_mfma_f32_16x16x32_bf16 v[26:29], v[126:129], v[228:231], v[26:29]
	v_mfma_f32_16x16x32_bf16 v[18:21], v[118:121], v[236:239], v[18:21]
	v_mfma_f32_16x16x32_bf16 v[10:13], v[126:129], v[236:239], v[10:13]
	v_mfma_f32_16x16x32_bf16 v[54:57], v[146:149], v[162:165], v[54:57]
	v_mfma_f32_16x16x32_bf16 v[46:49], v[154:157], v[162:165], v[46:49]
	v_mfma_f32_16x16x32_bf16 v[38:41], v[146:149], v[216:219], v[38:41]
	v_mfma_f32_16x16x32_bf16 v[30:33], v[154:157], v[216:219], v[30:33]
	v_mfma_f32_16x16x32_bf16 v[22:25], v[146:149], v[224:227], v[22:25]
	v_mfma_f32_16x16x32_bf16 v[14:17], v[154:157], v[224:227], v[14:17]
	v_mfma_f32_16x16x32_bf16 v[6:9], v[146:149], v[232:235], v[6:9]
	v_mfma_f32_16x16x32_bf16 v[2:5], v[154:157], v[232:235], v[2:5]
	v_mfma_f32_16x16x32_bf16 v[54:57], v[150:153], v[166:169], v[54:57]
	v_mfma_f32_16x16x32_bf16 v[46:49], v[158:161], v[166:169], v[46:49]
	v_mfma_f32_16x16x32_bf16 v[38:41], v[150:153], v[220:223], v[38:41]
	v_mfma_f32_16x16x32_bf16 v[30:33], v[158:161], v[220:223], v[30:33]
	v_mfma_f32_16x16x32_bf16 v[22:25], v[150:153], v[228:231], v[22:25]
	v_mfma_f32_16x16x32_bf16 v[14:17], v[158:161], v[228:231], v[14:17]
	v_mfma_f32_16x16x32_bf16 v[6:9], v[150:153], v[236:239], v[6:9]
	v_mfma_f32_16x16x32_bf16 v[2:5], v[158:161], v[236:239], v[2:5]
	s_setprio 0
	s_barrier
	s_add_u32 s10, s10, 0x100
	s_addc_u32 s11, s11, 0
	s_add_u32 vcc_lo, vcc_lo, 0x100
	s_addc_u32 vcc_hi, vcc_hi, 0
	s_cmp_ge_i32 s66, s18
	s_mov_b32 s94, s66
	s_cbranch_scc0 .LBB0_1428
	s_and_b64 vcc, exec, s[82:83]
	s_cbranch_vccz .LBB0_1431
	s_barrier

.LBB0_1618:
	s_add_u32 s24, s96, s20
	s_addc_u32 s25, s97, s21
	s_and_b64 s[14:15], s[4:5], exec
	s_cselect_b32 s14, s25, s29
	s_cselect_b32 s15, s24, s28
	s_add_u32 s26, s2, s22
	s_addc_u32 s27, s3, s23
	s_and_b64 s[36:37], s[4:5], exec
	s_cselect_b32 s17, s27, s31
	s_cselect_b32 s49, s26, s30
	s_add_u32 s28, s28, 0x40080
	s_addc_u32 s29, s29, 0
	s_add_u32 s50, s30, 0x100
	s_addc_u32 s51, s31, 0
	s_mov_b32 s62, -2
	ds_read_b128 v[154:157], v150
	ds_read_b128 v[158:161], v150 offset:1024
	ds_read_b128 v[162:165], v150 offset:2048
	ds_read_b128 v[166:169], v150 offset:3072
	ds_read_b128 v[170:173], v151
	ds_read_b128 v[174:177], v151 offset:1024
	ds_read_b128 v[178:181], v151 offset:2048
	ds_read_b128 v[182:185], v151 offset:3072
	ds_read_b128 v[186:189], v152
	ds_read_b128 v[190:193], v152 offset:1024
	ds_read_b128 v[194:197], v152 offset:2048
	ds_read_b128 v[198:201], v152 offset:3072
	ds_read_b128 v[206:209], v152 offset:4096
	ds_read_b128 v[210:213], v152 offset:5120
	ds_read_b128 v[214:217], v152 offset:6144
	ds_read_b128 v[218:221], v152 offset:7168
	s_add_u32 s30, s28, 0xfffc0080
	s_addc_u32 s31, s29, -1
	s_cmp_eq_u32 s62, 12
	s_cselect_b32 s37, s14, s31
	s_cselect_b32 s36, s15, s30
	s_cselect_b32 s31, s17, s51
	s_cselect_b32 s30, s49, s50
	s_add_i32 m0, s19, 0xc000
	v_lshl_add_u64 v[146:147], s[28:29], 0, v[138:139]
	global_load_lds_dwordx4 v[146:147], off
	v_lshl_add_u64 v[146:147], s[28:29], 0, v[140:141]
	s_add_i32 m0, s19, 0xe000
	s_nop 0
	global_load_lds_dwordx4 v[146:147], off
	s_waitcnt vmcnt(8) lgkmcnt(0)
	s_setprio 1
	s_barrier
	v_mfma_f32_16x16x32_bf16 v[126:129], v[154:157], v[186:189], 0
	v_mfma_f32_16x16x32_bf16 v[122:125], v[162:165], v[186:189], 0
	v_mfma_f32_16x16x32_bf16 v[110:113], v[154:157], v[194:197], 0
	v_mfma_f32_16x16x32_bf16 v[106:109], v[162:165], v[194:197], 0
	v_mfma_f32_16x16x32_bf16 v[94:97], v[154:157], v[206:209], 0
	v_mfma_f32_16x16x32_bf16 v[90:93], v[162:165], v[206:209], 0
	v_mfma_f32_16x16x32_bf16 v[78:81], v[154:157], v[214:217], 0
	v_mfma_f32_16x16x32_bf16 v[74:77], v[162:165], v[214:217], 0
	v_mfma_f32_16x16x32_bf16 v[126:129], v[158:161], v[190:193], v[126:129]
	v_mfma_f32_16x16x32_bf16 v[122:125], v[166:169], v[190:193], v[122:125]
	v_mfma_f32_16x16x32_bf16 v[110:113], v[158:161], v[198:201], v[110:113]
	v_mfma_f32_16x16x32_bf16 v[106:109], v[166:169], v[198:201], v[106:109]
	v_mfma_f32_16x16x32_bf16 v[94:97], v[158:161], v[210:213], v[94:97]
	v_mfma_f32_16x16x32_bf16 v[90:93], v[166:169], v[210:213], v[90:93]
	v_mfma_f32_16x16x32_bf16 v[78:81], v[158:161], v[218:221], v[78:81]
	v_mfma_f32_16x16x32_bf16 v[74:77], v[166:169], v[218:221], v[74:77]
	v_mfma_f32_16x16x32_bf16 v[118:121], v[170:173], v[186:189], 0
	v_mfma_f32_16x16x32_bf16 v[114:117], v[178:181], v[186:189], 0
	v_mfma_f32_16x16x32_bf16 v[102:105], v[170:173], v[194:197], 0
	v_mfma_f32_16x16x32_bf16 v[98:101], v[178:181], v[194:197], 0
	v_mfma_f32_16x16x32_bf16 v[86:89], v[170:173], v[206:209], 0
	v_mfma_f32_16x16x32_bf16 v[82:85], v[178:181], v[206:209], 0
	v_mfma_f32_16x16x32_bf16 v[70:73], v[170:173], v[214:217], 0
	v_mfma_f32_16x16x32_bf16 v[66:69], v[178:181], v[214:217], 0
	v_mfma_f32_16x16x32_bf16 v[118:121], v[174:177], v[190:193], v[118:121]
	v_mfma_f32_16x16x32_bf16 v[114:117], v[182:185], v[190:193], v[114:117]
	v_mfma_f32_16x16x32_bf16 v[102:105], v[174:177], v[198:201], v[102:105]
	v_mfma_f32_16x16x32_bf16 v[98:101], v[182:185], v[198:201], v[98:101]
	v_mfma_f32_16x16x32_bf16 v[86:89], v[174:177], v[210:213], v[86:89]
	v_mfma_f32_16x16x32_bf16 v[82:85], v[182:185], v[210:213], v[82:85]
	v_mfma_f32_16x16x32_bf16 v[70:73], v[174:177], v[218:221], v[70:73]
	v_mfma_f32_16x16x32_bf16 v[66:69], v[182:185], v[218:221], v[66:69]
	s_setprio 0
	s_barrier
	ds_read_b128 v[186:189], v152 offset:16384
	ds_read_b128 v[190:193], v152 offset:17408
	ds_read_b128 v[194:197], v152 offset:18432
	ds_read_b128 v[198:201], v152 offset:19456
	ds_read_b128 v[206:209], v152 offset:20480
	ds_read_b128 v[210:213], v152 offset:21504
	ds_read_b128 v[214:217], v152 offset:22528
	ds_read_b128 v[218:221], v152 offset:23552
	s_add_i32 s63, s45, s12
	s_mov_b32 m0, s63
	v_lshl_add_u64 v[146:147], s[30:31], 0, v[134:135]
	global_load_lds_dwordx4 v[146:147], off
	s_add_i32 m0, s63, 0x2000
	s_add_u32 s64, s30, 0x40000
	v_lshl_add_u64 v[202:203], s[30:31], 0, v[130:131]
	s_addc_u32 s65, s31, 0
	s_add_i32 s63, s46, s12
	global_load_lds_dwordx4 v[202:203], off
	v_lshl_add_u64 v[222:223], s[64:65], 0, v[134:135]
	s_mov_b32 m0, s63
	v_lshl_add_u64 v[224:225], s[36:37], 0, v[132:133]
	global_load_lds_dwordx4 v[222:223], off
	v_lshl_add_u64 v[222:223], s[64:65], 0, v[130:131]
	s_add_i32 m0, s63, 0x2000
	s_nop 0
	global_load_lds_dwordx4 v[222:223], off
	v_lshl_add_u64 v[222:223], s[36:37], 0, v[136:137]
	s_mov_b32 m0, s19
	s_nop 0
	global_load_lds_dwordx4 v[222:223], off
	s_mov_b32 m0, s33
	s_nop 0
	global_load_lds_dwordx4 v[224:225], off
	s_waitcnt vmcnt(8) lgkmcnt(0)
	s_setprio 1
	s_barrier
	v_mfma_f32_16x16x32_bf16 v[62:65], v[154:157], v[186:189], 0
	v_mfma_f32_16x16x32_bf16 v[58:61], v[162:165], v[186:189], 0
	v_mfma_f32_16x16x32_bf16 v[46:49], v[154:157], v[194:197], 0
	v_mfma_f32_16x16x32_bf16 v[42:45], v[162:165], v[194:197], 0
	v_mfma_f32_16x16x32_bf16 v[30:33], v[154:157], v[206:209], 0
	v_mfma_f32_16x16x32_bf16 v[26:29], v[162:165], v[206:209], 0
	v_mfma_f32_16x16x32_bf16 v[14:17], v[154:157], v[214:217], 0
	v_mfma_f32_16x16x32_bf16 v[10:13], v[162:165], v[214:217], 0
	v_mfma_f32_16x16x32_bf16 v[62:65], v[158:161], v[190:193], v[62:65]
	v_mfma_f32_16x16x32_bf16 v[58:61], v[166:169], v[190:193], v[58:61]
	v_mfma_f32_16x16x32_bf16 v[46:49], v[158:161], v[198:201], v[46:49]
	v_mfma_f32_16x16x32_bf16 v[42:45], v[166:169], v[198:201], v[42:45]
	v_mfma_f32_16x16x32_bf16 v[30:33], v[158:161], v[210:213], v[30:33]
	v_mfma_f32_16x16x32_bf16 v[26:29], v[166:169], v[210:213], v[26:29]
	v_mfma_f32_16x16x32_bf16 v[14:17], v[158:161], v[218:221], v[14:17]
	v_mfma_f32_16x16x32_bf16 v[10:13], v[166:169], v[218:221], v[10:13]
	v_mfma_f32_16x16x32_bf16 v[54:57], v[170:173], v[186:189], 0
	v_mfma_f32_16x16x32_bf16 v[50:53], v[178:181], v[186:189], 0
	v_mfma_f32_16x16x32_bf16 v[38:41], v[170:173], v[194:197], 0
	v_mfma_f32_16x16x32_bf16 v[34:37], v[178:181], v[194:197], 0
	v_mfma_f32_16x16x32_bf16 v[22:25], v[170:173], v[206:209], 0
	v_mfma_f32_16x16x32_bf16 v[18:21], v[178:181], v[206:209], 0
	v_mfma_f32_16x16x32_bf16 v[6:9], v[170:173], v[214:217], 0
	v_mfma_f32_16x16x32_bf16 v[2:5], v[178:181], v[214:217], 0
	v_mfma_f32_16x16x32_bf16 v[54:57], v[174:177], v[190:193], v[54:57]
	v_mfma_f32_16x16x32_bf16 v[50:53], v[182:185], v[190:193], v[50:53]
	v_mfma_f32_16x16x32_bf16 v[38:41], v[174:177], v[198:201], v[38:41]
	v_mfma_f32_16x16x32_bf16 v[34:37], v[182:185], v[198:201], v[34:37]
	v_mfma_f32_16x16x32_bf16 v[22:25], v[174:177], v[210:213], v[22:25]
	v_mfma_f32_16x16x32_bf16 v[18:21], v[182:185], v[210:213], v[18:21]
	v_mfma_f32_16x16x32_bf16 v[6:9], v[174:177], v[218:221], v[6:9]
	v_mfma_f32_16x16x32_bf16 v[2:5], v[182:185], v[218:221], v[2:5]
	s_setprio 0
	s_barrier
	s_add_i32 s63, 0, 0x18000
	v_add_u32_e32 v153, s63, v149
	s_add_i32 s64, 0, 0x1c000
	ds_read_b128 v[154:157], v153
	ds_read_b128 v[158:161], v153 offset:1024
	ds_read_b128 v[162:165], v153 offset:2048
	ds_read_b128 v[166:169], v153 offset:3072
	v_add_u32_e32 v153, s64, v149
	ds_read_b128 v[170:173], v153
	ds_read_b128 v[174:177], v153 offset:1024
	ds_read_b128 v[178:181], v153 offset:2048
	ds_read_b128 v[182:185], v153 offset:3072
	s_add_u32 s36, s36, 0x40000
	s_addc_u32 s37, s37, 0
	s_mov_b32 m0, s35
	v_lshl_add_u64 v[226:227], s[36:37], 0, v[136:137]
	ds_read_b128 v[186:189], v152 offset:32768
	ds_read_b128 v[190:193], v152 offset:33792
	ds_read_b128 v[194:197], v152 offset:34816
	ds_read_b128 v[198:201], v152 offset:35840
	ds_read_b128 v[206:209], v152 offset:36864
	ds_read_b128 v[210:213], v152 offset:37888
	ds_read_b128 v[214:217], v152 offset:38912
	ds_read_b128 v[218:221], v152 offset:39936
	global_load_lds_dwordx4 v[226:227], off
	v_lshl_add_u64 v[226:227], s[36:37], 0, v[132:133]
	s_mov_b32 m0, s38
	s_nop 0
	global_load_lds_dwordx4 v[226:227], off
	s_waitcnt vmcnt(8) lgkmcnt(0)
	s_setprio 1
	s_barrier
	v_mfma_f32_16x16x32_bf16 v[126:129], v[154:157], v[186:189], v[126:129]
	v_mfma_f32_16x16x32_bf16 v[122:125], v[162:165], v[186:189], v[122:125]
	v_mfma_f32_16x16x32_bf16 v[110:113], v[154:157], v[194:197], v[110:113]
	v_mfma_f32_16x16x32_bf16 v[106:109], v[162:165], v[194:197], v[106:109]
	v_mfma_f32_16x16x32_bf16 v[94:97], v[154:157], v[206:209], v[94:97]
	v_mfma_f32_16x16x32_bf16 v[90:93], v[162:165], v[206:209], v[90:93]
	v_mfma_f32_16x16x32_bf16 v[78:81], v[154:157], v[214:217], v[78:81]
	v_mfma_f32_16x16x32_bf16 v[74:77], v[162:165], v[214:217], v[74:77]
	v_mfma_f32_16x16x32_bf16 v[126:129], v[158:161], v[190:193], v[126:129]
	v_mfma_f32_16x16x32_bf16 v[122:125], v[166:169], v[190:193], v[122:125]
	v_mfma_f32_16x16x32_bf16 v[110:113], v[158:161], v[198:201], v[110:113]
	v_mfma_f32_16x16x32_bf16 v[106:109], v[166:169], v[198:201], v[106:109]
	v_mfma_f32_16x16x32_bf16 v[94:97], v[158:161], v[210:213], v[94:97]
	v_mfma_f32_16x16x32_bf16 v[90:93], v[166:169], v[210:213], v[90:93]
	v_mfma_f32_16x16x32_bf16 v[78:81], v[158:161], v[218:221], v[78:81]
	v_mfma_f32_16x16x32_bf16 v[74:77], v[166:169], v[218:221], v[74:77]
	v_mfma_f32_16x16x32_bf16 v[118:121], v[170:173], v[186:189], v[118:121]
	v_mfma_f32_16x16x32_bf16 v[114:117], v[178:181], v[186:189], v[114:117]
	v_mfma_f32_16x16x32_bf16 v[102:105], v[170:173], v[194:197], v[102:105]
	v_mfma_f32_16x16x32_bf16 v[98:101], v[178:181], v[194:197], v[98:101]
	v_mfma_f32_16x16x32_bf16 v[86:89], v[170:173], v[206:209], v[86:89]
	v_mfma_f32_16x16x32_bf16 v[82:85], v[178:181], v[206:209], v[82:85]
	v_mfma_f32_16x16x32_bf16 v[70:73], v[170:173], v[214:217], v[70:73]
	v_mfma_f32_16x16x32_bf16 v[66:69], v[178:181], v[214:217], v[66:69]
	v_mfma_f32_16x16x32_bf16 v[118:121], v[174:177], v[190:193], v[118:121]
	v_mfma_f32_16x16x32_bf16 v[114:117], v[182:185], v[190:193], v[114:117]
	v_mfma_f32_16x16x32_bf16 v[102:105], v[174:177], v[198:201], v[102:105]
	v_mfma_f32_16x16x32_bf16 v[98:101], v[182:185], v[198:201], v[98:101]
	v_mfma_f32_16x16x32_bf16 v[86:89], v[174:177], v[210:213], v[86:89]
	v_mfma_f32_16x16x32_bf16 v[82:85], v[182:185], v[210:213], v[82:85]
	v_mfma_f32_16x16x32_bf16 v[70:73], v[174:177], v[218:221], v[70:73]
	v_mfma_f32_16x16x32_bf16 v[66:69], v[182:185], v[218:221], v[66:69]
	s_setprio 0
	s_barrier
	ds_read_b128 v[186:189], v152 offset:49152
	ds_read_b128 v[190:193], v152 offset:50176
	ds_read_b128 v[194:197], v152 offset:51200
	ds_read_b128 v[198:201], v152 offset:52224
	ds_read_b128 v[206:209], v152 offset:53248
	ds_read_b128 v[210:213], v152 offset:54272
	ds_read_b128 v[214:217], v152 offset:55296
	ds_read_b128 v[218:221], v152 offset:56320
	s_add_i32 s36, s63, s12
	s_mov_b32 m0, s36
	v_lshl_add_u64 v[146:147], v[146:147], 0, s[8:9]
	global_load_lds_dwordx4 v[146:147], off
	s_add_i32 m0, s36, 0x2000
	s_add_u32 s30, s30, 0x40080
	v_lshl_add_u64 v[146:147], v[202:203], 0, s[8:9]
	s_addc_u32 s31, s31, 0
	s_add_i32 s36, s64, s12
	global_load_lds_dwordx4 v[146:147], off
	v_lshl_add_u64 v[146:147], s[30:31], 0, v[134:135]
	s_mov_b32 m0, s36
	s_nop 0
	global_load_lds_dwordx4 v[146:147], off
	v_lshl_add_u64 v[146:147], s[30:31], 0, v[130:131]
	s_add_i32 m0, s36, 0x2000
	s_nop 0
	global_load_lds_dwordx4 v[146:147], off
	v_lshl_add_u64 v[146:147], v[222:223], 0, s[8:9]
	s_mov_b32 m0, s42
	s_nop 0
	global_load_lds_dwordx4 v[146:147], off
	v_lshl_add_u64 v[146:147], v[224:225], 0, s[8:9]
	s_mov_b32 m0, s43
	s_nop 0
	global_load_lds_dwordx4 v[146:147], off
	s_waitcnt vmcnt(8) lgkmcnt(0)
	s_setprio 1
	s_barrier
	v_mfma_f32_16x16x32_bf16 v[62:65], v[154:157], v[186:189], v[62:65]
	v_mfma_f32_16x16x32_bf16 v[58:61], v[162:165], v[186:189], v[58:61]
	v_mfma_f32_16x16x32_bf16 v[46:49], v[154:157], v[194:197], v[46:49]
	v_mfma_f32_16x16x32_bf16 v[42:45], v[162:165], v[194:197], v[42:45]
	v_mfma_f32_16x16x32_bf16 v[30:33], v[154:157], v[206:209], v[30:33]
	v_mfma_f32_16x16x32_bf16 v[26:29], v[162:165], v[206:209], v[26:29]
	v_mfma_f32_16x16x32_bf16 v[14:17], v[154:157], v[214:217], v[14:17]
	v_mfma_f32_16x16x32_bf16 v[10:13], v[162:165], v[214:217], v[10:13]
	v_mfma_f32_16x16x32_bf16 v[62:65], v[158:161], v[190:193], v[62:65]
	v_mfma_f32_16x16x32_bf16 v[58:61], v[166:169], v[190:193], v[58:61]
	v_mfma_f32_16x16x32_bf16 v[46:49], v[158:161], v[198:201], v[46:49]
	v_mfma_f32_16x16x32_bf16 v[42:45], v[166:169], v[198:201], v[42:45]
	v_mfma_f32_16x16x32_bf16 v[30:33], v[158:161], v[210:213], v[30:33]
	v_mfma_f32_16x16x32_bf16 v[26:29], v[166:169], v[210:213], v[26:29]
	v_mfma_f32_16x16x32_bf16 v[14:17], v[158:161], v[218:221], v[14:17]
	v_mfma_f32_16x16x32_bf16 v[10:13], v[166:169], v[218:221], v[10:13]
	v_mfma_f32_16x16x32_bf16 v[54:57], v[170:173], v[186:189], v[54:57]
	v_mfma_f32_16x16x32_bf16 v[50:53], v[178:181], v[186:189], v[50:53]
	v_mfma_f32_16x16x32_bf16 v[38:41], v[170:173], v[194:197], v[38:41]
	v_mfma_f32_16x16x32_bf16 v[34:37], v[178:181], v[194:197], v[34:37]
	v_mfma_f32_16x16x32_bf16 v[22:25], v[170:173], v[206:209], v[22:25]
	v_mfma_f32_16x16x32_bf16 v[18:21], v[178:181], v[206:209], v[18:21]
	v_mfma_f32_16x16x32_bf16 v[6:9], v[170:173], v[214:217], v[6:9]
	v_mfma_f32_16x16x32_bf16 v[2:5], v[178:181], v[214:217], v[2:5]
	v_mfma_f32_16x16x32_bf16 v[54:57], v[174:177], v[190:193], v[54:57]
	v_mfma_f32_16x16x32_bf16 v[50:53], v[182:185], v[190:193], v[50:53]
	v_mfma_f32_16x16x32_bf16 v[38:41], v[174:177], v[198:201], v[38:41]
	v_mfma_f32_16x16x32_bf16 v[34:37], v[182:185], v[198:201], v[34:37]
	v_mfma_f32_16x16x32_bf16 v[22:25], v[174:177], v[210:213], v[22:25]
	v_mfma_f32_16x16x32_bf16 v[18:21], v[182:185], v[210:213], v[18:21]
	v_mfma_f32_16x16x32_bf16 v[6:9], v[174:177], v[218:221], v[6:9]
	v_mfma_f32_16x16x32_bf16 v[2:5], v[182:185], v[218:221], v[2:5]
	s_setprio 0
	s_barrier
	s_add_i32 s62, s62, 2
	s_add_u32 s28, s28, 0x100
	s_addc_u32 s29, s29, 0
	s_add_u32 s50, s50, 0x100
	s_addc_u32 s51, s51, 0
	s_cmp_gt_u32 s62, 13
.LBB0_1619:
	ds_read_b128 v[154:157], v150
	ds_read_b128 v[158:161], v150 offset:1024
	ds_read_b128 v[162:165], v150 offset:2048
	ds_read_b128 v[166:169], v150 offset:3072
	ds_read_b128 v[170:173], v151
	ds_read_b128 v[174:177], v151 offset:1024
	ds_read_b128 v[178:181], v151 offset:2048
	ds_read_b128 v[182:185], v151 offset:3072
	ds_read_b128 v[186:189], v152
	ds_read_b128 v[190:193], v152 offset:1024
	ds_read_b128 v[194:197], v152 offset:2048
	ds_read_b128 v[198:201], v152 offset:3072
	ds_read_b128 v[206:209], v152 offset:4096
	ds_read_b128 v[210:213], v152 offset:5120
	ds_read_b128 v[214:217], v152 offset:6144
	ds_read_b128 v[218:221], v152 offset:7168
	s_add_u32 s30, s28, 0xfffc0080
	s_addc_u32 s31, s29, -1
	s_cmp_eq_u32 s62, 12
	s_cselect_b32 s37, s14, s31
	s_cselect_b32 s36, s15, s30
	s_cselect_b32 s31, s17, s51
	s_cselect_b32 s30, s49, s50
	s_add_i32 m0, s19, 0xc000
	v_lshl_add_u64 v[146:147], s[28:29], 0, v[138:139]
	global_load_lds_dwordx4 v[146:147], off
	v_lshl_add_u64 v[146:147], s[28:29], 0, v[140:141]
	s_add_i32 m0, s19, 0xe000
	s_nop 0
	global_load_lds_dwordx4 v[146:147], off
	s_waitcnt vmcnt(8) lgkmcnt(0)
	s_setprio 1
	s_barrier
	v_mfma_f32_16x16x32_bf16 v[126:129], v[154:157], v[186:189], v[126:129]
	v_mfma_f32_16x16x32_bf16 v[122:125], v[162:165], v[186:189], v[122:125]
	v_mfma_f32_16x16x32_bf16 v[110:113], v[154:157], v[194:197], v[110:113]
	v_mfma_f32_16x16x32_bf16 v[106:109], v[162:165], v[194:197], v[106:109]
	v_mfma_f32_16x16x32_bf16 v[94:97], v[154:157], v[206:209], v[94:97]
	v_mfma_f32_16x16x32_bf16 v[90:93], v[162:165], v[206:209], v[90:93]
	v_mfma_f32_16x16x32_bf16 v[78:81], v[154:157], v[214:217], v[78:81]
	v_mfma_f32_16x16x32_bf16 v[74:77], v[162:165], v[214:217], v[74:77]
	v_mfma_f32_16x16x32_bf16 v[126:129], v[158:161], v[190:193], v[126:129]
	v_mfma_f32_16x16x32_bf16 v[122:125], v[166:169], v[190:193], v[122:125]
	v_mfma_f32_16x16x32_bf16 v[110:113], v[158:161], v[198:201], v[110:113]
	v_mfma_f32_16x16x32_bf16 v[106:109], v[166:169], v[198:201], v[106:109]
	v_mfma_f32_16x16x32_bf16 v[94:97], v[158:161], v[210:213], v[94:97]
	v_mfma_f32_16x16x32_bf16 v[90:93], v[166:169], v[210:213], v[90:93]
	v_mfma_f32_16x16x32_bf16 v[78:81], v[158:161], v[218:221], v[78:81]
	v_mfma_f32_16x16x32_bf16 v[74:77], v[166:169], v[218:221], v[74:77]
	v_mfma_f32_16x16x32_bf16 v[118:121], v[170:173], v[186:189], v[118:121]
	v_mfma_f32_16x16x32_bf16 v[114:117], v[178:181], v[186:189], v[114:117]
	v_mfma_f32_16x16x32_bf16 v[102:105], v[170:173], v[194:197], v[102:105]
	v_mfma_f32_16x16x32_bf16 v[98:101], v[178:181], v[194:197], v[98:101]
	v_mfma_f32_16x16x32_bf16 v[86:89], v[170:173], v[206:209], v[86:89]
	v_mfma_f32_16x16x32_bf16 v[82:85], v[178:181], v[206:209], v[82:85]
	v_mfma_f32_16x16x32_bf16 v[70:73], v[170:173], v[214:217], v[70:73]
	v_mfma_f32_16x16x32_bf16 v[66:69], v[178:181], v[214:217], v[66:69]
	v_mfma_f32_16x16x32_bf16 v[118:121], v[174:177], v[190:193], v[118:121]
	v_mfma_f32_16x16x32_bf16 v[114:117], v[182:185], v[190:193], v[114:117]
	v_mfma_f32_16x16x32_bf16 v[102:105], v[174:177], v[198:201], v[102:105]
	v_mfma_f32_16x16x32_bf16 v[98:101], v[182:185], v[198:201], v[98:101]
	v_mfma_f32_16x16x32_bf16 v[86:89], v[174:177], v[210:213], v[86:89]
	v_mfma_f32_16x16x32_bf16 v[82:85], v[182:185], v[210:213], v[82:85]
	v_mfma_f32_16x16x32_bf16 v[70:73], v[174:177], v[218:221], v[70:73]
	v_mfma_f32_16x16x32_bf16 v[66:69], v[182:185], v[218:221], v[66:69]
	s_setprio 0
	s_barrier
	ds_read_b128 v[186:189], v152 offset:16384
	ds_read_b128 v[190:193], v152 offset:17408
	ds_read_b128 v[194:197], v152 offset:18432
	ds_read_b128 v[198:201], v152 offset:19456
	ds_read_b128 v[206:209], v152 offset:20480
	ds_read_b128 v[210:213], v152 offset:21504
	ds_read_b128 v[214:217], v152 offset:22528
	ds_read_b128 v[218:221], v152 offset:23552
	s_add_i32 s63, s45, s12
	s_mov_b32 m0, s63
	v_lshl_add_u64 v[146:147], s[30:31], 0, v[134:135]
	global_load_lds_dwordx4 v[146:147], off
	s_add_i32 m0, s63, 0x2000
	s_add_u32 s64, s30, 0x40000
	v_lshl_add_u64 v[202:203], s[30:31], 0, v[130:131]
	s_addc_u32 s65, s31, 0
	s_add_i32 s63, s46, s12
	global_load_lds_dwordx4 v[202:203], off
	v_lshl_add_u64 v[222:223], s[64:65], 0, v[134:135]
	s_mov_b32 m0, s63
	v_lshl_add_u64 v[224:225], s[36:37], 0, v[132:133]
	global_load_lds_dwordx4 v[222:223], off
	v_lshl_add_u64 v[222:223], s[64:65], 0, v[130:131]
	s_add_i32 m0, s63, 0x2000
	s_nop 0
	global_load_lds_dwordx4 v[222:223], off
	v_lshl_add_u64 v[222:223], s[36:37], 0, v[136:137]
	s_mov_b32 m0, s19
	s_nop 0
	global_load_lds_dwordx4 v[222:223], off
	s_mov_b32 m0, s33
	s_nop 0
	global_load_lds_dwordx4 v[224:225], off
	s_waitcnt vmcnt(8) lgkmcnt(0)
	s_setprio 1
	s_barrier
	v_mfma_f32_16x16x32_bf16 v[62:65], v[154:157], v[186:189], v[62:65]
	v_mfma_f32_16x16x32_bf16 v[58:61], v[162:165], v[186:189], v[58:61]
	v_mfma_f32_16x16x32_bf16 v[46:49], v[154:157], v[194:197], v[46:49]
	v_mfma_f32_16x16x32_bf16 v[42:45], v[162:165], v[194:197], v[42:45]
	v_mfma_f32_16x16x32_bf16 v[30:33], v[154:157], v[206:209], v[30:33]
	v_mfma_f32_16x16x32_bf16 v[26:29], v[162:165], v[206:209], v[26:29]
	v_mfma_f32_16x16x32_bf16 v[14:17], v[154:157], v[214:217], v[14:17]
	v_mfma_f32_16x16x32_bf16 v[10:13], v[162:165], v[214:217], v[10:13]
	v_mfma_f32_16x16x32_bf16 v[62:65], v[158:161], v[190:193], v[62:65]
	v_mfma_f32_16x16x32_bf16 v[58:61], v[166:169], v[190:193], v[58:61]
	v_mfma_f32_16x16x32_bf16 v[46:49], v[158:161], v[198:201], v[46:49]
	v_mfma_f32_16x16x32_bf16 v[42:45], v[166:169], v[198:201], v[42:45]
	v_mfma_f32_16x16x32_bf16 v[30:33], v[158:161], v[210:213], v[30:33]
	v_mfma_f32_16x16x32_bf16 v[26:29], v[166:169], v[210:213], v[26:29]
	v_mfma_f32_16x16x32_bf16 v[14:17], v[158:161], v[218:221], v[14:17]
	v_mfma_f32_16x16x32_bf16 v[10:13], v[166:169], v[218:221], v[10:13]
	v_mfma_f32_16x16x32_bf16 v[54:57], v[170:173], v[186:189], v[54:57]
	v_mfma_f32_16x16x32_bf16 v[50:53], v[178:181], v[186:189], v[50:53]
	v_mfma_f32_16x16x32_bf16 v[38:41], v[170:173], v[194:197], v[38:41]
	v_mfma_f32_16x16x32_bf16 v[34:37], v[178:181], v[194:197], v[34:37]
	v_mfma_f32_16x16x32_bf16 v[22:25], v[170:173], v[206:209], v[22:25]
	v_mfma_f32_16x16x32_bf16 v[18:21], v[178:181], v[206:209], v[18:21]
	v_mfma_f32_16x16x32_bf16 v[6:9], v[170:173], v[214:217], v[6:9]
	v_mfma_f32_16x16x32_bf16 v[2:5], v[178:181], v[214:217], v[2:5]
	v_mfma_f32_16x16x32_bf16 v[54:57], v[174:177], v[190:193], v[54:57]
	v_mfma_f32_16x16x32_bf16 v[50:53], v[182:185], v[190:193], v[50:53]
	v_mfma_f32_16x16x32_bf16 v[38:41], v[174:177], v[198:201], v[38:41]
	v_mfma_f32_16x16x32_bf16 v[34:37], v[182:185], v[198:201], v[34:37]
	v_mfma_f32_16x16x32_bf16 v[22:25], v[174:177], v[210:213], v[22:25]
	v_mfma_f32_16x16x32_bf16 v[18:21], v[182:185], v[210:213], v[18:21]
	v_mfma_f32_16x16x32_bf16 v[6:9], v[174:177], v[218:221], v[6:9]
	v_mfma_f32_16x16x32_bf16 v[2:5], v[182:185], v[218:221], v[2:5]
	s_setprio 0
	s_barrier
	s_add_i32 s63, 0, 0x18000
	v_add_u32_e32 v153, s63, v149
	s_add_i32 s64, 0, 0x1c000
	ds_read_b128 v[154:157], v153
	ds_read_b128 v[158:161], v153 offset:1024
	ds_read_b128 v[162:165], v153 offset:2048
	ds_read_b128 v[166:169], v153 offset:3072
	v_add_u32_e32 v153, s64, v149
	ds_read_b128 v[170:173], v153
	ds_read_b128 v[174:177], v153 offset:1024
	ds_read_b128 v[178:181], v153 offset:2048
	ds_read_b128 v[182:185], v153 offset:3072
	s_add_u32 s36, s36, 0x40000
	s_addc_u32 s37, s37, 0
	s_mov_b32 m0, s35
	v_lshl_add_u64 v[226:227], s[36:37], 0, v[136:137]
	ds_read_b128 v[186:189], v152 offset:32768
	ds_read_b128 v[190:193], v152 offset:33792
	ds_read_b128 v[194:197], v152 offset:34816
	ds_read_b128 v[198:201], v152 offset:35840
	ds_read_b128 v[206:209], v152 offset:36864
	ds_read_b128 v[210:213], v152 offset:37888
	ds_read_b128 v[214:217], v152 offset:38912
	ds_read_b128 v[218:221], v152 offset:39936
	global_load_lds_dwordx4 v[226:227], off
	v_lshl_add_u64 v[226:227], s[36:37], 0, v[132:133]
	s_mov_b32 m0, s38
	s_nop 0
	global_load_lds_dwordx4 v[226:227], off
	s_waitcnt vmcnt(8) lgkmcnt(0)
	s_setprio 1
	s_barrier
	v_mfma_f32_16x16x32_bf16 v[126:129], v[154:157], v[186:189], v[126:129]
	v_mfma_f32_16x16x32_bf16 v[122:125], v[162:165], v[186:189], v[122:125]
	v_mfma_f32_16x16x32_bf16 v[110:113], v[154:157], v[194:197], v[110:113]
	v_mfma_f32_16x16x32_bf16 v[106:109], v[162:165], v[194:197], v[106:109]
	v_mfma_f32_16x16x32_bf16 v[94:97], v[154:157], v[206:209], v[94:97]
	v_mfma_f32_16x16x32_bf16 v[90:93], v[162:165], v[206:209], v[90:93]
	v_mfma_f32_16x16x32_bf16 v[78:81], v[154:157], v[214:217], v[78:81]
	v_mfma_f32_16x16x32_bf16 v[74:77], v[162:165], v[214:217], v[74:77]
	v_mfma_f32_16x16x32_bf16 v[126:129], v[158:161], v[190:193], v[126:129]
	v_mfma_f32_16x16x32_bf16 v[122:125], v[166:169], v[190:193], v[122:125]
	v_mfma_f32_16x16x32_bf16 v[110:113], v[158:161], v[198:201], v[110:113]
	v_mfma_f32_16x16x32_bf16 v[106:109], v[166:169], v[198:201], v[106:109]
	v_mfma_f32_16x16x32_bf16 v[94:97], v[158:161], v[210:213], v[94:97]
	v_mfma_f32_16x16x32_bf16 v[90:93], v[166:169], v[210:213], v[90:93]
	v_mfma_f32_16x16x32_bf16 v[78:81], v[158:161], v[218:221], v[78:81]
	v_mfma_f32_16x16x32_bf16 v[74:77], v[166:169], v[218:221], v[74:77]
	v_mfma_f32_16x16x32_bf16 v[118:121], v[170:173], v[186:189], v[118:121]
	v_mfma_f32_16x16x32_bf16 v[114:117], v[178:181], v[186:189], v[114:117]
	v_mfma_f32_16x16x32_bf16 v[102:105], v[170:173], v[194:197], v[102:105]
	v_mfma_f32_16x16x32_bf16 v[98:101], v[178:181], v[194:197], v[98:101]
	v_mfma_f32_16x16x32_bf16 v[86:89], v[170:173], v[206:209], v[86:89]
	v_mfma_f32_16x16x32_bf16 v[82:85], v[178:181], v[206:209], v[82:85]
	v_mfma_f32_16x16x32_bf16 v[70:73], v[170:173], v[214:217], v[70:73]
	v_mfma_f32_16x16x32_bf16 v[66:69], v[178:181], v[214:217], v[66:69]
	v_mfma_f32_16x16x32_bf16 v[118:121], v[174:177], v[190:193], v[118:121]
	v_mfma_f32_16x16x32_bf16 v[114:117], v[182:185], v[190:193], v[114:117]
	v_mfma_f32_16x16x32_bf16 v[102:105], v[174:177], v[198:201], v[102:105]
	v_mfma_f32_16x16x32_bf16 v[98:101], v[182:185], v[198:201], v[98:101]
	v_mfma_f32_16x16x32_bf16 v[86:89], v[174:177], v[210:213], v[86:89]
	v_mfma_f32_16x16x32_bf16 v[82:85], v[182:185], v[210:213], v[82:85]
	v_mfma_f32_16x16x32_bf16 v[70:73], v[174:177], v[218:221], v[70:73]
	v_mfma_f32_16x16x32_bf16 v[66:69], v[182:185], v[218:221], v[66:69]
	s_setprio 0
	s_barrier
	ds_read_b128 v[186:189], v152 offset:49152
	ds_read_b128 v[190:193], v152 offset:50176
	ds_read_b128 v[194:197], v152 offset:51200
	ds_read_b128 v[198:201], v152 offset:52224
	ds_read_b128 v[206:209], v152 offset:53248
	ds_read_b128 v[210:213], v152 offset:54272
	ds_read_b128 v[214:217], v152 offset:55296
	ds_read_b128 v[218:221], v152 offset:56320
	s_add_i32 s36, s63, s12
	s_mov_b32 m0, s36
	v_lshl_add_u64 v[146:147], v[146:147], 0, s[8:9]
	global_load_lds_dwordx4 v[146:147], off
	s_add_i32 m0, s36, 0x2000
	s_add_u32 s30, s30, 0x40080
	v_lshl_add_u64 v[146:147], v[202:203], 0, s[8:9]
	s_addc_u32 s31, s31, 0
	s_add_i32 s36, s64, s12
	global_load_lds_dwordx4 v[146:147], off
	v_lshl_add_u64 v[146:147], s[30:31], 0, v[134:135]
	s_mov_b32 m0, s36
	s_nop 0
	global_load_lds_dwordx4 v[146:147], off
	v_lshl_add_u64 v[146:147], s[30:31], 0, v[130:131]
	s_add_i32 m0, s36, 0x2000
	s_nop 0
	global_load_lds_dwordx4 v[146:147], off
	v_lshl_add_u64 v[146:147], v[222:223], 0, s[8:9]
	s_mov_b32 m0, s42
	s_nop 0
	global_load_lds_dwordx4 v[146:147], off
	v_lshl_add_u64 v[146:147], v[224:225], 0, s[8:9]
	s_mov_b32 m0, s43
	s_nop 0
	global_load_lds_dwordx4 v[146:147], off
	s_waitcnt vmcnt(8) lgkmcnt(0)
	s_setprio 1
	s_barrier
	v_mfma_f32_16x16x32_bf16 v[62:65], v[154:157], v[186:189], v[62:65]
	v_mfma_f32_16x16x32_bf16 v[58:61], v[162:165], v[186:189], v[58:61]
	v_mfma_f32_16x16x32_bf16 v[46:49], v[154:157], v[194:197], v[46:49]
	v_mfma_f32_16x16x32_bf16 v[42:45], v[162:165], v[194:197], v[42:45]
	v_mfma_f32_16x16x32_bf16 v[30:33], v[154:157], v[206:209], v[30:33]
	v_mfma_f32_16x16x32_bf16 v[26:29], v[162:165], v[206:209], v[26:29]
	v_mfma_f32_16x16x32_bf16 v[14:17], v[154:157], v[214:217], v[14:17]
	v_mfma_f32_16x16x32_bf16 v[10:13], v[162:165], v[214:217], v[10:13]
	v_mfma_f32_16x16x32_bf16 v[62:65], v[158:161], v[190:193], v[62:65]
	v_mfma_f32_16x16x32_bf16 v[58:61], v[166:169], v[190:193], v[58:61]
	v_mfma_f32_16x16x32_bf16 v[46:49], v[158:161], v[198:201], v[46:49]
	v_mfma_f32_16x16x32_bf16 v[42:45], v[166:169], v[198:201], v[42:45]
	v_mfma_f32_16x16x32_bf16 v[30:33], v[158:161], v[210:213], v[30:33]
	v_mfma_f32_16x16x32_bf16 v[26:29], v[166:169], v[210:213], v[26:29]
	v_mfma_f32_16x16x32_bf16 v[14:17], v[158:161], v[218:221], v[14:17]
	v_mfma_f32_16x16x32_bf16 v[10:13], v[166:169], v[218:221], v[10:13]
	v_mfma_f32_16x16x32_bf16 v[54:57], v[170:173], v[186:189], v[54:57]
	v_mfma_f32_16x16x32_bf16 v[50:53], v[178:181], v[186:189], v[50:53]
	v_mfma_f32_16x16x32_bf16 v[38:41], v[170:173], v[194:197], v[38:41]
	v_mfma_f32_16x16x32_bf16 v[34:37], v[178:181], v[194:197], v[34:37]
	v_mfma_f32_16x16x32_bf16 v[22:25], v[170:173], v[206:209], v[22:25]
	v_mfma_f32_16x16x32_bf16 v[18:21], v[178:181], v[206:209], v[18:21]
	v_mfma_f32_16x16x32_bf16 v[6:9], v[170:173], v[214:217], v[6:9]
	v_mfma_f32_16x16x32_bf16 v[2:5], v[178:181], v[214:217], v[2:5]
	v_mfma_f32_16x16x32_bf16 v[54:57], v[174:177], v[190:193], v[54:57]
	v_mfma_f32_16x16x32_bf16 v[50:53], v[182:185], v[190:193], v[50:53]
	v_mfma_f32_16x16x32_bf16 v[38:41], v[174:177], v[198:201], v[38:41]
	v_mfma_f32_16x16x32_bf16 v[34:37], v[182:185], v[198:201], v[34:37]
	v_mfma_f32_16x16x32_bf16 v[22:25], v[174:177], v[210:213], v[22:25]
	v_mfma_f32_16x16x32_bf16 v[18:21], v[182:185], v[210:213], v[18:21]
	v_mfma_f32_16x16x32_bf16 v[6:9], v[174:177], v[218:221], v[6:9]
	v_mfma_f32_16x16x32_bf16 v[2:5], v[182:185], v[218:221], v[2:5]
	s_setprio 0
	s_barrier
	s_add_i32 s62, s62, 2
	s_add_u32 s28, s28, 0x100
	s_addc_u32 s29, s29, 0
	s_add_u32 s50, s50, 0x100
	s_addc_u32 s51, s51, 0
	s_cmp_gt_u32 s62, 13
	s_cbranch_scc0 .LBB0_1619
	s_and_b64 vcc, exec, s[10:11]
	s_cbranch_vccz .LBB0_1622
	s_barrier

.LBB0_1707:
	v_readlane_b32 s46, v249, 32
	v_readlane_b32 s47, v249, 33
	s_add_u32 s46, s46, s42
	s_addc_u32 s47, s47, s43
	s_and_b64 s[48:49], s[44:45], exec
	s_cselect_b32 s34, s47, s51
	s_cselect_b32 s66, s46, s50
	s_add_u32 s48, s35, s40
	s_addc_u32 s49, s70, s41
	s_and_b64 s[64:65], s[44:45], exec
	s_cselect_b32 s67, s49, s63
	s_cselect_b32 s68, s48, s62
	s_add_i32 s69, s7, -2
	s_add_u32 s50, s50, 0x100080
	s_addc_u32 s51, s51, 0
	s_add_u32 s91, s62, 0x100
	s_addc_u32 s92, s63, 0
	s_mov_b32 s62, 0
	s_waitcnt vmcnt(0)
	ds_read_b128 v[130:133], v168
	ds_read_b128 v[134:137], v168 offset:1024
	ds_read_b128 v[138:141], v168 offset:2048
	ds_read_b128 v[142:145], v168 offset:3072
	ds_read_b128 v[162:165], v169
	ds_read_b128 v[172:175], v169 offset:1024
	ds_read_b128 v[176:179], v169 offset:2048
	ds_read_b128 v[180:183], v169 offset:3072
	ds_read_b128 v[184:187], v170
	ds_read_b128 v[188:191], v170 offset:1024
	ds_read_b128 v[192:195], v170 offset:2048
	ds_read_b128 v[196:199], v170 offset:3072
	ds_read_b128 v[200:203], v170 offset:4096
	ds_read_b128 v[206:209], v170 offset:5120
	ds_read_b128 v[210:213], v170 offset:6144
	ds_read_b128 v[214:217], v170 offset:7168
	s_add_i32 s93, s62, 2
	s_add_u32 s63, s50, 0xfff00080
	s_addc_u32 s64, s51, -1
	s_cmp_eq_u32 s69, s62
	s_cselect_b32 s62, s68, s91
	s_cselect_b32 s65, s34, s64
	s_cselect_b32 s64, s66, s63
	s_cselect_b32 s63, s67, s92
	s_add_i32 m0, s12, 0xc000
	v_lshl_add_u64 v[218:219], s[50:51], 0, v[156:157]
	global_load_lds_dwordx4 v[218:219], off
	v_lshl_add_u64 v[218:219], s[50:51], 0, v[158:159]
	s_add_i32 m0, s12, 0xe000
	s_nop 0
	global_load_lds_dwordx4 v[218:219], off
	s_waitcnt vmcnt(8) lgkmcnt(0)
	s_setprio 1
	s_barrier
	v_mfma_f32_16x16x32_bf16 v[126:129], v[130:133], v[184:187], 0
	v_mfma_f32_16x16x32_bf16 v[122:125], v[138:141], v[184:187], 0
	v_mfma_f32_16x16x32_bf16 v[110:113], v[130:133], v[192:195], 0
	v_mfma_f32_16x16x32_bf16 v[106:109], v[138:141], v[192:195], 0
	v_mfma_f32_16x16x32_bf16 v[98:101], v[130:133], v[200:203], 0
	v_mfma_f32_16x16x32_bf16 v[90:93], v[138:141], v[200:203], 0
	v_mfma_f32_16x16x32_bf16 v[82:85], v[130:133], v[210:213], 0
	v_mfma_f32_16x16x32_bf16 v[74:77], v[138:141], v[210:213], 0
	v_mfma_f32_16x16x32_bf16 v[126:129], v[134:137], v[188:191], v[126:129]
	v_mfma_f32_16x16x32_bf16 v[122:125], v[142:145], v[188:191], v[122:125]
	v_mfma_f32_16x16x32_bf16 v[110:113], v[134:137], v[196:199], v[110:113]
	v_mfma_f32_16x16x32_bf16 v[106:109], v[142:145], v[196:199], v[106:109]
	v_mfma_f32_16x16x32_bf16 v[98:101], v[134:137], v[206:209], v[98:101]
	v_mfma_f32_16x16x32_bf16 v[90:93], v[142:145], v[206:209], v[90:93]
	v_mfma_f32_16x16x32_bf16 v[82:85], v[134:137], v[214:217], v[82:85]
	v_mfma_f32_16x16x32_bf16 v[74:77], v[142:145], v[214:217], v[74:77]
	v_mfma_f32_16x16x32_bf16 v[118:121], v[162:165], v[184:187], 0
	v_mfma_f32_16x16x32_bf16 v[114:117], v[176:179], v[184:187], 0
	v_mfma_f32_16x16x32_bf16 v[102:105], v[162:165], v[192:195], 0
	v_mfma_f32_16x16x32_bf16 v[94:97], v[176:179], v[192:195], 0
	v_mfma_f32_16x16x32_bf16 v[86:89], v[162:165], v[200:203], 0
	v_mfma_f32_16x16x32_bf16 v[78:81], v[176:179], v[200:203], 0
	v_mfma_f32_16x16x32_bf16 v[70:73], v[162:165], v[210:213], 0
	v_mfma_f32_16x16x32_bf16 v[66:69], v[176:179], v[210:213], 0
	v_mfma_f32_16x16x32_bf16 v[118:121], v[172:175], v[188:191], v[118:121]
	v_mfma_f32_16x16x32_bf16 v[114:117], v[180:183], v[188:191], v[114:117]
	v_mfma_f32_16x16x32_bf16 v[102:105], v[172:175], v[196:199], v[102:105]
	v_mfma_f32_16x16x32_bf16 v[94:97], v[180:183], v[196:199], v[94:97]
	v_mfma_f32_16x16x32_bf16 v[86:89], v[172:175], v[206:209], v[86:89]
	v_mfma_f32_16x16x32_bf16 v[78:81], v[180:183], v[206:209], v[78:81]
	v_mfma_f32_16x16x32_bf16 v[70:73], v[172:175], v[214:217], v[70:73]
	v_mfma_f32_16x16x32_bf16 v[66:69], v[180:183], v[214:217], v[66:69]
	s_setprio 0
	s_barrier
	ds_read_b128 v[184:187], v170 offset:16384
	ds_read_b128 v[188:191], v170 offset:17408
	ds_read_b128 v[192:195], v170 offset:18432
	ds_read_b128 v[196:199], v170 offset:19456
	ds_read_b128 v[200:203], v170 offset:20480
	ds_read_b128 v[206:209], v170 offset:21504
	ds_read_b128 v[210:213], v170 offset:22528
	ds_read_b128 v[214:217], v170 offset:23552
	s_add_i32 s94, s31, s2
	s_mov_b32 m0, s94
	v_lshl_add_u64 v[218:219], s[62:63], 0, v[148:149]
	global_load_lds_dwordx4 v[218:219], off
	s_add_i32 m0, s94, 0x2000
	s_add_u32 s94, s62, 0x100000
	v_lshl_add_u64 v[220:221], s[62:63], 0, v[152:153]
	s_addc_u32 s95, s63, 0
	s_add_i32 s96, s82, s2
	global_load_lds_dwordx4 v[220:221], off
	v_lshl_add_u64 v[222:223], s[94:95], 0, v[148:149]
	s_mov_b32 m0, s96
	v_lshl_add_u64 v[224:225], s[64:65], 0, v[150:151]
	global_load_lds_dwordx4 v[222:223], off
	v_lshl_add_u64 v[222:223], s[94:95], 0, v[152:153]
	s_add_i32 m0, s96, 0x2000
	s_nop 0
	global_load_lds_dwordx4 v[222:223], off
	v_lshl_add_u64 v[222:223], s[64:65], 0, v[146:147]
	s_mov_b32 m0, s12
	s_nop 0
	global_load_lds_dwordx4 v[222:223], off
	s_mov_b32 m0, s13
	s_nop 0
	global_load_lds_dwordx4 v[224:225], off
	s_waitcnt vmcnt(8) lgkmcnt(0)
	s_setprio 1
	s_barrier
	v_mfma_f32_16x16x32_bf16 v[62:65], v[130:133], v[184:187], 0
	v_mfma_f32_16x16x32_bf16 v[58:61], v[138:141], v[184:187], 0
	v_mfma_f32_16x16x32_bf16 v[50:53], v[130:133], v[192:195], 0
	v_mfma_f32_16x16x32_bf16 v[42:45], v[138:141], v[192:195], 0
	v_mfma_f32_16x16x32_bf16 v[34:37], v[130:133], v[200:203], 0
	v_mfma_f32_16x16x32_bf16 v[26:29], v[138:141], v[200:203], 0
	v_mfma_f32_16x16x32_bf16 v[18:21], v[130:133], v[210:213], 0
	v_mfma_f32_16x16x32_bf16 v[10:13], v[138:141], v[210:213], 0
	v_mfma_f32_16x16x32_bf16 v[62:65], v[134:137], v[188:191], v[62:65]
	v_mfma_f32_16x16x32_bf16 v[58:61], v[142:145], v[188:191], v[58:61]
	v_mfma_f32_16x16x32_bf16 v[50:53], v[134:137], v[196:199], v[50:53]
	v_mfma_f32_16x16x32_bf16 v[42:45], v[142:145], v[196:199], v[42:45]
	v_mfma_f32_16x16x32_bf16 v[34:37], v[134:137], v[206:209], v[34:37]
	v_mfma_f32_16x16x32_bf16 v[26:29], v[142:145], v[206:209], v[26:29]
	v_mfma_f32_16x16x32_bf16 v[18:21], v[134:137], v[214:217], v[18:21]
	v_mfma_f32_16x16x32_bf16 v[10:13], v[142:145], v[214:217], v[10:13]
	v_mfma_f32_16x16x32_bf16 v[54:57], v[162:165], v[184:187], 0
	v_mfma_f32_16x16x32_bf16 v[46:49], v[176:179], v[184:187], 0
	v_mfma_f32_16x16x32_bf16 v[38:41], v[162:165], v[192:195], 0
	v_mfma_f32_16x16x32_bf16 v[30:33], v[176:179], v[192:195], 0
	v_mfma_f32_16x16x32_bf16 v[22:25], v[162:165], v[200:203], 0
	v_mfma_f32_16x16x32_bf16 v[14:17], v[176:179], v[200:203], 0
	v_mfma_f32_16x16x32_bf16 v[6:9], v[162:165], v[210:213], 0
	v_mfma_f32_16x16x32_bf16 v[2:5], v[176:179], v[210:213], 0
	v_mfma_f32_16x16x32_bf16 v[54:57], v[172:175], v[188:191], v[54:57]
	v_mfma_f32_16x16x32_bf16 v[46:49], v[180:183], v[188:191], v[46:49]
	v_mfma_f32_16x16x32_bf16 v[38:41], v[172:175], v[196:199], v[38:41]
	v_mfma_f32_16x16x32_bf16 v[30:33], v[180:183], v[196:199], v[30:33]
	v_mfma_f32_16x16x32_bf16 v[22:25], v[172:175], v[206:209], v[22:25]
	v_mfma_f32_16x16x32_bf16 v[14:17], v[180:183], v[206:209], v[14:17]
	v_mfma_f32_16x16x32_bf16 v[6:9], v[172:175], v[214:217], v[6:9]
	v_mfma_f32_16x16x32_bf16 v[2:5], v[180:183], v[214:217], v[2:5]
	s_setprio 0
	s_barrier
	s_add_i32 s94, 0, 0x18000
	s_add_i32 s95, 0, 0x1c000
	v_add_u32_e32 v142, s94, v167
	v_add_u32_e32 v154, s95, v167
	ds_read_b128 v[130:133], v142
	ds_read_b128 v[134:137], v142 offset:1024
	ds_read_b128 v[138:141], v142 offset:2048
	ds_read_b128 v[142:145], v142 offset:3072
	ds_read_b128 v[162:165], v154
	ds_read_b128 v[172:175], v154 offset:1024
	ds_read_b128 v[176:179], v154 offset:2048
	ds_read_b128 v[180:183], v154 offset:3072
	s_add_u32 s64, s64, 0x100000
	s_addc_u32 s65, s65, 0
	s_mov_b32 m0, s18
	v_lshl_add_u64 v[226:227], s[64:65], 0, v[146:147]
	ds_read_b128 v[184:187], v170 offset:32768
	ds_read_b128 v[188:191], v170 offset:33792
	ds_read_b128 v[192:195], v170 offset:34816
	ds_read_b128 v[196:199], v170 offset:35840
	ds_read_b128 v[200:203], v170 offset:36864
	ds_read_b128 v[206:209], v170 offset:37888
	ds_read_b128 v[210:213], v170 offset:38912
	ds_read_b128 v[214:217], v170 offset:39936
	global_load_lds_dwordx4 v[226:227], off
	v_lshl_add_u64 v[226:227], s[64:65], 0, v[150:151]
	s_mov_b32 m0, s19
	s_nop 0
	global_load_lds_dwordx4 v[226:227], off
	s_waitcnt vmcnt(8) lgkmcnt(0)
	s_setprio 1
	s_barrier
	v_mfma_f32_16x16x32_bf16 v[126:129], v[130:133], v[184:187], v[126:129]
	v_mfma_f32_16x16x32_bf16 v[122:125], v[138:141], v[184:187], v[122:125]
	v_mfma_f32_16x16x32_bf16 v[110:113], v[130:133], v[192:195], v[110:113]
	v_mfma_f32_16x16x32_bf16 v[106:109], v[138:141], v[192:195], v[106:109]
	v_mfma_f32_16x16x32_bf16 v[98:101], v[130:133], v[200:203], v[98:101]
	v_mfma_f32_16x16x32_bf16 v[90:93], v[138:141], v[200:203], v[90:93]
	v_mfma_f32_16x16x32_bf16 v[82:85], v[130:133], v[210:213], v[82:85]
	v_mfma_f32_16x16x32_bf16 v[74:77], v[138:141], v[210:213], v[74:77]
	v_mfma_f32_16x16x32_bf16 v[126:129], v[134:137], v[188:191], v[126:129]
	v_mfma_f32_16x16x32_bf16 v[122:125], v[142:145], v[188:191], v[122:125]
	v_mfma_f32_16x16x32_bf16 v[110:113], v[134:137], v[196:199], v[110:113]
	v_mfma_f32_16x16x32_bf16 v[106:109], v[142:145], v[196:199], v[106:109]
	v_mfma_f32_16x16x32_bf16 v[98:101], v[134:137], v[206:209], v[98:101]
	v_mfma_f32_16x16x32_bf16 v[90:93], v[142:145], v[206:209], v[90:93]
	v_mfma_f32_16x16x32_bf16 v[82:85], v[134:137], v[214:217], v[82:85]
	v_mfma_f32_16x16x32_bf16 v[74:77], v[142:145], v[214:217], v[74:77]
	v_mfma_f32_16x16x32_bf16 v[118:121], v[162:165], v[184:187], v[118:121]
	v_mfma_f32_16x16x32_bf16 v[114:117], v[176:179], v[184:187], v[114:117]
	v_mfma_f32_16x16x32_bf16 v[102:105], v[162:165], v[192:195], v[102:105]
	v_mfma_f32_16x16x32_bf16 v[94:97], v[176:179], v[192:195], v[94:97]
	v_mfma_f32_16x16x32_bf16 v[86:89], v[162:165], v[200:203], v[86:89]
	v_mfma_f32_16x16x32_bf16 v[78:81], v[176:179], v[200:203], v[78:81]
	v_mfma_f32_16x16x32_bf16 v[70:73], v[162:165], v[210:213], v[70:73]
	v_mfma_f32_16x16x32_bf16 v[66:69], v[176:179], v[210:213], v[66:69]
	v_mfma_f32_16x16x32_bf16 v[118:121], v[172:175], v[188:191], v[118:121]
	v_mfma_f32_16x16x32_bf16 v[114:117], v[180:183], v[188:191], v[114:117]
	v_mfma_f32_16x16x32_bf16 v[102:105], v[172:175], v[196:199], v[102:105]
	v_mfma_f32_16x16x32_bf16 v[94:97], v[180:183], v[196:199], v[94:97]
	v_mfma_f32_16x16x32_bf16 v[86:89], v[172:175], v[206:209], v[86:89]
	v_mfma_f32_16x16x32_bf16 v[78:81], v[180:183], v[206:209], v[78:81]
	v_mfma_f32_16x16x32_bf16 v[70:73], v[172:175], v[214:217], v[70:73]
	v_mfma_f32_16x16x32_bf16 v[66:69], v[180:183], v[214:217], v[66:69]
	s_setprio 0
	s_barrier
	ds_read_b128 v[184:187], v170 offset:49152
	ds_read_b128 v[188:191], v170 offset:50176
	ds_read_b128 v[192:195], v170 offset:51200
	ds_read_b128 v[196:199], v170 offset:52224
	ds_read_b128 v[200:203], v170 offset:53248
	ds_read_b128 v[206:209], v170 offset:54272
	ds_read_b128 v[210:213], v170 offset:55296
	ds_read_b128 v[214:217], v170 offset:56320
	s_add_i32 s64, s94, s2
	s_mov_b32 m0, s64
	v_lshl_add_u64 v[218:219], v[218:219], 0, s[16:17]
	global_load_lds_dwordx4 v[218:219], off
	s_add_i32 m0, s64, 0x2000
	s_add_u32 s62, s62, 0x100080
	v_lshl_add_u64 v[218:219], v[220:221], 0, s[16:17]
	s_addc_u32 s63, s63, 0
	s_add_i32 s64, s95, s2
	global_load_lds_dwordx4 v[218:219], off
	v_lshl_add_u64 v[218:219], s[62:63], 0, v[148:149]
	s_mov_b32 m0, s64
	s_nop 0
	global_load_lds_dwordx4 v[218:219], off
	v_lshl_add_u64 v[218:219], s[62:63], 0, v[152:153]
	s_add_i32 m0, s64, 0x2000
	s_nop 0
	global_load_lds_dwordx4 v[218:219], off
	v_lshl_add_u64 v[218:219], v[222:223], 0, s[16:17]
	s_mov_b32 m0, s74
	s_nop 0
	global_load_lds_dwordx4 v[218:219], off
	v_lshl_add_u64 v[218:219], v[224:225], 0, s[16:17]
	s_mov_b32 m0, s75
	s_nop 0
	global_load_lds_dwordx4 v[218:219], off
	s_waitcnt vmcnt(8) lgkmcnt(0)
	s_setprio 1
	s_barrier
	v_mfma_f32_16x16x32_bf16 v[62:65], v[130:133], v[184:187], v[62:65]
	v_mfma_f32_16x16x32_bf16 v[58:61], v[138:141], v[184:187], v[58:61]
	v_mfma_f32_16x16x32_bf16 v[50:53], v[130:133], v[192:195], v[50:53]
	v_mfma_f32_16x16x32_bf16 v[42:45], v[138:141], v[192:195], v[42:45]
	v_mfma_f32_16x16x32_bf16 v[34:37], v[130:133], v[200:203], v[34:37]
	v_mfma_f32_16x16x32_bf16 v[26:29], v[138:141], v[200:203], v[26:29]
	v_mfma_f32_16x16x32_bf16 v[18:21], v[130:133], v[210:213], v[18:21]
	v_mfma_f32_16x16x32_bf16 v[10:13], v[138:141], v[210:213], v[10:13]
	v_mfma_f32_16x16x32_bf16 v[62:65], v[134:137], v[188:191], v[62:65]
	v_mfma_f32_16x16x32_bf16 v[58:61], v[142:145], v[188:191], v[58:61]
	v_mfma_f32_16x16x32_bf16 v[50:53], v[134:137], v[196:199], v[50:53]
	v_mfma_f32_16x16x32_bf16 v[42:45], v[142:145], v[196:199], v[42:45]
	v_mfma_f32_16x16x32_bf16 v[34:37], v[134:137], v[206:209], v[34:37]
	v_mfma_f32_16x16x32_bf16 v[26:29], v[142:145], v[206:209], v[26:29]
	v_mfma_f32_16x16x32_bf16 v[18:21], v[134:137], v[214:217], v[18:21]
	v_mfma_f32_16x16x32_bf16 v[10:13], v[142:145], v[214:217], v[10:13]
	v_mfma_f32_16x16x32_bf16 v[54:57], v[162:165], v[184:187], v[54:57]
	v_mfma_f32_16x16x32_bf16 v[46:49], v[176:179], v[184:187], v[46:49]
	v_mfma_f32_16x16x32_bf16 v[38:41], v[162:165], v[192:195], v[38:41]
	v_mfma_f32_16x16x32_bf16 v[30:33], v[176:179], v[192:195], v[30:33]
	v_mfma_f32_16x16x32_bf16 v[22:25], v[162:165], v[200:203], v[22:25]
	v_mfma_f32_16x16x32_bf16 v[14:17], v[176:179], v[200:203], v[14:17]
	v_mfma_f32_16x16x32_bf16 v[6:9], v[162:165], v[210:213], v[6:9]
	v_mfma_f32_16x16x32_bf16 v[2:5], v[176:179], v[210:213], v[2:5]
	v_mfma_f32_16x16x32_bf16 v[54:57], v[172:175], v[188:191], v[54:57]
	v_mfma_f32_16x16x32_bf16 v[46:49], v[180:183], v[188:191], v[46:49]
	v_mfma_f32_16x16x32_bf16 v[38:41], v[172:175], v[196:199], v[38:41]
	v_mfma_f32_16x16x32_bf16 v[30:33], v[180:183], v[196:199], v[30:33]
	v_mfma_f32_16x16x32_bf16 v[22:25], v[172:175], v[206:209], v[22:25]
	v_mfma_f32_16x16x32_bf16 v[14:17], v[180:183], v[206:209], v[14:17]
	v_mfma_f32_16x16x32_bf16 v[6:9], v[172:175], v[214:217], v[6:9]
	v_mfma_f32_16x16x32_bf16 v[2:5], v[180:183], v[214:217], v[2:5]
	s_setprio 0
	s_barrier
	s_add_u32 s50, s50, 0x100
	s_addc_u32 s51, s51, 0
	s_add_u32 s91, s91, 0x100
	s_addc_u32 s92, s92, 0
	s_cmp_ge_i32 s93, s7
	s_mov_b32 s62, s93
.LBB0_1708:
	ds_read_b128 v[130:133], v168
	ds_read_b128 v[134:137], v168 offset:1024
	ds_read_b128 v[138:141], v168 offset:2048
	ds_read_b128 v[142:145], v168 offset:3072
	ds_read_b128 v[162:165], v169
	ds_read_b128 v[172:175], v169 offset:1024
	ds_read_b128 v[176:179], v169 offset:2048
	ds_read_b128 v[180:183], v169 offset:3072
	ds_read_b128 v[184:187], v170
	ds_read_b128 v[188:191], v170 offset:1024
	ds_read_b128 v[192:195], v170 offset:2048
	ds_read_b128 v[196:199], v170 offset:3072
	ds_read_b128 v[200:203], v170 offset:4096
	ds_read_b128 v[206:209], v170 offset:5120
	ds_read_b128 v[210:213], v170 offset:6144
	ds_read_b128 v[214:217], v170 offset:7168
	s_add_i32 s93, s62, 2
	s_add_u32 s63, s50, 0xfff00080
	s_addc_u32 s64, s51, -1
	s_cmp_eq_u32 s69, s62
	s_cselect_b32 s62, s68, s91
	s_cselect_b32 s65, s34, s64
	s_cselect_b32 s64, s66, s63
	s_cselect_b32 s63, s67, s92
	s_add_i32 m0, s12, 0xc000
	v_lshl_add_u64 v[218:219], s[50:51], 0, v[156:157]
	global_load_lds_dwordx4 v[218:219], off
	v_lshl_add_u64 v[218:219], s[50:51], 0, v[158:159]
	s_add_i32 m0, s12, 0xe000
	s_nop 0
	global_load_lds_dwordx4 v[218:219], off
	s_waitcnt vmcnt(8) lgkmcnt(0)
	s_setprio 1
	s_barrier
	v_mfma_f32_16x16x32_bf16 v[126:129], v[130:133], v[184:187], v[126:129]
	v_mfma_f32_16x16x32_bf16 v[122:125], v[138:141], v[184:187], v[122:125]
	v_mfma_f32_16x16x32_bf16 v[110:113], v[130:133], v[192:195], v[110:113]
	v_mfma_f32_16x16x32_bf16 v[106:109], v[138:141], v[192:195], v[106:109]
	v_mfma_f32_16x16x32_bf16 v[98:101], v[130:133], v[200:203], v[98:101]
	v_mfma_f32_16x16x32_bf16 v[90:93], v[138:141], v[200:203], v[90:93]
	v_mfma_f32_16x16x32_bf16 v[82:85], v[130:133], v[210:213], v[82:85]
	v_mfma_f32_16x16x32_bf16 v[74:77], v[138:141], v[210:213], v[74:77]
	v_mfma_f32_16x16x32_bf16 v[126:129], v[134:137], v[188:191], v[126:129]
	v_mfma_f32_16x16x32_bf16 v[122:125], v[142:145], v[188:191], v[122:125]
	v_mfma_f32_16x16x32_bf16 v[110:113], v[134:137], v[196:199], v[110:113]
	v_mfma_f32_16x16x32_bf16 v[106:109], v[142:145], v[196:199], v[106:109]
	v_mfma_f32_16x16x32_bf16 v[98:101], v[134:137], v[206:209], v[98:101]
	v_mfma_f32_16x16x32_bf16 v[90:93], v[142:145], v[206:209], v[90:93]
	v_mfma_f32_16x16x32_bf16 v[82:85], v[134:137], v[214:217], v[82:85]
	v_mfma_f32_16x16x32_bf16 v[74:77], v[142:145], v[214:217], v[74:77]
	v_mfma_f32_16x16x32_bf16 v[118:121], v[162:165], v[184:187], v[118:121]
	v_mfma_f32_16x16x32_bf16 v[114:117], v[176:179], v[184:187], v[114:117]
	v_mfma_f32_16x16x32_bf16 v[102:105], v[162:165], v[192:195], v[102:105]
	v_mfma_f32_16x16x32_bf16 v[94:97], v[176:179], v[192:195], v[94:97]
	v_mfma_f32_16x16x32_bf16 v[86:89], v[162:165], v[200:203], v[86:89]
	v_mfma_f32_16x16x32_bf16 v[78:81], v[176:179], v[200:203], v[78:81]
	v_mfma_f32_16x16x32_bf16 v[70:73], v[162:165], v[210:213], v[70:73]
	v_mfma_f32_16x16x32_bf16 v[66:69], v[176:179], v[210:213], v[66:69]
	v_mfma_f32_16x16x32_bf16 v[118:121], v[172:175], v[188:191], v[118:121]
	v_mfma_f32_16x16x32_bf16 v[114:117], v[180:183], v[188:191], v[114:117]
	v_mfma_f32_16x16x32_bf16 v[102:105], v[172:175], v[196:199], v[102:105]
	v_mfma_f32_16x16x32_bf16 v[94:97], v[180:183], v[196:199], v[94:97]
	v_mfma_f32_16x16x32_bf16 v[86:89], v[172:175], v[206:209], v[86:89]
	v_mfma_f32_16x16x32_bf16 v[78:81], v[180:183], v[206:209], v[78:81]
	v_mfma_f32_16x16x32_bf16 v[70:73], v[172:175], v[214:217], v[70:73]
	v_mfma_f32_16x16x32_bf16 v[66:69], v[180:183], v[214:217], v[66:69]
	s_setprio 0
	s_barrier
	ds_read_b128 v[184:187], v170 offset:16384
	ds_read_b128 v[188:191], v170 offset:17408
	ds_read_b128 v[192:195], v170 offset:18432
	ds_read_b128 v[196:199], v170 offset:19456
	ds_read_b128 v[200:203], v170 offset:20480
	ds_read_b128 v[206:209], v170 offset:21504
	ds_read_b128 v[210:213], v170 offset:22528
	ds_read_b128 v[214:217], v170 offset:23552
	s_add_i32 s94, s31, s2
	s_mov_b32 m0, s94
	v_lshl_add_u64 v[218:219], s[62:63], 0, v[148:149]
	global_load_lds_dwordx4 v[218:219], off
	s_add_i32 m0, s94, 0x2000
	s_add_u32 s94, s62, 0x100000
	v_lshl_add_u64 v[220:221], s[62:63], 0, v[152:153]
	s_addc_u32 s95, s63, 0
	s_add_i32 s96, s82, s2
	global_load_lds_dwordx4 v[220:221], off
	v_lshl_add_u64 v[222:223], s[94:95], 0, v[148:149]
	s_mov_b32 m0, s96
	v_lshl_add_u64 v[224:225], s[64:65], 0, v[150:151]
	global_load_lds_dwordx4 v[222:223], off
	v_lshl_add_u64 v[222:223], s[94:95], 0, v[152:153]
	s_add_i32 m0, s96, 0x2000
	s_nop 0
	global_load_lds_dwordx4 v[222:223], off
	v_lshl_add_u64 v[222:223], s[64:65], 0, v[146:147]
	s_mov_b32 m0, s12
	s_nop 0
	global_load_lds_dwordx4 v[222:223], off
	s_mov_b32 m0, s13
	s_nop 0
	global_load_lds_dwordx4 v[224:225], off
	s_waitcnt vmcnt(8) lgkmcnt(0)
	s_setprio 1
	s_barrier
	v_mfma_f32_16x16x32_bf16 v[62:65], v[130:133], v[184:187], v[62:65]
	v_mfma_f32_16x16x32_bf16 v[58:61], v[138:141], v[184:187], v[58:61]
	v_mfma_f32_16x16x32_bf16 v[50:53], v[130:133], v[192:195], v[50:53]
	v_mfma_f32_16x16x32_bf16 v[42:45], v[138:141], v[192:195], v[42:45]
	v_mfma_f32_16x16x32_bf16 v[34:37], v[130:133], v[200:203], v[34:37]
	v_mfma_f32_16x16x32_bf16 v[26:29], v[138:141], v[200:203], v[26:29]
	v_mfma_f32_16x16x32_bf16 v[18:21], v[130:133], v[210:213], v[18:21]
	v_mfma_f32_16x16x32_bf16 v[10:13], v[138:141], v[210:213], v[10:13]
	v_mfma_f32_16x16x32_bf16 v[62:65], v[134:137], v[188:191], v[62:65]
	v_mfma_f32_16x16x32_bf16 v[58:61], v[142:145], v[188:191], v[58:61]
	v_mfma_f32_16x16x32_bf16 v[50:53], v[134:137], v[196:199], v[50:53]
	v_mfma_f32_16x16x32_bf16 v[42:45], v[142:145], v[196:199], v[42:45]
	v_mfma_f32_16x16x32_bf16 v[34:37], v[134:137], v[206:209], v[34:37]
	v_mfma_f32_16x16x32_bf16 v[26:29], v[142:145], v[206:209], v[26:29]
	v_mfma_f32_16x16x32_bf16 v[18:21], v[134:137], v[214:217], v[18:21]
	v_mfma_f32_16x16x32_bf16 v[10:13], v[142:145], v[214:217], v[10:13]
	v_mfma_f32_16x16x32_bf16 v[54:57], v[162:165], v[184:187], v[54:57]
	v_mfma_f32_16x16x32_bf16 v[46:49], v[176:179], v[184:187], v[46:49]
	v_mfma_f32_16x16x32_bf16 v[38:41], v[162:165], v[192:195], v[38:41]
	v_mfma_f32_16x16x32_bf16 v[30:33], v[176:179], v[192:195], v[30:33]
	v_mfma_f32_16x16x32_bf16 v[22:25], v[162:165], v[200:203], v[22:25]
	v_mfma_f32_16x16x32_bf16 v[14:17], v[176:179], v[200:203], v[14:17]
	v_mfma_f32_16x16x32_bf16 v[6:9], v[162:165], v[210:213], v[6:9]
	v_mfma_f32_16x16x32_bf16 v[2:5], v[176:179], v[210:213], v[2:5]
	v_mfma_f32_16x16x32_bf16 v[54:57], v[172:175], v[188:191], v[54:57]
	v_mfma_f32_16x16x32_bf16 v[46:49], v[180:183], v[188:191], v[46:49]
	v_mfma_f32_16x16x32_bf16 v[38:41], v[172:175], v[196:199], v[38:41]
	v_mfma_f32_16x16x32_bf16 v[30:33], v[180:183], v[196:199], v[30:33]
	v_mfma_f32_16x16x32_bf16 v[22:25], v[172:175], v[206:209], v[22:25]
	v_mfma_f32_16x16x32_bf16 v[14:17], v[180:183], v[206:209], v[14:17]
	v_mfma_f32_16x16x32_bf16 v[6:9], v[172:175], v[214:217], v[6:9]
	v_mfma_f32_16x16x32_bf16 v[2:5], v[180:183], v[214:217], v[2:5]
	s_setprio 0
	s_barrier
	s_add_i32 s94, 0, 0x18000
	s_add_i32 s95, 0, 0x1c000
	v_add_u32_e32 v142, s94, v167
	v_add_u32_e32 v154, s95, v167
	ds_read_b128 v[130:133], v142
	ds_read_b128 v[134:137], v142 offset:1024
	ds_read_b128 v[138:141], v142 offset:2048
	ds_read_b128 v[142:145], v142 offset:3072
	ds_read_b128 v[162:165], v154
	ds_read_b128 v[172:175], v154 offset:1024
	ds_read_b128 v[176:179], v154 offset:2048
	ds_read_b128 v[180:183], v154 offset:3072
	s_add_u32 s64, s64, 0x100000
	s_addc_u32 s65, s65, 0
	s_mov_b32 m0, s18
	v_lshl_add_u64 v[226:227], s[64:65], 0, v[146:147]
	ds_read_b128 v[184:187], v170 offset:32768
	ds_read_b128 v[188:191], v170 offset:33792
	ds_read_b128 v[192:195], v170 offset:34816
	ds_read_b128 v[196:199], v170 offset:35840
	ds_read_b128 v[200:203], v170 offset:36864
	ds_read_b128 v[206:209], v170 offset:37888
	ds_read_b128 v[210:213], v170 offset:38912
	ds_read_b128 v[214:217], v170 offset:39936
	global_load_lds_dwordx4 v[226:227], off
	v_lshl_add_u64 v[226:227], s[64:65], 0, v[150:151]
	s_mov_b32 m0, s19
	s_nop 0
	global_load_lds_dwordx4 v[226:227], off
	s_waitcnt vmcnt(8) lgkmcnt(0)
	s_setprio 1
	s_barrier
	v_mfma_f32_16x16x32_bf16 v[126:129], v[130:133], v[184:187], v[126:129]
	v_mfma_f32_16x16x32_bf16 v[122:125], v[138:141], v[184:187], v[122:125]
	v_mfma_f32_16x16x32_bf16 v[110:113], v[130:133], v[192:195], v[110:113]
	v_mfma_f32_16x16x32_bf16 v[106:109], v[138:141], v[192:195], v[106:109]
	v_mfma_f32_16x16x32_bf16 v[98:101], v[130:133], v[200:203], v[98:101]
	v_mfma_f32_16x16x32_bf16 v[90:93], v[138:141], v[200:203], v[90:93]
	v_mfma_f32_16x16x32_bf16 v[82:85], v[130:133], v[210:213], v[82:85]
	v_mfma_f32_16x16x32_bf16 v[74:77], v[138:141], v[210:213], v[74:77]
	v_mfma_f32_16x16x32_bf16 v[126:129], v[134:137], v[188:191], v[126:129]
	v_mfma_f32_16x16x32_bf16 v[122:125], v[142:145], v[188:191], v[122:125]
	v_mfma_f32_16x16x32_bf16 v[110:113], v[134:137], v[196:199], v[110:113]
	v_mfma_f32_16x16x32_bf16 v[106:109], v[142:145], v[196:199], v[106:109]
	v_mfma_f32_16x16x32_bf16 v[98:101], v[134:137], v[206:209], v[98:101]
	v_mfma_f32_16x16x32_bf16 v[90:93], v[142:145], v[206:209], v[90:93]
	v_mfma_f32_16x16x32_bf16 v[82:85], v[134:137], v[214:217], v[82:85]
	v_mfma_f32_16x16x32_bf16 v[74:77], v[142:145], v[214:217], v[74:77]
	v_mfma_f32_16x16x32_bf16 v[118:121], v[162:165], v[184:187], v[118:121]
	v_mfma_f32_16x16x32_bf16 v[114:117], v[176:179], v[184:187], v[114:117]
	v_mfma_f32_16x16x32_bf16 v[102:105], v[162:165], v[192:195], v[102:105]
	v_mfma_f32_16x16x32_bf16 v[94:97], v[176:179], v[192:195], v[94:97]
	v_mfma_f32_16x16x32_bf16 v[86:89], v[162:165], v[200:203], v[86:89]
	v_mfma_f32_16x16x32_bf16 v[78:81], v[176:179], v[200:203], v[78:81]
	v_mfma_f32_16x16x32_bf16 v[70:73], v[162:165], v[210:213], v[70:73]
	v_mfma_f32_16x16x32_bf16 v[66:69], v[176:179], v[210:213], v[66:69]
	v_mfma_f32_16x16x32_bf16 v[118:121], v[172:175], v[188:191], v[118:121]
	v_mfma_f32_16x16x32_bf16 v[114:117], v[180:183], v[188:191], v[114:117]
	v_mfma_f32_16x16x32_bf16 v[102:105], v[172:175], v[196:199], v[102:105]
	v_mfma_f32_16x16x32_bf16 v[94:97], v[180:183], v[196:199], v[94:97]
	v_mfma_f32_16x16x32_bf16 v[86:89], v[172:175], v[206:209], v[86:89]
	v_mfma_f32_16x16x32_bf16 v[78:81], v[180:183], v[206:209], v[78:81]
	v_mfma_f32_16x16x32_bf16 v[70:73], v[172:175], v[214:217], v[70:73]
	v_mfma_f32_16x16x32_bf16 v[66:69], v[180:183], v[214:217], v[66:69]
	s_setprio 0
	s_barrier
	ds_read_b128 v[184:187], v170 offset:49152
	ds_read_b128 v[188:191], v170 offset:50176
	ds_read_b128 v[192:195], v170 offset:51200
	ds_read_b128 v[196:199], v170 offset:52224
	ds_read_b128 v[200:203], v170 offset:53248
	ds_read_b128 v[206:209], v170 offset:54272
	ds_read_b128 v[210:213], v170 offset:55296
	ds_read_b128 v[214:217], v170 offset:56320
	s_add_i32 s64, s94, s2
	s_mov_b32 m0, s64
	v_lshl_add_u64 v[218:219], v[218:219], 0, s[16:17]
	global_load_lds_dwordx4 v[218:219], off
	s_add_i32 m0, s64, 0x2000
	s_add_u32 s62, s62, 0x100080
	v_lshl_add_u64 v[218:219], v[220:221], 0, s[16:17]
	s_addc_u32 s63, s63, 0
	s_add_i32 s64, s95, s2
	global_load_lds_dwordx4 v[218:219], off
	v_lshl_add_u64 v[218:219], s[62:63], 0, v[148:149]
	s_mov_b32 m0, s64
	s_nop 0
	global_load_lds_dwordx4 v[218:219], off
	v_lshl_add_u64 v[218:219], s[62:63], 0, v[152:153]
	s_add_i32 m0, s64, 0x2000
	s_nop 0
	global_load_lds_dwordx4 v[218:219], off
	v_lshl_add_u64 v[218:219], v[222:223], 0, s[16:17]
	s_mov_b32 m0, s74
	s_nop 0
	global_load_lds_dwordx4 v[218:219], off
	v_lshl_add_u64 v[218:219], v[224:225], 0, s[16:17]
	s_mov_b32 m0, s75
	s_nop 0
	global_load_lds_dwordx4 v[218:219], off
	s_waitcnt vmcnt(8) lgkmcnt(0)
	s_setprio 1
	s_barrier
	v_mfma_f32_16x16x32_bf16 v[62:65], v[130:133], v[184:187], v[62:65]
	v_mfma_f32_16x16x32_bf16 v[58:61], v[138:141], v[184:187], v[58:61]
	v_mfma_f32_16x16x32_bf16 v[50:53], v[130:133], v[192:195], v[50:53]
	v_mfma_f32_16x16x32_bf16 v[42:45], v[138:141], v[192:195], v[42:45]
	v_mfma_f32_16x16x32_bf16 v[34:37], v[130:133], v[200:203], v[34:37]
	v_mfma_f32_16x16x32_bf16 v[26:29], v[138:141], v[200:203], v[26:29]
	v_mfma_f32_16x16x32_bf16 v[18:21], v[130:133], v[210:213], v[18:21]
	v_mfma_f32_16x16x32_bf16 v[10:13], v[138:141], v[210:213], v[10:13]
	v_mfma_f32_16x16x32_bf16 v[62:65], v[134:137], v[188:191], v[62:65]
	v_mfma_f32_16x16x32_bf16 v[58:61], v[142:145], v[188:191], v[58:61]
	v_mfma_f32_16x16x32_bf16 v[50:53], v[134:137], v[196:199], v[50:53]
	v_mfma_f32_16x16x32_bf16 v[42:45], v[142:145], v[196:199], v[42:45]
	v_mfma_f32_16x16x32_bf16 v[34:37], v[134:137], v[206:209], v[34:37]
	v_mfma_f32_16x16x32_bf16 v[26:29], v[142:145], v[206:209], v[26:29]
	v_mfma_f32_16x16x32_bf16 v[18:21], v[134:137], v[214:217], v[18:21]
	v_mfma_f32_16x16x32_bf16 v[10:13], v[142:145], v[214:217], v[10:13]
	v_mfma_f32_16x16x32_bf16 v[54:57], v[162:165], v[184:187], v[54:57]
	v_mfma_f32_16x16x32_bf16 v[46:49], v[176:179], v[184:187], v[46:49]
	v_mfma_f32_16x16x32_bf16 v[38:41], v[162:165], v[192:195], v[38:41]
	v_mfma_f32_16x16x32_bf16 v[30:33], v[176:179], v[192:195], v[30:33]
	v_mfma_f32_16x16x32_bf16 v[22:25], v[162:165], v[200:203], v[22:25]
	v_mfma_f32_16x16x32_bf16 v[14:17], v[176:179], v[200:203], v[14:17]
	v_mfma_f32_16x16x32_bf16 v[6:9], v[162:165], v[210:213], v[6:9]
	v_mfma_f32_16x16x32_bf16 v[2:5], v[176:179], v[210:213], v[2:5]
	v_mfma_f32_16x16x32_bf16 v[54:57], v[172:175], v[188:191], v[54:57]
	v_mfma_f32_16x16x32_bf16 v[46:49], v[180:183], v[188:191], v[46:49]
	v_mfma_f32_16x16x32_bf16 v[38:41], v[172:175], v[196:199], v[38:41]
	v_mfma_f32_16x16x32_bf16 v[30:33], v[180:183], v[196:199], v[30:33]
	v_mfma_f32_16x16x32_bf16 v[22:25], v[172:175], v[206:209], v[22:25]
	v_mfma_f32_16x16x32_bf16 v[14:17], v[180:183], v[206:209], v[14:17]
	v_mfma_f32_16x16x32_bf16 v[6:9], v[172:175], v[214:217], v[6:9]
	v_mfma_f32_16x16x32_bf16 v[2:5], v[180:183], v[214:217], v[2:5]
	s_setprio 0
	s_barrier
	s_add_u32 s50, s50, 0x100
	s_addc_u32 s51, s51, 0
	s_add_u32 s91, s91, 0x100
	s_addc_u32 s92, s92, 0
	s_cmp_ge_i32 s93, s7
	s_mov_b32 s62, s93
	s_cbranch_scc0 .LBB0_1708
	s_and_b64 vcc, exec, s[20:21]
	s_cbranch_vccz .LBB0_1711
	s_barrier
